# v30 + every packed f32 op (v_pk_mul/add/fma_f32, 973 sites) split into its two scalar ops (same IEEE f32 results)
# speedup vs baseline: 1.0204x; 1.0019x over previous
.LBB0_18:
	s_mul_hi_i32 s2, s53, 0x3e0f83e1
	s_lshr_b32 s4, s2, 31
	s_ashr_i32 s2, s2, 11
	s_add_i32 s14, s2, s4
	s_mul_i32 s2, s14, 0xffffdf00
	s_add_i32 s2, s53, s2
	s_mul_i32 s4, s2, 0x3e1
	s_lshr_b32 s5, s4, 31
	s_ashr_i32 s55, s4, 22
	s_add_i32 s55, s55, s5
	s_mul_i32 s4, s55, 0x1080
	s_sub_i32 s4, s2, s4
	s_sext_i32_i16 s5, s4
	s_mulk_i32 s5, 0xba3
	s_lshr_b32 s6, s5, 31
	s_ashr_i32 s54, s5, 22
	s_add_i32 s54, s54, s6
	s_mul_i32 s5, s54, 0x580
	s_sub_i32 s9, s4, s5
	s_ashr_i32 s15, s14, 31
	s_addk_i32 s2, 0x107f
	s_cmpk_lt_u32 s2, 0x20ff
	s_cselect_b64 s[4:5], -1, 0
	s_and_b64 s[6:7], s[4:5], exec
	s_cselect_b32 s2, 8, 48
	s_add_u32 s16, s12, s2
	s_addc_u32 s17, s13, 0
	s_and_b64 s[4:5], s[4:5], exec
	s_cselect_b32 s2, 2, 7
	s_add_i32 s2, s2, s54
	s_lshl_b64 s[4:5], s[2:3], 3
	s_add_u32 s4, s12, s4
	s_addc_u32 s5, s13, s5
	s_load_dwordx2 s[4:5], s[4:5], 0x0
	s_mul_i32 s6, s14, 0xb00000
	s_mul_hi_i32 s2, s14, 0xb00000
	s_waitcnt lgkmcnt(0)
	s_add_u32 s56, s4, s6
	s_addc_u32 s57, s5, s2
	s_sext_i32_i16 s2, s9
	s_mulk_i32 s2, 0xba3
	s_lshr_b32 s4, s2, 31
	s_ashr_i32 s2, s2, 18
	s_add_i32 s4, s2, s4
	s_mul_i32 s2, s4, 0x58
	s_lshl_b32 s4, s4, 6
	s_sub_i32 s2, s9, s2
	v_or_b32_e32 v6, s4, v45
	s_sext_i32_i16 s5, s2
	v_mul_i32_i24_e32 v6, 0xb00, v6
	s_lshl_b32 s6, s5, 5
	v_ashrrev_i32_e32 v7, 31, v6
	v_lshl_add_u64 v[6:7], v[6:7], 2, s[56:57]
	s_ashr_i32 s7, s6, 31
	v_lshl_add_u64 v[6:7], s[6:7], 2, v[6:7]
	v_lshl_add_u64 v[30:31], v[6:7], 0, v[4:5]
	v_add_co_u32_e32 v8, vcc, s18, v30
	s_ashr_i32 s5, s4, 31
	s_nop 0
	v_addc_co_u32_e32 v9, vcc, 0, v31, vcc
	v_add_co_u32_e32 v10, vcc, s19, v30
	s_nop 1
	v_addc_co_u32_e32 v11, vcc, 0, v31, vcc
	v_add_co_u32_e32 v12, vcc, s24, v30
	s_nop 1
	v_addc_co_u32_e32 v13, vcc, 0, v31, vcc
	v_add_co_u32_e32 v14, vcc, s25, v30
	s_nop 1
	v_addc_co_u32_e32 v15, vcc, 0, v31, vcc
	v_add_co_u32_e32 v16, vcc, s26, v30
	s_nop 1
	v_addc_co_u32_e32 v17, vcc, 0, v31, vcc
	v_add_co_u32_e32 v18, vcc, s27, v30
	s_nop 1
	v_addc_co_u32_e32 v19, vcc, 0, v31, vcc
	v_add_co_u32_e32 v20, vcc, s28, v30
	s_nop 1
	v_addc_co_u32_e32 v21, vcc, 0, v31, vcc
	global_load_dword v6, v[30:31], off
	global_load_dword v7, v[8:9], off offset:2048
	s_nop 0
	global_load_dword v10, v[10:11], off
	s_nop 0
	global_load_dword v11, v[12:13], off offset:2048
	global_load_dword v8, v[14:15], off
	global_load_dword v9, v[16:17], off offset:2048
	s_nop 0
	global_load_dword v12, v[18:19], off
	global_load_dword v13, v[20:21], off offset:2048
	v_add_co_u32_e32 v14, vcc, s29, v30
	s_nop 1
	v_addc_co_u32_e32 v15, vcc, 0, v31, vcc
	v_add_co_u32_e32 v16, vcc, s30, v30
	s_nop 1
	v_addc_co_u32_e32 v17, vcc, 0, v31, vcc
	v_add_co_u32_e32 v18, vcc, s31, v30
	s_nop 1
	v_addc_co_u32_e32 v19, vcc, 0, v31, vcc
	v_add_co_u32_e32 v20, vcc, s34, v30
	s_nop 1
	v_addc_co_u32_e32 v21, vcc, 0, v31, vcc
	v_add_co_u32_e32 v22, vcc, s35, v30
	s_nop 1
	v_addc_co_u32_e32 v23, vcc, 0, v31, vcc
	v_add_co_u32_e32 v24, vcc, s36, v30
	s_nop 1
	v_addc_co_u32_e32 v25, vcc, 0, v31, vcc
	v_add_co_u32_e32 v26, vcc, s37, v30
	s_nop 1
	v_addc_co_u32_e32 v27, vcc, 0, v31, vcc
	v_add_co_u32_e32 v28, vcc, s38, v30
	s_nop 1
	v_addc_co_u32_e32 v29, vcc, 0, v31, vcc
	global_load_dword v14, v[14:15], off
	s_nop 0
	global_load_dword v15, v[16:17], off offset:2048
	s_nop 0
	global_load_dword v18, v[18:19], off
	s_nop 0
	global_load_dword v19, v[20:21], off offset:2048
	global_load_dword v16, v[22:23], off
	global_load_dword v17, v[24:25], off offset:2048
	s_nop 0
	global_load_dword v20, v[26:27], off
	global_load_dword v21, v[28:29], off offset:2048
	v_add_co_u32_e32 v22, vcc, s39, v30
	s_nop 1
	v_addc_co_u32_e32 v23, vcc, 0, v31, vcc
	v_add_co_u32_e32 v24, vcc, s40, v30
	s_nop 1
	v_addc_co_u32_e32 v25, vcc, 0, v31, vcc
	v_add_co_u32_e32 v26, vcc, s41, v30
	s_nop 1
	v_addc_co_u32_e32 v27, vcc, 0, v31, vcc
	v_add_co_u32_e32 v28, vcc, s42, v30
	s_nop 1
	v_addc_co_u32_e32 v29, vcc, 0, v31, vcc
	v_add_co_u32_e32 v32, vcc, s43, v30
	s_nop 1
	v_addc_co_u32_e32 v33, vcc, 0, v31, vcc
	v_add_co_u32_e32 v34, vcc, s44, v30
	s_nop 1
	v_addc_co_u32_e32 v35, vcc, 0, v31, vcc
	v_add_co_u32_e32 v36, vcc, s45, v30
	s_nop 1
	v_addc_co_u32_e32 v37, vcc, 0, v31, vcc
	v_add_co_u32_e32 v40, vcc, s46, v30
	s_nop 1
	v_addc_co_u32_e32 v41, vcc, 0, v31, vcc
	global_load_dword v22, v[22:23], off
	s_nop 0
	global_load_dword v23, v[24:25], off offset:2048
	s_nop 0
	global_load_dword v26, v[26:27], off
	s_nop 0
	global_load_dword v27, v[28:29], off offset:2048
	global_load_dword v24, v[32:33], off
	global_load_dword v25, v[34:35], off offset:2048
	s_nop 0
	global_load_dword v28, v[36:37], off
	global_load_dword v29, v[40:41], off offset:2048
	v_add_co_u32_e32 v32, vcc, s47, v30
	s_nop 1
	v_addc_co_u32_e32 v33, vcc, 0, v31, vcc
	v_add_co_u32_e32 v34, vcc, s48, v30
	s_nop 1
	v_addc_co_u32_e32 v35, vcc, 0, v31, vcc
	v_add_co_u32_e32 v36, vcc, s49, v30
	s_nop 1
	v_addc_co_u32_e32 v37, vcc, 0, v31, vcc
	v_add_co_u32_e32 v40, vcc, s50, v30
	s_nop 1
	v_addc_co_u32_e32 v41, vcc, 0, v31, vcc
	v_add_co_u32_e32 v42, vcc, s51, v30
	s_nop 1
	v_addc_co_u32_e32 v43, vcc, 0, v31, vcc
	v_add_co_u32_e32 v52, vcc, s52, v30
	s_nop 1
	v_addc_co_u32_e32 v53, vcc, 0, v31, vcc
	v_add_co_u32_e32 v54, vcc, 0xa5000, v30
	s_nop 1
	v_addc_co_u32_e32 v55, vcc, 0, v31, vcc
	v_add_co_u32_e32 v56, vcc, 0xaa000, v30
	s_nop 1
	v_addc_co_u32_e32 v57, vcc, 0, v31, vcc
	global_load_dword v30, v[32:33], off
	global_load_dword v31, v[34:35], off offset:2048
	s_nop 0
	global_load_dword v36, v[36:37], off
	s_nop 0
	global_load_dword v37, v[40:41], off offset:2048
	global_load_dword v34, v[42:43], off
	global_load_dword v35, v[52:53], off offset:2048
	global_load_dword v32, v[54:55], off
	global_load_dword v33, v[56:57], off offset:2048
	s_load_dwordx2 s[16:17], s[16:17], 0x0
	s_waitcnt lgkmcnt(0)
	s_cmp_eq_u64 s[16:17], 0
	s_cbranch_scc1 .LBB0_17
	s_lshl_b64 s[56:57], s[14:15], 12
	s_add_u32 s7, s16, s56
	s_addc_u32 s9, s17, s57
	s_lshl_b64 s[16:17], s[4:5], 2
	s_add_u32 s16, s7, s16
	s_addc_u32 s17, s9, s17
	v_lshlrev_b32_e32 v39, 2, v45
	global_load_dword v40, v39, s[16:17]
	global_load_dword v41, v39, s[16:17] offset:8
	global_load_dword v42, v39, s[16:17] offset:16
	global_load_dword v43, v39, s[16:17] offset:24
	global_load_dword v52, v39, s[16:17] offset:32
	global_load_dword v53, v39, s[16:17] offset:40
	global_load_dword v54, v39, s[16:17] offset:48
	global_load_dword v55, v39, s[16:17] offset:56
	global_load_dword v56, v39, s[16:17] offset:64
	global_load_dword v57, v39, s[16:17] offset:72
	global_load_dword v58, v39, s[16:17] offset:80
	global_load_dword v59, v39, s[16:17] offset:88
	global_load_dword v60, v39, s[16:17] offset:96
	global_load_dword v61, v39, s[16:17] offset:104
	global_load_dword v62, v39, s[16:17] offset:112
	global_load_dword v63, v39, s[16:17] offset:120
	global_load_dword v64, v39, s[16:17] offset:128
	global_load_dword v65, v39, s[16:17] offset:136
	global_load_dword v66, v39, s[16:17] offset:144
	global_load_dword v67, v39, s[16:17] offset:152
	global_load_dword v68, v39, s[16:17] offset:160
	global_load_dword v69, v39, s[16:17] offset:168
	global_load_dword v70, v39, s[16:17] offset:176
	global_load_dword v71, v39, s[16:17] offset:184
	global_load_dword v72, v39, s[16:17] offset:192
	global_load_dword v73, v39, s[16:17] offset:200
	global_load_dword v74, v39, s[16:17] offset:208
	global_load_dword v75, v39, s[16:17] offset:216
	global_load_dword v76, v39, s[16:17] offset:224
	global_load_dword v77, v39, s[16:17] offset:232
	global_load_dword v78, v39, s[16:17] offset:240
	global_load_dword v79, v39, s[16:17] offset:248
	s_waitcnt vmcnt(30)
	v_mul_f32_e64 v6, v6, v40
	v_mul_f32_e64 v7, v7, v41
	s_waitcnt vmcnt(28)
	v_mul_f32_e64 v10, v10, v42
	v_mul_f32_e64 v11, v11, v43
	s_waitcnt vmcnt(26)
	v_mul_f32_e64 v8, v8, v52
	v_mul_f32_e64 v9, v9, v53
	s_waitcnt vmcnt(24)
	v_mul_f32_e64 v12, v12, v54
	v_mul_f32_e64 v13, v13, v55
	s_waitcnt vmcnt(22)
	v_mul_f32_e64 v14, v14, v56
	v_mul_f32_e64 v15, v15, v57
	s_waitcnt vmcnt(20)
	v_mul_f32_e64 v18, v18, v58
	v_mul_f32_e64 v19, v19, v59
	s_waitcnt vmcnt(18)
	v_mul_f32_e64 v16, v16, v60
	v_mul_f32_e64 v17, v17, v61
	s_waitcnt vmcnt(16)
	v_mul_f32_e64 v20, v20, v62
	v_mul_f32_e64 v21, v21, v63
	s_waitcnt vmcnt(14)
	v_mul_f32_e64 v22, v22, v64
	v_mul_f32_e64 v23, v23, v65
	s_waitcnt vmcnt(12)
	v_mul_f32_e64 v26, v26, v66
	v_mul_f32_e64 v27, v27, v67
	s_waitcnt vmcnt(10)
	v_mul_f32_e64 v24, v24, v68
	v_mul_f32_e64 v25, v25, v69
	s_waitcnt vmcnt(8)
	v_mul_f32_e64 v28, v28, v70
	v_mul_f32_e64 v29, v29, v71
	s_waitcnt vmcnt(6)
	v_mul_f32_e64 v30, v30, v72
	v_mul_f32_e64 v31, v31, v73
	s_waitcnt vmcnt(4)
	v_mul_f32_e64 v36, v36, v74
	v_mul_f32_e64 v37, v37, v75
	s_waitcnt vmcnt(2)
	v_mul_f32_e64 v34, v34, v76
	v_mul_f32_e64 v35, v35, v77
	s_waitcnt vmcnt(0)
	v_mul_f32_e64 v32, v32, v78
	v_mul_f32_e64 v33, v33, v79
	s_branch .LBB0_17

.LBB0_29:
	s_andn2_b64 vcc, exec, s[4:5]
	s_cbranch_vccnz .LBB0_33
	s_load_dwordx4 s[4:7], s[12:13], 0x68
	s_and_b32 s9, s25, 0x7c0
	s_addk_i32 s9, 0xfa40
	v_or_b32_e32 v12, s9, v45
	v_mov_b32_e32 v13, v5
	s_and_b32 s14, s27, 0x3e0
	v_lshlrev_b64 v[12:13], 12, v[12:13]
	s_waitcnt lgkmcnt(0)
	v_lshl_add_u64 v[12:13], s[6:7], 0, v[12:13]
	s_lshl_b32 s14, s14, 2
	v_lshl_add_u64 v[12:13], v[12:13], 0, s[14:15]
	v_lshl_add_u64 v[36:37], v[12:13], 0, v[4:5]
	v_add_co_u32_e32 v14, vcc, s31, v36
	s_cmp_eq_u64 s[4:5], 0
	s_nop 0
	v_addc_co_u32_e32 v15, vcc, 0, v37, vcc
	v_add_co_u32_e32 v16, vcc, s34, v36
	s_mov_b32 s14, s9
	s_nop 0
	v_addc_co_u32_e32 v17, vcc, 0, v37, vcc
	v_add_co_u32_e32 v18, vcc, s35, v36
	s_nop 1
	v_addc_co_u32_e32 v19, vcc, 0, v37, vcc
	v_add_co_u32_e32 v20, vcc, s36, v36
	s_nop 1
	v_addc_co_u32_e32 v21, vcc, 0, v37, vcc
	v_add_co_u32_e32 v22, vcc, s37, v36
	s_nop 1
	v_addc_co_u32_e32 v23, vcc, 0, v37, vcc
	v_add_co_u32_e32 v24, vcc, s38, v36
	s_nop 1
	v_addc_co_u32_e32 v25, vcc, 0, v37, vcc
	v_add_co_u32_e32 v26, vcc, s39, v36
	s_nop 1
	v_addc_co_u32_e32 v27, vcc, 0, v37, vcc
	global_load_dword v12, v[36:37], off
	global_load_dword v13, v[14:15], off
	s_nop 0
	global_load_dword v14, v[16:17], off
	global_load_dword v15, v[18:19], off
	s_nop 0
	global_load_dword v16, v[20:21], off
	global_load_dword v17, v[22:23], off
	global_load_dword v18, v[24:25], off
	global_load_dword v19, v[26:27], off
	v_add_co_u32_e32 v20, vcc, s40, v36
	s_nop 1
	v_addc_co_u32_e32 v21, vcc, 0, v37, vcc
	v_add_co_u32_e32 v22, vcc, s41, v36
	s_nop 1
	v_addc_co_u32_e32 v23, vcc, 0, v37, vcc
	v_add_co_u32_e32 v24, vcc, s42, v36
	s_nop 1
	v_addc_co_u32_e32 v25, vcc, 0, v37, vcc
	v_add_co_u32_e32 v26, vcc, s43, v36
	s_nop 1
	v_addc_co_u32_e32 v27, vcc, 0, v37, vcc
	v_add_co_u32_e32 v28, vcc, s44, v36
	s_nop 1
	v_addc_co_u32_e32 v29, vcc, 0, v37, vcc
	v_add_co_u32_e32 v30, vcc, s45, v36
	s_nop 1
	v_addc_co_u32_e32 v31, vcc, 0, v37, vcc
	v_add_co_u32_e32 v32, vcc, s46, v36
	s_nop 1
	v_addc_co_u32_e32 v33, vcc, 0, v37, vcc
	v_add_co_u32_e32 v34, vcc, s47, v36
	s_nop 1
	v_addc_co_u32_e32 v35, vcc, 0, v37, vcc
	global_load_dword v20, v[20:21], off
	s_nop 0
	global_load_dword v21, v[22:23], off
	s_nop 0
	global_load_dword v22, v[24:25], off
	global_load_dword v23, v[26:27], off
	s_nop 0
	global_load_dword v24, v[28:29], off
	global_load_dword v25, v[30:31], off
	global_load_dword v26, v[32:33], off
	global_load_dword v27, v[34:35], off
	v_add_co_u32_e32 v28, vcc, s48, v36
	s_nop 1
	v_addc_co_u32_e32 v29, vcc, 0, v37, vcc
	v_add_co_u32_e32 v30, vcc, s49, v36
	s_nop 1
	v_addc_co_u32_e32 v31, vcc, 0, v37, vcc
	v_add_co_u32_e32 v32, vcc, s50, v36
	s_nop 1
	v_addc_co_u32_e32 v33, vcc, 0, v37, vcc
	v_add_co_u32_e32 v34, vcc, s51, v36
	s_nop 1
	v_addc_co_u32_e32 v35, vcc, 0, v37, vcc
	v_add_co_u32_e32 v38, vcc, s52, v36
	s_nop 1
	v_addc_co_u32_e32 v39, vcc, 0, v37, vcc
	v_add_co_u32_e32 v40, vcc, s53, v36
	s_nop 1
	v_addc_co_u32_e32 v41, vcc, 0, v37, vcc
	v_add_co_u32_e32 v42, vcc, s54, v36
	s_nop 1
	v_addc_co_u32_e32 v43, vcc, 0, v37, vcc
	v_add_co_u32_e32 v60, vcc, s55, v36
	s_nop 1
	v_addc_co_u32_e32 v61, vcc, 0, v37, vcc
	global_load_dword v28, v[28:29], off
	s_nop 0
	global_load_dword v29, v[30:31], off
	s_nop 0
	global_load_dword v30, v[32:33], off
	global_load_dword v31, v[34:35], off
	s_nop 0
	global_load_dword v32, v[38:39], off
	global_load_dword v33, v[40:41], off
	global_load_dword v34, v[42:43], off
	global_load_dword v35, v[60:61], off
	v_add_co_u32_e32 v38, vcc, s56, v36
	s_nop 1
	v_addc_co_u32_e32 v39, vcc, 0, v37, vcc
	v_add_co_u32_e32 v40, vcc, s57, v36
	s_nop 1
	v_addc_co_u32_e32 v41, vcc, 0, v37, vcc
	v_add_co_u32_e32 v42, vcc, s58, v36
	s_nop 1
	v_addc_co_u32_e32 v43, vcc, 0, v37, vcc
	v_add_co_u32_e32 v60, vcc, s59, v36
	s_nop 1
	v_addc_co_u32_e32 v61, vcc, 0, v37, vcc
	v_add_co_u32_e32 v62, vcc, s60, v36
	s_nop 1
	v_addc_co_u32_e32 v63, vcc, 0, v37, vcc
	v_add_co_u32_e32 v64, vcc, 0x3a000, v36
	s_nop 1
	v_addc_co_u32_e32 v65, vcc, 0, v37, vcc
	v_add_co_u32_e32 v66, vcc, 0x3c000, v36
	s_nop 1
	v_addc_co_u32_e32 v67, vcc, 0, v37, vcc
	v_add_co_u32_e32 v68, vcc, 0x3e000, v36
	s_nop 1
	v_addc_co_u32_e32 v69, vcc, 0, v37, vcc
	global_load_dword v36, v[38:39], off
	global_load_dword v37, v[40:41], off
	s_nop 0
	global_load_dword v38, v[42:43], off
	global_load_dword v39, v[60:61], off
	s_nop 0
	global_load_dword v42, v[62:63], off
	global_load_dword v43, v[64:65], off
	global_load_dword v40, v[66:67], off
	global_load_dword v41, v[68:69], off
	s_cbranch_scc1 .LBB0_32
	s_lshl_b64 s[6:7], s[14:15], 2
	s_add_u32 s4, s4, s6
	s_addc_u32 s5, s5, s7
	v_lshlrev_b32_e32 v3, 2, v45
	global_load_dword v60, v3, s[4:5]
	global_load_dword v61, v3, s[4:5] offset:8
	global_load_dword v62, v3, s[4:5] offset:16
	global_load_dword v63, v3, s[4:5] offset:24
	global_load_dword v64, v3, s[4:5] offset:32
	global_load_dword v65, v3, s[4:5] offset:40
	global_load_dword v66, v3, s[4:5] offset:48
	global_load_dword v67, v3, s[4:5] offset:56
	global_load_dword v68, v3, s[4:5] offset:64
	global_load_dword v69, v3, s[4:5] offset:72
	global_load_dword v70, v3, s[4:5] offset:80
	global_load_dword v71, v3, s[4:5] offset:88
	global_load_dword v72, v3, s[4:5] offset:96
	global_load_dword v73, v3, s[4:5] offset:104
	global_load_dword v74, v3, s[4:5] offset:112
	global_load_dword v75, v3, s[4:5] offset:120
	global_load_dword v76, v3, s[4:5] offset:128
	global_load_dword v77, v3, s[4:5] offset:136
	global_load_dword v78, v3, s[4:5] offset:144
	global_load_dword v79, v3, s[4:5] offset:152
	global_load_dword v80, v3, s[4:5] offset:160
	global_load_dword v81, v3, s[4:5] offset:168
	global_load_dword v82, v3, s[4:5] offset:176
	global_load_dword v83, v3, s[4:5] offset:184
	global_load_dword v84, v3, s[4:5] offset:192
	global_load_dword v85, v3, s[4:5] offset:200
	global_load_dword v86, v3, s[4:5] offset:208
	global_load_dword v87, v3, s[4:5] offset:216
	global_load_dword v88, v3, s[4:5] offset:224
	global_load_dword v89, v3, s[4:5] offset:232
	global_load_dword v90, v3, s[4:5] offset:240
	global_load_dword v91, v3, s[4:5] offset:248
	s_waitcnt vmcnt(30)
	v_mul_f32_e64 v12, v12, v60
	v_mul_f32_e64 v13, v13, v61
	s_waitcnt vmcnt(28)
	v_mul_f32_e64 v14, v14, v62
	v_mul_f32_e64 v15, v15, v63
	s_waitcnt vmcnt(26)
	v_mul_f32_e64 v16, v16, v64
	v_mul_f32_e64 v17, v17, v65
	s_waitcnt vmcnt(24)
	v_mul_f32_e64 v18, v18, v66
	v_mul_f32_e64 v19, v19, v67
	s_waitcnt vmcnt(22)
	v_mul_f32_e64 v20, v20, v68
	v_mul_f32_e64 v21, v21, v69
	s_waitcnt vmcnt(20)
	v_mul_f32_e64 v22, v22, v70
	v_mul_f32_e64 v23, v23, v71
	s_waitcnt vmcnt(18)
	v_mul_f32_e64 v24, v24, v72
	v_mul_f32_e64 v25, v25, v73
	s_waitcnt vmcnt(16)
	v_mul_f32_e64 v26, v26, v74
	v_mul_f32_e64 v27, v27, v75
	s_waitcnt vmcnt(14)
	v_mul_f32_e64 v28, v28, v76
	v_mul_f32_e64 v29, v29, v77
	s_waitcnt vmcnt(12)
	v_mul_f32_e64 v30, v30, v78
	v_mul_f32_e64 v31, v31, v79
	s_waitcnt vmcnt(10)
	v_mul_f32_e64 v32, v32, v80
	v_mul_f32_e64 v33, v33, v81
	s_waitcnt vmcnt(8)
	v_mul_f32_e64 v34, v34, v82
	v_mul_f32_e64 v35, v35, v83
	s_waitcnt vmcnt(6)
	v_mul_f32_e64 v36, v36, v84
	v_mul_f32_e64 v37, v37, v85
	s_waitcnt vmcnt(4)
	v_mul_f32_e64 v38, v38, v86
	v_mul_f32_e64 v39, v39, v87
	s_waitcnt vmcnt(2)
	v_mul_f32_e64 v42, v42, v88
	v_mul_f32_e64 v43, v43, v89
	s_waitcnt vmcnt(0)
	v_mul_f32_e64 v40, v40, v90
	v_mul_f32_e64 v41, v41, v91

.LBB0_34:
	s_andn2_b64 vcc, exec, s[4:5]
	s_cbranch_vccnz .LBB0_38
	s_add_i32 s4, s22, 0xffb0
	s_and_b32 s5, s4, 0xff
	s_mulk_i32 s5, 0xab
	s_bfe_u32 s9, s5, 0x4000c
	s_mul_i32 s5, s9, 24
	s_sub_i32 s4, s4, s5
	s_and_b32 s17, s4, 0xff
	s_load_dwordx4 s[4:7], s[12:13], 0x58
	s_lshl_b32 s18, s9, 6
	v_or_b32_e32 v3, s18, v45
	v_mul_u32_u24_e32 v3, 0x300, v3
	v_lshlrev_b32_e32 v12, 2, v3
	v_mov_b32_e32 v13, v5
	s_waitcnt lgkmcnt(0)
	v_lshl_add_u64 v[12:13], s[6:7], 0, v[12:13]
	s_lshl_b32 s14, s17, 7
	v_lshl_add_u64 v[12:13], v[12:13], 0, s[14:15]
	v_lshl_add_u64 v[36:37], v[12:13], 0, v[4:5]
	s_movk_i32 s6, 0x1000
	v_add_co_u32_e32 v14, vcc, s6, v36
	s_movk_i32 s6, 0x3000
	s_nop 0
	v_addc_co_u32_e32 v15, vcc, 0, v37, vcc
	v_add_co_u32_e32 v16, vcc, s6, v36
	s_movk_i32 s6, 0x7000
	s_nop 0
	v_addc_co_u32_e32 v17, vcc, 0, v37, vcc
	v_add_co_u32_e32 v18, vcc, s34, v36
	s_cmp_eq_u64 s[4:5], 0
	s_nop 0
	v_addc_co_u32_e32 v19, vcc, 0, v37, vcc
	v_add_co_u32_e32 v20, vcc, s35, v36
	s_nop 1
	v_addc_co_u32_e32 v21, vcc, 0, v37, vcc
	v_add_co_u32_e32 v22, vcc, s6, v36
	s_mov_b32 s6, 0xf000
	s_nop 0
	v_addc_co_u32_e32 v23, vcc, 0, v37, vcc
	v_add_co_u32_e32 v24, vcc, s64, v36
	s_nop 1
	v_addc_co_u32_e32 v25, vcc, 0, v37, vcc
	v_add_co_u32_e32 v26, vcc, s37, v36
	s_nop 1
	v_addc_co_u32_e32 v27, vcc, 0, v37, vcc
	global_load_dword v12, v[36:37], off
	global_load_dword v13, v[14:15], off offset:2048
	s_nop 0
	global_load_dword v14, v[16:17], off
	global_load_dword v15, v[18:19], off offset:2048
	s_nop 0
	global_load_dword v16, v[20:21], off
	global_load_dword v17, v[22:23], off offset:2048
	global_load_dword v18, v[24:25], off
	global_load_dword v19, v[26:27], off offset:2048
	v_add_co_u32_e32 v20, vcc, s38, v36
	s_nop 1
	v_addc_co_u32_e32 v21, vcc, 0, v37, vcc
	v_add_co_u32_e32 v22, vcc, s65, v36
	s_nop 1
	v_addc_co_u32_e32 v23, vcc, 0, v37, vcc
	v_add_co_u32_e32 v24, vcc, s6, v36
	s_mov_b32 s6, 0x13000
	s_nop 0
	v_addc_co_u32_e32 v25, vcc, 0, v37, vcc
	v_add_co_u32_e32 v26, vcc, s40, v36
	s_nop 1
	v_addc_co_u32_e32 v27, vcc, 0, v37, vcc
	v_add_co_u32_e32 v28, vcc, s41, v36
	s_nop 1
	v_addc_co_u32_e32 v29, vcc, 0, v37, vcc
	v_add_co_u32_e32 v30, vcc, s6, v36
	s_mov_b32 s6, 0x15000
	s_nop 0
	v_addc_co_u32_e32 v31, vcc, 0, v37, vcc
	v_add_co_u32_e32 v32, vcc, s6, v36
	s_mov_b32 s6, 0x1f000
	s_nop 0
	v_addc_co_u32_e32 v33, vcc, 0, v37, vcc
	v_add_co_u32_e32 v34, vcc, s43, v36
	s_nop 1
	v_addc_co_u32_e32 v35, vcc, 0, v37, vcc
	global_load_dword v20, v[20:21], off
	s_nop 0
	global_load_dword v21, v[22:23], off offset:2048
	s_nop 0
	global_load_dword v22, v[24:25], off
	global_load_dword v23, v[26:27], off offset:2048
	s_nop 0
	global_load_dword v24, v[28:29], off
	global_load_dword v25, v[30:31], off offset:2048
	global_load_dword v26, v[32:33], off
	global_load_dword v27, v[34:35], off offset:2048
	v_add_co_u32_e32 v28, vcc, s44, v36
	s_nop 1
	v_addc_co_u32_e32 v29, vcc, 0, v37, vcc
	v_add_co_u32_e32 v30, vcc, s66, v36
	s_nop 1
	v_addc_co_u32_e32 v31, vcc, 0, v37, vcc
	v_add_co_u32_e32 v32, vcc, s67, v36
	s_nop 1
	v_addc_co_u32_e32 v33, vcc, 0, v37, vcc
	v_add_co_u32_e32 v34, vcc, s46, v36
	s_nop 1
	v_addc_co_u32_e32 v35, vcc, 0, v37, vcc
	v_add_co_u32_e32 v38, vcc, s47, v36
	s_nop 1
	v_addc_co_u32_e32 v39, vcc, 0, v37, vcc
	v_add_co_u32_e32 v40, vcc, s6, v36
	s_nop 1
	v_addc_co_u32_e32 v41, vcc, 0, v37, vcc
	v_add_co_u32_e32 v42, vcc, s68, v36
	s_nop 1
	v_addc_co_u32_e32 v43, vcc, 0, v37, vcc
	v_add_co_u32_e32 v60, vcc, s49, v36
	s_nop 1
	v_addc_co_u32_e32 v61, vcc, 0, v37, vcc
	global_load_dword v28, v[28:29], off
	s_nop 0
	global_load_dword v29, v[30:31], off offset:2048
	s_nop 0
	global_load_dword v30, v[32:33], off
	global_load_dword v31, v[34:35], off offset:2048
	s_nop 0
	global_load_dword v32, v[38:39], off
	global_load_dword v33, v[40:41], off offset:2048
	global_load_dword v34, v[42:43], off
	global_load_dword v35, v[60:61], off offset:2048
	v_add_co_u32_e32 v38, vcc, s50, v36
	s_nop 1
	v_addc_co_u32_e32 v39, vcc, 0, v37, vcc
	v_add_co_u32_e32 v40, vcc, s69, v36
	s_nop 1
	v_addc_co_u32_e32 v41, vcc, 0, v37, vcc
	v_add_co_u32_e32 v42, vcc, s71, v36
	s_nop 1
	v_addc_co_u32_e32 v43, vcc, 0, v37, vcc
	v_add_co_u32_e32 v60, vcc, s52, v36
	s_nop 1
	v_addc_co_u32_e32 v61, vcc, 0, v37, vcc
	v_add_co_u32_e32 v62, vcc, s53, v36
	s_nop 1
	v_addc_co_u32_e32 v63, vcc, 0, v37, vcc
	v_add_co_u32_e32 v64, vcc, 0x2b000, v36
	s_nop 1
	v_addc_co_u32_e32 v65, vcc, 0, v37, vcc
	v_add_co_u32_e32 v66, vcc, 0x2d000, v36
	s_nop 1
	v_addc_co_u32_e32 v67, vcc, 0, v37, vcc
	v_add_co_u32_e32 v68, vcc, 0x2e000, v36
	s_nop 1
	v_addc_co_u32_e32 v69, vcc, 0, v37, vcc
	global_load_dword v36, v[38:39], off
	global_load_dword v37, v[40:41], off offset:2048
	s_nop 0
	global_load_dword v38, v[42:43], off
	global_load_dword v39, v[60:61], off offset:2048
	s_nop 0
	global_load_dword v42, v[62:63], off
	global_load_dword v43, v[64:65], off offset:2048
	global_load_dword v40, v[66:67], off
	global_load_dword v41, v[68:69], off offset:2048
	s_cbranch_scc1 .LBB0_37
	s_lshl_b32 s6, s18, 2
	s_add_u32 s4, s4, s6
	s_addc_u32 s5, s5, 0
	v_lshlrev_b32_e32 v3, 2, v45
	global_load_dword v60, v3, s[4:5]
	global_load_dword v61, v3, s[4:5] offset:8
	global_load_dword v62, v3, s[4:5] offset:16
	global_load_dword v63, v3, s[4:5] offset:24
	global_load_dword v64, v3, s[4:5] offset:32
	global_load_dword v65, v3, s[4:5] offset:40
	global_load_dword v66, v3, s[4:5] offset:48
	global_load_dword v67, v3, s[4:5] offset:56
	global_load_dword v68, v3, s[4:5] offset:64
	global_load_dword v69, v3, s[4:5] offset:72
	global_load_dword v70, v3, s[4:5] offset:80
	global_load_dword v71, v3, s[4:5] offset:88
	global_load_dword v72, v3, s[4:5] offset:96
	global_load_dword v73, v3, s[4:5] offset:104
	global_load_dword v74, v3, s[4:5] offset:112
	global_load_dword v75, v3, s[4:5] offset:120
	global_load_dword v76, v3, s[4:5] offset:128
	global_load_dword v77, v3, s[4:5] offset:136
	global_load_dword v78, v3, s[4:5] offset:144
	global_load_dword v79, v3, s[4:5] offset:152
	global_load_dword v80, v3, s[4:5] offset:160
	global_load_dword v81, v3, s[4:5] offset:168
	global_load_dword v82, v3, s[4:5] offset:176
	global_load_dword v83, v3, s[4:5] offset:184
	global_load_dword v84, v3, s[4:5] offset:192
	global_load_dword v85, v3, s[4:5] offset:200
	global_load_dword v86, v3, s[4:5] offset:208
	global_load_dword v87, v3, s[4:5] offset:216
	global_load_dword v88, v3, s[4:5] offset:224
	global_load_dword v89, v3, s[4:5] offset:232
	global_load_dword v90, v3, s[4:5] offset:240
	global_load_dword v91, v3, s[4:5] offset:248
	s_waitcnt vmcnt(30)
	v_mul_f32_e64 v12, v12, v60
	v_mul_f32_e64 v13, v13, v61
	s_waitcnt vmcnt(28)
	v_mul_f32_e64 v14, v14, v62
	v_mul_f32_e64 v15, v15, v63
	s_waitcnt vmcnt(26)
	v_mul_f32_e64 v16, v16, v64
	v_mul_f32_e64 v17, v17, v65
	s_waitcnt vmcnt(24)
	v_mul_f32_e64 v18, v18, v66
	v_mul_f32_e64 v19, v19, v67
	s_waitcnt vmcnt(22)
	v_mul_f32_e64 v20, v20, v68
	v_mul_f32_e64 v21, v21, v69
	s_waitcnt vmcnt(20)
	v_mul_f32_e64 v22, v22, v70
	v_mul_f32_e64 v23, v23, v71
	s_waitcnt vmcnt(18)
	v_mul_f32_e64 v24, v24, v72
	v_mul_f32_e64 v25, v25, v73
	s_waitcnt vmcnt(16)
	v_mul_f32_e64 v26, v26, v74
	v_mul_f32_e64 v27, v27, v75
	s_waitcnt vmcnt(14)
	v_mul_f32_e64 v28, v28, v76
	v_mul_f32_e64 v29, v29, v77
	s_waitcnt vmcnt(12)
	v_mul_f32_e64 v30, v30, v78
	v_mul_f32_e64 v31, v31, v79
	s_waitcnt vmcnt(10)
	v_mul_f32_e64 v32, v32, v80
	v_mul_f32_e64 v33, v33, v81
	s_waitcnt vmcnt(8)
	v_mul_f32_e64 v34, v34, v82
	v_mul_f32_e64 v35, v35, v83
	s_waitcnt vmcnt(6)
	v_mul_f32_e64 v36, v36, v84
	v_mul_f32_e64 v37, v37, v85
	s_waitcnt vmcnt(4)
	v_mul_f32_e64 v38, v38, v86
	v_mul_f32_e64 v39, v39, v87
	s_waitcnt vmcnt(2)
	v_mul_f32_e64 v42, v42, v88
	v_mul_f32_e64 v43, v43, v89
	s_waitcnt vmcnt(0)
	v_mul_f32_e64 v40, v40, v90
	v_mul_f32_e64 v41, v41, v91

.LBB0_39:
	s_andn2_b64 vcc, exec, s[4:5]
	s_cbranch_vccnz .LBB0_43
	s_and_b32 s4, s16, 0xffff
	s_mul_i32 s6, s4, 0x1bad
	s_lshr_b32 s4, s6, 18
	s_mul_i32 s4, s4, 37
	s_sub_i32 s16, s16, s4
	s_load_dwordx2 s[4:5], s[12:13], 0x50
	s_lshr_b32 s6, s6, 12
	s_and_b32 s17, s6, 0xffc0
	v_or_b32_e32 v3, s17, v45
	v_mul_u32_u24_e32 v3, 0x4a0, v3
	v_lshlrev_b32_e32 v12, 2, v3
	v_mov_b32_e32 v13, v5
	s_load_dwordx2 s[6:7], s[12:13], 0x28
	s_waitcnt lgkmcnt(0)
	v_lshl_add_u64 v[12:13], s[4:5], 0, v[12:13]
	s_lshl_b32 s4, s16, 7
	s_and_b32 s14, s4, 0x3ff80
	v_lshl_add_u64 v[12:13], v[12:13], 0, s[14:15]
	v_lshl_add_u64 v[36:37], v[12:13], 0, v[4:5]
	v_add_co_u32_e32 v14, vcc, s31, v36
	s_mov_b32 s4, 0x17000
	s_nop 0
	v_addc_co_u32_e32 v15, vcc, 0, v37, vcc
	v_add_co_u32_e32 v16, vcc, s34, v36
	s_cmp_eq_u64 s[6:7], 0
	s_nop 0
	v_addc_co_u32_e32 v17, vcc, 0, v37, vcc
	v_add_co_u32_e32 v18, vcc, s35, v36
	s_nop 1
	v_addc_co_u32_e32 v19, vcc, 0, v37, vcc
	v_add_co_u32_e32 v20, vcc, s64, v36
	s_nop 1
	v_addc_co_u32_e32 v21, vcc, 0, v37, vcc
	v_add_co_u32_e32 v22, vcc, s72, v36
	s_nop 1
	v_addc_co_u32_e32 v23, vcc, 0, v37, vcc
	v_add_co_u32_e32 v24, vcc, s65, v36
	s_nop 1
	v_addc_co_u32_e32 v25, vcc, 0, v37, vcc
	v_add_co_u32_e32 v26, vcc, s40, v36
	s_nop 1
	v_addc_co_u32_e32 v27, vcc, 0, v37, vcc
	global_load_dword v12, v[36:37], off
	global_load_dword v13, v[14:15], off offset:1280
	s_nop 0
	global_load_dword v14, v[16:17], off offset:2560
	global_load_dword v15, v[18:19], off offset:3840
	s_nop 0
	global_load_dword v16, v[20:21], off offset:1024
	global_load_dword v17, v[22:23], off offset:2304
	global_load_dword v18, v[24:25], off offset:3584
	global_load_dword v19, v[26:27], off offset:768
	v_add_co_u32_e32 v20, vcc, s41, v36
	s_nop 1
	v_addc_co_u32_e32 v21, vcc, 0, v37, vcc
	v_add_co_u32_e32 v22, vcc, s42, v36
	s_nop 1
	v_addc_co_u32_e32 v23, vcc, 0, v37, vcc
	v_add_co_u32_e32 v24, vcc, s4, v36
	s_mov_b32 s4, 0x29000
	s_nop 0
	v_addc_co_u32_e32 v25, vcc, 0, v37, vcc
	v_add_co_u32_e32 v26, vcc, s66, v36
	s_nop 1
	v_addc_co_u32_e32 v27, vcc, 0, v37, vcc
	v_add_co_u32_e32 v28, vcc, s67, v36
	s_nop 1
	v_addc_co_u32_e32 v29, vcc, 0, v37, vcc
	v_add_co_u32_e32 v30, vcc, s47, v36
	s_nop 1
	v_addc_co_u32_e32 v31, vcc, 0, v37, vcc
	v_add_co_u32_e32 v32, vcc, s48, v36
	s_nop 1
	v_addc_co_u32_e32 v33, vcc, 0, v37, vcc
	v_add_co_u32_e32 v34, vcc, s49, v36
	s_nop 1
	v_addc_co_u32_e32 v35, vcc, 0, v37, vcc
	global_load_dword v20, v[20:21], off offset:2048
	s_nop 0
	global_load_dword v21, v[22:23], off offset:3328
	s_nop 0
	global_load_dword v22, v[24:25], off offset:512
	global_load_dword v23, v[26:27], off offset:1792
	s_nop 0
	global_load_dword v24, v[28:29], off offset:3072
	global_load_dword v25, v[30:31], off offset:256
	global_load_dword v26, v[32:33], off offset:1536
	global_load_dword v27, v[34:35], off offset:2816
	v_add_co_u32_e32 v28, vcc, s69, v36
	s_nop 1
	v_addc_co_u32_e32 v29, vcc, 0, v37, vcc
	v_add_co_u32_e32 v30, vcc, s71, v36
	s_nop 1
	v_addc_co_u32_e32 v31, vcc, 0, v37, vcc
	v_add_co_u32_e32 v32, vcc, s4, v36
	s_mov_b32 s4, 0x2b000
	s_nop 0
	v_addc_co_u32_e32 v33, vcc, 0, v37, vcc
	v_add_co_u32_e32 v34, vcc, s4, v36
	s_mov_b32 s4, 0x35000
	s_nop 0
	v_addc_co_u32_e32 v35, vcc, 0, v37, vcc
	v_add_co_u32_e32 v38, vcc, s55, v36
	s_nop 1
	v_addc_co_u32_e32 v39, vcc, 0, v37, vcc
	v_add_co_u32_e32 v40, vcc, s56, v36
	s_nop 1
	v_addc_co_u32_e32 v41, vcc, 0, v37, vcc
	v_add_co_u32_e32 v42, vcc, s57, v36
	s_nop 1
	v_addc_co_u32_e32 v43, vcc, 0, v37, vcc
	v_add_co_u32_e32 v60, vcc, s4, v36
	s_mov_b32 s4, 0x39000
	s_nop 0
	v_addc_co_u32_e32 v61, vcc, 0, v37, vcc
	global_load_dword v28, v[28:29], off
	s_nop 0
	global_load_dword v29, v[30:31], off offset:1280
	s_nop 0
	global_load_dword v30, v[32:33], off offset:2560
	global_load_dword v31, v[34:35], off offset:3840
	s_nop 0
	global_load_dword v32, v[38:39], off offset:1024
	global_load_dword v33, v[40:41], off offset:2304
	global_load_dword v34, v[42:43], off offset:3584
	global_load_dword v35, v[60:61], off offset:768
	v_add_co_u32_e32 v38, vcc, s73, v36
	s_nop 1
	v_addc_co_u32_e32 v39, vcc, 0, v37, vcc
	v_add_co_u32_e32 v40, vcc, s4, v36
	s_mov_b32 s4, 0x40000
	s_nop 0
	v_addc_co_u32_e32 v41, vcc, 0, v37, vcc
	v_add_co_u32_e32 v42, vcc, s62, v36
	s_nop 1
	v_addc_co_u32_e32 v43, vcc, 0, v37, vcc
	v_add_co_u32_e32 v60, vcc, s63, v36
	s_nop 1
	v_addc_co_u32_e32 v61, vcc, 0, v37, vcc
	v_add_co_u32_e32 v62, vcc, s4, v36
	s_nop 1
	v_addc_co_u32_e32 v63, vcc, 0, v37, vcc
	v_add_co_u32_e32 v64, vcc, 0x43000, v36
	s_nop 1
	v_addc_co_u32_e32 v65, vcc, 0, v37, vcc
	v_add_co_u32_e32 v66, vcc, 0x45000, v36
	s_nop 1
	v_addc_co_u32_e32 v67, vcc, 0, v37, vcc
	v_add_co_u32_e32 v68, vcc, 0x47000, v36
	s_nop 1
	v_addc_co_u32_e32 v69, vcc, 0, v37, vcc
	global_load_dword v36, v[38:39], off offset:2048
	global_load_dword v37, v[40:41], off offset:3328
	s_nop 0
	global_load_dword v38, v[42:43], off offset:512
	global_load_dword v39, v[60:61], off offset:1792
	s_nop 0
	global_load_dword v42, v[62:63], off offset:3072
	global_load_dword v43, v[64:65], off offset:256
	global_load_dword v40, v[66:67], off offset:1536
	global_load_dword v41, v[68:69], off offset:2816
	s_cbranch_scc1 .LBB0_42
	s_lshl_b32 s4, s17, 2
	s_add_u32 s4, s6, s4
	s_addc_u32 s5, s7, 0
	v_lshlrev_b32_e32 v3, 2, v45
	global_load_dword v60, v3, s[4:5]
	global_load_dword v61, v3, s[4:5] offset:8
	global_load_dword v62, v3, s[4:5] offset:16
	global_load_dword v63, v3, s[4:5] offset:24
	global_load_dword v64, v3, s[4:5] offset:32
	global_load_dword v65, v3, s[4:5] offset:40
	global_load_dword v66, v3, s[4:5] offset:48
	global_load_dword v67, v3, s[4:5] offset:56
	global_load_dword v68, v3, s[4:5] offset:64
	global_load_dword v69, v3, s[4:5] offset:72
	global_load_dword v70, v3, s[4:5] offset:80
	global_load_dword v71, v3, s[4:5] offset:88
	global_load_dword v72, v3, s[4:5] offset:96
	global_load_dword v73, v3, s[4:5] offset:104
	global_load_dword v74, v3, s[4:5] offset:112
	global_load_dword v75, v3, s[4:5] offset:120
	global_load_dword v76, v3, s[4:5] offset:128
	global_load_dword v77, v3, s[4:5] offset:136
	global_load_dword v78, v3, s[4:5] offset:144
	global_load_dword v79, v3, s[4:5] offset:152
	global_load_dword v80, v3, s[4:5] offset:160
	global_load_dword v81, v3, s[4:5] offset:168
	global_load_dword v82, v3, s[4:5] offset:176
	global_load_dword v83, v3, s[4:5] offset:184
	global_load_dword v84, v3, s[4:5] offset:192
	global_load_dword v85, v3, s[4:5] offset:200
	global_load_dword v86, v3, s[4:5] offset:208
	global_load_dword v87, v3, s[4:5] offset:216
	global_load_dword v88, v3, s[4:5] offset:224
	global_load_dword v89, v3, s[4:5] offset:232
	global_load_dword v90, v3, s[4:5] offset:240
	global_load_dword v91, v3, s[4:5] offset:248
	s_waitcnt vmcnt(30)
	v_mul_f32_e64 v12, v12, v60
	v_mul_f32_e64 v13, v13, v61
	s_waitcnt vmcnt(28)
	v_mul_f32_e64 v14, v14, v62
	v_mul_f32_e64 v15, v15, v63
	s_waitcnt vmcnt(26)
	v_mul_f32_e64 v16, v16, v64
	v_mul_f32_e64 v17, v17, v65
	s_waitcnt vmcnt(24)
	v_mul_f32_e64 v18, v18, v66
	v_mul_f32_e64 v19, v19, v67
	s_waitcnt vmcnt(22)
	v_mul_f32_e64 v20, v20, v68
	v_mul_f32_e64 v21, v21, v69
	s_waitcnt vmcnt(20)
	v_mul_f32_e64 v22, v22, v70
	v_mul_f32_e64 v23, v23, v71
	s_waitcnt vmcnt(18)
	v_mul_f32_e64 v24, v24, v72
	v_mul_f32_e64 v25, v25, v73
	s_waitcnt vmcnt(16)
	v_mul_f32_e64 v26, v26, v74
	v_mul_f32_e64 v27, v27, v75
	s_waitcnt vmcnt(14)
	v_mul_f32_e64 v28, v28, v76
	v_mul_f32_e64 v29, v29, v77
	s_waitcnt vmcnt(12)
	v_mul_f32_e64 v30, v30, v78
	v_mul_f32_e64 v31, v31, v79
	s_waitcnt vmcnt(10)
	v_mul_f32_e64 v32, v32, v80
	v_mul_f32_e64 v33, v33, v81
	s_waitcnt vmcnt(8)
	v_mul_f32_e64 v34, v34, v82
	v_mul_f32_e64 v35, v35, v83
	s_waitcnt vmcnt(6)
	v_mul_f32_e64 v36, v36, v84
	v_mul_f32_e64 v37, v37, v85
	s_waitcnt vmcnt(4)
	v_mul_f32_e64 v38, v38, v86
	v_mul_f32_e64 v39, v39, v87
	s_waitcnt vmcnt(2)
	v_mul_f32_e64 v42, v42, v88
	v_mul_f32_e64 v43, v43, v89
	s_waitcnt vmcnt(0)
	v_mul_f32_e64 v40, v40, v90
	v_mul_f32_e64 v41, v41, v91

.LBB0_47:
	s_andn2_b64 vcc, exec, s[16:17]
	s_cbranch_vccnz .LBB0_23
	s_and_b64 s[16:17], s[6:7], exec
	s_cselect_b32 s14, 8, 48
	s_sext_i32_i16 s95, s18
	s_add_u32 s18, s12, s14
	s_addc_u32 s19, s13, 0
	s_and_b64 s[6:7], s[6:7], exec
	s_cselect_b32 s6, 2, 7
	s_add_i32 s14, s6, s95
	s_lshl_b64 s[6:7], s[14:15], 3
	s_add_u32 s6, s12, s6
	s_addc_u32 s7, s13, s7
	s_load_dwordx2 s[6:7], s[6:7], 0x0
	s_sext_i32_i16 s14, s96
	s_mulk_i32 s14, 0xba3
	s_waitcnt lgkmcnt(0)
	s_add_u32 vcc_lo, s6, s9
	s_addc_u32 vcc_hi, s7, s97
	s_lshr_b32 s6, s14, 31
	s_ashr_i32 s7, s14, 18
	s_add_i32 s6, s7, s6
	s_mul_i32 s7, s6, 0x58
	s_lshl_b32 s6, s6, 6
	s_sub_i32 s14, s96, s7
	v_or_b32_e32 v3, s6, v45
	s_sext_i32_i16 s7, s14
	v_mul_i32_i24_e32 v12, 0xb00, v3
	s_lshl_b32 s16, s7, 5
	v_ashrrev_i32_e32 v13, 31, v12
	v_lshl_add_u64 v[12:13], v[12:13], 2, vcc
	s_ashr_i32 s17, s16, 31
	v_lshl_add_u64 v[12:13], s[16:17], 2, v[12:13]
	v_lshl_add_u64 v[36:37], v[12:13], 0, v[4:5]
	v_add_co_u32_e32 v14, vcc, s74, v36
	s_mov_b32 s7, 0x47000
	s_nop 0
	v_addc_co_u32_e32 v15, vcc, 0, v37, vcc
	v_add_co_u32_e32 v16, vcc, s72, v36
	s_nop 1
	v_addc_co_u32_e32 v17, vcc, 0, v37, vcc
	v_add_co_u32_e32 v18, vcc, s40, v36
	s_nop 1
	v_addc_co_u32_e32 v19, vcc, 0, v37, vcc
	v_add_co_u32_e32 v20, vcc, s43, v36
	s_nop 1
	v_addc_co_u32_e32 v21, vcc, 0, v37, vcc
	v_add_co_u32_e32 v22, vcc, s67, v36
	s_nop 1
	v_addc_co_u32_e32 v23, vcc, 0, v37, vcc
	v_add_co_u32_e32 v24, vcc, s68, v36
	s_nop 1
	v_addc_co_u32_e32 v25, vcc, 0, v37, vcc
	v_add_co_u32_e32 v26, vcc, s51, v36
	s_nop 1
	v_addc_co_u32_e32 v27, vcc, 0, v37, vcc
	global_load_dword v12, v[36:37], off
	global_load_dword v13, v[14:15], off offset:2048
	s_nop 0
	global_load_dword v14, v[16:17], off
	global_load_dword v15, v[18:19], off offset:2048
	s_nop 0
	global_load_dword v16, v[20:21], off
	global_load_dword v17, v[22:23], off offset:2048
	global_load_dword v18, v[24:25], off
	global_load_dword v19, v[26:27], off offset:2048
	v_add_co_u32_e32 v20, vcc, s54, v36
	s_nop 1
	v_addc_co_u32_e32 v21, vcc, 0, v37, vcc
	v_add_co_u32_e32 v22, vcc, s75, v36
	s_nop 1
	v_addc_co_u32_e32 v23, vcc, 0, v37, vcc
	v_add_co_u32_e32 v24, vcc, s73, v36
	s_nop 1
	v_addc_co_u32_e32 v25, vcc, 0, v37, vcc
	v_add_co_u32_e32 v26, vcc, s62, v36
	s_nop 1
	v_addc_co_u32_e32 v27, vcc, 0, v37, vcc
	v_add_co_u32_e32 v28, vcc, s76, v36
	s_nop 1
	v_addc_co_u32_e32 v29, vcc, 0, v37, vcc
	v_add_co_u32_e32 v30, vcc, s7, v36
	s_ashr_i32 s7, s6, 31
	s_nop 0
	v_addc_co_u32_e32 v31, vcc, 0, v37, vcc
	v_add_co_u32_e32 v32, vcc, s77, v36
	s_nop 1
	v_addc_co_u32_e32 v33, vcc, 0, v37, vcc
	v_add_co_u32_e32 v34, vcc, s78, v36
	s_nop 1
	v_addc_co_u32_e32 v35, vcc, 0, v37, vcc
	global_load_dword v20, v[20:21], off
	s_nop 0
	global_load_dword v21, v[22:23], off offset:2048
	s_nop 0
	global_load_dword v22, v[24:25], off
	global_load_dword v23, v[26:27], off offset:2048
	s_nop 0
	global_load_dword v24, v[28:29], off
	global_load_dword v25, v[30:31], off offset:2048
	global_load_dword v26, v[32:33], off
	global_load_dword v27, v[34:35], off offset:2048
	v_add_co_u32_e32 v28, vcc, s79, v36
	s_nop 1
	v_addc_co_u32_e32 v29, vcc, 0, v37, vcc
	v_add_co_u32_e32 v30, vcc, s80, v36
	s_nop 1
	v_addc_co_u32_e32 v31, vcc, 0, v37, vcc
	v_add_co_u32_e32 v32, vcc, s81, v36
	s_nop 1
	v_addc_co_u32_e32 v33, vcc, 0, v37, vcc
	v_add_co_u32_e32 v34, vcc, s82, v36
	s_nop 1
	v_addc_co_u32_e32 v35, vcc, 0, v37, vcc
	v_add_co_u32_e32 v38, vcc, s83, v36
	s_nop 1
	v_addc_co_u32_e32 v39, vcc, 0, v37, vcc
	v_add_co_u32_e32 v40, vcc, s84, v36
	s_nop 1
	v_addc_co_u32_e32 v41, vcc, 0, v37, vcc
	v_add_co_u32_e32 v42, vcc, s85, v36
	s_nop 1
	v_addc_co_u32_e32 v43, vcc, 0, v37, vcc
	v_add_co_u32_e32 v60, vcc, s86, v36
	s_nop 1
	v_addc_co_u32_e32 v61, vcc, 0, v37, vcc
	global_load_dword v28, v[28:29], off
	s_nop 0
	global_load_dword v29, v[30:31], off offset:2048
	s_nop 0
	global_load_dword v30, v[32:33], off
	global_load_dword v31, v[34:35], off offset:2048
	s_nop 0
	global_load_dword v32, v[38:39], off
	global_load_dword v33, v[40:41], off offset:2048
	global_load_dword v34, v[42:43], off
	global_load_dword v35, v[60:61], off offset:2048
	v_add_co_u32_e32 v38, vcc, s87, v36
	s_nop 1
	v_addc_co_u32_e32 v39, vcc, 0, v37, vcc
	v_add_co_u32_e32 v40, vcc, s88, v36
	s_nop 1
	v_addc_co_u32_e32 v41, vcc, 0, v37, vcc
	v_add_co_u32_e32 v42, vcc, s89, v36
	s_nop 1
	v_addc_co_u32_e32 v43, vcc, 0, v37, vcc
	v_add_co_u32_e32 v60, vcc, s90, v36
	s_nop 1
	v_addc_co_u32_e32 v61, vcc, 0, v37, vcc
	v_add_co_u32_e32 v62, vcc, s91, v36
	s_nop 1
	v_addc_co_u32_e32 v63, vcc, 0, v37, vcc
	v_add_co_u32_e32 v64, vcc, s92, v36
	s_nop 1
	v_addc_co_u32_e32 v65, vcc, 0, v37, vcc
	v_add_co_u32_e32 v66, vcc, 0xa5000, v36
	s_nop 1
	v_addc_co_u32_e32 v67, vcc, 0, v37, vcc
	v_add_co_u32_e32 v68, vcc, 0xaa000, v36
	s_nop 1
	v_addc_co_u32_e32 v69, vcc, 0, v37, vcc
	global_load_dword v36, v[38:39], off
	global_load_dword v37, v[40:41], off offset:2048
	s_nop 0
	global_load_dword v38, v[42:43], off
	global_load_dword v39, v[60:61], off offset:2048
	s_nop 0
	global_load_dword v42, v[62:63], off
	global_load_dword v43, v[64:65], off offset:2048
	global_load_dword v40, v[66:67], off
	global_load_dword v41, v[68:69], off offset:2048
	s_load_dwordx2 s[18:19], s[18:19], 0x0
	s_waitcnt lgkmcnt(0)
	s_cmp_eq_u64 s[18:19], 0
	s_cbranch_scc1 .LBB0_22
	s_lshl_b64 s[4:5], s[4:5], 12
	s_add_u32 s9, s18, s4
	s_addc_u32 s17, s19, s5
	s_lshl_b64 s[4:5], s[6:7], 2
	s_add_u32 s4, s9, s4
	s_addc_u32 s5, s17, s5
	v_lshlrev_b32_e32 v3, 2, v45
	global_load_dword v60, v3, s[4:5]
	global_load_dword v61, v3, s[4:5] offset:8
	global_load_dword v62, v3, s[4:5] offset:16
	global_load_dword v63, v3, s[4:5] offset:24
	global_load_dword v64, v3, s[4:5] offset:32
	global_load_dword v65, v3, s[4:5] offset:40
	global_load_dword v66, v3, s[4:5] offset:48
	global_load_dword v67, v3, s[4:5] offset:56
	global_load_dword v68, v3, s[4:5] offset:64
	global_load_dword v69, v3, s[4:5] offset:72
	global_load_dword v70, v3, s[4:5] offset:80
	global_load_dword v71, v3, s[4:5] offset:88
	global_load_dword v72, v3, s[4:5] offset:96
	global_load_dword v73, v3, s[4:5] offset:104
	global_load_dword v74, v3, s[4:5] offset:112
	global_load_dword v75, v3, s[4:5] offset:120
	global_load_dword v76, v3, s[4:5] offset:128
	global_load_dword v77, v3, s[4:5] offset:136
	global_load_dword v78, v3, s[4:5] offset:144
	global_load_dword v79, v3, s[4:5] offset:152
	global_load_dword v80, v3, s[4:5] offset:160
	global_load_dword v81, v3, s[4:5] offset:168
	global_load_dword v82, v3, s[4:5] offset:176
	global_load_dword v83, v3, s[4:5] offset:184
	global_load_dword v84, v3, s[4:5] offset:192
	global_load_dword v85, v3, s[4:5] offset:200
	global_load_dword v86, v3, s[4:5] offset:208
	global_load_dword v87, v3, s[4:5] offset:216
	global_load_dword v88, v3, s[4:5] offset:224
	global_load_dword v89, v3, s[4:5] offset:232
	global_load_dword v90, v3, s[4:5] offset:240
	global_load_dword v91, v3, s[4:5] offset:248
	s_waitcnt vmcnt(30)
	v_mul_f32_e64 v12, v12, v60
	v_mul_f32_e64 v13, v13, v61
	s_waitcnt vmcnt(28)
	v_mul_f32_e64 v14, v14, v62
	v_mul_f32_e64 v15, v15, v63
	s_waitcnt vmcnt(26)
	v_mul_f32_e64 v16, v16, v64
	v_mul_f32_e64 v17, v17, v65
	s_waitcnt vmcnt(24)
	v_mul_f32_e64 v18, v18, v66
	v_mul_f32_e64 v19, v19, v67
	s_waitcnt vmcnt(22)
	v_mul_f32_e64 v20, v20, v68
	v_mul_f32_e64 v21, v21, v69
	s_waitcnt vmcnt(20)
	v_mul_f32_e64 v22, v22, v70
	v_mul_f32_e64 v23, v23, v71
	s_waitcnt vmcnt(18)
	v_mul_f32_e64 v24, v24, v72
	v_mul_f32_e64 v25, v25, v73
	s_waitcnt vmcnt(16)
	v_mul_f32_e64 v26, v26, v74
	v_mul_f32_e64 v27, v27, v75
	s_waitcnt vmcnt(14)
	v_mul_f32_e64 v28, v28, v76
	v_mul_f32_e64 v29, v29, v77
	s_waitcnt vmcnt(12)
	v_mul_f32_e64 v30, v30, v78
	v_mul_f32_e64 v31, v31, v79
	s_waitcnt vmcnt(10)
	v_mul_f32_e64 v32, v32, v80
	v_mul_f32_e64 v33, v33, v81
	s_waitcnt vmcnt(8)
	v_mul_f32_e64 v34, v34, v82
	v_mul_f32_e64 v35, v35, v83
	s_waitcnt vmcnt(6)
	v_mul_f32_e64 v36, v36, v84
	v_mul_f32_e64 v37, v37, v85
	s_waitcnt vmcnt(4)
	v_mul_f32_e64 v38, v38, v86
	v_mul_f32_e64 v39, v39, v87
	s_waitcnt vmcnt(2)
	v_mul_f32_e64 v42, v42, v88
	v_mul_f32_e64 v43, v43, v89
	s_waitcnt vmcnt(0)
	v_mul_f32_e64 v40, v40, v90
	v_mul_f32_e64 v41, v41, v91
	s_branch .LBB0_22

.LBB0_53:
	s_lshl_b32 s9, s22, 11
	s_lshl_b32 s14, s21, 2
	s_and_b32 s9, s9, 0x180000
	s_and_b32 s30, s14, 0xf00
	s_add_u32 s26, s18, s9
	s_addc_u32 s27, s19, 0
	s_lshr_b32 s9, s22, 1
	s_and_b32 s24, s9, 0x180
	s_and_b32 s23, s9, 0x78
	s_or_b32 s9, s24, s23
	s_lshl_b32 s28, s24, 2
	s_mov_b32 s29, s15
	s_lshl_b32 s14, s9, 9
	v_lshl_add_u64 v[10:11], v[4:5], 0, s[28:29]
	global_load_dwordx4 v[16:19], v[10:11], off
	v_lshl_add_u64 v[10:11], v[8:9], 0, s[14:15]
	global_load_dwordx4 v[20:23], v[10:11], off
	global_load_dwordx4 v[24:27], v[10:11], off offset:1024
	global_load_dwordx4 v[28:31], v[10:11], off offset:2048
	global_load_dwordx4 v[32:35], v[10:11], off offset:3072
	v_mov_b32_e32 v12, 0
	v_lshl_or_b32 v2, v44, 2, s30
	s_mov_b32 s14, -16
	s_mov_b32 s25, s20
	v_mov_b32_e32 v13, v12
	v_mov_b32_e32 v14, v12
	v_mov_b32_e32 v15, v12
	v_lshl_add_u64 v[10:11], s[26:27], 0, v[2:3]
	s_waitcnt vmcnt(3)
	v_mul_f32_e64 v22, v18, v22
	v_mul_f32_e64 v23, v19, v23
	v_mul_f32_e64 v20, v16, v20
	v_mul_f32_e64 v21, v17, v21
	s_waitcnt vmcnt(2)
	v_mul_f32_e64 v26, v18, v26
	v_mul_f32_e64 v27, v19, v27
	v_mul_f32_e64 v24, v16, v24
	v_mul_f32_e64 v25, v17, v25
	s_waitcnt vmcnt(1)
	v_mul_f32_e64 v30, v18, v30
	v_mul_f32_e64 v31, v19, v31
	v_mul_f32_e64 v28, v16, v28
	v_mul_f32_e64 v29, v17, v29
	s_waitcnt vmcnt(0)
	v_mul_f32_e64 v18, v18, v34
	v_mul_f32_e64 v19, v19, v35
	v_mul_f32_e64 v16, v16, v32
	v_mul_f32_e64 v17, v17, v33
	ds_write_b128 v7, v[20:23]
	ds_write_b128 v7, v[24:27] offset:1024
	ds_write_b128 v7, v[28:31] offset:2048
	ds_write_b128 v7, v[16:19] offset:3072
	s_waitcnt lgkmcnt(0)
	v_mov_b32_e32 v16, v12
	v_mov_b32_e32 v17, v12
	v_mov_b32_e32 v18, v12
	v_mov_b32_e32 v19, v12
.LBB0_54:
	v_add_co_u32_e32 v20, vcc, 0xffff1000, v10
	v_mov_b32_e32 v2, s25
	s_nop 0
	v_addc_co_u32_e32 v21, vcc, -1, v11, vcc
	v_add_co_u32_e32 v24, vcc, 0xffff2000, v10
	v_mov_b32_e32 v22, v18
	s_nop 0
	v_addc_co_u32_e32 v25, vcc, -1, v11, vcc
	v_add_co_u32_e32 v26, vcc, 0xffff3000, v10
	global_load_dword v154, v[20:21], off
	global_load_dword v156, v[24:25], off
	v_addc_co_u32_e32 v27, vcc, -1, v11, vcc
	v_add_co_u32_e32 v20, vcc, 0xffff4000, v10
	s_add_i32 s14, s14, 16
	s_nop 0
	v_addc_co_u32_e32 v21, vcc, -1, v11, vcc
	v_add_co_u32_e32 v24, vcc, 0xffff5000, v10
	global_load_dword v157, v[26:27], off
	global_load_dword v155, v[20:21], off
	v_addc_co_u32_e32 v25, vcc, -1, v11, vcc
	v_add_co_u32_e32 v20, vcc, 0xffff6000, v10
	s_add_i32 s25, s25, 64
	s_nop 0
	v_addc_co_u32_e32 v21, vcc, -1, v11, vcc
	v_add_co_u32_e32 v26, vcc, 0xffff7000, v10
	global_load_dword v158, v[24:25], off
	global_load_dword v159, v[20:21], off
	v_addc_co_u32_e32 v27, vcc, -1, v11, vcc
	v_add_co_u32_e32 v20, vcc, 0xffff8000, v10
	s_cmpk_lt_u32 s14, 0x70
	s_nop 0
	v_addc_co_u32_e32 v21, vcc, -1, v11, vcc
	v_add_co_u32_e32 v24, vcc, 0xffff9000, v10
	global_load_dword v160, v[26:27], off
	global_load_dword v161, v[20:21], off
	v_addc_co_u32_e32 v25, vcc, -1, v11, vcc
	v_add_co_u32_e32 v20, vcc, 0xffffa000, v10
	s_nop 1
	v_addc_co_u32_e32 v21, vcc, -1, v11, vcc
	v_add_co_u32_e32 v26, vcc, 0xffffb000, v10
	global_load_dword v162, v[24:25], off
	global_load_dword v163, v[20:21], off
	v_addc_co_u32_e32 v27, vcc, -1, v11, vcc
	v_add_co_u32_e32 v20, vcc, 0xffffc000, v10
	s_nop 1
	v_addc_co_u32_e32 v21, vcc, -1, v11, vcc
	v_add_co_u32_e32 v24, vcc, 0xffffd000, v10
	global_load_dword v164, v[26:27], off
	global_load_dword v165, v[20:21], off
	v_addc_co_u32_e32 v25, vcc, -1, v11, vcc
	v_add_co_u32_e32 v20, vcc, 0xffffe000, v10
	s_nop 1
	v_addc_co_u32_e32 v21, vcc, -1, v11, vcc
	global_load_dword v166, v[24:25], off
	global_load_dword v168, v[20:21], off
	global_load_dword v170, v[10:11], off offset:-4096
	global_load_dword v172, v[10:11], off
	ds_read_b128 v[24:27], v2
	ds_read_b128 v[28:31], v2 offset:16
	ds_read_b128 v[32:35], v2 offset:32
	ds_read_b128 v[36:39], v2 offset:48
	ds_read_b128 v[40:43], v2 offset:512
	ds_read_b128 v[46:49], v2 offset:528
	ds_read_b128 v[50:53], v2 offset:1024
	ds_read_b128 v[54:57], v2 offset:1040
	ds_read_b128 v[58:61], v2 offset:1536
	ds_read_b128 v[62:65], v2 offset:1552
	ds_read_b128 v[66:69], v2 offset:544
	ds_read_b128 v[70:73], v2 offset:560
	ds_read_b128 v[74:77], v2 offset:1056
	ds_read_b128 v[78:81], v2 offset:1072
	ds_read_b128 v[82:85], v2 offset:1568
	ds_read_b128 v[86:89], v2 offset:1584
	ds_read_b128 v[90:93], v2 offset:2048
	ds_read_b128 v[94:97], v2 offset:2064
	ds_read_b128 v[98:101], v2 offset:2560
	ds_read_b128 v[102:105], v2 offset:2576
	ds_read_b128 v[106:109], v2 offset:2080
	ds_read_b128 v[110:113], v2 offset:2096
	ds_read_b128 v[114:117], v2 offset:2592
	ds_read_b128 v[118:121], v2 offset:2608
	ds_read_b128 v[122:125], v2 offset:3072
	ds_read_b128 v[126:129], v2 offset:3088
	ds_read_b128 v[130:133], v2 offset:3584
	ds_read_b128 v[134:137], v2 offset:3600
	ds_read_b128 v[138:141], v2 offset:3104
	ds_read_b128 v[142:145], v2 offset:3120
	ds_read_b128 v[146:149], v2 offset:3616
	ds_read_b128 v[150:153], v2 offset:3632
	s_waitcnt lgkmcnt(14)
	v_mov_b32_e32 v21, v40
	v_mov_b32_e32 v40, v25
	v_mov_b32_e32 v25, v42
	v_mov_b32_e32 v42, v27
	v_mov_b32_e32 v27, v46
	v_mov_b32_e32 v46, v29
	v_mov_b32_e32 v29, v48
	v_mov_b32_e32 v48, v31
	v_mov_b32_e32 v31, v66
	v_mov_b32_e32 v66, v33
	v_mov_b32_e32 v33, v68
	v_mov_b32_e32 v68, v35
	v_mov_b32_e32 v35, v70
	v_mov_b32_e32 v70, v37
	v_mov_b32_e32 v37, v72
	v_mov_b32_e32 v72, v39
	v_mov_b32_e32 v39, v58
	v_mov_b32_e32 v58, v51
	v_mov_b32_e32 v20, v24
	v_mov_b32_e32 v24, v26
	v_mov_b32_e32 v26, v28
	v_mov_b32_e32 v28, v30
	v_mov_b32_e32 v30, v32
	v_mov_b32_e32 v32, v34
	v_mov_b32_e32 v34, v36
	v_mov_b32_e32 v36, v38
	v_mov_b32_e32 v38, v50
	v_mov_b32_e32 v51, v60
	s_waitcnt vmcnt(13)
	v_mul_f32_e64 v58, v156, v58
	v_mul_f32_e64 v59, v156, v59
	v_mov_b32_e32 v60, v53
	v_mov_b32_e32 v53, v62
	v_mov_b32_e32 v62, v55
	v_mov_b32_e32 v55, v64
	v_mov_b32_e32 v64, v57
	v_mov_b32_e32 v57, v82
	v_mov_b32_e32 v82, v75
	v_mov_b32_e32 v75, v84
	v_mov_b32_e32 v84, v77
	v_mov_b32_e32 v77, v86
	v_mov_b32_e32 v86, v79
	v_mov_b32_e32 v79, v88
	v_mov_b32_e32 v88, v81
	s_waitcnt lgkmcnt(13)
	v_mov_b32_e32 v81, v98
	v_mov_b32_e32 v98, v91
	v_mov_b32_e32 v91, v100
	v_mov_b32_e32 v100, v93
	s_waitcnt vmcnt(12)
	v_fma_f32 v38, v154, v38, v58
	v_fma_f32 v39, v154, v39, v59
	v_mov_b32_e32 v58, v155
	v_mov_b32_e32 v50, v52
	v_mov_b32_e32 v52, v54
	v_mov_b32_e32 v54, v56
	v_mov_b32_e32 v56, v74
	v_mov_b32_e32 v74, v76
	v_mov_b32_e32 v76, v78
	v_mov_b32_e32 v78, v80
	v_mov_b32_e32 v80, v90
	v_mov_b32_e32 v90, v92
	s_waitcnt lgkmcnt(12)
	v_mov_b32_e32 v93, v102
	v_mov_b32_e32 v102, v95
	v_mov_b32_e32 v95, v104
	v_mov_b32_e32 v104, v97
	s_waitcnt lgkmcnt(9)
	v_mov_b32_e32 v97, v114
	v_mov_b32_e32 v114, v107
	v_mov_b32_e32 v107, v116
	v_mov_b32_e32 v116, v109
	s_waitcnt lgkmcnt(8)
	v_mov_b32_e32 v109, v118
	v_mov_b32_e32 v118, v111
	v_mov_b32_e32 v111, v120
	v_mov_b32_e32 v120, v113
	s_waitcnt lgkmcnt(7)
	v_mov_b32_e32 v113, v124
	s_waitcnt lgkmcnt(5)
	v_mov_b32_e32 v124, v131
	v_mov_b32_e32 v131, v133
	v_mul_f32_e64 v40, v156, v40
	v_mul_f32_e64 v41, v156, v41
	v_mul_f32_e64 v98, v156, v98
	v_mul_f32_e64 v99, v156, v99
	v_mov_b32_e32 v2, v157
	v_mul_f32_e64 v42, v58, v42
	v_mul_f32_e64 v43, v58, v43
	v_mul_f32_e64 v60, v58, v60
	v_mul_f32_e64 v61, v58, v61
	v_mul_f32_e64 v59, v58, v101
	v_mul_f32_e64 v58, v58, v100
	v_mov_b32_e32 v92, v94
	v_mov_b32_e32 v94, v96
	v_mov_b32_e32 v96, v106
	v_mov_b32_e32 v106, v108
	v_mov_b32_e32 v108, v110
	v_mov_b32_e32 v110, v112
	v_mov_b32_e32 v112, v123
	v_mov_b32_e32 v123, v125
	v_mov_b32_e32 v125, v132
	v_mul_f32_e64 v130, v154, v130
	v_mul_f32_e64 v131, v155, v131
	v_fma_f32 v20, v154, v20, v40
	v_fma_f32 v21, v154, v21, v41
	v_fma_f32 v40, v154, v80, v98
	v_fma_f32 v41, v154, v81, v99
	v_fma_f32 v24, v2, v24, v42
	v_fma_f32 v25, v2, v25, v43
	v_fma_f32 v42, v2, v50, v60
	v_fma_f32 v43, v2, v51, v61
	v_fma_f32 v50, v2, v90, v58
	v_fma_f32 v51, v2, v91, v59
	v_fma_f32 v98, v156, v124, v130
	v_fma_f32 v99, v157, v125, v131
	s_waitcnt vmcnt(10)
	v_mul_f32_e32 v2, v159, v127
	v_mov_b32_e32 v58, v159
	v_add_f32_e64 v20, v20, v24
	v_add_f32_e64 v21, v21, v25
	v_add_f32_e64 v24, v38, v42
	v_add_f32_e64 v25, v39, v43
	v_add_f32_e64 v38, v40, v50
	v_add_f32_e64 v39, v41, v51
	s_waitcnt vmcnt(8)
	v_mov_b32_e32 v50, v161
	s_waitcnt lgkmcnt(4)
	v_mov_b32_e32 v132, v135
	v_mov_b32_e32 v135, v137
	v_mul_f32_e64 v122, v154, v122
	v_mul_f32_e64 v123, v155, v123
	v_mov_b32_e32 v100, v158
	v_add_f32_e64 v90, v98, v99
	v_add_f32_e64 v91, v99, v98
	v_fma_f32 v98, v158, v126, v2
	v_fma_f32 v99, v159, v127, v2
	v_mul_f32_e64 v46, v58, v46
	v_mul_f32_e64 v47, v58, v47
	v_mul_f32_e64 v62, v58, v62
	v_mul_f32_e64 v63, v58, v63
	v_mov_b32_e32 v101, v161
	v_mul_f32_e32 v2, v161, v129
	v_add_f32_e64 v16, v16, v38
	v_add_f32_e64 v17, v17, v39
	v_mul_f32_e64 v38, v50, v48
	v_mul_f32_e64 v39, v50, v49
	v_mul_f32_e64 v48, v50, v64
	v_mul_f32_e64 v49, v50, v65
	v_mov_b32_e32 v133, v136
	v_fma_f32 v80, v156, v112, v122
	v_fma_f32 v81, v157, v113, v123
	v_mov_b32_e32 v60, v159
	v_mul_f32_e64 v59, v58, v103
	v_mul_f32_e64 v58, v58, v102
	v_mov_b32_e32 v61, v160
	v_fma_f32 v26, v158, v26, v46
	v_fma_f32 v27, v158, v27, v47
	v_fma_f32 v46, v158, v52, v62
	v_fma_f32 v47, v158, v53, v63
	v_add_f32_e64 v12, v12, v20
	v_add_f32_e64 v13, v13, v21
	v_add_f32_e64 v14, v14, v24
	v_add_f32_e64 v15, v15, v25
	v_mul_f32_e64 v20, v100, v134
	v_mul_f32_e64 v21, v101, v135
	v_fma_f32 v24, v160, v128, v2
	v_fma_f32 v25, v161, v129, v2
	v_fma_f32 v28, v160, v28, v38
	v_fma_f32 v29, v160, v29, v39
	v_fma_f32 v38, v160, v54, v48
	v_fma_f32 v39, v160, v55, v49
	s_waitcnt vmcnt(6)
	v_mov_b32_e32 v2, v163
	v_add_f32_e64 v80, v80, v81
	v_mov_b32_e32 v81, v80
	v_fma_f32 v52, v158, v92, v58
	v_fma_f32 v53, v158, v93, v59
	v_mul_f32_e64 v51, v50, v105
	v_mul_f32_e64 v50, v50, v104
	v_fma_f32 v20, v60, v132, v20
	v_fma_f32 v21, v61, v133, v21
	v_mul_f32_e64 v54, v2, v66
	v_mul_f32_e64 v55, v2, v67
	v_mul_f32_e64 v58, v2, v82
	v_mul_f32_e64 v59, v2, v83
	v_mul_f32_e64 v60, v2, v114
	v_mul_f32_e64 v61, v2, v115
	v_add_f32_e64 v26, v26, v28
	v_add_f32_e64 v27, v27, v29
	v_add_f32_e64 v28, v46, v38
	v_add_f32_e64 v29, v47, v39
	s_waitcnt vmcnt(4)
	v_mov_b32_e32 v2, v165
	s_waitcnt lgkmcnt(3)
	v_mul_f32_e32 v99, v162, v138
	v_fma_f32 v48, v160, v94, v50
	v_fma_f32 v49, v160, v95, v51
	v_mul_f32_e32 v25, v163, v139
	s_waitcnt lgkmcnt(1)
	v_mul_f32_e32 v50, v163, v147
	v_mul_f32_e32 v23, v164, v140
	v_mul_f32_e32 v81, v165, v141
	v_add_f32_e64 v14, v14, v28
	v_add_f32_e64 v15, v15, v29
	v_mul_f32_e64 v28, v2, v68
	v_mul_f32_e64 v29, v2, v69
	s_waitcnt lgkmcnt(0)
	v_pk_mov_b32 v[18:19], v[18:19], v[150:151] op_sel:[1,0]
	v_mov_b32_e32 v40, v90
	v_add_f32_e64 v38, v52, v48
	v_add_f32_e64 v39, v53, v49
	v_fma_f32 v46, v162, v146, v50
	v_fma_f32 v47, v163, v147, v50
	v_fma_f32 v30, v162, v30, v54
	v_fma_f32 v31, v162, v31, v55
	v_fma_f32 v48, v162, v56, v58
	v_fma_f32 v49, v162, v57, v59
	v_fma_f32 v50, v162, v96, v60
	v_fma_f32 v51, v162, v97, v61
	v_add_f32_e64 v24, v98, v24
	v_add_f32_e64 v25, v99, v25
	v_add_f32_e64 v12, v12, v26
	v_add_f32_e64 v13, v13, v27
	v_mul_f32_e32 v26, v165, v149
	s_waitcnt vmcnt(3)
	v_mov_b32_e32 v41, v166
	v_add_f32_e64 v22, v22, v80
	v_add_f32_e64 v23, v23, v81
	v_fma_f32 v28, v164, v32, v28
	v_fma_f32 v29, v164, v33, v29
	s_waitcnt vmcnt(2)
	v_mul_f32_e64 v32, v168, v70
	v_mul_f32_e64 v33, v168, v71
	s_waitcnt vmcnt(0)
	v_mul_f32_e64 v54, v172, v72
	v_mul_f32_e64 v55, v172, v73
	v_mul_f32_e64 v56, v168, v86
	v_mul_f32_e64 v57, v168, v87
	v_mul_f32_e64 v60, v168, v118
	v_mul_f32_e64 v61, v168, v119
	v_mov_b32_e32 v136, v143
	v_mov_b32_e32 v143, v145
	v_add_f32_e64 v42, v18, v90
	v_add_f32_e64 v43, v19, v91
	v_add_f32_e64 v20, v20, v21
	v_mov_b32_e32 v21, v20
	v_fma_f32 v27, v165, v149, v26
	v_fma_f32 v26, v164, v148, v26
	v_mul_f32_e32 v45, v172, v153
	v_mul_f32_e64 v18, v18, v40
	v_mul_f32_e64 v19, v19, v41
	v_add_f32_e64 v22, v24, v22
	v_add_f32_e64 v23, v25, v23
	v_add_f32_e64 v24, v30, v28
	v_add_f32_e64 v25, v31, v29
	v_fma_f32 v28, v166, v34, v32
	v_fma_f32 v29, v166, v35, v33
	v_fma_f32 v30, v170, v36, v54
	v_fma_f32 v31, v170, v37, v55
	v_fma_f32 v34, v166, v76, v56
	v_fma_f32 v35, v166, v77, v57
	v_fma_f32 v40, v166, v108, v60
	v_fma_f32 v41, v166, v109, v61
	v_mov_b32_e32 v167, v172
	v_mov_b32_e32 v137, v144
	v_add_f32_e64 v16, v16, v38
	v_add_f32_e64 v17, v17, v39
	v_mul_f32_e64 v38, v2, v84
	v_mul_f32_e64 v39, v2, v85
	v_mul_f32_e64 v52, v2, v116
	v_mul_f32_e64 v53, v2, v117
	v_mov_b32_e32 v169, v170
	v_mul_f32_e32 v21, v168, v151
	v_mul_f32_e32 v47, v170, v152
	v_mov_b32_e32 v43, v19
	v_mov_b32_e32 v27, v45
	v_add_f32_e64 v18, v22, v23
	v_add_f32_e64 v19, v23, v22
	v_add_f32_e64 v12, v12, v24
	v_add_f32_e64 v13, v13, v25
	v_add_f32_e64 v22, v28, v30
	v_add_f32_e64 v23, v29, v31
	v_mul_f32_e64 v30, v166, v142
	v_mul_f32_e64 v31, v167, v143
	v_fma_f32 v38, v164, v74, v38
	v_fma_f32 v39, v164, v75, v39
	v_mul_f32_e64 v58, v172, v88
	v_mul_f32_e64 v59, v172, v89
	v_fma_f32 v52, v164, v106, v52
	v_fma_f32 v53, v164, v107, v53
	v_mul_f32_e64 v62, v172, v120
	v_mul_f32_e64 v63, v172, v121
	v_add_f32_e64 v20, v42, v20
	v_add_f32_e64 v21, v43, v21
	v_add_f32_e64 v26, v46, v26
	v_add_f32_e64 v27, v47, v27
	v_add_f32_e64 v12, v12, v22
	v_add_f32_e64 v13, v13, v23
	v_fma_f32 v22, v168, v136, v30
	v_fma_f32 v23, v169, v137, v31
	v_add_f32_e64 v32, v48, v38
	v_add_f32_e64 v33, v49, v39
	v_fma_f32 v36, v170, v78, v58
	v_fma_f32 v37, v170, v79, v59
	v_add_f32_e64 v38, v50, v52
	v_add_f32_e64 v39, v51, v53
	v_fma_f32 v48, v170, v110, v62
	v_fma_f32 v49, v170, v111, v63
	v_add_f32_e64 v20, v20, v26
	v_add_f32_e64 v21, v21, v27
	v_add_f32_e64 v22, v22, v23
	v_mov_b32_e32 v23, v22
	v_add_f32_e64 v14, v14, v32
	v_add_f32_e64 v15, v15, v33
	v_add_f32_e64 v24, v34, v36
	v_add_f32_e64 v25, v35, v37
	v_add_f32_e64 v16, v16, v38
	v_add_f32_e64 v17, v17, v39
	v_add_f32_e64 v28, v40, v48
	v_add_f32_e64 v29, v41, v49
	v_mov_b32_e32 v19, v20
	v_mov_b32_e32 v23, v21
	v_lshl_add_u64 v[10:11], v[10:11], 0, s[16:17]
	v_add_f32_e64 v14, v14, v24
	v_add_f32_e64 v15, v15, v25
	v_add_f32_e64 v16, v16, v28
	v_add_f32_e64 v17, v17, v29
	v_add_f32_e64 v18, v18, v22
	v_add_f32_e64 v19, v19, v23
	s_cbranch_scc1 .LBB0_54
	s_lshl_b32 s9, s22, 6
	s_and_b32 s9, s9, 0x3c0
	v_or_b32_e32 v2, s9, v44
	v_lshlrev_b32_e32 v2, 11, v2
	v_cvt_pk_bf16_f32 v10, v12, v13
	v_cvt_pk_bf16_f32 v11, v14, v15
	v_lshl_add_u64 v[14:15], s[4:5], 0, v[2:3]
	s_lshl_b32 s14, s24, 1
	v_lshl_add_u64 v[14:15], v[14:15], 0, s[14:15]
	s_lshl_b32 s14, s23, 1
	v_lshl_add_u64 v[14:15], v[14:15], 0, s[14:15]
	v_cvt_pk_bf16_f32 v12, v16, v17
	v_cvt_pk_bf16_f32 v13, v18, v19
	global_store_dwordx4 v[14:15], v[10:13], off
	s_waitcnt lgkmcnt(0)
	s_add_i32 s22, s22, s10
	s_add_i32 s21, s21, s2
	s_cmpk_gt_i32 s22, 0x3ff
	s_cbranch_scc0 .LBB0_53

.LBB0_149:
	s_bitcmp1_b32 s47, 0
	s_cselect_b64 s[24:25], -1, 0
	s_and_b64 vcc, exec, s[24:25]
	s_cbranch_vccnz .LBB0_151
	s_and_b64 s[24:25], s[12:13], exec
	s_cselect_b32 s15, s22, s49
	v_lshl_or_b32 v140, s15, 8, v145
	v_ashrrev_i32_e32 v141, 31, v140
	v_lshlrev_b64 v[140:141], 6, v[140:141]
	v_lshl_add_u64 v[140:141], s[4:5], 0, v[140:141]
	global_load_dwordx4 v[150:153], v[140:141], off offset:48
	global_load_dwordx4 v[154:157], v[140:141], off offset:32
	global_load_dwordx4 v[158:161], v[140:141], off offset:16
	global_load_dwordx4 v[162:165], v[140:141], off
	s_waitcnt vmcnt(0)
	v_add_f32_e32 v154, v154, v155
	v_add_f32_e32 v156, v156, v157
	v_mov_b32_e32 v140, v163
	v_mov_b32_e32 v141, v164
	v_mov_b32_e32 v163, v165
	v_add_f32_e64 v140, v140, v162
	v_add_f32_e64 v141, v141, v163
	v_mov_b32_e32 v162, v159
	v_mov_b32_e32 v163, v160
	v_mov_b32_e32 v159, v161
	v_add_f32_e64 v158, v162, v158
	v_add_f32_e64 v159, v163, v159
	v_add_f32_e64 v140, v140, v141
	v_mov_b32_e32 v141, v140
	v_add_f32_e64 v158, v158, v159
	v_mov_b32_e32 v159, v158
	v_mov_b32_e32 v141, v150
	v_mov_b32_e32 v159, v151
	v_mov_b32_e32 v155, v152
	v_mov_b32_e32 v157, v153
	v_add_f32_e64 v140, v140, v158
	v_add_f32_e64 v141, v141, v159
	v_add_f32_e64 v150, v154, v156
	v_add_f32_e64 v151, v155, v157
	s_nop 0
	v_add_f32_e64 v140, v140, v150
	v_add_f32_e64 v141, v141, v151
	s_nop 0
	v_add_f32_e32 v140, v140, v141
	v_fmamk_f32 v140, v140, 0x3a800000, v249
	v_rsq_f32_e32 v140, v140
	ds_write_b32 v147, v140
	s_waitcnt lgkmcnt(0)
	s_barrier

.LBB0_165:
	s_and_b64 s[8:9], s[6:7], exec
	s_cselect_b32 s8, 8, 48
	s_add_u32 s8, s2, s8
	s_addc_u32 s9, s3, 0
	s_and_b64 s[6:7], s[6:7], exec
	s_sext_i32_i16 s29, s10
	s_cselect_b32 s6, 2, 7
	s_add_i32 s60, s6, s29
	s_lshl_b64 s[6:7], s[60:61], 3
	s_add_u32 s6, s2, s6
	s_addc_u32 s7, s3, s7
	s_load_dwordx2 s[10:11], s[8:9], 0x0
	s_nop 0
	s_load_dwordx2 s[6:7], s[6:7], 0x0
	s_waitcnt lgkmcnt(0)
	s_add_u32 s34, s6, s28
	s_sext_i32_i16 s6, s26
	s_mulk_i32 s6, 0xba3
	s_addc_u32 s35, s7, s27
	s_lshr_b32 s7, s6, 31
	s_ashr_i32 s6, s6, 18
	s_add_i32 s6, s6, s7
	s_mul_i32 s7, s6, 0x58
	s_lshl_b32 s6, s6, 6
	s_sub_i32 s26, s26, s7
	v_or_b32_e32 v7, s6, v0
	s_sext_i32_i16 s7, s26
	v_mul_i32_i24_e32 v8, 0xb00, v7
	s_lshl_b32 s8, s7, 5
	v_ashrrev_i32_e32 v9, 31, v8
	v_lshl_add_u64 v[8:9], v[8:9], 2, s[34:35]
	s_ashr_i32 s9, s8, 31
	v_lshl_add_u64 v[8:9], s[8:9], 2, v[8:9]
	v_lshl_add_u64 v[38:39], v[8:9], 0, v[96:97]
	s_movk_i32 s7, 0x5000
	v_add_co_u32_e32 v10, vcc, s7, v38
	s_mov_b32 s7, 0x10000
	s_nop 0
	v_addc_co_u32_e32 v11, vcc, 0, v39, vcc
	global_load_dword v9, v[10:11], off offset:2048
	v_add_co_u32_e32 v10, vcc, s76, v38
	global_load_dword v8, v[38:39], off
	s_nop 0
	v_addc_co_u32_e32 v11, vcc, 0, v39, vcc
	v_add_co_u32_e32 v12, vcc, s7, v38
	global_load_dword v10, v[10:11], off
	s_nop 0
	v_addc_co_u32_e32 v13, vcc, 0, v39, vcc
	global_load_dword v11, v[12:13], off offset:2048
	v_add_co_u32_e32 v12, vcc, s74, v38
	s_mov_b32 s7, 0x1b000
	s_nop 0
	v_addc_co_u32_e32 v13, vcc, 0, v39, vcc
	v_add_co_u32_e32 v14, vcc, s7, v38
	s_mov_b32 s7, 0x21000
	s_nop 0
	v_addc_co_u32_e32 v15, vcc, 0, v39, vcc
	global_load_dword v12, v[12:13], off
	s_nop 0
	global_load_dword v13, v[14:15], off offset:2048
	v_add_co_u32_e32 v14, vcc, s7, v38
	s_mov_b32 s7, 0x31000
	s_nop 0
	v_addc_co_u32_e32 v15, vcc, 0, v39, vcc
	v_add_co_u32_e32 v16, vcc, s40, v38
	global_load_dword v14, v[14:15], off
	s_nop 0
	v_addc_co_u32_e32 v17, vcc, 0, v39, vcc
	global_load_dword v15, v[16:17], off offset:2048
	v_add_co_u32_e32 v16, vcc, s41, v38
	s_nop 1
	v_addc_co_u32_e32 v17, vcc, 0, v39, vcc
	v_add_co_u32_e32 v18, vcc, s7, v38
	s_mov_b32 s7, 0x37000
	s_nop 0
	v_addc_co_u32_e32 v19, vcc, 0, v39, vcc
	global_load_dword v16, v[16:17], off
	s_nop 0
	global_load_dword v17, v[18:19], off offset:2048
	v_add_co_u32_e32 v18, vcc, s7, v38
	s_mov_b32 s7, 0x3c000
	s_nop 0
	v_addc_co_u32_e32 v19, vcc, 0, v39, vcc
	v_add_co_u32_e32 v20, vcc, s7, v38
	s_mov_b32 s7, 0x42000
	s_nop 0
	v_addc_co_u32_e32 v21, vcc, 0, v39, vcc
	global_load_dword v18, v[18:19], off
	s_nop 0
	global_load_dword v19, v[20:21], off offset:2048
	v_add_co_u32_e32 v20, vcc, s7, v38
	s_mov_b32 s7, 0x47000
	s_nop 0
	v_addc_co_u32_e32 v21, vcc, 0, v39, vcc
	v_add_co_u32_e32 v22, vcc, s7, v38
	s_mov_b32 s7, 0x4d000
	s_nop 0
	v_addc_co_u32_e32 v23, vcc, 0, v39, vcc
	global_load_dword v20, v[20:21], off
	s_nop 0
	global_load_dword v21, v[22:23], off offset:2048
	v_add_co_u32_e32 v22, vcc, s7, v38
	s_mov_b32 s7, 0x52000
	s_nop 0
	v_addc_co_u32_e32 v23, vcc, 0, v39, vcc
	v_add_co_u32_e32 v24, vcc, s7, v38
	s_mov_b32 s7, 0x58000
	s_nop 0
	v_addc_co_u32_e32 v25, vcc, 0, v39, vcc
	global_load_dword v22, v[22:23], off
	s_nop 0
	global_load_dword v23, v[24:25], off offset:2048
	v_add_co_u32_e32 v24, vcc, s7, v38
	s_mov_b32 s7, 0x5d000
	s_nop 0
	v_addc_co_u32_e32 v25, vcc, 0, v39, vcc
	v_add_co_u32_e32 v26, vcc, s7, v38
	s_mov_b32 s7, 0x63000
	s_nop 0
	v_addc_co_u32_e32 v27, vcc, 0, v39, vcc
	global_load_dword v24, v[24:25], off
	s_nop 0
	global_load_dword v25, v[26:27], off offset:2048
	v_add_co_u32_e32 v26, vcc, s7, v38
	s_mov_b32 s7, 0x68000
	s_nop 0
	v_addc_co_u32_e32 v27, vcc, 0, v39, vcc
	v_add_co_u32_e32 v28, vcc, s7, v38
	s_mov_b32 s7, 0x6e000
	s_nop 0
	v_addc_co_u32_e32 v29, vcc, 0, v39, vcc
	global_load_dword v26, v[26:27], off
	s_nop 0
	global_load_dword v27, v[28:29], off offset:2048
	v_add_co_u32_e32 v28, vcc, s7, v38
	s_mov_b32 s7, 0x73000
	s_nop 0
	v_addc_co_u32_e32 v29, vcc, 0, v39, vcc
	v_add_co_u32_e32 v30, vcc, s7, v38
	s_mov_b32 s7, 0x79000
	s_nop 0
	v_addc_co_u32_e32 v31, vcc, 0, v39, vcc
	global_load_dword v28, v[28:29], off
	s_nop 0
	global_load_dword v29, v[30:31], off offset:2048
	v_add_co_u32_e32 v30, vcc, s7, v38
	s_mov_b32 s7, 0x7e000
	s_nop 0
	v_addc_co_u32_e32 v31, vcc, 0, v39, vcc
	v_add_co_u32_e32 v32, vcc, s7, v38
	s_mov_b32 s7, 0x84000
	s_nop 0
	v_addc_co_u32_e32 v33, vcc, 0, v39, vcc
	global_load_dword v30, v[30:31], off
	s_nop 0
	global_load_dword v31, v[32:33], off offset:2048
	v_add_co_u32_e32 v32, vcc, s7, v38
	s_mov_b32 s7, 0x89000
	s_nop 0
	v_addc_co_u32_e32 v33, vcc, 0, v39, vcc
	v_add_co_u32_e32 v34, vcc, s7, v38
	s_mov_b32 s7, 0x8f000
	s_nop 0
	v_addc_co_u32_e32 v35, vcc, 0, v39, vcc
	global_load_dword v32, v[32:33], off
	s_nop 0
	global_load_dword v33, v[34:35], off offset:2048
	v_add_co_u32_e32 v34, vcc, s7, v38
	s_mov_b32 s7, 0x94000
	s_nop 0
	v_addc_co_u32_e32 v35, vcc, 0, v39, vcc
	v_add_co_u32_e32 v36, vcc, s7, v38
	s_mov_b32 s7, 0x9a000
	s_nop 0
	v_addc_co_u32_e32 v37, vcc, 0, v39, vcc
	global_load_dword v34, v[34:35], off
	s_nop 0
	global_load_dword v35, v[36:37], off offset:2048
	v_add_co_u32_e32 v36, vcc, s7, v38
	s_mov_b32 s7, 0x9f000
	s_nop 0
	v_addc_co_u32_e32 v37, vcc, 0, v39, vcc
	v_add_co_u32_e32 v40, vcc, s7, v38
	global_load_dword v36, v[36:37], off
	s_nop 0
	v_addc_co_u32_e32 v41, vcc, 0, v39, vcc
	global_load_dword v37, v[40:41], off offset:2048
	v_add_co_u32_e32 v40, vcc, 0xa5000, v38
	s_ashr_i32 s7, s6, 31
	s_nop 0
	v_addc_co_u32_e32 v41, vcc, 0, v39, vcc
	v_add_co_u32_e32 v38, vcc, 0xaa000, v38
	global_load_dword v40, v[40:41], off
	s_nop 0
	v_addc_co_u32_e32 v39, vcc, 0, v39, vcc
	global_load_dword v41, v[38:39], off offset:2048
	s_cmp_eq_u64 s[10:11], 0
	s_cbranch_scc1 .LBB0_160
	s_lshl_b64 s[4:5], s[4:5], 12
	s_add_u32 s9, s10, s4
	s_addc_u32 s10, s11, s5
	s_lshl_b64 s[4:5], s[6:7], 2
	s_add_u32 s4, s9, s4
	s_addc_u32 s5, s10, s5
	v_lshlrev_b32_e32 v7, 2, v0
	global_load_dword v38, v7, s[4:5]
	global_load_dword v39, v7, s[4:5] offset:8
	global_load_dword v52, v7, s[4:5] offset:16
	global_load_dword v53, v7, s[4:5] offset:24
	global_load_dword v54, v7, s[4:5] offset:32
	global_load_dword v55, v7, s[4:5] offset:40
	global_load_dword v56, v7, s[4:5] offset:48
	global_load_dword v57, v7, s[4:5] offset:56
	global_load_dword v58, v7, s[4:5] offset:64
	global_load_dword v59, v7, s[4:5] offset:72
	global_load_dword v60, v7, s[4:5] offset:80
	global_load_dword v61, v7, s[4:5] offset:88
	global_load_dword v62, v7, s[4:5] offset:96
	global_load_dword v63, v7, s[4:5] offset:104
	global_load_dword v64, v7, s[4:5] offset:112
	global_load_dword v65, v7, s[4:5] offset:120
	global_load_dword v66, v7, s[4:5] offset:128
	global_load_dword v67, v7, s[4:5] offset:136
	global_load_dword v68, v7, s[4:5] offset:144
	global_load_dword v69, v7, s[4:5] offset:152
	global_load_dword v70, v7, s[4:5] offset:160
	global_load_dword v71, v7, s[4:5] offset:168
	global_load_dword v72, v7, s[4:5] offset:176
	global_load_dword v73, v7, s[4:5] offset:184
	global_load_dword v74, v7, s[4:5] offset:192
	global_load_dword v75, v7, s[4:5] offset:200
	global_load_dword v76, v7, s[4:5] offset:208
	global_load_dword v77, v7, s[4:5] offset:216
	global_load_dword v78, v7, s[4:5] offset:224
	global_load_dword v79, v7, s[4:5] offset:232
	global_load_dword v80, v7, s[4:5] offset:240
	global_load_dword v81, v7, s[4:5] offset:248
	s_waitcnt vmcnt(0)
	v_mul_f32_e64 v8, v8, v38
	v_mul_f32_e64 v9, v9, v39
	v_mul_f32_e64 v10, v10, v52
	v_mul_f32_e64 v11, v11, v53
	v_mul_f32_e64 v12, v12, v54
	v_mul_f32_e64 v13, v13, v55
	v_mul_f32_e64 v14, v14, v56
	v_mul_f32_e64 v15, v15, v57
	v_mul_f32_e64 v16, v16, v58
	v_mul_f32_e64 v17, v17, v59
	v_mul_f32_e64 v18, v18, v60
	v_mul_f32_e64 v19, v19, v61
	v_mul_f32_e64 v20, v20, v62
	v_mul_f32_e64 v21, v21, v63
	v_mul_f32_e64 v22, v22, v64
	v_mul_f32_e64 v23, v23, v65
	v_mul_f32_e64 v24, v24, v66
	v_mul_f32_e64 v25, v25, v67
	v_mul_f32_e64 v26, v26, v68
	v_mul_f32_e64 v27, v27, v69
	v_mul_f32_e64 v28, v28, v70
	v_mul_f32_e64 v29, v29, v71
	v_mul_f32_e64 v30, v30, v72
	v_mul_f32_e64 v31, v31, v73
	v_mul_f32_e64 v32, v32, v74
	v_mul_f32_e64 v33, v33, v75
	v_mul_f32_e64 v34, v34, v76
	v_mul_f32_e64 v35, v35, v77
	v_mul_f32_e64 v36, v36, v78
	v_mul_f32_e64 v37, v37, v79
	v_mul_f32_e64 v40, v40, v80
	v_mul_f32_e64 v41, v41, v81
	s_branch .LBB0_160

.LBB0_190:
	s_andn2_b64 vcc, exec, s[4:5]
	s_cbranch_vccnz .LBB0_194
	s_load_dwordx4 s[4:7], s[2:3], 0x68
	s_and_b64 s[34:35], s[12:13], exec
	s_cselect_b32 s31, 0x100000, 0
	s_waitcnt lgkmcnt(0)
	s_add_u32 s34, s6, s31
	s_addc_u32 s35, s7, 0
	s_lshl_b32 s6, s29, 1
	s_and_b32 s6, s6, 0x7c0
	s_addk_i32 s6, 0xfa40
	v_or_b32_e32 v96, s6, v0
	v_lshlrev_b64 v[6:7], 12, v[96:97]
	s_lshl_b32 s7, s29, 7
	v_lshl_add_u64 v[6:7], s[34:35], 0, v[6:7]
	s_and_b32 s60, s7, 0xf80
	v_lshl_add_u64 v[6:7], v[6:7], 0, s[60:61]
	v_lshlrev_b32_e32 v96, 2, v2
	v_lshl_add_u64 v[38:39], v[6:7], 0, v[96:97]
	v_add_co_u32_e32 v8, vcc, s68, v38
	global_load_dword v6, v[38:39], off
	s_nop 0
	v_addc_co_u32_e32 v9, vcc, 0, v39, vcc
	global_load_dword v7, v[8:9], off
	v_add_co_u32_e32 v8, vcc, s75, v38
	s_mov_b32 s7, 0x10000
	s_nop 0
	v_addc_co_u32_e32 v9, vcc, 0, v39, vcc
	v_add_co_u32_e32 v10, vcc, s79, v38
	global_load_dword v8, v[8:9], off
	s_nop 0
	v_addc_co_u32_e32 v11, vcc, 0, v39, vcc
	global_load_dword v9, v[10:11], off
	v_add_co_u32_e32 v10, vcc, s87, v38
	s_cmp_eq_u64 s[4:5], 0
	s_nop 0
	v_addc_co_u32_e32 v11, vcc, 0, v39, vcc
	v_add_co_u32_e32 v12, vcc, s88, v38
	global_load_dword v10, v[10:11], off
	s_nop 0
	v_addc_co_u32_e32 v13, vcc, 0, v39, vcc
	global_load_dword v11, v[12:13], off
	v_add_co_u32_e32 v12, vcc, s62, v38
	s_mov_b32 s60, s6
	s_nop 0
	v_addc_co_u32_e32 v13, vcc, 0, v39, vcc
	v_add_co_u32_e32 v14, vcc, s94, v38
	global_load_dword v12, v[12:13], off
	s_nop 0
	v_addc_co_u32_e32 v15, vcc, 0, v39, vcc
	global_load_dword v13, v[14:15], off
	v_add_co_u32_e32 v14, vcc, s7, v38
	s_mov_b32 s7, 0x22000
	s_nop 0
	v_addc_co_u32_e32 v15, vcc, 0, v39, vcc
	v_add_co_u32_e32 v16, vcc, s72, v38
	global_load_dword v14, v[14:15], off
	s_nop 0
	v_addc_co_u32_e32 v17, vcc, 0, v39, vcc
	global_load_dword v15, v[16:17], off
	v_add_co_u32_e32 v16, vcc, s73, v38
	s_nop 1
	v_addc_co_u32_e32 v17, vcc, 0, v39, vcc
	v_add_co_u32_e32 v18, vcc, s74, v38
	global_load_dword v16, v[16:17], off
	s_nop 0
	v_addc_co_u32_e32 v19, vcc, 0, v39, vcc
	global_load_dword v17, v[18:19], off
	v_add_co_u32_e32 v18, vcc, s85, v38
	s_nop 1
	v_addc_co_u32_e32 v19, vcc, 0, v39, vcc
	v_add_co_u32_e32 v20, vcc, s86, v38
	global_load_dword v18, v[18:19], off
	s_nop 0
	v_addc_co_u32_e32 v21, vcc, 0, v39, vcc
	global_load_dword v19, v[20:21], off
	v_add_co_u32_e32 v20, vcc, s90, v38
	s_nop 1
	v_addc_co_u32_e32 v21, vcc, 0, v39, vcc
	v_add_co_u32_e32 v22, vcc, s91, v38
	global_load_dword v20, v[20:21], off
	s_nop 0
	v_addc_co_u32_e32 v23, vcc, 0, v39, vcc
	global_load_dword v21, v[22:23], off
	v_add_co_u32_e32 v22, vcc, s95, v38
	s_nop 1
	v_addc_co_u32_e32 v23, vcc, 0, v39, vcc
	v_add_co_u32_e32 v24, vcc, s7, v38
	s_mov_b32 s7, 0x24000
	s_nop 0
	v_addc_co_u32_e32 v25, vcc, 0, v39, vcc
	global_load_dword v22, v[22:23], off
	s_nop 0
	global_load_dword v23, v[24:25], off
	v_add_co_u32_e32 v24, vcc, s7, v38
	s_mov_b32 s7, 0x28000
	s_nop 0
	v_addc_co_u32_e32 v25, vcc, 0, v39, vcc
	v_add_co_u32_e32 v26, vcc, s40, v38
	global_load_dword v24, v[24:25], off
	s_nop 0
	v_addc_co_u32_e32 v27, vcc, 0, v39, vcc
	global_load_dword v25, v[26:27], off
	v_add_co_u32_e32 v26, vcc, s7, v38
	s_mov_b32 s7, 0x2a000
	s_nop 0
	v_addc_co_u32_e32 v27, vcc, 0, v39, vcc
	v_add_co_u32_e32 v28, vcc, s7, v38
	global_load_dword v26, v[26:27], off
	s_nop 0
	v_addc_co_u32_e32 v29, vcc, 0, v39, vcc
	global_load_dword v27, v[28:29], off
	v_add_co_u32_e32 v28, vcc, s41, v38
	s_mov_b32 s7, 0x2e000
	s_nop 0
	v_addc_co_u32_e32 v29, vcc, 0, v39, vcc
	v_add_co_u32_e32 v30, vcc, s7, v38
	s_mov_b32 s7, 0x30000
	s_nop 0
	v_addc_co_u32_e32 v31, vcc, 0, v39, vcc
	global_load_dword v28, v[28:29], off
	s_nop 0
	global_load_dword v29, v[30:31], off
	v_add_co_u32_e32 v30, vcc, s7, v38
	s_mov_b32 s7, 0x32000
	s_nop 0
	v_addc_co_u32_e32 v31, vcc, 0, v39, vcc
	v_add_co_u32_e32 v32, vcc, s7, v38
	s_mov_b32 s7, 0x34000
	s_nop 0
	v_addc_co_u32_e32 v33, vcc, 0, v39, vcc
	global_load_dword v30, v[30:31], off
	s_nop 0
	global_load_dword v31, v[32:33], off
	v_add_co_u32_e32 v32, vcc, s7, v38
	s_mov_b32 s7, 0x36000
	s_nop 0
	v_addc_co_u32_e32 v33, vcc, 0, v39, vcc
	v_add_co_u32_e32 v34, vcc, s7, v38
	s_mov_b32 s7, 0x38000
	s_nop 0
	v_addc_co_u32_e32 v35, vcc, 0, v39, vcc
	global_load_dword v32, v[32:33], off
	s_nop 0
	global_load_dword v33, v[34:35], off
	v_add_co_u32_e32 v34, vcc, s7, v38
	s_nop 1
	v_addc_co_u32_e32 v35, vcc, 0, v39, vcc
	v_add_co_u32_e32 v36, vcc, 0x3a000, v38
	global_load_dword v34, v[34:35], off
	s_nop 0
	v_addc_co_u32_e32 v37, vcc, 0, v39, vcc
	global_load_dword v35, v[36:37], off
	v_add_co_u32_e32 v36, vcc, 0x3c000, v38
	s_nop 1
	v_addc_co_u32_e32 v37, vcc, 0, v39, vcc
	v_add_co_u32_e32 v38, vcc, 0x3e000, v38
	global_load_dword v36, v[36:37], off
	s_nop 0
	v_addc_co_u32_e32 v39, vcc, 0, v39, vcc
	global_load_dword v37, v[38:39], off
	s_cbranch_scc1 .LBB0_193
	s_and_b64 s[6:7], s[12:13], exec
	s_cselect_b32 s6, 0x400, 0
	s_add_u32 s6, s4, s6
	s_addc_u32 s7, s5, 0
	s_lshl_b64 s[4:5], s[60:61], 2
	s_add_u32 s4, s6, s4
	s_addc_u32 s5, s7, s5
	v_lshlrev_b32_e32 v45, 2, v0
	global_load_dword v38, v45, s[4:5]
	global_load_dword v39, v45, s[4:5] offset:8
	global_load_dword v40, v45, s[4:5] offset:16
	global_load_dword v41, v45, s[4:5] offset:24
	global_load_dword v46, v45, s[4:5] offset:32
	global_load_dword v47, v45, s[4:5] offset:40
	global_load_dword v48, v45, s[4:5] offset:48
	global_load_dword v49, v45, s[4:5] offset:56
	global_load_dword v50, v45, s[4:5] offset:64
	global_load_dword v51, v45, s[4:5] offset:72
	global_load_dword v52, v45, s[4:5] offset:80
	global_load_dword v53, v45, s[4:5] offset:88
	global_load_dword v54, v45, s[4:5] offset:96
	global_load_dword v55, v45, s[4:5] offset:104
	global_load_dword v56, v45, s[4:5] offset:112
	global_load_dword v57, v45, s[4:5] offset:120
	global_load_dword v58, v45, s[4:5] offset:128
	global_load_dword v59, v45, s[4:5] offset:136
	global_load_dword v60, v45, s[4:5] offset:144
	global_load_dword v61, v45, s[4:5] offset:152
	global_load_dword v62, v45, s[4:5] offset:160
	global_load_dword v63, v45, s[4:5] offset:168
	global_load_dword v64, v45, s[4:5] offset:176
	global_load_dword v65, v45, s[4:5] offset:184
	global_load_dword v66, v45, s[4:5] offset:192
	global_load_dword v67, v45, s[4:5] offset:200
	global_load_dword v68, v45, s[4:5] offset:208
	global_load_dword v69, v45, s[4:5] offset:216
	global_load_dword v70, v45, s[4:5] offset:224
	global_load_dword v71, v45, s[4:5] offset:232
	global_load_dword v72, v45, s[4:5] offset:240
	global_load_dword v73, v45, s[4:5] offset:248
	s_waitcnt vmcnt(0)
	v_mul_f32_e64 v6, v6, v38
	v_mul_f32_e64 v7, v7, v39
	v_mul_f32_e64 v8, v8, v40
	v_mul_f32_e64 v9, v9, v41
	v_mul_f32_e64 v10, v10, v46
	v_mul_f32_e64 v11, v11, v47
	v_mul_f32_e64 v12, v12, v48
	v_mul_f32_e64 v13, v13, v49
	v_mul_f32_e64 v14, v14, v50
	v_mul_f32_e64 v15, v15, v51
	v_mul_f32_e64 v16, v16, v52
	v_mul_f32_e64 v17, v17, v53
	v_mul_f32_e64 v18, v18, v54
	v_mul_f32_e64 v19, v19, v55
	v_mul_f32_e64 v20, v20, v56
	v_mul_f32_e64 v21, v21, v57
	v_mul_f32_e64 v22, v22, v58
	v_mul_f32_e64 v23, v23, v59
	v_mul_f32_e64 v24, v24, v60
	v_mul_f32_e64 v25, v25, v61
	v_mul_f32_e64 v26, v26, v62
	v_mul_f32_e64 v27, v27, v63
	v_mul_f32_e64 v28, v28, v64
	v_mul_f32_e64 v29, v29, v65
	v_mul_f32_e64 v30, v30, v66
	v_mul_f32_e64 v31, v31, v67
	v_mul_f32_e64 v32, v32, v68
	v_mul_f32_e64 v33, v33, v69
	v_mul_f32_e64 v34, v34, v70
	v_mul_f32_e64 v35, v35, v71
	v_mul_f32_e64 v36, v36, v72
	v_mul_f32_e64 v37, v37, v73

.LBB0_195:
	s_andn2_b64 vcc, exec, s[4:5]
	s_cbranch_vccnz .LBB0_199
	s_add_i32 s4, s29, 0xffb0
	s_and_b32 s5, s4, 0xff
	s_mulk_i32 s5, 0xab
	s_bfe_u32 s36, s5, 0x4000c
	s_mul_i32 s5, s36, 24
	s_sub_i32 s4, s4, s5
	s_and_b32 s31, s4, 0xff
	s_load_dwordx4 s[4:7], s[2:3], 0x58
	s_and_b64 s[34:35], s[12:13], exec
	s_cselect_b32 s34, 0x120000, 0
	s_waitcnt lgkmcnt(0)
	s_add_u32 s34, s6, s34
	s_addc_u32 s35, s7, 0
	s_lshl_b32 s6, s36, 6
	v_or_b32_e32 v6, s6, v0
	v_mul_u32_u24_e32 v6, 0x300, v6
	v_lshlrev_b32_e32 v96, 2, v6
	v_lshl_add_u64 v[6:7], s[34:35], 0, v[96:97]
	s_lshl_b32 s60, s31, 7
	v_lshl_add_u64 v[6:7], v[6:7], 0, s[60:61]
	v_lshlrev_b32_e32 v96, 2, v2
	v_lshl_add_u64 v[34:35], v[6:7], 0, v[96:97]
	s_movk_i32 s7, 0x1000
	v_add_co_u32_e32 v8, vcc, s7, v34
	s_movk_i32 s7, 0x3000
	s_nop 0
	v_addc_co_u32_e32 v9, vcc, 0, v35, vcc
	global_load_dword v7, v[8:9], off offset:2048
	v_add_co_u32_e32 v8, vcc, s7, v34
	global_load_dword v6, v[34:35], off
	s_nop 0
	v_addc_co_u32_e32 v9, vcc, 0, v35, vcc
	v_add_co_u32_e32 v10, vcc, s75, v34
	global_load_dword v8, v[8:9], off
	s_nop 0
	v_addc_co_u32_e32 v11, vcc, 0, v35, vcc
	global_load_dword v9, v[10:11], off offset:2048
	v_add_co_u32_e32 v10, vcc, s79, v34
	s_movk_i32 s7, 0x7000
	s_nop 0
	v_addc_co_u32_e32 v11, vcc, 0, v35, vcc
	v_add_co_u32_e32 v12, vcc, s7, v34
	s_mov_b32 s7, 0x9000
	s_nop 0
	v_addc_co_u32_e32 v13, vcc, 0, v35, vcc
	global_load_dword v10, v[10:11], off
	s_cmp_eq_u64 s[4:5], 0
	global_load_dword v11, v[12:13], off offset:2048
	v_add_co_u32_e32 v12, vcc, s7, v34
	s_mov_b32 s7, 0xd000
	s_nop 0
	v_addc_co_u32_e32 v13, vcc, 0, v35, vcc
	v_add_co_u32_e32 v14, vcc, s88, v34
	global_load_dword v12, v[12:13], off
	s_nop 0
	v_addc_co_u32_e32 v15, vcc, 0, v35, vcc
	global_load_dword v13, v[14:15], off offset:2048
	v_add_co_u32_e32 v14, vcc, s62, v34
	s_nop 1
	v_addc_co_u32_e32 v15, vcc, 0, v35, vcc
	v_add_co_u32_e32 v16, vcc, s7, v34
	s_mov_b32 s7, 0xf000
	s_nop 0
	v_addc_co_u32_e32 v17, vcc, 0, v35, vcc
	global_load_dword v14, v[14:15], off
	s_nop 0
	global_load_dword v15, v[16:17], off offset:2048
	v_add_co_u32_e32 v16, vcc, s7, v34
	s_mov_b32 s7, 0x10000
	s_nop 0
	v_addc_co_u32_e32 v17, vcc, 0, v35, vcc
	v_add_co_u32_e32 v18, vcc, s7, v34
	global_load_dword v16, v[16:17], off
	s_nop 0
	v_addc_co_u32_e32 v19, vcc, 0, v35, vcc
	global_load_dword v17, v[18:19], off offset:2048
	v_add_co_u32_e32 v18, vcc, s72, v34
	s_mov_b32 s7, 0x13000
	s_nop 0
	v_addc_co_u32_e32 v19, vcc, 0, v35, vcc
	v_add_co_u32_e32 v20, vcc, s7, v34
	s_mov_b32 s7, 0x15000
	s_nop 0
	v_addc_co_u32_e32 v21, vcc, 0, v35, vcc
	global_load_dword v18, v[18:19], off
	s_nop 0
	global_load_dword v19, v[20:21], off offset:2048
	v_add_co_u32_e32 v20, vcc, s7, v34
	s_mov_b32 s7, 0x19000
	s_nop 0
	v_addc_co_u32_e32 v21, vcc, 0, v35, vcc
	v_add_co_u32_e32 v22, vcc, s74, v34
	global_load_dword v20, v[20:21], off
	s_nop 0
	v_addc_co_u32_e32 v23, vcc, 0, v35, vcc
	global_load_dword v21, v[22:23], off offset:2048
	v_add_co_u32_e32 v22, vcc, s85, v34
	s_nop 1
	v_addc_co_u32_e32 v23, vcc, 0, v35, vcc
	v_add_co_u32_e32 v24, vcc, s7, v34
	s_mov_b32 s7, 0x1b000
	s_nop 0
	v_addc_co_u32_e32 v25, vcc, 0, v35, vcc
	global_load_dword v22, v[22:23], off
	s_nop 0
	global_load_dword v23, v[24:25], off offset:2048
	v_add_co_u32_e32 v24, vcc, s7, v34
	s_mov_b32 s7, 0x1f000
	s_nop 0
	v_addc_co_u32_e32 v25, vcc, 0, v35, vcc
	v_add_co_u32_e32 v26, vcc, s90, v34
	global_load_dword v24, v[24:25], off
	s_nop 0
	v_addc_co_u32_e32 v27, vcc, 0, v35, vcc
	global_load_dword v25, v[26:27], off offset:2048
	v_add_co_u32_e32 v26, vcc, s91, v34
	s_nop 1
	v_addc_co_u32_e32 v27, vcc, 0, v35, vcc
	v_add_co_u32_e32 v28, vcc, s7, v34
	s_mov_b32 s7, 0x21000
	s_nop 0
	v_addc_co_u32_e32 v29, vcc, 0, v35, vcc
	global_load_dword v26, v[26:27], off
	s_nop 0
	global_load_dword v27, v[28:29], off offset:2048
	v_add_co_u32_e32 v28, vcc, s7, v34
	s_mov_b32 s7, 0x22000
	s_nop 0
	v_addc_co_u32_e32 v29, vcc, 0, v35, vcc
	v_add_co_u32_e32 v30, vcc, s7, v34
	s_mov_b32 s7, 0x24000
	s_nop 0
	v_addc_co_u32_e32 v31, vcc, 0, v35, vcc
	global_load_dword v28, v[28:29], off
	s_nop 0
	global_load_dword v29, v[30:31], off offset:2048
	v_add_co_u32_e32 v30, vcc, s7, v34
	s_mov_b32 s7, 0x25000
	s_nop 0
	v_addc_co_u32_e32 v31, vcc, 0, v35, vcc
	v_add_co_u32_e32 v32, vcc, s7, v34
	s_mov_b32 s7, 0x27000
	s_nop 0
	v_addc_co_u32_e32 v33, vcc, 0, v35, vcc
	global_load_dword v30, v[30:31], off
	s_nop 0
	global_load_dword v31, v[32:33], off offset:2048
	v_add_co_u32_e32 v32, vcc, s7, v34
	s_mov_b32 s7, 0x28000
	s_nop 0
	v_addc_co_u32_e32 v33, vcc, 0, v35, vcc
	v_add_co_u32_e32 v36, vcc, s7, v34
	s_mov_b32 s7, 0x2a000
	s_nop 0
	v_addc_co_u32_e32 v37, vcc, 0, v35, vcc
	global_load_dword v32, v[32:33], off
	s_nop 0
	global_load_dword v33, v[36:37], off offset:2048
	v_add_co_u32_e32 v36, vcc, s7, v34
	s_nop 1
	v_addc_co_u32_e32 v37, vcc, 0, v35, vcc
	v_add_co_u32_e32 v38, vcc, 0x2b000, v34
	global_load_dword v36, v[36:37], off
	s_nop 0
	v_addc_co_u32_e32 v39, vcc, 0, v35, vcc
	global_load_dword v37, v[38:39], off offset:2048
	v_add_co_u32_e32 v38, vcc, 0x2d000, v34
	s_nop 1
	v_addc_co_u32_e32 v39, vcc, 0, v35, vcc
	v_add_co_u32_e32 v34, vcc, 0x2e000, v34
	global_load_dword v38, v[38:39], off
	s_nop 0
	v_addc_co_u32_e32 v35, vcc, 0, v35, vcc
	global_load_dword v39, v[34:35], off offset:2048
	s_cbranch_scc1 .LBB0_198
	s_and_b64 s[34:35], s[12:13], exec
	s_cselect_b32 s7, 0x600, 0
	s_add_u32 s4, s4, s7
	s_addc_u32 s5, s5, 0
	s_lshl_b32 s7, s6, 2
	s_add_u32 s4, s4, s7
	s_addc_u32 s5, s5, 0
	v_lshlrev_b32_e32 v45, 2, v0
	global_load_dword v34, v45, s[4:5]
	global_load_dword v35, v45, s[4:5] offset:8
	global_load_dword v40, v45, s[4:5] offset:16
	global_load_dword v41, v45, s[4:5] offset:24
	global_load_dword v46, v45, s[4:5] offset:32
	global_load_dword v47, v45, s[4:5] offset:40
	global_load_dword v48, v45, s[4:5] offset:48
	global_load_dword v49, v45, s[4:5] offset:56
	global_load_dword v50, v45, s[4:5] offset:64
	global_load_dword v51, v45, s[4:5] offset:72
	global_load_dword v52, v45, s[4:5] offset:80
	global_load_dword v53, v45, s[4:5] offset:88
	global_load_dword v54, v45, s[4:5] offset:96
	global_load_dword v55, v45, s[4:5] offset:104
	global_load_dword v56, v45, s[4:5] offset:112
	global_load_dword v57, v45, s[4:5] offset:120
	global_load_dword v58, v45, s[4:5] offset:128
	global_load_dword v59, v45, s[4:5] offset:136
	global_load_dword v60, v45, s[4:5] offset:144
	global_load_dword v61, v45, s[4:5] offset:152
	global_load_dword v62, v45, s[4:5] offset:160
	global_load_dword v63, v45, s[4:5] offset:168
	global_load_dword v64, v45, s[4:5] offset:176
	global_load_dword v65, v45, s[4:5] offset:184
	global_load_dword v66, v45, s[4:5] offset:192
	global_load_dword v67, v45, s[4:5] offset:200
	global_load_dword v68, v45, s[4:5] offset:208
	global_load_dword v69, v45, s[4:5] offset:216
	global_load_dword v70, v45, s[4:5] offset:224
	global_load_dword v71, v45, s[4:5] offset:232
	global_load_dword v72, v45, s[4:5] offset:240
	global_load_dword v73, v45, s[4:5] offset:248
	s_waitcnt vmcnt(0)
	v_mul_f32_e64 v6, v6, v34
	v_mul_f32_e64 v7, v7, v35
	v_mul_f32_e64 v8, v8, v40
	v_mul_f32_e64 v9, v9, v41
	v_mul_f32_e64 v10, v10, v46
	v_mul_f32_e64 v11, v11, v47
	v_mul_f32_e64 v12, v12, v48
	v_mul_f32_e64 v13, v13, v49
	v_mul_f32_e64 v14, v14, v50
	v_mul_f32_e64 v15, v15, v51
	v_mul_f32_e64 v16, v16, v52
	v_mul_f32_e64 v17, v17, v53
	v_mul_f32_e64 v18, v18, v54
	v_mul_f32_e64 v19, v19, v55
	v_mul_f32_e64 v20, v20, v56
	v_mul_f32_e64 v21, v21, v57
	v_mul_f32_e64 v22, v22, v58
	v_mul_f32_e64 v23, v23, v59
	v_mul_f32_e64 v24, v24, v60
	v_mul_f32_e64 v25, v25, v61
	v_mul_f32_e64 v26, v26, v62
	v_mul_f32_e64 v27, v27, v63
	v_mul_f32_e64 v28, v28, v64
	v_mul_f32_e64 v29, v29, v65
	v_mul_f32_e64 v30, v30, v66
	v_mul_f32_e64 v31, v31, v67
	v_mul_f32_e64 v32, v32, v68
	v_mul_f32_e64 v33, v33, v69
	v_mul_f32_e64 v36, v36, v70
	v_mul_f32_e64 v37, v37, v71
	v_mul_f32_e64 v38, v38, v72
	v_mul_f32_e64 v39, v39, v73

.LBB0_200:
	s_andn2_b64 vcc, exec, s[4:5]
	s_cbranch_vccnz .LBB0_204
	s_and_b32 s4, s29, 0xffff
	s_mul_i32 s7, s4, 0x1bad
	s_lshr_b32 s6, s7, 18
	s_load_dwordx2 s[4:5], s[2:3], 0x50
	s_mul_i32 s6, s6, 37
	s_sub_i32 s6, s29, s6
	s_and_b64 s[34:35], s[12:13], exec
	s_cselect_b32 s29, 0x4a0000, 0
	s_waitcnt lgkmcnt(0)
	s_add_u32 s4, s4, s29
	s_addc_u32 s5, s5, 0
	s_lshr_b32 s7, s7, 12
	s_and_b32 s7, s7, 0xffc0
	v_or_b32_e32 v6, s7, v0
	v_mul_u32_u24_e32 v6, 0x4a0, v6
	v_lshlrev_b32_e32 v96, 2, v6
	v_lshl_add_u64 v[6:7], s[4:5], 0, v[96:97]
	s_lshl_b32 s4, s6, 7
	s_and_b32 s60, s4, 0x3ff80
	v_lshl_add_u64 v[6:7], v[6:7], 0, s[60:61]
	v_lshlrev_b32_e32 v96, 2, v2
	v_lshl_add_u64 v[30:31], v[6:7], 0, v[96:97]
	v_add_co_u32_e32 v8, vcc, s68, v30
	s_mov_b32 s4, 0x9000
	s_nop 0
	v_addc_co_u32_e32 v9, vcc, 0, v31, vcc
	v_add_co_u32_e32 v10, vcc, s75, v30
	s_nop 1
	v_addc_co_u32_e32 v11, vcc, 0, v31, vcc
	v_add_co_u32_e32 v12, vcc, s79, v30
	s_nop 1
	v_addc_co_u32_e32 v13, vcc, 0, v31, vcc
	v_add_co_u32_e32 v14, vcc, s4, v30
	s_mov_b32 s4, 0xd000
	s_nop 0
	v_addc_co_u32_e32 v15, vcc, 0, v31, vcc
	v_add_co_u32_e32 v16, vcc, s76, v30
	s_nop 1
	v_addc_co_u32_e32 v17, vcc, 0, v31, vcc
	v_add_co_u32_e32 v18, vcc, s4, v30
	s_mov_b32 s4, 0x10000
	s_nop 0
	v_addc_co_u32_e32 v19, vcc, 0, v31, vcc
	v_add_co_u32_e32 v20, vcc, s4, v30
	s_mov_b32 s4, 0x17000
	s_nop 0
	v_addc_co_u32_e32 v21, vcc, 0, v31, vcc
	global_load_dword v6, v[30:31], off
	global_load_dword v7, v[8:9], off offset:1280
	s_nop 0
	global_load_dword v10, v[10:11], off offset:2560
	s_nop 0
	global_load_dword v11, v[12:13], off offset:3840
	global_load_dword v8, v[14:15], off offset:1024
	global_load_dword v9, v[16:17], off offset:2304
	s_nop 0
	global_load_dword v12, v[18:19], off offset:3584
	global_load_dword v13, v[20:21], off offset:768
	v_add_co_u32_e32 v14, vcc, s72, v30
	s_nop 1
	v_addc_co_u32_e32 v15, vcc, 0, v31, vcc
	v_add_co_u32_e32 v16, vcc, s73, v30
	s_nop 1
	v_addc_co_u32_e32 v17, vcc, 0, v31, vcc
	v_add_co_u32_e32 v18, vcc, s4, v30
	s_mov_b32 s4, 0x19000
	s_nop 0
	v_addc_co_u32_e32 v19, vcc, 0, v31, vcc
	v_add_co_u32_e32 v20, vcc, s4, v30
	s_mov_b32 s4, 0x1b000
	s_nop 0
	v_addc_co_u32_e32 v21, vcc, 0, v31, vcc
	v_add_co_u32_e32 v22, vcc, s4, v30
	s_mov_b32 s4, 0x22000
	s_nop 0
	v_addc_co_u32_e32 v23, vcc, 0, v31, vcc
	v_add_co_u32_e32 v24, vcc, s91, v30
	s_nop 1
	v_addc_co_u32_e32 v25, vcc, 0, v31, vcc
	v_add_co_u32_e32 v26, vcc, s95, v30
	s_nop 1
	v_addc_co_u32_e32 v27, vcc, 0, v31, vcc
	v_add_co_u32_e32 v28, vcc, s4, v30
	s_mov_b32 s4, 0x25000
	s_nop 0
	v_addc_co_u32_e32 v29, vcc, 0, v31, vcc
	global_load_dword v14, v[14:15], off offset:2048
	s_nop 0
	global_load_dword v15, v[16:17], off offset:3328
	s_nop 0
	global_load_dword v18, v[18:19], off offset:512
	s_nop 0
	global_load_dword v19, v[20:21], off offset:1792
	global_load_dword v16, v[22:23], off offset:3072
	global_load_dword v17, v[24:25], off offset:256
	s_nop 0
	global_load_dword v20, v[26:27], off offset:1536
	global_load_dword v21, v[28:29], off offset:2816
	v_add_co_u32_e32 v22, vcc, s4, v30
	s_mov_b32 s4, 0x27000
	s_nop 0
	v_addc_co_u32_e32 v23, vcc, 0, v31, vcc
	v_add_co_u32_e32 v24, vcc, s4, v30
	s_mov_b32 s4, 0x29000
	s_nop 0
	v_addc_co_u32_e32 v25, vcc, 0, v31, vcc
	v_add_co_u32_e32 v26, vcc, s4, v30
	s_mov_b32 s4, 0x2b000
	s_nop 0
	v_addc_co_u32_e32 v27, vcc, 0, v31, vcc
	v_add_co_u32_e32 v28, vcc, s4, v30
	s_mov_b32 s4, 0x2e000
	s_nop 0
	v_addc_co_u32_e32 v29, vcc, 0, v31, vcc
	v_add_co_u32_e32 v32, vcc, s4, v30
	s_mov_b32 s4, 0x30000
	s_nop 0
	v_addc_co_u32_e32 v33, vcc, 0, v31, vcc
	v_add_co_u32_e32 v34, vcc, s4, v30
	s_mov_b32 s4, 0x32000
	s_nop 0
	v_addc_co_u32_e32 v35, vcc, 0, v31, vcc
	v_add_co_u32_e32 v36, vcc, s4, v30
	s_mov_b32 s4, 0x35000
	s_nop 0
	v_addc_co_u32_e32 v37, vcc, 0, v31, vcc
	v_add_co_u32_e32 v38, vcc, s4, v30
	s_mov_b32 s4, 0x37000
	s_nop 0
	v_addc_co_u32_e32 v39, vcc, 0, v31, vcc
	global_load_dword v22, v[22:23], off
	s_nop 0
	global_load_dword v23, v[24:25], off offset:1280
	s_nop 0
	global_load_dword v26, v[26:27], off offset:2560
	s_nop 0
	global_load_dword v27, v[28:29], off offset:3840
	global_load_dword v24, v[32:33], off offset:1024
	global_load_dword v25, v[34:35], off offset:2304
	s_nop 0
	global_load_dword v28, v[36:37], off offset:3584
	global_load_dword v29, v[38:39], off offset:768
	v_add_co_u32_e32 v32, vcc, s4, v30
	s_mov_b32 s4, 0x39000
	s_nop 0
	v_addc_co_u32_e32 v33, vcc, 0, v31, vcc
	v_add_co_u32_e32 v34, vcc, s4, v30
	s_mov_b32 s4, 0x3c000
	s_nop 0
	v_addc_co_u32_e32 v35, vcc, 0, v31, vcc
	v_add_co_u32_e32 v36, vcc, s4, v30
	s_mov_b32 s4, 0x3e000
	s_nop 0
	v_addc_co_u32_e32 v37, vcc, 0, v31, vcc
	v_add_co_u32_e32 v38, vcc, s4, v30
	s_nop 1
	v_addc_co_u32_e32 v39, vcc, 0, v31, vcc
	v_add_co_u32_e32 v40, vcc, 0x40000, v30
	s_nop 1
	v_addc_co_u32_e32 v41, vcc, 0, v31, vcc
	v_add_co_u32_e32 v46, vcc, 0x43000, v30
	s_nop 1
	v_addc_co_u32_e32 v47, vcc, 0, v31, vcc
	v_add_co_u32_e32 v48, vcc, 0x45000, v30
	s_nop 1
	v_addc_co_u32_e32 v49, vcc, 0, v31, vcc
	v_add_co_u32_e32 v50, vcc, 0x47000, v30
	s_nop 1
	v_addc_co_u32_e32 v51, vcc, 0, v31, vcc
	global_load_dword v30, v[32:33], off offset:2048
	global_load_dword v31, v[34:35], off offset:3328
	s_nop 0
	global_load_dword v36, v[36:37], off offset:512
	s_nop 0
	global_load_dword v37, v[38:39], off offset:1792
	global_load_dword v34, v[40:41], off offset:3072
	global_load_dword v35, v[46:47], off offset:256
	global_load_dword v32, v[48:49], off offset:1536
	global_load_dword v33, v[50:51], off offset:2816
	s_load_dwordx2 s[4:5], s[2:3], 0x28
	s_waitcnt lgkmcnt(0)
	s_cmp_eq_u64 s[4:5], 0
	s_cbranch_scc1 .LBB0_203
	s_and_b64 s[12:13], s[12:13], exec
	s_cselect_b32 s12, 0x2000, 0
	s_add_u32 s4, s4, s12
	s_addc_u32 s5, s5, 0
	s_lshl_b32 s12, s7, 2
	s_add_u32 s4, s4, s12
	s_addc_u32 s5, s5, 0
	v_lshlrev_b32_e32 v45, 2, v0
	global_load_dword v38, v45, s[4:5]
	global_load_dword v39, v45, s[4:5] offset:8
	global_load_dword v40, v45, s[4:5] offset:16
	global_load_dword v41, v45, s[4:5] offset:24
	global_load_dword v46, v45, s[4:5] offset:32
	global_load_dword v47, v45, s[4:5] offset:40
	global_load_dword v48, v45, s[4:5] offset:48
	global_load_dword v49, v45, s[4:5] offset:56
	global_load_dword v50, v45, s[4:5] offset:64
	global_load_dword v51, v45, s[4:5] offset:72
	global_load_dword v52, v45, s[4:5] offset:80
	global_load_dword v53, v45, s[4:5] offset:88
	global_load_dword v54, v45, s[4:5] offset:96
	global_load_dword v55, v45, s[4:5] offset:104
	global_load_dword v56, v45, s[4:5] offset:112
	global_load_dword v57, v45, s[4:5] offset:120
	global_load_dword v58, v45, s[4:5] offset:128
	global_load_dword v59, v45, s[4:5] offset:136
	global_load_dword v60, v45, s[4:5] offset:144
	global_load_dword v61, v45, s[4:5] offset:152
	global_load_dword v62, v45, s[4:5] offset:160
	global_load_dword v63, v45, s[4:5] offset:168
	global_load_dword v64, v45, s[4:5] offset:176
	global_load_dword v65, v45, s[4:5] offset:184
	global_load_dword v66, v45, s[4:5] offset:192
	global_load_dword v67, v45, s[4:5] offset:200
	global_load_dword v68, v45, s[4:5] offset:208
	global_load_dword v69, v45, s[4:5] offset:216
	global_load_dword v70, v45, s[4:5] offset:224
	global_load_dword v71, v45, s[4:5] offset:232
	global_load_dword v72, v45, s[4:5] offset:240
	global_load_dword v73, v45, s[4:5] offset:248
	s_waitcnt vmcnt(0)
	v_mul_f32_e64 v6, v6, v38
	v_mul_f32_e64 v7, v7, v39
	v_mul_f32_e64 v10, v10, v40
	v_mul_f32_e64 v11, v11, v41
	v_mul_f32_e64 v8, v8, v46
	v_mul_f32_e64 v9, v9, v47
	v_mul_f32_e64 v12, v12, v48
	v_mul_f32_e64 v13, v13, v49
	v_mul_f32_e64 v14, v14, v50
	v_mul_f32_e64 v15, v15, v51
	v_mul_f32_e64 v18, v18, v52
	v_mul_f32_e64 v19, v19, v53
	v_mul_f32_e64 v16, v16, v54
	v_mul_f32_e64 v17, v17, v55
	v_mul_f32_e64 v20, v20, v56
	v_mul_f32_e64 v21, v21, v57
	v_mul_f32_e64 v22, v22, v58
	v_mul_f32_e64 v23, v23, v59
	v_mul_f32_e64 v26, v26, v60
	v_mul_f32_e64 v27, v27, v61
	v_mul_f32_e64 v24, v24, v62
	v_mul_f32_e64 v25, v25, v63
	v_mul_f32_e64 v28, v28, v64
	v_mul_f32_e64 v29, v29, v65
	v_mul_f32_e64 v30, v30, v66
	v_mul_f32_e64 v31, v31, v67
	v_mul_f32_e64 v36, v36, v68
	v_mul_f32_e64 v37, v37, v69
	v_mul_f32_e64 v34, v34, v70
	v_mul_f32_e64 v35, v35, v71
	v_mul_f32_e64 v32, v32, v72
	v_mul_f32_e64 v33, v33, v73

.LBB0_208:
	s_andn2_b64 vcc, exec, s[10:11]
	s_cbranch_vccnz .LBB0_173
	s_and_b64 s[10:11], s[6:7], exec
	s_cselect_b32 s10, 8, 48
	s_add_u32 s10, s2, s10
	s_addc_u32 s11, s3, 0
	s_and_b64 s[6:7], s[6:7], exec
	s_sext_i32_i16 s37, s12
	s_cselect_b32 s6, 2, 7
	s_add_i32 s60, s6, s37
	s_lshl_b64 s[6:7], s[60:61], 3
	s_add_u32 s6, s2, s6
	s_addc_u32 s7, s3, s7
	s_load_dwordx2 s[12:13], s[10:11], 0x0
	s_nop 0
	s_load_dwordx2 s[6:7], s[6:7], 0x0
	s_waitcnt lgkmcnt(0)
	s_add_u32 s38, s6, s36
	s_sext_i32_i16 s6, s34
	s_mulk_i32 s6, 0xba3
	s_addc_u32 s39, s7, s35
	s_lshr_b32 s7, s6, 31
	s_ashr_i32 s6, s6, 18
	s_add_i32 s6, s6, s7
	s_mul_i32 s7, s6, 0x58
	s_lshl_b32 s6, s6, 6
	s_sub_i32 s34, s34, s7
	v_or_b32_e32 v7, s6, v0
	s_sext_i32_i16 s7, s34
	v_mul_i32_i24_e32 v8, 0xb00, v7
	s_lshl_b32 s10, s7, 5
	v_ashrrev_i32_e32 v9, 31, v8
	v_lshl_add_u64 v[8:9], v[8:9], 2, s[38:39]
	s_ashr_i32 s11, s10, 31
	v_lshl_add_u64 v[8:9], s[10:11], 2, v[8:9]
	v_lshl_add_u64 v[38:39], v[8:9], 0, v[96:97]
	s_movk_i32 s7, 0x5000
	v_add_co_u32_e32 v10, vcc, s7, v38
	s_mov_b32 s7, 0x10000
	s_nop 0
	v_addc_co_u32_e32 v11, vcc, 0, v39, vcc
	global_load_dword v9, v[10:11], off offset:2048
	v_add_co_u32_e32 v10, vcc, s76, v38
	global_load_dword v8, v[38:39], off
	s_nop 0
	v_addc_co_u32_e32 v11, vcc, 0, v39, vcc
	v_add_co_u32_e32 v12, vcc, s7, v38
	global_load_dword v10, v[10:11], off
	s_nop 0
	v_addc_co_u32_e32 v13, vcc, 0, v39, vcc
	global_load_dword v11, v[12:13], off offset:2048
	v_add_co_u32_e32 v12, vcc, s74, v38
	s_mov_b32 s7, 0x1b000
	s_nop 0
	v_addc_co_u32_e32 v13, vcc, 0, v39, vcc
	v_add_co_u32_e32 v14, vcc, s7, v38
	s_mov_b32 s7, 0x21000
	s_nop 0
	v_addc_co_u32_e32 v15, vcc, 0, v39, vcc
	global_load_dword v12, v[12:13], off
	s_nop 0
	global_load_dword v13, v[14:15], off offset:2048
	v_add_co_u32_e32 v14, vcc, s7, v38
	s_mov_b32 s7, 0x31000
	s_nop 0
	v_addc_co_u32_e32 v15, vcc, 0, v39, vcc
	v_add_co_u32_e32 v16, vcc, s40, v38
	global_load_dword v14, v[14:15], off
	s_nop 0
	v_addc_co_u32_e32 v17, vcc, 0, v39, vcc
	global_load_dword v15, v[16:17], off offset:2048
	v_add_co_u32_e32 v16, vcc, s41, v38
	s_nop 1
	v_addc_co_u32_e32 v17, vcc, 0, v39, vcc
	v_add_co_u32_e32 v18, vcc, s7, v38
	s_mov_b32 s7, 0x37000
	s_nop 0
	v_addc_co_u32_e32 v19, vcc, 0, v39, vcc
	global_load_dword v16, v[16:17], off
	s_nop 0
	global_load_dword v17, v[18:19], off offset:2048
	v_add_co_u32_e32 v18, vcc, s7, v38
	s_mov_b32 s7, 0x3c000
	s_nop 0
	v_addc_co_u32_e32 v19, vcc, 0, v39, vcc
	v_add_co_u32_e32 v20, vcc, s7, v38
	s_mov_b32 s7, 0x42000
	s_nop 0
	v_addc_co_u32_e32 v21, vcc, 0, v39, vcc
	global_load_dword v18, v[18:19], off
	s_nop 0
	global_load_dword v19, v[20:21], off offset:2048
	v_add_co_u32_e32 v20, vcc, s7, v38
	s_mov_b32 s7, 0x47000
	s_nop 0
	v_addc_co_u32_e32 v21, vcc, 0, v39, vcc
	v_add_co_u32_e32 v22, vcc, s7, v38
	s_mov_b32 s7, 0x4d000
	s_nop 0
	v_addc_co_u32_e32 v23, vcc, 0, v39, vcc
	global_load_dword v20, v[20:21], off
	s_nop 0
	global_load_dword v21, v[22:23], off offset:2048
	v_add_co_u32_e32 v22, vcc, s7, v38
	s_mov_b32 s7, 0x52000
	s_nop 0
	v_addc_co_u32_e32 v23, vcc, 0, v39, vcc
	v_add_co_u32_e32 v24, vcc, s7, v38
	s_mov_b32 s7, 0x58000
	s_nop 0
	v_addc_co_u32_e32 v25, vcc, 0, v39, vcc
	global_load_dword v22, v[22:23], off
	s_nop 0
	global_load_dword v23, v[24:25], off offset:2048
	v_add_co_u32_e32 v24, vcc, s7, v38
	s_mov_b32 s7, 0x5d000
	s_nop 0
	v_addc_co_u32_e32 v25, vcc, 0, v39, vcc
	v_add_co_u32_e32 v26, vcc, s7, v38
	s_mov_b32 s7, 0x63000
	s_nop 0
	v_addc_co_u32_e32 v27, vcc, 0, v39, vcc
	global_load_dword v24, v[24:25], off
	s_nop 0
	global_load_dword v25, v[26:27], off offset:2048
	v_add_co_u32_e32 v26, vcc, s7, v38
	s_mov_b32 s7, 0x68000
	s_nop 0
	v_addc_co_u32_e32 v27, vcc, 0, v39, vcc
	v_add_co_u32_e32 v28, vcc, s7, v38
	s_mov_b32 s7, 0x6e000
	s_nop 0
	v_addc_co_u32_e32 v29, vcc, 0, v39, vcc
	global_load_dword v26, v[26:27], off
	s_nop 0
	global_load_dword v27, v[28:29], off offset:2048
	v_add_co_u32_e32 v28, vcc, s7, v38
	s_mov_b32 s7, 0x73000
	s_nop 0
	v_addc_co_u32_e32 v29, vcc, 0, v39, vcc
	v_add_co_u32_e32 v30, vcc, s7, v38
	s_mov_b32 s7, 0x79000
	s_nop 0
	v_addc_co_u32_e32 v31, vcc, 0, v39, vcc
	global_load_dword v28, v[28:29], off
	s_nop 0
	global_load_dword v29, v[30:31], off offset:2048
	v_add_co_u32_e32 v30, vcc, s7, v38
	s_mov_b32 s7, 0x7e000
	s_nop 0
	v_addc_co_u32_e32 v31, vcc, 0, v39, vcc
	v_add_co_u32_e32 v32, vcc, s7, v38
	s_mov_b32 s7, 0x84000
	s_nop 0
	v_addc_co_u32_e32 v33, vcc, 0, v39, vcc
	global_load_dword v30, v[30:31], off
	s_nop 0
	global_load_dword v31, v[32:33], off offset:2048
	v_add_co_u32_e32 v32, vcc, s7, v38
	s_mov_b32 s7, 0x89000
	s_nop 0
	v_addc_co_u32_e32 v33, vcc, 0, v39, vcc
	v_add_co_u32_e32 v34, vcc, s7, v38
	s_mov_b32 s7, 0x8f000
	s_nop 0
	v_addc_co_u32_e32 v35, vcc, 0, v39, vcc
	global_load_dword v32, v[32:33], off
	s_nop 0
	global_load_dword v33, v[34:35], off offset:2048
	v_add_co_u32_e32 v34, vcc, s7, v38
	s_mov_b32 s7, 0x94000
	s_nop 0
	v_addc_co_u32_e32 v35, vcc, 0, v39, vcc
	v_add_co_u32_e32 v36, vcc, s7, v38
	s_mov_b32 s7, 0x9a000
	s_nop 0
	v_addc_co_u32_e32 v37, vcc, 0, v39, vcc
	global_load_dword v34, v[34:35], off
	s_nop 0
	global_load_dword v35, v[36:37], off offset:2048
	v_add_co_u32_e32 v36, vcc, s7, v38
	s_mov_b32 s7, 0x9f000
	s_nop 0
	v_addc_co_u32_e32 v37, vcc, 0, v39, vcc
	v_add_co_u32_e32 v40, vcc, s7, v38
	global_load_dword v36, v[36:37], off
	s_nop 0
	v_addc_co_u32_e32 v41, vcc, 0, v39, vcc
	global_load_dword v37, v[40:41], off offset:2048
	v_add_co_u32_e32 v40, vcc, 0xa5000, v38
	s_ashr_i32 s7, s6, 31
	s_nop 0
	v_addc_co_u32_e32 v41, vcc, 0, v39, vcc
	v_add_co_u32_e32 v38, vcc, 0xaa000, v38
	global_load_dword v40, v[40:41], off
	s_nop 0
	v_addc_co_u32_e32 v39, vcc, 0, v39, vcc
	global_load_dword v41, v[38:39], off offset:2048
	s_cmp_eq_u64 s[12:13], 0
	s_cbranch_scc1 .LBB0_172
	s_lshl_b64 s[4:5], s[4:5], 12
	s_add_u32 s11, s12, s4
	s_addc_u32 s12, s13, s5
	s_lshl_b64 s[4:5], s[6:7], 2
	s_add_u32 s4, s11, s4
	s_addc_u32 s5, s12, s5
	v_lshlrev_b32_e32 v7, 2, v0
	global_load_dword v38, v7, s[4:5]
	global_load_dword v39, v7, s[4:5] offset:8
	global_load_dword v52, v7, s[4:5] offset:16
	global_load_dword v53, v7, s[4:5] offset:24
	global_load_dword v54, v7, s[4:5] offset:32
	global_load_dword v55, v7, s[4:5] offset:40
	global_load_dword v56, v7, s[4:5] offset:48
	global_load_dword v57, v7, s[4:5] offset:56
	global_load_dword v58, v7, s[4:5] offset:64
	global_load_dword v59, v7, s[4:5] offset:72
	global_load_dword v60, v7, s[4:5] offset:80
	global_load_dword v61, v7, s[4:5] offset:88
	global_load_dword v62, v7, s[4:5] offset:96
	global_load_dword v63, v7, s[4:5] offset:104
	global_load_dword v64, v7, s[4:5] offset:112
	global_load_dword v65, v7, s[4:5] offset:120
	global_load_dword v66, v7, s[4:5] offset:128
	global_load_dword v67, v7, s[4:5] offset:136
	global_load_dword v68, v7, s[4:5] offset:144
	global_load_dword v69, v7, s[4:5] offset:152
	global_load_dword v70, v7, s[4:5] offset:160
	global_load_dword v71, v7, s[4:5] offset:168
	global_load_dword v72, v7, s[4:5] offset:176
	global_load_dword v73, v7, s[4:5] offset:184
	global_load_dword v74, v7, s[4:5] offset:192
	global_load_dword v75, v7, s[4:5] offset:200
	global_load_dword v76, v7, s[4:5] offset:208
	global_load_dword v77, v7, s[4:5] offset:216
	global_load_dword v78, v7, s[4:5] offset:224
	global_load_dword v79, v7, s[4:5] offset:232
	global_load_dword v80, v7, s[4:5] offset:240
	global_load_dword v81, v7, s[4:5] offset:248
	s_waitcnt vmcnt(0)
	v_mul_f32_e64 v8, v8, v38
	v_mul_f32_e64 v9, v9, v39
	v_mul_f32_e64 v10, v10, v52
	v_mul_f32_e64 v11, v11, v53
	v_mul_f32_e64 v12, v12, v54
	v_mul_f32_e64 v13, v13, v55
	v_mul_f32_e64 v14, v14, v56
	v_mul_f32_e64 v15, v15, v57
	v_mul_f32_e64 v16, v16, v58
	v_mul_f32_e64 v17, v17, v59
	v_mul_f32_e64 v18, v18, v60
	v_mul_f32_e64 v19, v19, v61
	v_mul_f32_e64 v20, v20, v62
	v_mul_f32_e64 v21, v21, v63
	v_mul_f32_e64 v22, v22, v64
	v_mul_f32_e64 v23, v23, v65
	v_mul_f32_e64 v24, v24, v66
	v_mul_f32_e64 v25, v25, v67
	v_mul_f32_e64 v26, v26, v68
	v_mul_f32_e64 v27, v27, v69
	v_mul_f32_e64 v28, v28, v70
	v_mul_f32_e64 v29, v29, v71
	v_mul_f32_e64 v30, v30, v72
	v_mul_f32_e64 v31, v31, v73
	v_mul_f32_e64 v32, v32, v74
	v_mul_f32_e64 v33, v33, v75
	v_mul_f32_e64 v34, v34, v76
	v_mul_f32_e64 v35, v35, v77
	v_mul_f32_e64 v36, v36, v78
	v_mul_f32_e64 v37, v37, v79
	v_mul_f32_e64 v40, v40, v80
	v_mul_f32_e64 v41, v41, v81
	s_branch .LBB0_172

.LBB0_222:
	s_andn2_b64 vcc, exec, s[4:5]
	s_cbranch_vccnz .LBB0_226
	s_load_dwordx4 s[4:7], s[2:3], 0x68
	s_and_b64 s[28:29], s[12:13], exec
	s_cselect_b32 s27, 0x100000, 0
	s_waitcnt lgkmcnt(0)
	s_add_u32 s28, s6, s27
	s_addc_u32 s29, s7, 0
	s_lshl_b32 s6, s26, 1
	s_and_b32 s6, s6, 0x7c0
	s_addk_i32 s6, 0xfa40
	v_or_b32_e32 v96, s6, v0
	v_lshlrev_b64 v[6:7], 12, v[96:97]
	s_lshl_b32 s7, s26, 7
	v_lshl_add_u64 v[6:7], s[28:29], 0, v[6:7]
	s_and_b32 s60, s7, 0xf80
	v_lshl_add_u64 v[6:7], v[6:7], 0, s[60:61]
	v_lshlrev_b32_e32 v96, 2, v2
	v_lshl_add_u64 v[38:39], v[6:7], 0, v[96:97]
	v_add_co_u32_e32 v8, vcc, s68, v38
	global_load_dword v6, v[38:39], off
	s_nop 0
	v_addc_co_u32_e32 v9, vcc, 0, v39, vcc
	global_load_dword v7, v[8:9], off
	v_add_co_u32_e32 v8, vcc, s75, v38
	s_mov_b32 s7, 0x10000
	s_nop 0
	v_addc_co_u32_e32 v9, vcc, 0, v39, vcc
	v_add_co_u32_e32 v10, vcc, s79, v38
	global_load_dword v8, v[8:9], off
	s_nop 0
	v_addc_co_u32_e32 v11, vcc, 0, v39, vcc
	global_load_dword v9, v[10:11], off
	v_add_co_u32_e32 v10, vcc, s87, v38
	s_cmp_eq_u64 s[4:5], 0
	s_nop 0
	v_addc_co_u32_e32 v11, vcc, 0, v39, vcc
	v_add_co_u32_e32 v12, vcc, s88, v38
	global_load_dword v10, v[10:11], off
	s_nop 0
	v_addc_co_u32_e32 v13, vcc, 0, v39, vcc
	global_load_dword v11, v[12:13], off
	v_add_co_u32_e32 v12, vcc, s62, v38
	s_mov_b32 s60, s6
	s_nop 0
	v_addc_co_u32_e32 v13, vcc, 0, v39, vcc
	v_add_co_u32_e32 v14, vcc, s94, v38
	global_load_dword v12, v[12:13], off
	s_nop 0
	v_addc_co_u32_e32 v15, vcc, 0, v39, vcc
	global_load_dword v13, v[14:15], off
	v_add_co_u32_e32 v14, vcc, s7, v38
	s_mov_b32 s7, 0x22000
	s_nop 0
	v_addc_co_u32_e32 v15, vcc, 0, v39, vcc
	v_add_co_u32_e32 v16, vcc, s72, v38
	global_load_dword v14, v[14:15], off
	s_nop 0
	v_addc_co_u32_e32 v17, vcc, 0, v39, vcc
	global_load_dword v15, v[16:17], off
	v_add_co_u32_e32 v16, vcc, s73, v38
	s_nop 1
	v_addc_co_u32_e32 v17, vcc, 0, v39, vcc
	v_add_co_u32_e32 v18, vcc, s74, v38
	global_load_dword v16, v[16:17], off
	s_nop 0
	v_addc_co_u32_e32 v19, vcc, 0, v39, vcc
	global_load_dword v17, v[18:19], off
	v_add_co_u32_e32 v18, vcc, s85, v38
	s_nop 1
	v_addc_co_u32_e32 v19, vcc, 0, v39, vcc
	v_add_co_u32_e32 v20, vcc, s86, v38
	global_load_dword v18, v[18:19], off
	s_nop 0
	v_addc_co_u32_e32 v21, vcc, 0, v39, vcc
	global_load_dword v19, v[20:21], off
	v_add_co_u32_e32 v20, vcc, s90, v38
	s_nop 1
	v_addc_co_u32_e32 v21, vcc, 0, v39, vcc
	v_add_co_u32_e32 v22, vcc, s91, v38
	global_load_dword v20, v[20:21], off
	s_nop 0
	v_addc_co_u32_e32 v23, vcc, 0, v39, vcc
	global_load_dword v21, v[22:23], off
	v_add_co_u32_e32 v22, vcc, s95, v38
	s_nop 1
	v_addc_co_u32_e32 v23, vcc, 0, v39, vcc
	v_add_co_u32_e32 v24, vcc, s7, v38
	s_mov_b32 s7, 0x24000
	s_nop 0
	v_addc_co_u32_e32 v25, vcc, 0, v39, vcc
	global_load_dword v22, v[22:23], off
	s_nop 0
	global_load_dword v23, v[24:25], off
	v_add_co_u32_e32 v24, vcc, s7, v38
	s_mov_b32 s7, 0x28000
	s_nop 0
	v_addc_co_u32_e32 v25, vcc, 0, v39, vcc
	v_add_co_u32_e32 v26, vcc, s40, v38
	global_load_dword v24, v[24:25], off
	s_nop 0
	v_addc_co_u32_e32 v27, vcc, 0, v39, vcc
	global_load_dword v25, v[26:27], off
	v_add_co_u32_e32 v26, vcc, s7, v38
	s_mov_b32 s7, 0x2a000
	s_nop 0
	v_addc_co_u32_e32 v27, vcc, 0, v39, vcc
	v_add_co_u32_e32 v28, vcc, s7, v38
	global_load_dword v26, v[26:27], off
	s_nop 0
	v_addc_co_u32_e32 v29, vcc, 0, v39, vcc
	global_load_dword v27, v[28:29], off
	v_add_co_u32_e32 v28, vcc, s41, v38
	s_mov_b32 s7, 0x2e000
	s_nop 0
	v_addc_co_u32_e32 v29, vcc, 0, v39, vcc
	v_add_co_u32_e32 v30, vcc, s7, v38
	s_mov_b32 s7, 0x30000
	s_nop 0
	v_addc_co_u32_e32 v31, vcc, 0, v39, vcc
	global_load_dword v28, v[28:29], off
	s_nop 0
	global_load_dword v29, v[30:31], off
	v_add_co_u32_e32 v30, vcc, s7, v38
	s_mov_b32 s7, 0x32000
	s_nop 0
	v_addc_co_u32_e32 v31, vcc, 0, v39, vcc
	v_add_co_u32_e32 v32, vcc, s7, v38
	s_mov_b32 s7, 0x34000
	s_nop 0
	v_addc_co_u32_e32 v33, vcc, 0, v39, vcc
	global_load_dword v30, v[30:31], off
	s_nop 0
	global_load_dword v31, v[32:33], off
	v_add_co_u32_e32 v32, vcc, s7, v38
	s_mov_b32 s7, 0x36000
	s_nop 0
	v_addc_co_u32_e32 v33, vcc, 0, v39, vcc
	v_add_co_u32_e32 v34, vcc, s7, v38
	s_mov_b32 s7, 0x38000
	s_nop 0
	v_addc_co_u32_e32 v35, vcc, 0, v39, vcc
	global_load_dword v32, v[32:33], off
	s_nop 0
	global_load_dword v33, v[34:35], off
	v_add_co_u32_e32 v34, vcc, s7, v38
	s_nop 1
	v_addc_co_u32_e32 v35, vcc, 0, v39, vcc
	v_add_co_u32_e32 v36, vcc, 0x3a000, v38
	global_load_dword v34, v[34:35], off
	s_nop 0
	v_addc_co_u32_e32 v37, vcc, 0, v39, vcc
	global_load_dword v35, v[36:37], off
	v_add_co_u32_e32 v36, vcc, 0x3c000, v38
	s_nop 1
	v_addc_co_u32_e32 v37, vcc, 0, v39, vcc
	v_add_co_u32_e32 v38, vcc, 0x3e000, v38
	global_load_dword v36, v[36:37], off
	s_nop 0
	v_addc_co_u32_e32 v39, vcc, 0, v39, vcc
	global_load_dword v37, v[38:39], off
	s_cbranch_scc1 .LBB0_225
	s_and_b64 s[6:7], s[12:13], exec
	s_cselect_b32 s6, 0x400, 0
	s_add_u32 s6, s4, s6
	s_addc_u32 s7, s5, 0
	s_lshl_b64 s[4:5], s[60:61], 2
	s_add_u32 s4, s6, s4
	s_addc_u32 s5, s7, s5
	v_lshlrev_b32_e32 v45, 2, v0
	global_load_dword v38, v45, s[4:5]
	global_load_dword v39, v45, s[4:5] offset:8
	global_load_dword v40, v45, s[4:5] offset:16
	global_load_dword v41, v45, s[4:5] offset:24
	global_load_dword v46, v45, s[4:5] offset:32
	global_load_dword v47, v45, s[4:5] offset:40
	global_load_dword v48, v45, s[4:5] offset:48
	global_load_dword v49, v45, s[4:5] offset:56
	global_load_dword v50, v45, s[4:5] offset:64
	global_load_dword v51, v45, s[4:5] offset:72
	global_load_dword v52, v45, s[4:5] offset:80
	global_load_dword v53, v45, s[4:5] offset:88
	global_load_dword v54, v45, s[4:5] offset:96
	global_load_dword v55, v45, s[4:5] offset:104
	global_load_dword v56, v45, s[4:5] offset:112
	global_load_dword v57, v45, s[4:5] offset:120
	global_load_dword v58, v45, s[4:5] offset:128
	global_load_dword v59, v45, s[4:5] offset:136
	global_load_dword v60, v45, s[4:5] offset:144
	global_load_dword v61, v45, s[4:5] offset:152
	global_load_dword v62, v45, s[4:5] offset:160
	global_load_dword v63, v45, s[4:5] offset:168
	global_load_dword v64, v45, s[4:5] offset:176
	global_load_dword v65, v45, s[4:5] offset:184
	global_load_dword v66, v45, s[4:5] offset:192
	global_load_dword v67, v45, s[4:5] offset:200
	global_load_dword v68, v45, s[4:5] offset:208
	global_load_dword v69, v45, s[4:5] offset:216
	global_load_dword v70, v45, s[4:5] offset:224
	global_load_dword v71, v45, s[4:5] offset:232
	global_load_dword v72, v45, s[4:5] offset:240
	global_load_dword v73, v45, s[4:5] offset:248
	s_waitcnt vmcnt(0)
	v_mul_f32_e64 v6, v6, v38
	v_mul_f32_e64 v7, v7, v39
	v_mul_f32_e64 v8, v8, v40
	v_mul_f32_e64 v9, v9, v41
	v_mul_f32_e64 v10, v10, v46
	v_mul_f32_e64 v11, v11, v47
	v_mul_f32_e64 v12, v12, v48
	v_mul_f32_e64 v13, v13, v49
	v_mul_f32_e64 v14, v14, v50
	v_mul_f32_e64 v15, v15, v51
	v_mul_f32_e64 v16, v16, v52
	v_mul_f32_e64 v17, v17, v53
	v_mul_f32_e64 v18, v18, v54
	v_mul_f32_e64 v19, v19, v55
	v_mul_f32_e64 v20, v20, v56
	v_mul_f32_e64 v21, v21, v57
	v_mul_f32_e64 v22, v22, v58
	v_mul_f32_e64 v23, v23, v59
	v_mul_f32_e64 v24, v24, v60
	v_mul_f32_e64 v25, v25, v61
	v_mul_f32_e64 v26, v26, v62
	v_mul_f32_e64 v27, v27, v63
	v_mul_f32_e64 v28, v28, v64
	v_mul_f32_e64 v29, v29, v65
	v_mul_f32_e64 v30, v30, v66
	v_mul_f32_e64 v31, v31, v67
	v_mul_f32_e64 v32, v32, v68
	v_mul_f32_e64 v33, v33, v69
	v_mul_f32_e64 v34, v34, v70
	v_mul_f32_e64 v35, v35, v71
	v_mul_f32_e64 v36, v36, v72
	v_mul_f32_e64 v37, v37, v73

.LBB0_227:
	s_andn2_b64 vcc, exec, s[4:5]
	s_cbranch_vccnz .LBB0_231
	s_add_i32 s4, s26, 0xffb0
	s_and_b32 s5, s4, 0xff
	s_mulk_i32 s5, 0xab
	s_bfe_u32 s31, s5, 0x4000c
	s_mul_i32 s5, s31, 24
	s_sub_i32 s4, s4, s5
	s_and_b32 s27, s4, 0xff
	s_load_dwordx4 s[4:7], s[2:3], 0x58
	s_and_b64 s[28:29], s[12:13], exec
	s_cselect_b32 s28, 0x120000, 0
	s_waitcnt lgkmcnt(0)
	s_add_u32 s28, s6, s28
	s_addc_u32 s29, s7, 0
	s_lshl_b32 s6, s31, 6
	v_or_b32_e32 v6, s6, v0
	v_mul_u32_u24_e32 v6, 0x300, v6
	v_lshlrev_b32_e32 v96, 2, v6
	v_lshl_add_u64 v[6:7], s[28:29], 0, v[96:97]
	s_lshl_b32 s60, s27, 7
	v_lshl_add_u64 v[6:7], v[6:7], 0, s[60:61]
	v_lshlrev_b32_e32 v96, 2, v2
	v_lshl_add_u64 v[34:35], v[6:7], 0, v[96:97]
	s_movk_i32 s7, 0x1000
	v_add_co_u32_e32 v8, vcc, s7, v34
	s_movk_i32 s7, 0x3000
	s_nop 0
	v_addc_co_u32_e32 v9, vcc, 0, v35, vcc
	global_load_dword v7, v[8:9], off offset:2048
	v_add_co_u32_e32 v8, vcc, s7, v34
	global_load_dword v6, v[34:35], off
	s_nop 0
	v_addc_co_u32_e32 v9, vcc, 0, v35, vcc
	v_add_co_u32_e32 v10, vcc, s75, v34
	global_load_dword v8, v[8:9], off
	s_nop 0
	v_addc_co_u32_e32 v11, vcc, 0, v35, vcc
	global_load_dword v9, v[10:11], off offset:2048
	v_add_co_u32_e32 v10, vcc, s79, v34
	s_movk_i32 s7, 0x7000
	s_nop 0
	v_addc_co_u32_e32 v11, vcc, 0, v35, vcc
	v_add_co_u32_e32 v12, vcc, s7, v34
	s_mov_b32 s7, 0x9000
	s_nop 0
	v_addc_co_u32_e32 v13, vcc, 0, v35, vcc
	global_load_dword v10, v[10:11], off
	s_cmp_eq_u64 s[4:5], 0
	global_load_dword v11, v[12:13], off offset:2048
	v_add_co_u32_e32 v12, vcc, s7, v34
	s_mov_b32 s7, 0xd000
	s_nop 0
	v_addc_co_u32_e32 v13, vcc, 0, v35, vcc
	v_add_co_u32_e32 v14, vcc, s88, v34
	global_load_dword v12, v[12:13], off
	s_nop 0
	v_addc_co_u32_e32 v15, vcc, 0, v35, vcc
	global_load_dword v13, v[14:15], off offset:2048
	v_add_co_u32_e32 v14, vcc, s62, v34
	s_nop 1
	v_addc_co_u32_e32 v15, vcc, 0, v35, vcc
	v_add_co_u32_e32 v16, vcc, s7, v34
	s_mov_b32 s7, 0xf000
	s_nop 0
	v_addc_co_u32_e32 v17, vcc, 0, v35, vcc
	global_load_dword v14, v[14:15], off
	s_nop 0
	global_load_dword v15, v[16:17], off offset:2048
	v_add_co_u32_e32 v16, vcc, s7, v34
	s_mov_b32 s7, 0x10000
	s_nop 0
	v_addc_co_u32_e32 v17, vcc, 0, v35, vcc
	v_add_co_u32_e32 v18, vcc, s7, v34
	global_load_dword v16, v[16:17], off
	s_nop 0
	v_addc_co_u32_e32 v19, vcc, 0, v35, vcc
	global_load_dword v17, v[18:19], off offset:2048
	v_add_co_u32_e32 v18, vcc, s72, v34
	s_mov_b32 s7, 0x13000
	s_nop 0
	v_addc_co_u32_e32 v19, vcc, 0, v35, vcc
	v_add_co_u32_e32 v20, vcc, s7, v34
	s_mov_b32 s7, 0x15000
	s_nop 0
	v_addc_co_u32_e32 v21, vcc, 0, v35, vcc
	global_load_dword v18, v[18:19], off
	s_nop 0
	global_load_dword v19, v[20:21], off offset:2048
	v_add_co_u32_e32 v20, vcc, s7, v34
	s_mov_b32 s7, 0x19000
	s_nop 0
	v_addc_co_u32_e32 v21, vcc, 0, v35, vcc
	v_add_co_u32_e32 v22, vcc, s74, v34
	global_load_dword v20, v[20:21], off
	s_nop 0
	v_addc_co_u32_e32 v23, vcc, 0, v35, vcc
	global_load_dword v21, v[22:23], off offset:2048
	v_add_co_u32_e32 v22, vcc, s85, v34
	s_nop 1
	v_addc_co_u32_e32 v23, vcc, 0, v35, vcc
	v_add_co_u32_e32 v24, vcc, s7, v34
	s_mov_b32 s7, 0x1b000
	s_nop 0
	v_addc_co_u32_e32 v25, vcc, 0, v35, vcc
	global_load_dword v22, v[22:23], off
	s_nop 0
	global_load_dword v23, v[24:25], off offset:2048
	v_add_co_u32_e32 v24, vcc, s7, v34
	s_mov_b32 s7, 0x1f000
	s_nop 0
	v_addc_co_u32_e32 v25, vcc, 0, v35, vcc
	v_add_co_u32_e32 v26, vcc, s90, v34
	global_load_dword v24, v[24:25], off
	s_nop 0
	v_addc_co_u32_e32 v27, vcc, 0, v35, vcc
	global_load_dword v25, v[26:27], off offset:2048
	v_add_co_u32_e32 v26, vcc, s91, v34
	s_nop 1
	v_addc_co_u32_e32 v27, vcc, 0, v35, vcc
	v_add_co_u32_e32 v28, vcc, s7, v34
	s_mov_b32 s7, 0x21000
	s_nop 0
	v_addc_co_u32_e32 v29, vcc, 0, v35, vcc
	global_load_dword v26, v[26:27], off
	s_nop 0
	global_load_dword v27, v[28:29], off offset:2048
	v_add_co_u32_e32 v28, vcc, s7, v34
	s_mov_b32 s7, 0x22000
	s_nop 0
	v_addc_co_u32_e32 v29, vcc, 0, v35, vcc
	v_add_co_u32_e32 v30, vcc, s7, v34
	s_mov_b32 s7, 0x24000
	s_nop 0
	v_addc_co_u32_e32 v31, vcc, 0, v35, vcc
	global_load_dword v28, v[28:29], off
	s_nop 0
	global_load_dword v29, v[30:31], off offset:2048
	v_add_co_u32_e32 v30, vcc, s7, v34
	s_mov_b32 s7, 0x25000
	s_nop 0
	v_addc_co_u32_e32 v31, vcc, 0, v35, vcc
	v_add_co_u32_e32 v32, vcc, s7, v34
	s_mov_b32 s7, 0x27000
	s_nop 0
	v_addc_co_u32_e32 v33, vcc, 0, v35, vcc
	global_load_dword v30, v[30:31], off
	s_nop 0
	global_load_dword v31, v[32:33], off offset:2048
	v_add_co_u32_e32 v32, vcc, s7, v34
	s_mov_b32 s7, 0x28000
	s_nop 0
	v_addc_co_u32_e32 v33, vcc, 0, v35, vcc
	v_add_co_u32_e32 v36, vcc, s7, v34
	s_mov_b32 s7, 0x2a000
	s_nop 0
	v_addc_co_u32_e32 v37, vcc, 0, v35, vcc
	global_load_dword v32, v[32:33], off
	s_nop 0
	global_load_dword v33, v[36:37], off offset:2048
	v_add_co_u32_e32 v36, vcc, s7, v34
	s_nop 1
	v_addc_co_u32_e32 v37, vcc, 0, v35, vcc
	v_add_co_u32_e32 v38, vcc, 0x2b000, v34
	global_load_dword v36, v[36:37], off
	s_nop 0
	v_addc_co_u32_e32 v39, vcc, 0, v35, vcc
	global_load_dword v37, v[38:39], off offset:2048
	v_add_co_u32_e32 v38, vcc, 0x2d000, v34
	s_nop 1
	v_addc_co_u32_e32 v39, vcc, 0, v35, vcc
	v_add_co_u32_e32 v34, vcc, 0x2e000, v34
	global_load_dword v38, v[38:39], off
	s_nop 0
	v_addc_co_u32_e32 v35, vcc, 0, v35, vcc
	global_load_dword v39, v[34:35], off offset:2048
	s_cbranch_scc1 .LBB0_230
	s_and_b64 s[28:29], s[12:13], exec
	s_cselect_b32 s7, 0x600, 0
	s_add_u32 s4, s4, s7
	s_addc_u32 s5, s5, 0
	s_lshl_b32 s7, s6, 2
	s_add_u32 s4, s4, s7
	s_addc_u32 s5, s5, 0
	v_lshlrev_b32_e32 v45, 2, v0
	global_load_dword v34, v45, s[4:5]
	global_load_dword v35, v45, s[4:5] offset:8
	global_load_dword v40, v45, s[4:5] offset:16
	global_load_dword v41, v45, s[4:5] offset:24
	global_load_dword v46, v45, s[4:5] offset:32
	global_load_dword v47, v45, s[4:5] offset:40
	global_load_dword v48, v45, s[4:5] offset:48
	global_load_dword v49, v45, s[4:5] offset:56
	global_load_dword v50, v45, s[4:5] offset:64
	global_load_dword v51, v45, s[4:5] offset:72
	global_load_dword v52, v45, s[4:5] offset:80
	global_load_dword v53, v45, s[4:5] offset:88
	global_load_dword v54, v45, s[4:5] offset:96
	global_load_dword v55, v45, s[4:5] offset:104
	global_load_dword v56, v45, s[4:5] offset:112
	global_load_dword v57, v45, s[4:5] offset:120
	global_load_dword v58, v45, s[4:5] offset:128
	global_load_dword v59, v45, s[4:5] offset:136
	global_load_dword v60, v45, s[4:5] offset:144
	global_load_dword v61, v45, s[4:5] offset:152
	global_load_dword v62, v45, s[4:5] offset:160
	global_load_dword v63, v45, s[4:5] offset:168
	global_load_dword v64, v45, s[4:5] offset:176
	global_load_dword v65, v45, s[4:5] offset:184
	global_load_dword v66, v45, s[4:5] offset:192
	global_load_dword v67, v45, s[4:5] offset:200
	global_load_dword v68, v45, s[4:5] offset:208
	global_load_dword v69, v45, s[4:5] offset:216
	global_load_dword v70, v45, s[4:5] offset:224
	global_load_dword v71, v45, s[4:5] offset:232
	global_load_dword v72, v45, s[4:5] offset:240
	global_load_dword v73, v45, s[4:5] offset:248
	s_waitcnt vmcnt(0)
	v_mul_f32_e64 v6, v6, v34
	v_mul_f32_e64 v7, v7, v35
	v_mul_f32_e64 v8, v8, v40
	v_mul_f32_e64 v9, v9, v41
	v_mul_f32_e64 v10, v10, v46
	v_mul_f32_e64 v11, v11, v47
	v_mul_f32_e64 v12, v12, v48
	v_mul_f32_e64 v13, v13, v49
	v_mul_f32_e64 v14, v14, v50
	v_mul_f32_e64 v15, v15, v51
	v_mul_f32_e64 v16, v16, v52
	v_mul_f32_e64 v17, v17, v53
	v_mul_f32_e64 v18, v18, v54
	v_mul_f32_e64 v19, v19, v55
	v_mul_f32_e64 v20, v20, v56
	v_mul_f32_e64 v21, v21, v57
	v_mul_f32_e64 v22, v22, v58
	v_mul_f32_e64 v23, v23, v59
	v_mul_f32_e64 v24, v24, v60
	v_mul_f32_e64 v25, v25, v61
	v_mul_f32_e64 v26, v26, v62
	v_mul_f32_e64 v27, v27, v63
	v_mul_f32_e64 v28, v28, v64
	v_mul_f32_e64 v29, v29, v65
	v_mul_f32_e64 v30, v30, v66
	v_mul_f32_e64 v31, v31, v67
	v_mul_f32_e64 v32, v32, v68
	v_mul_f32_e64 v33, v33, v69
	v_mul_f32_e64 v36, v36, v70
	v_mul_f32_e64 v37, v37, v71
	v_mul_f32_e64 v38, v38, v72
	v_mul_f32_e64 v39, v39, v73

.LBB0_232:
	s_andn2_b64 vcc, exec, s[4:5]
	s_cbranch_vccnz .LBB0_236
	s_and_b32 s4, s26, 0xffff
	s_mul_i32 s7, s4, 0x1bad
	s_lshr_b32 s6, s7, 18
	s_load_dwordx2 s[4:5], s[2:3], 0x50
	s_mul_i32 s6, s6, 37
	s_sub_i32 s6, s26, s6
	s_and_b64 s[26:27], s[12:13], exec
	s_cselect_b32 s26, 0x4a0000, 0
	s_waitcnt lgkmcnt(0)
	s_add_u32 s4, s4, s26
	s_addc_u32 s5, s5, 0
	s_lshr_b32 s7, s7, 12
	s_and_b32 s7, s7, 0xffc0
	v_or_b32_e32 v6, s7, v0
	v_mul_u32_u24_e32 v6, 0x4a0, v6
	v_lshlrev_b32_e32 v96, 2, v6
	v_lshl_add_u64 v[6:7], s[4:5], 0, v[96:97]
	s_lshl_b32 s4, s6, 7
	s_and_b32 s60, s4, 0x3ff80
	v_lshl_add_u64 v[6:7], v[6:7], 0, s[60:61]
	v_lshlrev_b32_e32 v96, 2, v2
	v_lshl_add_u64 v[30:31], v[6:7], 0, v[96:97]
	v_add_co_u32_e32 v8, vcc, s68, v30
	s_mov_b32 s4, 0x9000
	s_nop 0
	v_addc_co_u32_e32 v9, vcc, 0, v31, vcc
	v_add_co_u32_e32 v10, vcc, s75, v30
	s_nop 1
	v_addc_co_u32_e32 v11, vcc, 0, v31, vcc
	v_add_co_u32_e32 v12, vcc, s79, v30
	s_nop 1
	v_addc_co_u32_e32 v13, vcc, 0, v31, vcc
	v_add_co_u32_e32 v14, vcc, s4, v30
	s_mov_b32 s4, 0xd000
	s_nop 0
	v_addc_co_u32_e32 v15, vcc, 0, v31, vcc
	v_add_co_u32_e32 v16, vcc, s76, v30
	s_nop 1
	v_addc_co_u32_e32 v17, vcc, 0, v31, vcc
	v_add_co_u32_e32 v18, vcc, s4, v30
	s_mov_b32 s4, 0x10000
	s_nop 0
	v_addc_co_u32_e32 v19, vcc, 0, v31, vcc
	v_add_co_u32_e32 v20, vcc, s4, v30
	s_mov_b32 s4, 0x17000
	s_nop 0
	v_addc_co_u32_e32 v21, vcc, 0, v31, vcc
	global_load_dword v6, v[30:31], off
	global_load_dword v7, v[8:9], off offset:1280
	s_nop 0
	global_load_dword v10, v[10:11], off offset:2560
	s_nop 0
	global_load_dword v11, v[12:13], off offset:3840
	global_load_dword v8, v[14:15], off offset:1024
	global_load_dword v9, v[16:17], off offset:2304
	s_nop 0
	global_load_dword v12, v[18:19], off offset:3584
	global_load_dword v13, v[20:21], off offset:768
	v_add_co_u32_e32 v14, vcc, s72, v30
	s_nop 1
	v_addc_co_u32_e32 v15, vcc, 0, v31, vcc
	v_add_co_u32_e32 v16, vcc, s73, v30
	s_nop 1
	v_addc_co_u32_e32 v17, vcc, 0, v31, vcc
	v_add_co_u32_e32 v18, vcc, s4, v30
	s_mov_b32 s4, 0x19000
	s_nop 0
	v_addc_co_u32_e32 v19, vcc, 0, v31, vcc
	v_add_co_u32_e32 v20, vcc, s4, v30
	s_mov_b32 s4, 0x1b000
	s_nop 0
	v_addc_co_u32_e32 v21, vcc, 0, v31, vcc
	v_add_co_u32_e32 v22, vcc, s4, v30
	s_mov_b32 s4, 0x22000
	s_nop 0
	v_addc_co_u32_e32 v23, vcc, 0, v31, vcc
	v_add_co_u32_e32 v24, vcc, s91, v30
	s_nop 1
	v_addc_co_u32_e32 v25, vcc, 0, v31, vcc
	v_add_co_u32_e32 v26, vcc, s95, v30
	s_nop 1
	v_addc_co_u32_e32 v27, vcc, 0, v31, vcc
	v_add_co_u32_e32 v28, vcc, s4, v30
	s_mov_b32 s4, 0x25000
	s_nop 0
	v_addc_co_u32_e32 v29, vcc, 0, v31, vcc
	global_load_dword v14, v[14:15], off offset:2048
	s_nop 0
	global_load_dword v15, v[16:17], off offset:3328
	s_nop 0
	global_load_dword v18, v[18:19], off offset:512
	s_nop 0
	global_load_dword v19, v[20:21], off offset:1792
	global_load_dword v16, v[22:23], off offset:3072
	global_load_dword v17, v[24:25], off offset:256
	s_nop 0
	global_load_dword v20, v[26:27], off offset:1536
	global_load_dword v21, v[28:29], off offset:2816
	v_add_co_u32_e32 v22, vcc, s4, v30
	s_mov_b32 s4, 0x27000
	s_nop 0
	v_addc_co_u32_e32 v23, vcc, 0, v31, vcc
	v_add_co_u32_e32 v24, vcc, s4, v30
	s_mov_b32 s4, 0x29000
	s_nop 0
	v_addc_co_u32_e32 v25, vcc, 0, v31, vcc
	v_add_co_u32_e32 v26, vcc, s4, v30
	s_mov_b32 s4, 0x2b000
	s_nop 0
	v_addc_co_u32_e32 v27, vcc, 0, v31, vcc
	v_add_co_u32_e32 v28, vcc, s4, v30
	s_mov_b32 s4, 0x2e000
	s_nop 0
	v_addc_co_u32_e32 v29, vcc, 0, v31, vcc
	v_add_co_u32_e32 v32, vcc, s4, v30
	s_mov_b32 s4, 0x30000
	s_nop 0
	v_addc_co_u32_e32 v33, vcc, 0, v31, vcc
	v_add_co_u32_e32 v34, vcc, s4, v30
	s_mov_b32 s4, 0x32000
	s_nop 0
	v_addc_co_u32_e32 v35, vcc, 0, v31, vcc
	v_add_co_u32_e32 v36, vcc, s4, v30
	s_mov_b32 s4, 0x35000
	s_nop 0
	v_addc_co_u32_e32 v37, vcc, 0, v31, vcc
	v_add_co_u32_e32 v38, vcc, s4, v30
	s_mov_b32 s4, 0x37000
	s_nop 0
	v_addc_co_u32_e32 v39, vcc, 0, v31, vcc
	global_load_dword v22, v[22:23], off
	s_nop 0
	global_load_dword v23, v[24:25], off offset:1280
	s_nop 0
	global_load_dword v26, v[26:27], off offset:2560
	s_nop 0
	global_load_dword v27, v[28:29], off offset:3840
	global_load_dword v24, v[32:33], off offset:1024
	global_load_dword v25, v[34:35], off offset:2304
	s_nop 0
	global_load_dword v28, v[36:37], off offset:3584
	global_load_dword v29, v[38:39], off offset:768
	v_add_co_u32_e32 v32, vcc, s4, v30
	s_mov_b32 s4, 0x39000
	s_nop 0
	v_addc_co_u32_e32 v33, vcc, 0, v31, vcc
	v_add_co_u32_e32 v34, vcc, s4, v30
	s_mov_b32 s4, 0x3c000
	s_nop 0
	v_addc_co_u32_e32 v35, vcc, 0, v31, vcc
	v_add_co_u32_e32 v36, vcc, s4, v30
	s_mov_b32 s4, 0x3e000
	s_nop 0
	v_addc_co_u32_e32 v37, vcc, 0, v31, vcc
	v_add_co_u32_e32 v38, vcc, s4, v30
	s_nop 1
	v_addc_co_u32_e32 v39, vcc, 0, v31, vcc
	v_add_co_u32_e32 v40, vcc, 0x40000, v30
	s_nop 1
	v_addc_co_u32_e32 v41, vcc, 0, v31, vcc
	v_add_co_u32_e32 v46, vcc, 0x43000, v30
	s_nop 1
	v_addc_co_u32_e32 v47, vcc, 0, v31, vcc
	v_add_co_u32_e32 v48, vcc, 0x45000, v30
	s_nop 1
	v_addc_co_u32_e32 v49, vcc, 0, v31, vcc
	v_add_co_u32_e32 v50, vcc, 0x47000, v30
	s_nop 1
	v_addc_co_u32_e32 v51, vcc, 0, v31, vcc
	global_load_dword v30, v[32:33], off offset:2048
	global_load_dword v31, v[34:35], off offset:3328
	s_nop 0
	global_load_dword v36, v[36:37], off offset:512
	s_nop 0
	global_load_dword v37, v[38:39], off offset:1792
	global_load_dword v34, v[40:41], off offset:3072
	global_load_dword v35, v[46:47], off offset:256
	global_load_dword v32, v[48:49], off offset:1536
	global_load_dword v33, v[50:51], off offset:2816
	s_load_dwordx2 s[4:5], s[2:3], 0x28
	s_waitcnt lgkmcnt(0)
	s_cmp_eq_u64 s[4:5], 0
	s_cbranch_scc1 .LBB0_235
	s_and_b64 s[12:13], s[12:13], exec
	s_cselect_b32 s12, 0x2000, 0
	s_add_u32 s4, s4, s12
	s_addc_u32 s5, s5, 0
	s_lshl_b32 s12, s7, 2
	s_add_u32 s4, s4, s12
	s_addc_u32 s5, s5, 0
	v_lshlrev_b32_e32 v45, 2, v0
	global_load_dword v38, v45, s[4:5]
	global_load_dword v39, v45, s[4:5] offset:8
	global_load_dword v40, v45, s[4:5] offset:16
	global_load_dword v41, v45, s[4:5] offset:24
	global_load_dword v46, v45, s[4:5] offset:32
	global_load_dword v47, v45, s[4:5] offset:40
	global_load_dword v48, v45, s[4:5] offset:48
	global_load_dword v49, v45, s[4:5] offset:56
	global_load_dword v50, v45, s[4:5] offset:64
	global_load_dword v51, v45, s[4:5] offset:72
	global_load_dword v52, v45, s[4:5] offset:80
	global_load_dword v53, v45, s[4:5] offset:88
	global_load_dword v54, v45, s[4:5] offset:96
	global_load_dword v55, v45, s[4:5] offset:104
	global_load_dword v56, v45, s[4:5] offset:112
	global_load_dword v57, v45, s[4:5] offset:120
	global_load_dword v58, v45, s[4:5] offset:128
	global_load_dword v59, v45, s[4:5] offset:136
	global_load_dword v60, v45, s[4:5] offset:144
	global_load_dword v61, v45, s[4:5] offset:152
	global_load_dword v62, v45, s[4:5] offset:160
	global_load_dword v63, v45, s[4:5] offset:168
	global_load_dword v64, v45, s[4:5] offset:176
	global_load_dword v65, v45, s[4:5] offset:184
	global_load_dword v66, v45, s[4:5] offset:192
	global_load_dword v67, v45, s[4:5] offset:200
	global_load_dword v68, v45, s[4:5] offset:208
	global_load_dword v69, v45, s[4:5] offset:216
	global_load_dword v70, v45, s[4:5] offset:224
	global_load_dword v71, v45, s[4:5] offset:232
	global_load_dword v72, v45, s[4:5] offset:240
	global_load_dword v73, v45, s[4:5] offset:248
	s_waitcnt vmcnt(0)
	v_mul_f32_e64 v6, v6, v38
	v_mul_f32_e64 v7, v7, v39
	v_mul_f32_e64 v10, v10, v40
	v_mul_f32_e64 v11, v11, v41
	v_mul_f32_e64 v8, v8, v46
	v_mul_f32_e64 v9, v9, v47
	v_mul_f32_e64 v12, v12, v48
	v_mul_f32_e64 v13, v13, v49
	v_mul_f32_e64 v14, v14, v50
	v_mul_f32_e64 v15, v15, v51
	v_mul_f32_e64 v18, v18, v52
	v_mul_f32_e64 v19, v19, v53
	v_mul_f32_e64 v16, v16, v54
	v_mul_f32_e64 v17, v17, v55
	v_mul_f32_e64 v20, v20, v56
	v_mul_f32_e64 v21, v21, v57
	v_mul_f32_e64 v22, v22, v58
	v_mul_f32_e64 v23, v23, v59
	v_mul_f32_e64 v26, v26, v60
	v_mul_f32_e64 v27, v27, v61
	v_mul_f32_e64 v24, v24, v62
	v_mul_f32_e64 v25, v25, v63
	v_mul_f32_e64 v28, v28, v64
	v_mul_f32_e64 v29, v29, v65
	v_mul_f32_e64 v30, v30, v66
	v_mul_f32_e64 v31, v31, v67
	v_mul_f32_e64 v36, v36, v68
	v_mul_f32_e64 v37, v37, v69
	v_mul_f32_e64 v34, v34, v70
	v_mul_f32_e64 v35, v35, v71
	v_mul_f32_e64 v32, v32, v72
	v_mul_f32_e64 v33, v33, v73

.LBB0_240:
	s_andn2_b64 vcc, exec, s[10:11]
	s_cbranch_vccnz .LBB0_216
	s_and_b64 s[10:11], s[6:7], exec
	s_cselect_b32 s10, 8, 48
	s_add_u32 s10, s2, s10
	s_addc_u32 s11, s3, 0
	s_and_b64 s[6:7], s[6:7], exec
	s_sext_i32_i16 s34, s12
	s_cselect_b32 s6, 2, 7
	s_add_i32 s60, s6, s34
	s_lshl_b64 s[6:7], s[60:61], 3
	s_add_u32 s6, s2, s6
	s_addc_u32 s7, s3, s7
	s_load_dwordx2 s[12:13], s[10:11], 0x0
	s_nop 0
	s_load_dwordx2 s[6:7], s[6:7], 0x0
	s_waitcnt lgkmcnt(0)
	s_add_u32 s36, s6, s31
	s_sext_i32_i16 s6, s28
	s_mulk_i32 s6, 0xba3
	s_addc_u32 s37, s7, s29
	s_lshr_b32 s7, s6, 31
	s_ashr_i32 s6, s6, 18
	s_add_i32 s6, s6, s7
	s_mul_i32 s7, s6, 0x58
	s_lshl_b32 s6, s6, 6
	s_sub_i32 s28, s28, s7
	v_or_b32_e32 v7, s6, v0
	s_sext_i32_i16 s7, s28
	v_mul_i32_i24_e32 v8, 0xb00, v7
	s_lshl_b32 s10, s7, 5
	v_ashrrev_i32_e32 v9, 31, v8
	v_lshl_add_u64 v[8:9], v[8:9], 2, s[36:37]
	s_ashr_i32 s11, s10, 31
	v_lshl_add_u64 v[8:9], s[10:11], 2, v[8:9]
	v_lshl_add_u64 v[38:39], v[8:9], 0, v[96:97]
	s_movk_i32 s7, 0x5000
	v_add_co_u32_e32 v10, vcc, s7, v38
	s_mov_b32 s7, 0x10000
	s_nop 0
	v_addc_co_u32_e32 v11, vcc, 0, v39, vcc
	global_load_dword v9, v[10:11], off offset:2048
	v_add_co_u32_e32 v10, vcc, s76, v38
	global_load_dword v8, v[38:39], off
	s_nop 0
	v_addc_co_u32_e32 v11, vcc, 0, v39, vcc
	v_add_co_u32_e32 v12, vcc, s7, v38
	global_load_dword v10, v[10:11], off
	s_nop 0
	v_addc_co_u32_e32 v13, vcc, 0, v39, vcc
	global_load_dword v11, v[12:13], off offset:2048
	v_add_co_u32_e32 v12, vcc, s74, v38
	s_mov_b32 s7, 0x1b000
	s_nop 0
	v_addc_co_u32_e32 v13, vcc, 0, v39, vcc
	v_add_co_u32_e32 v14, vcc, s7, v38
	s_mov_b32 s7, 0x21000
	s_nop 0
	v_addc_co_u32_e32 v15, vcc, 0, v39, vcc
	global_load_dword v12, v[12:13], off
	s_nop 0
	global_load_dword v13, v[14:15], off offset:2048
	v_add_co_u32_e32 v14, vcc, s7, v38
	s_mov_b32 s7, 0x31000
	s_nop 0
	v_addc_co_u32_e32 v15, vcc, 0, v39, vcc
	v_add_co_u32_e32 v16, vcc, s40, v38
	global_load_dword v14, v[14:15], off
	s_nop 0
	v_addc_co_u32_e32 v17, vcc, 0, v39, vcc
	global_load_dword v15, v[16:17], off offset:2048
	v_add_co_u32_e32 v16, vcc, s41, v38
	s_nop 1
	v_addc_co_u32_e32 v17, vcc, 0, v39, vcc
	v_add_co_u32_e32 v18, vcc, s7, v38
	s_mov_b32 s7, 0x37000
	s_nop 0
	v_addc_co_u32_e32 v19, vcc, 0, v39, vcc
	global_load_dword v16, v[16:17], off
	s_nop 0
	global_load_dword v17, v[18:19], off offset:2048
	v_add_co_u32_e32 v18, vcc, s7, v38
	s_mov_b32 s7, 0x3c000
	s_nop 0
	v_addc_co_u32_e32 v19, vcc, 0, v39, vcc
	v_add_co_u32_e32 v20, vcc, s7, v38
	s_mov_b32 s7, 0x42000
	s_nop 0
	v_addc_co_u32_e32 v21, vcc, 0, v39, vcc
	global_load_dword v18, v[18:19], off
	s_nop 0
	global_load_dword v19, v[20:21], off offset:2048
	v_add_co_u32_e32 v20, vcc, s7, v38
	s_mov_b32 s7, 0x47000
	s_nop 0
	v_addc_co_u32_e32 v21, vcc, 0, v39, vcc
	v_add_co_u32_e32 v22, vcc, s7, v38
	s_mov_b32 s7, 0x4d000
	s_nop 0
	v_addc_co_u32_e32 v23, vcc, 0, v39, vcc
	global_load_dword v20, v[20:21], off
	s_nop 0
	global_load_dword v21, v[22:23], off offset:2048
	v_add_co_u32_e32 v22, vcc, s7, v38
	s_mov_b32 s7, 0x52000
	s_nop 0
	v_addc_co_u32_e32 v23, vcc, 0, v39, vcc
	v_add_co_u32_e32 v24, vcc, s7, v38
	s_mov_b32 s7, 0x58000
	s_nop 0
	v_addc_co_u32_e32 v25, vcc, 0, v39, vcc
	global_load_dword v22, v[22:23], off
	s_nop 0
	global_load_dword v23, v[24:25], off offset:2048
	v_add_co_u32_e32 v24, vcc, s7, v38
	s_mov_b32 s7, 0x5d000
	s_nop 0
	v_addc_co_u32_e32 v25, vcc, 0, v39, vcc
	v_add_co_u32_e32 v26, vcc, s7, v38
	s_mov_b32 s7, 0x63000
	s_nop 0
	v_addc_co_u32_e32 v27, vcc, 0, v39, vcc
	global_load_dword v24, v[24:25], off
	s_nop 0
	global_load_dword v25, v[26:27], off offset:2048
	v_add_co_u32_e32 v26, vcc, s7, v38
	s_mov_b32 s7, 0x68000
	s_nop 0
	v_addc_co_u32_e32 v27, vcc, 0, v39, vcc
	v_add_co_u32_e32 v28, vcc, s7, v38
	s_mov_b32 s7, 0x6e000
	s_nop 0
	v_addc_co_u32_e32 v29, vcc, 0, v39, vcc
	global_load_dword v26, v[26:27], off
	s_nop 0
	global_load_dword v27, v[28:29], off offset:2048
	v_add_co_u32_e32 v28, vcc, s7, v38
	s_mov_b32 s7, 0x73000
	s_nop 0
	v_addc_co_u32_e32 v29, vcc, 0, v39, vcc
	v_add_co_u32_e32 v30, vcc, s7, v38
	s_mov_b32 s7, 0x79000
	s_nop 0
	v_addc_co_u32_e32 v31, vcc, 0, v39, vcc
	global_load_dword v28, v[28:29], off
	s_nop 0
	global_load_dword v29, v[30:31], off offset:2048
	v_add_co_u32_e32 v30, vcc, s7, v38
	s_mov_b32 s7, 0x7e000
	s_nop 0
	v_addc_co_u32_e32 v31, vcc, 0, v39, vcc
	v_add_co_u32_e32 v32, vcc, s7, v38
	s_mov_b32 s7, 0x84000
	s_nop 0
	v_addc_co_u32_e32 v33, vcc, 0, v39, vcc
	global_load_dword v30, v[30:31], off
	s_nop 0
	global_load_dword v31, v[32:33], off offset:2048
	v_add_co_u32_e32 v32, vcc, s7, v38
	s_mov_b32 s7, 0x89000
	s_nop 0
	v_addc_co_u32_e32 v33, vcc, 0, v39, vcc
	v_add_co_u32_e32 v34, vcc, s7, v38
	s_mov_b32 s7, 0x8f000
	s_nop 0
	v_addc_co_u32_e32 v35, vcc, 0, v39, vcc
	global_load_dword v32, v[32:33], off
	s_nop 0
	global_load_dword v33, v[34:35], off offset:2048
	v_add_co_u32_e32 v34, vcc, s7, v38
	s_mov_b32 s7, 0x94000
	s_nop 0
	v_addc_co_u32_e32 v35, vcc, 0, v39, vcc
	v_add_co_u32_e32 v36, vcc, s7, v38
	s_mov_b32 s7, 0x9a000
	s_nop 0
	v_addc_co_u32_e32 v37, vcc, 0, v39, vcc
	global_load_dword v34, v[34:35], off
	s_nop 0
	global_load_dword v35, v[36:37], off offset:2048
	v_add_co_u32_e32 v36, vcc, s7, v38
	s_mov_b32 s7, 0x9f000
	s_nop 0
	v_addc_co_u32_e32 v37, vcc, 0, v39, vcc
	v_add_co_u32_e32 v40, vcc, s7, v38
	global_load_dword v36, v[36:37], off
	s_nop 0
	v_addc_co_u32_e32 v41, vcc, 0, v39, vcc
	global_load_dword v37, v[40:41], off offset:2048
	v_add_co_u32_e32 v40, vcc, 0xa5000, v38
	s_ashr_i32 s7, s6, 31
	s_nop 0
	v_addc_co_u32_e32 v41, vcc, 0, v39, vcc
	v_add_co_u32_e32 v38, vcc, 0xaa000, v38
	global_load_dword v40, v[40:41], off
	s_nop 0
	v_addc_co_u32_e32 v39, vcc, 0, v39, vcc
	global_load_dword v41, v[38:39], off offset:2048
	s_cmp_eq_u64 s[12:13], 0
	s_cbranch_scc1 .LBB0_215
	s_lshl_b64 s[4:5], s[4:5], 12
	s_add_u32 s11, s12, s4
	s_addc_u32 s12, s13, s5
	s_lshl_b64 s[4:5], s[6:7], 2
	s_add_u32 s4, s11, s4
	s_addc_u32 s5, s12, s5
	v_lshlrev_b32_e32 v7, 2, v0
	global_load_dword v38, v7, s[4:5]
	global_load_dword v39, v7, s[4:5] offset:8
	global_load_dword v52, v7, s[4:5] offset:16
	global_load_dword v53, v7, s[4:5] offset:24
	global_load_dword v54, v7, s[4:5] offset:32
	global_load_dword v55, v7, s[4:5] offset:40
	global_load_dword v56, v7, s[4:5] offset:48
	global_load_dword v57, v7, s[4:5] offset:56
	global_load_dword v58, v7, s[4:5] offset:64
	global_load_dword v59, v7, s[4:5] offset:72
	global_load_dword v60, v7, s[4:5] offset:80
	global_load_dword v61, v7, s[4:5] offset:88
	global_load_dword v62, v7, s[4:5] offset:96
	global_load_dword v63, v7, s[4:5] offset:104
	global_load_dword v64, v7, s[4:5] offset:112
	global_load_dword v65, v7, s[4:5] offset:120
	global_load_dword v66, v7, s[4:5] offset:128
	global_load_dword v67, v7, s[4:5] offset:136
	global_load_dword v68, v7, s[4:5] offset:144
	global_load_dword v69, v7, s[4:5] offset:152
	global_load_dword v70, v7, s[4:5] offset:160
	global_load_dword v71, v7, s[4:5] offset:168
	global_load_dword v72, v7, s[4:5] offset:176
	global_load_dword v73, v7, s[4:5] offset:184
	global_load_dword v74, v7, s[4:5] offset:192
	global_load_dword v75, v7, s[4:5] offset:200
	global_load_dword v76, v7, s[4:5] offset:208
	global_load_dword v77, v7, s[4:5] offset:216
	global_load_dword v78, v7, s[4:5] offset:224
	global_load_dword v79, v7, s[4:5] offset:232
	global_load_dword v80, v7, s[4:5] offset:240
	global_load_dword v81, v7, s[4:5] offset:248
	s_waitcnt vmcnt(0)
	v_mul_f32_e64 v8, v8, v38
	v_mul_f32_e64 v9, v9, v39
	v_mul_f32_e64 v10, v10, v52
	v_mul_f32_e64 v11, v11, v53
	v_mul_f32_e64 v12, v12, v54
	v_mul_f32_e64 v13, v13, v55
	v_mul_f32_e64 v14, v14, v56
	v_mul_f32_e64 v15, v15, v57
	v_mul_f32_e64 v16, v16, v58
	v_mul_f32_e64 v17, v17, v59
	v_mul_f32_e64 v18, v18, v60
	v_mul_f32_e64 v19, v19, v61
	v_mul_f32_e64 v20, v20, v62
	v_mul_f32_e64 v21, v21, v63
	v_mul_f32_e64 v22, v22, v64
	v_mul_f32_e64 v23, v23, v65
	v_mul_f32_e64 v24, v24, v66
	v_mul_f32_e64 v25, v25, v67
	v_mul_f32_e64 v26, v26, v68
	v_mul_f32_e64 v27, v27, v69
	v_mul_f32_e64 v28, v28, v70
	v_mul_f32_e64 v29, v29, v71
	v_mul_f32_e64 v30, v30, v72
	v_mul_f32_e64 v31, v31, v73
	v_mul_f32_e64 v32, v32, v74
	v_mul_f32_e64 v33, v33, v75
	v_mul_f32_e64 v34, v34, v76
	v_mul_f32_e64 v35, v35, v77
	v_mul_f32_e64 v36, v36, v78
	v_mul_f32_e64 v37, v37, v79
	v_mul_f32_e64 v40, v40, v80
	v_mul_f32_e64 v41, v41, v81
	s_branch .LBB0_215

.LBB0_245:
	s_lshl_b32 s19, s18, 11
	s_lshl_b32 s20, s13, 2
	s_and_b32 s19, s19, 0x180000
	s_and_b32 s20, s20, 0xf00
	v_lshl_or_b32 v96, v118, 2, s20
	s_add_u32 s20, s8, s19
	s_addc_u32 s21, s9, 0
	s_lshr_b32 s19, s18, 1
	v_lshl_add_u64 v[82:83], s[20:21], 0, v[96:97]
	s_and_b32 s20, s19, 0x180
	s_and_b32 s19, s19, 0x78
	s_lshl_b32 s22, s20, 2
	s_mov_b32 s23, s61
	s_or_b32 s21, s20, s19
	v_lshl_add_u64 v[0:1], v[78:79], 0, s[22:23]
	s_lshl_b32 s60, s21, 9
	global_load_dwordx4 v[0:3], v[0:1], off
	v_lshl_add_u64 v[16:17], v[80:81], 0, s[60:61]
	global_load_dwordx4 v[4:7], v[16:17], off
	global_load_dwordx4 v[8:11], v[16:17], off offset:1024
	global_load_dwordx4 v[12:15], v[16:17], off offset:2048
	s_nop 0
	global_load_dwordx4 v[16:19], v[16:17], off offset:3072
	v_add_u32_e32 v20, s11, v76
	v_mov_b32_e32 v86, 0
	s_mov_b32 s21, -16
	s_mov_b32 s22, s11
	v_mov_b32_e32 v87, v86
	v_mov_b32_e32 v84, v86
	v_mov_b32_e32 v85, v86
	v_mov_b32_e32 v90, v86
	v_mov_b32_e32 v91, v86
	v_mov_b32_e32 v88, v86
	v_mov_b32_e32 v89, v86
	s_waitcnt vmcnt(0)
	v_mul_f32_e64 v6, v2, v6
	v_mul_f32_e64 v7, v3, v7
	v_mul_f32_e64 v4, v0, v4
	v_mul_f32_e64 v5, v1, v5
	ds_write_b128 v20, v[4:7]
	v_mul_f32_e64 v6, v2, v10
	v_mul_f32_e64 v7, v3, v11
	v_mul_f32_e64 v4, v0, v8
	v_mul_f32_e64 v5, v1, v9
	ds_write_b128 v20, v[4:7] offset:1024
	v_mul_f32_e64 v6, v2, v14
	v_mul_f32_e64 v7, v3, v15
	v_mul_f32_e64 v4, v0, v12
	v_mul_f32_e64 v5, v1, v13
	v_mul_f32_e64 v2, v2, v18
	v_mul_f32_e64 v3, v3, v19
	v_mul_f32_e64 v0, v0, v16
	v_mul_f32_e64 v1, v1, v17
	ds_write_b128 v20, v[4:7] offset:2048
	ds_write_b128 v20, v[0:3] offset:3072
	s_waitcnt lgkmcnt(0)
.LBB0_246:
	v_add_co_u32_e32 v0, vcc, 0xffff1000, v82
	s_movk_i32 s23, 0x8000
	s_nop 0
	v_addc_co_u32_e32 v1, vcc, -1, v83, vcc
	global_load_dword v98, v[0:1], off
	v_add_co_u32_e32 v0, vcc, 0xffff2000, v82
	v_mov_b32_e32 v77, s22
	s_nop 0
	v_addc_co_u32_e32 v1, vcc, -1, v83, vcc
	global_load_dword v102, v[0:1], off
	v_add_co_u32_e32 v0, vcc, 0xffff3000, v82
	s_add_i32 s21, s21, 16
	s_nop 0
	v_addc_co_u32_e32 v1, vcc, -1, v83, vcc
	global_load_dword v103, v[0:1], off
	v_add_co_u32_e32 v0, vcc, 0xffff4000, v82
	s_add_i32 s22, s22, 64
	s_nop 0
	v_addc_co_u32_e32 v1, vcc, -1, v83, vcc
	global_load_dword v99, v[0:1], off
	v_add_co_u32_e32 v0, vcc, 0xffff5000, v82
	s_mov_b64 s[24:25], 0x10000
	s_nop 0
	v_addc_co_u32_e32 v1, vcc, -1, v83, vcc
	global_load_dword v100, v[0:1], off
	v_add_co_u32_e32 v0, vcc, 0xffff6000, v82
	s_cmpk_lt_u32 s21, 0x70
	s_nop 0
	v_addc_co_u32_e32 v1, vcc, -1, v83, vcc
	global_load_dword v101, v[0:1], off
	v_add_co_u32_e32 v0, vcc, 0xffff7000, v82
	s_waitcnt vmcnt(1)
	v_mov_b32_e32 v40, v100
	v_addc_co_u32_e32 v1, vcc, -1, v83, vcc
	global_load_dword v104, v[0:1], off
	v_add_co_u32_e32 v0, vcc, s23, v82
	s_waitcnt vmcnt(1)
	v_mov_b32_e32 v20, v101
	v_addc_co_u32_e32 v1, vcc, -1, v83, vcc
	global_load_dword v105, v[0:1], off
	v_add_co_u32_e32 v0, vcc, 0xffff9000, v82
	s_waitcnt vmcnt(1)
	v_mov_b32_e32 v21, v104
	v_addc_co_u32_e32 v1, vcc, -1, v83, vcc
	global_load_dword v92, v[0:1], off
	v_add_co_u32_e32 v0, vcc, 0xffffa000, v82
	s_waitcnt vmcnt(1)
	v_mov_b32_e32 v41, v105
	v_addc_co_u32_e32 v1, vcc, -1, v83, vcc
	global_load_dword v93, v[0:1], off
	v_add_co_u32_e32 v0, vcc, 0xffffb000, v82
	s_nop 1
	v_addc_co_u32_e32 v1, vcc, -1, v83, vcc
	global_load_dword v94, v[0:1], off
	v_add_co_u32_e32 v0, vcc, 0xffffc000, v82
	s_nop 1
	v_addc_co_u32_e32 v1, vcc, -1, v83, vcc
	global_load_dword v95, v[0:1], off
	v_add_co_u32_e32 v0, vcc, 0xffffd000, v82
	s_nop 1
	v_addc_co_u32_e32 v1, vcc, -1, v83, vcc
	global_load_dword v106, v[0:1], off
	v_add_co_u32_e32 v0, vcc, 0xffffe000, v82
	s_nop 1
	v_addc_co_u32_e32 v1, vcc, -1, v83, vcc
	global_load_dword v110, v[0:1], off
	global_load_dword v96, v[82:83], off offset:-4096
	global_load_dword v108, v[82:83], off
	ds_read_b128 v[60:63], v77
	ds_read_b128 v[56:59], v77 offset:16
	ds_read_b128 v[52:55], v77 offset:32
	ds_read_b128 v[48:51], v77 offset:48
	ds_read_b128 v[64:67], v77 offset:512
	ds_read_b128 v[24:27], v77 offset:1024
	ds_read_b128 v[28:31], v77 offset:1536
	ds_read_b128 v[0:3], v77 offset:2048
	ds_read_b128 v[4:7], v77 offset:2560
	ds_read_b128 v[8:11], v77 offset:3072
	s_waitcnt lgkmcnt(5)
	v_mov_b32_e32 v129, v64
	v_mov_b32_e32 v64, v61
	v_mov_b32_e32 v128, v60
	v_mul_f32_e64 v60, v102, v64
	v_mul_f32_e64 v61, v102, v65
	s_waitcnt lgkmcnt(0)
	v_mov_b32_e32 v12, v9
	v_mov_b32_e32 v9, v11
	v_mov_b32_e32 v13, v10
	v_mul_f32_e64 v8, v98, v8
	v_mul_f32_e64 v9, v99, v9
	v_fma_f32 v60, v98, v128, v60
	v_fma_f32 v61, v98, v129, v61
	v_fma_f32 v116, v102, v12, v8
	v_fma_f32 v117, v103, v13, v9
	ds_read_b128 v[8:11], v77 offset:3584
	v_mov_b32_e32 v128, v62
	v_mov_b32_e32 v129, v66
	v_mov_b32_e32 v62, v99
	v_mov_b32_e32 v66, v63
	s_waitcnt lgkmcnt(0)
	v_mov_b32_e32 v12, v9
	v_mov_b32_e32 v9, v11
	v_mov_b32_e32 v13, v10
	v_mul_f32_e64 v8, v98, v8
	v_mul_f32_e64 v9, v99, v9
	v_mov_b32_e32 v64, v103
	v_fma_f32 v112, v102, v12, v8
	v_fma_f32 v113, v103, v13, v9
	ds_read_b128 v[68:71], v77 offset:528
	ds_read_b128 v[32:35], v77 offset:1040
	ds_read_b128 v[36:39], v77 offset:1552
	ds_read_b128 v[8:11], v77 offset:2064
	ds_read_b128 v[12:15], v77 offset:2576
	ds_read_b128 v[120:123], v77 offset:3088
	ds_read_b128 v[16:19], v77 offset:3600
	v_mul_f32_e64 v66, v62, v66
	v_mul_f32_e64 v67, v62, v67
	v_fma_f32 v66, v64, v128, v66
	v_fma_f32 v67, v64, v129, v67
	v_add_f32_e64 v60, v60, v66
	v_add_f32_e64 v61, v61, v67
	v_mov_b32_e32 v66, v56
	s_waitcnt lgkmcnt(0)
	v_mov_b32_e32 v22, v17
	v_mov_b32_e32 v17, v19
	v_mov_b32_e32 v67, v68
	v_mov_b32_e32 v56, v101
	v_mov_b32_e32 v68, v57
	v_mov_b32_e32 v23, v18
	v_mul_f32_e64 v16, v40, v16
	v_mul_f32_e64 v17, v41, v17
	v_mul_f32_e64 v68, v56, v68
	v_mul_f32_e64 v69, v56, v69
	v_fma_f32 v114, v20, v22, v16
	v_fma_f32 v115, v21, v23, v17
	ds_read_b128 v[72:75], v77 offset:544
	ds_read_b128 v[40:43], v77 offset:1056
	ds_read_b128 v[44:47], v77 offset:1568
	ds_read_b128 v[16:19], v77 offset:2080
	ds_read_b128 v[20:23], v77 offset:2592
	ds_read_b128 v[124:127], v77 offset:3104
	v_fma_f32 v66, v100, v66, v68
	v_fma_f32 v67, v100, v67, v69
	v_mov_b32_e32 v68, v58
	v_mov_b32_e32 v69, v70
	v_mov_b32_e32 v58, v105
	v_mov_b32_e32 v70, v59
	v_mul_f32_e64 v70, v58, v70
	v_mul_f32_e64 v71, v58, v71
	v_fma_f32 v68, v104, v68, v70
	v_fma_f32 v69, v104, v69, v71
	v_add_f32_e64 v60, v86, v60
	v_add_f32_e64 v61, v87, v61
	v_add_f32_e64 v66, v66, v68
	v_add_f32_e64 v67, v67, v69
	v_add_f32_e64 v116, v116, v117
	v_mov_b32_e32 v117, v116
	v_add_f32_e64 v60, v60, v66
	v_add_f32_e64 v61, v61, v67
	s_waitcnt lgkmcnt(5)
	v_mov_b32_e32 v67, v72
	v_mov_b32_e32 v72, v53
	s_waitcnt vmcnt(7) lgkmcnt(0)
	v_mul_f32_e32 v107, v92, v124
	v_mul_f32_e32 v124, v101, v121
	v_mov_b32_e32 v66, v52
	v_lshl_add_u64 v[82:83], v[82:83], 0, s[24:25]
	s_waitcnt vmcnt(6)
	v_mov_b32_e32 v68, v93
	v_mul_f32_e32 v111, v93, v125
	v_mul_f32_e64 v52, v68, v72
	v_mul_f32_e64 v53, v68, v73
	v_fma_f32 v52, v92, v66, v52
	v_fma_f32 v53, v92, v67, v53
	v_mov_b32_e32 v67, v74
	v_mov_b32_e32 v74, v55
	s_waitcnt vmcnt(5)
	v_mul_f32_e32 v125, v94, v126
	v_fma_f32 v120, v100, v120, v124
	v_fma_f32 v121, v101, v121, v124
	v_mul_f32_e32 v124, v105, v123
	v_fma_f32 v122, v104, v122, v124
	v_fma_f32 v123, v105, v123, v124
	v_mov_b32_e32 v66, v54
	v_mov_b32_e32 v121, v107
	s_waitcnt vmcnt(4)
	v_mov_b32_e32 v70, v95
	v_mul_f32_e32 v119, v95, v127
	v_mul_f32_e64 v54, v70, v74
	v_mul_f32_e64 v55, v70, v75
	v_mov_b32_e32 v123, v111
	v_mov_b32_e32 v124, v88
	v_mov_b32_e32 v117, v119
	v_fma_f32 v54, v94, v66, v54
	v_fma_f32 v55, v94, v67, v55
	v_add_f32_e64 v120, v120, v122
	v_add_f32_e64 v121, v121, v123
	v_add_f32_e64 v116, v124, v116
	v_add_f32_e64 v117, v125, v117
	v_add_f32_e64 v52, v52, v54
	v_add_f32_e64 v53, v53, v55
	v_add_f32_e64 v116, v120, v116
	v_add_f32_e64 v117, v121, v117
	ds_read_b128 v[120:123], v77 offset:3616
	ds_read_b128 v[124:127], v77 offset:560
	v_add_f32_e64 v52, v60, v52
	v_add_f32_e64 v53, v61, v53
	v_mov_b32_e32 v61, v28
	v_mov_b32_e32 v28, v25
	v_mov_b32_e32 v60, v24
	v_mul_f32_e64 v24, v102, v28
	v_mul_f32_e64 v25, v102, v29
	v_mov_b32_e32 v29, v30
	v_mov_b32_e32 v30, v27
	v_mov_b32_e32 v28, v26
	v_mul_f32_e64 v26, v62, v30
	v_mul_f32_e64 v27, v62, v31
	v_fma_f32 v24, v98, v60, v24
	v_fma_f32 v25, v98, v61, v25
	v_fma_f32 v26, v64, v28, v26
	v_fma_f32 v27, v64, v29, v27
	v_add_f32_e64 v24, v24, v26
	v_add_f32_e64 v25, v25, v27
	v_mov_b32_e32 v27, v36
	v_mov_b32_e32 v36, v33
	s_waitcnt lgkmcnt(0)
	v_mov_b32_e32 v55, v124
	v_mov_b32_e32 v124, v49
	v_mov_b32_e32 v26, v32
	v_mul_f32_e64 v28, v56, v36
	v_mul_f32_e64 v29, v56, v37
	v_mov_b32_e32 v54, v48
	s_waitcnt vmcnt(2)
	v_mul_f32_e64 v48, v110, v124
	v_mul_f32_e64 v49, v110, v125
	v_fma_f32 v26, v100, v26, v28
	v_fma_f32 v27, v100, v27, v29
	v_mov_b32_e32 v29, v38
	v_mov_b32_e32 v38, v35
	v_fma_f32 v48, v106, v54, v48
	v_fma_f32 v49, v106, v55, v49
	v_mov_b32_e32 v55, v126
	v_mov_b32_e32 v126, v51
	v_mov_b32_e32 v28, v34
	v_mul_f32_e64 v30, v58, v38
	v_mul_f32_e64 v31, v58, v39
	v_mov_b32_e32 v54, v50
	s_waitcnt vmcnt(0)
	v_mul_f32_e64 v50, v108, v126
	v_mul_f32_e64 v51, v108, v127
	v_fma_f32 v28, v104, v28, v30
	v_fma_f32 v29, v104, v29, v31
	v_fma_f32 v50, v96, v54, v50
	v_fma_f32 v51, v96, v55, v51
	v_add_f32_e64 v24, v84, v24
	v_add_f32_e64 v25, v85, v25
	v_add_f32_e64 v26, v26, v28
	v_add_f32_e64 v27, v27, v29
	v_add_f32_e64 v48, v48, v50
	v_add_f32_e64 v49, v49, v51
	v_add_f32_e64 v24, v24, v26
	v_add_f32_e64 v25, v25, v27
	v_mov_b32_e32 v27, v44
	v_mov_b32_e32 v44, v41
	v_add_f32_e64 v86, v52, v48
	v_add_f32_e64 v87, v53, v49
	ds_read_b128 v[48:51], v77 offset:1072
	ds_read_b128 v[52:55], v77 offset:1584
	v_mov_b32_e32 v26, v40
	v_mul_f32_e64 v28, v68, v44
	v_mul_f32_e64 v29, v68, v45
	v_mov_b32_e32 v33, v4
	v_mov_b32_e32 v4, v1
	v_fma_f32 v26, v92, v26, v28
	v_fma_f32 v27, v92, v27, v29
	v_mov_b32_e32 v29, v46
	v_mov_b32_e32 v46, v43
	v_mov_b32_e32 v32, v0
	v_mul_f32_e64 v0, v102, v4
	v_mul_f32_e64 v1, v102, v5
	v_mov_b32_e32 v5, v6
	v_mov_b32_e32 v6, v3
	v_mov_b32_e32 v28, v42
	v_mul_f32_e64 v30, v70, v46
	v_mul_f32_e64 v31, v70, v47
	v_mov_b32_e32 v4, v2
	v_mul_f32_e64 v2, v62, v6
	v_mul_f32_e64 v3, v62, v7
	v_fma_f32 v28, v94, v28, v30
	v_fma_f32 v29, v94, v29, v31
	v_fma_f32 v0, v98, v32, v0
	v_fma_f32 v1, v98, v33, v1
	v_fma_f32 v2, v64, v4, v2
	v_fma_f32 v3, v64, v5, v3
	v_add_f32_e64 v26, v26, v28
	v_add_f32_e64 v27, v27, v29
	v_add_f32_e64 v0, v0, v2
	v_add_f32_e64 v1, v1, v3
	v_mov_b32_e32 v3, v12
	v_mov_b32_e32 v12, v9
	v_add_f32_e64 v24, v24, v26
	v_add_f32_e64 v25, v25, v27
	s_waitcnt lgkmcnt(0)
	v_mov_b32_e32 v27, v52
	v_mov_b32_e32 v52, v49
	v_mov_b32_e32 v2, v8
	v_mul_f32_e64 v4, v56, v12
	v_mul_f32_e64 v5, v56, v13
	v_mov_b32_e32 v26, v48
	v_mul_f32_e64 v28, v110, v52
	v_mul_f32_e64 v29, v110, v53
	v_fma_f32 v2, v100, v2, v4
	v_fma_f32 v3, v100, v3, v5
	v_mov_b32_e32 v5, v14
	v_mov_b32_e32 v14, v11
	v_fma_f32 v26, v106, v26, v28
	v_fma_f32 v27, v106, v27, v29
	v_mov_b32_e32 v29, v54
	v_mov_b32_e32 v54, v51
	v_mov_b32_e32 v4, v10
	v_mul_f32_e64 v6, v58, v14
	v_mul_f32_e64 v7, v58, v15
	v_mov_b32_e32 v28, v50
	v_mul_f32_e64 v30, v108, v54
	v_mul_f32_e64 v31, v108, v55
	v_fma_f32 v4, v104, v4, v6
	v_fma_f32 v5, v104, v5, v7
	v_fma_f32 v28, v96, v28, v30
	v_fma_f32 v29, v96, v29, v31
	v_add_f32_e64 v0, v90, v0
	v_add_f32_e64 v1, v91, v1
	v_add_f32_e64 v2, v2, v4
	v_add_f32_e64 v3, v3, v5
	v_add_f32_e64 v26, v26, v28
	v_add_f32_e64 v27, v27, v29
	v_add_f32_e64 v0, v0, v2
	v_add_f32_e64 v1, v1, v3
	v_mov_b32_e32 v3, v20
	v_mov_b32_e32 v20, v17
	v_add_f32_e64 v84, v24, v26
	v_add_f32_e64 v85, v25, v27
	ds_read_b128 v[24:27], v77 offset:2096
	ds_read_b128 v[28:31], v77 offset:2608
	v_mov_b32_e32 v2, v16
	v_mul_f32_e64 v4, v68, v20
	v_mul_f32_e64 v5, v68, v21
	v_fma_f32 v2, v92, v2, v4
	v_fma_f32 v3, v92, v3, v5
	v_mov_b32_e32 v5, v22
	v_mov_b32_e32 v22, v19
	v_mov_b32_e32 v4, v18
	v_mul_f32_e64 v6, v70, v22
	v_mul_f32_e64 v7, v70, v23
	v_fma_f32 v4, v94, v4, v6
	v_fma_f32 v5, v94, v5, v7
	v_add_f32_e64 v2, v2, v4
	v_add_f32_e64 v3, v3, v5
	v_add_f32_e64 v116, v116, v117
	v_mov_b32_e32 v117, v116
	v_add_f32_e64 v0, v0, v2
	v_add_f32_e64 v1, v1, v3
	s_waitcnt lgkmcnt(0)
	v_mov_b32_e32 v3, v28
	v_mov_b32_e32 v28, v25
	v_mov_b32_e32 v2, v24
	v_mul_f32_e64 v4, v110, v28
	v_mul_f32_e64 v5, v110, v29
	v_fma_f32 v2, v106, v2, v4
	v_fma_f32 v3, v106, v3, v5
	v_mov_b32_e32 v5, v30
	v_mov_b32_e32 v30, v27
	v_mov_b32_e32 v4, v26
	v_mul_f32_e64 v6, v108, v30
	v_mul_f32_e64 v7, v108, v31
	v_fma_f32 v4, v96, v4, v6
	v_fma_f32 v5, v96, v5, v7
	v_add_f32_e64 v2, v2, v4
	v_add_f32_e64 v3, v3, v5
	v_mov_b32_e32 v107, v108
	v_add_f32_e64 v90, v0, v2
	v_add_f32_e64 v91, v1, v3
	ds_read_b128 v[0:3], v77 offset:3120
	v_mov_b32_e32 v111, v96
	v_mov_b32_e32 v7, v106
	s_waitcnt lgkmcnt(0)
	v_mov_b32_e32 v4, v1
	v_mov_b32_e32 v1, v3
	v_mov_b32_e32 v5, v2
	v_mul_f32_e64 v0, v106, v0
	v_mul_f32_e64 v1, v107, v1
	s_nop 0
	v_fma_f32 v0, v110, v4, v0
	v_fma_f32 v1, v111, v5, v1
	s_nop 0
	v_add_f32_e64 v4, v0, v1
	v_add_f32_e64 v5, v1, v0
	ds_read_b128 v[0:3], v77 offset:3632
	s_waitcnt lgkmcnt(0)
	v_mul_f32_e32 v8, v96, v2
	v_mul_f32_e32 v9, v108, v3
	v_add_f32_e64 v2, v112, v113
	v_add_f32_e64 v3, v113, v112
	v_mul_f32_e32 v5, v110, v1
	v_pk_mov_b32 v[0:1], v[88:89], v[0:1] op_sel:[1,0]
	v_mov_b32_e32 v6, v2
	v_add_f32_e64 v2, v0, v2
	v_add_f32_e64 v3, v1, v3
	v_mul_f32_e64 v0, v0, v6
	v_mul_f32_e64 v1, v1, v7
	v_mul_f32_e32 v6, v95, v123
	v_mov_b32_e32 v3, v1
	v_add_f32_e64 v0, v114, v115
	v_add_f32_e64 v1, v115, v114
	v_fma_f32 v7, v95, v123, v6
	v_fma_f32 v6, v94, v122, v6
	v_mov_b32_e32 v1, v5
	v_add_f32_e64 v0, v2, v0
	v_add_f32_e64 v1, v3, v1
	v_mul_f32_e32 v2, v93, v121
	v_fma_f32 v3, v93, v121, v2
	v_fma_f32 v2, v92, v120, v2
	v_mov_b32_e32 v7, v9
	v_mov_b32_e32 v3, v8
	v_add_f32_e64 v2, v2, v6
	v_add_f32_e64 v3, v3, v7
	s_nop 0
	v_add_f32_e64 v0, v0, v2
	v_add_f32_e64 v1, v1, v3
	s_nop 0
	v_mov_b32_e32 v117, v0
	v_mov_b32_e32 v5, v1
	v_add_f32_e64 v88, v116, v4
	v_add_f32_e64 v89, v117, v5
	s_cbranch_scc1 .LBB0_246
	s_lshl_b32 s21, s18, 6
	s_and_b32 s21, s21, 0x3c0
	v_or_b32_e32 v4, s21, v118
	v_lshlrev_b32_e32 v96, 11, v4
	v_lshl_add_u64 v[4:5], s[6:7], 0, v[96:97]
	s_lshl_b32 s60, s20, 1
	v_lshl_add_u64 v[4:5], v[4:5], 0, s[60:61]
	s_lshl_b32 s60, s19, 1
	v_lshl_add_u64 v[4:5], v[4:5], 0, s[60:61]
	v_cvt_pk_bf16_f32 v0, v86, v87
	v_cvt_pk_bf16_f32 v1, v84, v85
	v_cvt_pk_bf16_f32 v2, v90, v91
	v_cvt_pk_bf16_f32 v3, v88, v89
	global_store_dwordx4 v[4:5], v[0:3], off
	s_waitcnt lgkmcnt(0)
	s_add_i32 s18, s18, s14
	s_add_i32 s13, s13, s12
	s_cmpk_gt_i32 s18, 0x3ff
	s_cbranch_scc0 .LBB0_245

.LBB0_260:
	s_and_b64 s[8:9], s[6:7], exec
	s_cselect_b32 s8, 8, 48
	s_add_u32 s8, s2, s8
	s_addc_u32 s9, s3, 0
	s_and_b64 s[6:7], s[6:7], exec
	s_sext_i32_i16 s21, s10
	s_cselect_b32 s6, 2, 7
	s_add_i32 s60, s6, s21
	s_lshl_b64 s[6:7], s[60:61], 3
	s_add_u32 s6, s2, s6
	s_addc_u32 s7, s3, s7
	s_load_dwordx2 s[10:11], s[8:9], 0x0
	s_nop 0
	s_load_dwordx2 s[6:7], s[6:7], 0x0
	s_waitcnt lgkmcnt(0)
	s_add_u32 s22, s6, s20
	s_sext_i32_i16 s6, s18
	s_mulk_i32 s6, 0xba3
	s_addc_u32 s23, s7, s19
	s_lshr_b32 s7, s6, 31
	s_ashr_i32 s6, s6, 18
	s_add_i32 s6, s6, s7
	s_mul_i32 s7, s6, 0x58
	s_lshl_b32 s6, s6, 6
	s_sub_i32 s18, s18, s7
	v_or_b32_e32 v7, s6, v0
	s_sext_i32_i16 s7, s18
	v_mul_i32_i24_e32 v8, 0xb00, v7
	s_lshl_b32 s8, s7, 5
	v_ashrrev_i32_e32 v9, 31, v8
	v_lshl_add_u64 v[8:9], v[8:9], 2, s[22:23]
	s_ashr_i32 s9, s8, 31
	v_lshl_add_u64 v[8:9], s[8:9], 2, v[8:9]
	v_lshl_add_u64 v[38:39], v[8:9], 0, v[96:97]
	s_movk_i32 s7, 0x5000
	v_add_co_u32_e32 v10, vcc, s7, v38
	global_load_dword v8, v[38:39], off
	s_nop 0
	v_addc_co_u32_e32 v11, vcc, 0, v39, vcc
	global_load_dword v9, v[10:11], off offset:2048
	v_add_co_u32_e32 v10, vcc, s76, v38
	s_mov_b32 s7, 0x1b000
	s_nop 0
	v_addc_co_u32_e32 v11, vcc, 0, v39, vcc
	v_add_co_u32_e32 v12, vcc, s26, v38
	global_load_dword v10, v[10:11], off
	s_nop 0
	v_addc_co_u32_e32 v13, vcc, 0, v39, vcc
	global_load_dword v11, v[12:13], off offset:2048
	v_add_co_u32_e32 v12, vcc, s74, v38
	s_nop 1
	v_addc_co_u32_e32 v13, vcc, 0, v39, vcc
	v_add_co_u32_e32 v14, vcc, s7, v38
	global_load_dword v12, v[12:13], off
	s_nop 0
	v_addc_co_u32_e32 v15, vcc, 0, v39, vcc
	global_load_dword v13, v[14:15], off offset:2048
	v_add_co_u32_e32 v14, vcc, s27, v38
	s_mov_b32 s7, 0x37000
	s_nop 0
	v_addc_co_u32_e32 v15, vcc, 0, v39, vcc
	v_add_co_u32_e32 v16, vcc, s40, v38
	global_load_dword v14, v[14:15], off
	s_nop 0
	v_addc_co_u32_e32 v17, vcc, 0, v39, vcc
	global_load_dword v15, v[16:17], off offset:2048
	v_add_co_u32_e32 v16, vcc, s41, v38
	s_nop 1
	v_addc_co_u32_e32 v17, vcc, 0, v39, vcc
	v_add_co_u32_e32 v18, vcc, s28, v38
	global_load_dword v16, v[16:17], off
	s_nop 0
	v_addc_co_u32_e32 v19, vcc, 0, v39, vcc
	global_load_dword v17, v[18:19], off offset:2048
	v_add_co_u32_e32 v18, vcc, s7, v38
	s_mov_b32 s7, 0x4d000
	s_nop 0
	v_addc_co_u32_e32 v19, vcc, 0, v39, vcc
	v_add_co_u32_e32 v20, vcc, s25, v38
	global_load_dword v18, v[18:19], off
	s_nop 0
	v_addc_co_u32_e32 v21, vcc, 0, v39, vcc
	global_load_dword v19, v[20:21], off offset:2048
	v_add_co_u32_e32 v20, vcc, s29, v38
	s_nop 1
	v_addc_co_u32_e32 v21, vcc, 0, v39, vcc
	v_add_co_u32_e32 v22, vcc, s30, v38
	global_load_dword v20, v[20:21], off
	s_nop 0
	v_addc_co_u32_e32 v23, vcc, 0, v39, vcc
	global_load_dword v21, v[22:23], off offset:2048
	v_add_co_u32_e32 v22, vcc, s7, v38
	s_mov_b32 s7, 0x52000
	s_nop 0
	v_addc_co_u32_e32 v23, vcc, 0, v39, vcc
	v_add_co_u32_e32 v24, vcc, s7, v38
	s_mov_b32 s7, 0x58000
	s_nop 0
	v_addc_co_u32_e32 v25, vcc, 0, v39, vcc
	global_load_dword v22, v[22:23], off
	s_nop 0
	global_load_dword v23, v[24:25], off offset:2048
	v_add_co_u32_e32 v24, vcc, s7, v38
	s_mov_b32 s7, 0x5d000
	s_nop 0
	v_addc_co_u32_e32 v25, vcc, 0, v39, vcc
	v_add_co_u32_e32 v26, vcc, s7, v38
	s_mov_b32 s7, 0x63000
	s_nop 0
	v_addc_co_u32_e32 v27, vcc, 0, v39, vcc
	global_load_dword v24, v[24:25], off
	s_nop 0
	global_load_dword v25, v[26:27], off offset:2048
	v_add_co_u32_e32 v26, vcc, s7, v38
	s_mov_b32 s7, 0x68000
	s_nop 0
	v_addc_co_u32_e32 v27, vcc, 0, v39, vcc
	v_add_co_u32_e32 v28, vcc, s7, v38
	s_mov_b32 s7, 0x6e000
	s_nop 0
	v_addc_co_u32_e32 v29, vcc, 0, v39, vcc
	global_load_dword v26, v[26:27], off
	s_nop 0
	global_load_dword v27, v[28:29], off offset:2048
	v_add_co_u32_e32 v28, vcc, s7, v38
	s_mov_b32 s7, 0x73000
	s_nop 0
	v_addc_co_u32_e32 v29, vcc, 0, v39, vcc
	v_add_co_u32_e32 v30, vcc, s7, v38
	s_mov_b32 s7, 0x79000
	s_nop 0
	v_addc_co_u32_e32 v31, vcc, 0, v39, vcc
	global_load_dword v28, v[28:29], off
	s_nop 0
	global_load_dword v29, v[30:31], off offset:2048
	v_add_co_u32_e32 v30, vcc, s7, v38
	s_mov_b32 s7, 0x7e000
	s_nop 0
	v_addc_co_u32_e32 v31, vcc, 0, v39, vcc
	v_add_co_u32_e32 v32, vcc, s7, v38
	s_mov_b32 s7, 0x84000
	s_nop 0
	v_addc_co_u32_e32 v33, vcc, 0, v39, vcc
	global_load_dword v30, v[30:31], off
	s_nop 0
	global_load_dword v31, v[32:33], off offset:2048
	v_add_co_u32_e32 v32, vcc, s7, v38
	s_mov_b32 s7, 0x89000
	s_nop 0
	v_addc_co_u32_e32 v33, vcc, 0, v39, vcc
	v_add_co_u32_e32 v34, vcc, s7, v38
	s_mov_b32 s7, 0x8f000
	s_nop 0
	v_addc_co_u32_e32 v35, vcc, 0, v39, vcc
	global_load_dword v32, v[32:33], off
	s_nop 0
	global_load_dword v33, v[34:35], off offset:2048
	v_add_co_u32_e32 v34, vcc, s7, v38
	s_mov_b32 s7, 0x94000
	s_nop 0
	v_addc_co_u32_e32 v35, vcc, 0, v39, vcc
	v_add_co_u32_e32 v36, vcc, s7, v38
	s_mov_b32 s7, 0x9a000
	s_nop 0
	v_addc_co_u32_e32 v37, vcc, 0, v39, vcc
	global_load_dword v34, v[34:35], off
	s_nop 0
	global_load_dword v35, v[36:37], off offset:2048
	v_add_co_u32_e32 v36, vcc, s7, v38
	s_mov_b32 s7, 0x9f000
	s_nop 0
	v_addc_co_u32_e32 v37, vcc, 0, v39, vcc
	v_add_co_u32_e32 v40, vcc, s7, v38
	global_load_dword v36, v[36:37], off
	s_nop 0
	v_addc_co_u32_e32 v41, vcc, 0, v39, vcc
	global_load_dword v37, v[40:41], off offset:2048
	v_add_co_u32_e32 v40, vcc, 0xa5000, v38
	s_ashr_i32 s7, s6, 31
	s_nop 0
	v_addc_co_u32_e32 v41, vcc, 0, v39, vcc
	v_add_co_u32_e32 v38, vcc, 0xaa000, v38
	global_load_dword v40, v[40:41], off
	s_nop 0
	v_addc_co_u32_e32 v39, vcc, 0, v39, vcc
	global_load_dword v41, v[38:39], off offset:2048
	s_cmp_eq_u64 s[10:11], 0
	s_cbranch_scc1 .LBB0_255
	s_lshl_b64 s[4:5], s[4:5], 12
	s_add_u32 s9, s10, s4
	s_addc_u32 s10, s11, s5
	s_lshl_b64 s[4:5], s[6:7], 2
	s_add_u32 s4, s9, s4
	s_addc_u32 s5, s10, s5
	v_lshlrev_b32_e32 v7, 2, v0
	global_load_dword v38, v7, s[4:5]
	global_load_dword v39, v7, s[4:5] offset:8
	global_load_dword v52, v7, s[4:5] offset:16
	global_load_dword v53, v7, s[4:5] offset:24
	global_load_dword v54, v7, s[4:5] offset:32
	global_load_dword v55, v7, s[4:5] offset:40
	global_load_dword v56, v7, s[4:5] offset:48
	global_load_dword v57, v7, s[4:5] offset:56
	global_load_dword v58, v7, s[4:5] offset:64
	global_load_dword v59, v7, s[4:5] offset:72
	global_load_dword v60, v7, s[4:5] offset:80
	global_load_dword v61, v7, s[4:5] offset:88
	global_load_dword v62, v7, s[4:5] offset:96
	global_load_dword v63, v7, s[4:5] offset:104
	global_load_dword v64, v7, s[4:5] offset:112
	global_load_dword v65, v7, s[4:5] offset:120
	global_load_dword v66, v7, s[4:5] offset:128
	global_load_dword v67, v7, s[4:5] offset:136
	global_load_dword v68, v7, s[4:5] offset:144
	global_load_dword v69, v7, s[4:5] offset:152
	global_load_dword v70, v7, s[4:5] offset:160
	global_load_dword v71, v7, s[4:5] offset:168
	global_load_dword v72, v7, s[4:5] offset:176
	global_load_dword v73, v7, s[4:5] offset:184
	global_load_dword v74, v7, s[4:5] offset:192
	global_load_dword v75, v7, s[4:5] offset:200
	global_load_dword v76, v7, s[4:5] offset:208
	global_load_dword v77, v7, s[4:5] offset:216
	global_load_dword v78, v7, s[4:5] offset:224
	global_load_dword v79, v7, s[4:5] offset:232
	global_load_dword v80, v7, s[4:5] offset:240
	global_load_dword v81, v7, s[4:5] offset:248
	s_waitcnt vmcnt(0)
	v_mul_f32_e64 v8, v8, v38
	v_mul_f32_e64 v9, v9, v39
	v_mul_f32_e64 v10, v10, v52
	v_mul_f32_e64 v11, v11, v53
	v_mul_f32_e64 v12, v12, v54
	v_mul_f32_e64 v13, v13, v55
	v_mul_f32_e64 v14, v14, v56
	v_mul_f32_e64 v15, v15, v57
	v_mul_f32_e64 v16, v16, v58
	v_mul_f32_e64 v17, v17, v59
	v_mul_f32_e64 v18, v18, v60
	v_mul_f32_e64 v19, v19, v61
	v_mul_f32_e64 v20, v20, v62
	v_mul_f32_e64 v21, v21, v63
	v_mul_f32_e64 v22, v22, v64
	v_mul_f32_e64 v23, v23, v65
	v_mul_f32_e64 v24, v24, v66
	v_mul_f32_e64 v25, v25, v67
	v_mul_f32_e64 v26, v26, v68
	v_mul_f32_e64 v27, v27, v69
	v_mul_f32_e64 v28, v28, v70
	v_mul_f32_e64 v29, v29, v71
	v_mul_f32_e64 v30, v30, v72
	v_mul_f32_e64 v31, v31, v73
	v_mul_f32_e64 v32, v32, v74
	v_mul_f32_e64 v33, v33, v75
	v_mul_f32_e64 v34, v34, v76
	v_mul_f32_e64 v35, v35, v77
	v_mul_f32_e64 v36, v36, v78
	v_mul_f32_e64 v37, v37, v79
	v_mul_f32_e64 v40, v40, v80
	v_mul_f32_e64 v41, v41, v81
	s_branch .LBB0_255

.LBB0_342:
	v_lshl_add_u32 v242, s52, 8, v251
	v_lshl_or_b32 v216, s51, 8, v253
	v_ashrrev_i32_e32 v217, 31, v216
	v_ashrrev_i32_e32 v243, 31, v242
	v_or_b32_e32 v238, 16, v242
	v_lshl_add_u64 v[72:73], v[216:217], 1, s[16:17]
	v_lshlrev_b64 v[74:75], 11, v[242:243]
	v_ashrrev_i32_e32 v239, 31, v238
	v_or_b32_e32 v234, 32, v242
	v_lshl_add_u64 v[244:245], v[72:73], 0, v[74:75]
	v_lshlrev_b64 v[74:75], 11, v[238:239]
	v_ashrrev_i32_e32 v235, 31, v234
	v_or_b32_e32 v230, 48, v242
	v_lshl_add_u64 v[240:241], v[72:73], 0, v[74:75]
	v_lshlrev_b64 v[74:75], 11, v[234:235]
	v_ashrrev_i32_e32 v231, 31, v230
	v_add_u32_e32 v226, 0x80, v242
	v_lshl_add_u64 v[236:237], v[72:73], 0, v[74:75]
	v_lshlrev_b64 v[74:75], 11, v[230:231]
	v_ashrrev_i32_e32 v227, 31, v226
	v_add_u32_e32 v222, 0x90, v242
	global_load_dwordx4 v[190:193], v[244:245], off
	global_load_dwordx4 v[186:189], v[244:245], off offset:256
	v_lshl_add_u64 v[232:233], v[72:73], 0, v[74:75]
	v_lshlrev_b64 v[74:75], 11, v[226:227]
	v_ashrrev_i32_e32 v223, 31, v222
	v_add_u32_e32 v218, 0xa0, v242
	v_lshl_add_u64 v[228:229], v[72:73], 0, v[74:75]
	v_lshlrev_b64 v[74:75], 11, v[222:223]
	v_ashrrev_i32_e32 v219, 31, v218
	v_add_u32_e32 v212, 0xb0, v242
	v_lshl_add_u64 v[224:225], v[72:73], 0, v[74:75]
	v_lshlrev_b64 v[74:75], 11, v[218:219]
	v_ashrrev_i32_e32 v213, 31, v212
	v_lshl_add_u64 v[220:221], v[72:73], 0, v[74:75]
	v_lshlrev_b64 v[74:75], 11, v[212:213]
	v_lshl_add_u64 v[214:215], v[72:73], 0, v[74:75]
	global_load_dwordx4 v[182:185], v[240:241], off
	global_load_dwordx4 v[178:181], v[240:241], off offset:256
	global_load_dwordx4 v[174:177], v[236:237], off
	global_load_dwordx4 v[170:173], v[236:237], off offset:256
	global_load_dwordx4 v[166:169], v[232:233], off
	global_load_dwordx4 v[162:165], v[232:233], off offset:256
	global_load_dwordx4 v[150:153], v[228:229], off
	global_load_dwordx4 v[142:145], v[228:229], off offset:256
	global_load_dwordx4 v[126:129], v[224:225], off
	global_load_dwordx4 v[122:125], v[224:225], off offset:256
	global_load_dwordx4 v[106:109], v[220:221], off
	global_load_dwordx4 v[98:101], v[220:221], off offset:256
	global_load_dwordx4 v[84:87], v[214:215], off
	global_load_dwordx4 v[72:75], v[214:215], off offset:256
	v_lshlrev_b64 v[194:195], 10, v[242:243]
	v_lshl_add_u64 v[194:195], v[194:195], 0, v[216:217]
	s_andn2_b64 vcc, exec, s[20:21]
	v_lshl_add_u64 v[246:247], v[194:195], 2, s[8:9]
	s_waitcnt vmcnt(0)
	v_lshlrev_b32_e32 v196, 16, v190
	v_and_b32_e32 v197, 0xffff0000, v190
	v_lshlrev_b32_e32 v190, 16, v191
	v_and_b32_e32 v191, 0xffff0000, v191
	v_fma_f32 v160, v160, 0.5, v190
	v_fma_f32 v161, v161, 0.5, v191
	v_lshlrev_b32_e32 v190, 16, v192
	v_and_b32_e32 v191, 0xffff0000, v192
	v_fma_f32 v190, v154, 0.5, v190
	v_fma_f32 v191, v155, 0.5, v191
	v_lshlrev_b32_e32 v154, 16, v193
	v_and_b32_e32 v155, 0xffff0000, v193
	v_fma_f32 v158, v158, 0.5, v196
	v_fma_f32 v159, v159, 0.5, v197
	v_fma_f32 v192, v156, 0.5, v154
	v_fma_f32 v193, v157, 0.5, v155
	v_cvt_pk_bf16_f32 v154, v158, v159
	v_cvt_pk_bf16_f32 v155, v160, v161
	v_cvt_pk_bf16_f32 v156, v190, v191
	v_cndmask_b32_e64 v196, 0, 1, s[20:21]
	v_cvt_pk_bf16_f32 v157, v192, v193
	v_cmp_ne_u32_e64 s[6:7], 1, v196
	global_store_dwordx4 v[244:245], v[154:157], off sc1
	s_nop 1
	s_cbranch_vccnz .LBB0_344
	global_store_dwordx4 v[246:247], v[158:161], off
	global_store_dwordx4 v[246:247], v[190:193], off offset:16
.LBB0_344:
	s_nop 0
	v_lshlrev_b32_e32 v158, 16, v186
	v_and_b32_e32 v159, 0xffff0000, v186
	v_fma_f32 v146, v146, 0.5, v158
	v_fma_f32 v147, v147, 0.5, v159
	v_lshlrev_b32_e32 v158, 16, v187
	v_and_b32_e32 v159, 0xffff0000, v187
	v_fma_f32 v148, v148, 0.5, v158
	v_fma_f32 v149, v149, 0.5, v159
	v_lshlrev_b32_e32 v158, 16, v188
	v_and_b32_e32 v159, 0xffff0000, v188
	v_fma_f32 v158, v138, 0.5, v158
	v_fma_f32 v159, v139, 0.5, v159
	v_lshlrev_b32_e32 v138, 16, v189
	v_and_b32_e32 v139, 0xffff0000, v189
	v_fma_f32 v160, v140, 0.5, v138
	v_fma_f32 v161, v141, 0.5, v139
	v_cvt_pk_bf16_f32 v138, v146, v147
	v_cvt_pk_bf16_f32 v139, v148, v149
	v_cvt_pk_bf16_f32 v140, v158, v159
	v_lshl_add_u64 v[186:187], v[244:245], 0, s[66:67]
	v_cvt_pk_bf16_f32 v141, v160, v161
	s_and_b64 vcc, exec, s[6:7]
	global_store_dwordx4 v[186:187], v[138:141], off sc1
	s_nop 1
	s_cbranch_vccnz .LBB0_346
	global_store_dwordx4 v[246:247], v[146:149], off offset:512
	global_store_dwordx4 v[246:247], v[158:161], off offset:528

.LBB0_348:
	s_or_b64 exec, exec, s[28:29]
	s_waitcnt lgkmcnt(0)
	v_lshlrev_b64 v[138:139], 10, v[238:239]
	v_lshl_add_u64 v[146:147], v[138:139], 0, v[216:217]
	v_lshlrev_b32_e32 v138, 16, v182
	v_and_b32_e32 v139, 0xffff0000, v182
	v_fma_f32 v134, v134, 0.5, v138
	v_fma_f32 v135, v135, 0.5, v139
	v_lshlrev_b32_e32 v138, 16, v183
	v_and_b32_e32 v139, 0xffff0000, v183
	v_fma_f32 v136, v136, 0.5, v138
	v_fma_f32 v137, v137, 0.5, v139
	v_lshlrev_b32_e32 v138, 16, v184
	v_and_b32_e32 v139, 0xffff0000, v184
	v_fma_f32 v138, v130, 0.5, v138
	v_fma_f32 v139, v131, 0.5, v139
	v_lshlrev_b32_e32 v130, 16, v185
	v_and_b32_e32 v131, 0xffff0000, v185
	v_fma_f32 v140, v132, 0.5, v130
	v_fma_f32 v141, v133, 0.5, v131
	v_cvt_pk_bf16_f32 v130, v134, v135
	v_cvt_pk_bf16_f32 v131, v136, v137
	v_cvt_pk_bf16_f32 v132, v138, v139
	s_and_b64 vcc, exec, s[6:7]
	v_cvt_pk_bf16_f32 v133, v140, v141
	v_lshl_add_u64 v[146:147], v[146:147], 2, s[8:9]
	global_store_dwordx4 v[240:241], v[130:133], off sc1
	s_nop 1
	s_cbranch_vccnz .LBB0_350
	global_store_dwordx4 v[146:147], v[134:137], off
	global_store_dwordx4 v[146:147], v[138:141], off offset:16
.LBB0_350:
	s_nop 0
	v_lshlrev_b32_e32 v134, 16, v178
	v_and_b32_e32 v135, 0xffff0000, v178
	v_fma_f32 v118, v118, 0.5, v134
	v_fma_f32 v119, v119, 0.5, v135
	v_lshlrev_b32_e32 v134, 16, v179
	v_and_b32_e32 v135, 0xffff0000, v179
	v_fma_f32 v120, v120, 0.5, v134
	v_fma_f32 v121, v121, 0.5, v135
	v_lshlrev_b32_e32 v134, 16, v180
	v_and_b32_e32 v135, 0xffff0000, v180
	v_fma_f32 v134, v114, 0.5, v134
	v_fma_f32 v135, v115, 0.5, v135
	v_lshlrev_b32_e32 v114, 16, v181
	v_and_b32_e32 v115, 0xffff0000, v181
	v_fma_f32 v136, v116, 0.5, v114
	v_fma_f32 v137, v117, 0.5, v115
	v_cvt_pk_bf16_f32 v114, v118, v119
	v_cvt_pk_bf16_f32 v115, v120, v121
	v_cvt_pk_bf16_f32 v116, v134, v135
	v_lshl_add_u64 v[138:139], v[240:241], 0, s[66:67]
	v_cvt_pk_bf16_f32 v117, v136, v137
	s_and_b64 vcc, exec, s[6:7]
	global_store_dwordx4 v[138:139], v[114:117], off sc1
	s_nop 1
	s_cbranch_vccnz .LBB0_352
	global_store_dwordx4 v[146:147], v[118:121], off offset:512
	global_store_dwordx4 v[146:147], v[134:137], off offset:528

.LBB0_354:
	s_or_b64 exec, exec, s[28:29]
	s_waitcnt lgkmcnt(0)
	v_lshlrev_b64 v[114:115], 10, v[234:235]
	v_lshl_add_u64 v[118:119], v[114:115], 0, v[216:217]
	v_lshlrev_b32_e32 v114, 16, v174
	v_and_b32_e32 v115, 0xffff0000, v174
	v_fma_f32 v110, v110, 0.5, v114
	v_fma_f32 v111, v111, 0.5, v115
	v_lshlrev_b32_e32 v114, 16, v175
	v_and_b32_e32 v115, 0xffff0000, v175
	v_fma_f32 v112, v112, 0.5, v114
	v_fma_f32 v113, v113, 0.5, v115
	v_lshlrev_b32_e32 v114, 16, v176
	v_and_b32_e32 v115, 0xffff0000, v176
	v_fma_f32 v114, v102, 0.5, v114
	v_fma_f32 v115, v103, 0.5, v115
	v_lshlrev_b32_e32 v102, 16, v177
	v_and_b32_e32 v103, 0xffff0000, v177
	v_fma_f32 v116, v104, 0.5, v102
	v_fma_f32 v117, v105, 0.5, v103
	v_cvt_pk_bf16_f32 v102, v110, v111
	v_cvt_pk_bf16_f32 v103, v112, v113
	v_cvt_pk_bf16_f32 v104, v114, v115
	s_and_b64 vcc, exec, s[6:7]
	v_cvt_pk_bf16_f32 v105, v116, v117
	v_lshl_add_u64 v[118:119], v[118:119], 2, s[8:9]
	global_store_dwordx4 v[236:237], v[102:105], off sc1
	s_nop 1
	s_cbranch_vccnz .LBB0_356
	global_store_dwordx4 v[118:119], v[110:113], off
	global_store_dwordx4 v[118:119], v[114:117], off offset:16
.LBB0_356:
	s_nop 0
	v_lshlrev_b32_e32 v110, 16, v170
	v_and_b32_e32 v111, 0xffff0000, v170
	v_fma_f32 v92, v92, 0.5, v110
	v_fma_f32 v93, v93, 0.5, v111
	v_lshlrev_b32_e32 v110, 16, v171
	v_and_b32_e32 v111, 0xffff0000, v171
	v_fma_f32 v94, v94, 0.5, v110
	v_fma_f32 v95, v95, 0.5, v111
	v_lshlrev_b32_e32 v110, 16, v172
	v_and_b32_e32 v111, 0xffff0000, v172
	v_fma_f32 v110, v88, 0.5, v110
	v_fma_f32 v111, v89, 0.5, v111
	v_lshlrev_b32_e32 v88, 16, v173
	v_and_b32_e32 v89, 0xffff0000, v173
	v_fma_f32 v112, v90, 0.5, v88
	v_fma_f32 v113, v91, 0.5, v89
	v_cvt_pk_bf16_f32 v88, v92, v93
	v_cvt_pk_bf16_f32 v89, v94, v95
	v_cvt_pk_bf16_f32 v90, v110, v111
	v_lshl_add_u64 v[114:115], v[236:237], 0, s[66:67]
	v_cvt_pk_bf16_f32 v91, v112, v113
	s_and_b64 vcc, exec, s[6:7]
	global_store_dwordx4 v[114:115], v[88:91], off sc1
	s_nop 1
	s_cbranch_vccnz .LBB0_358
	global_store_dwordx4 v[118:119], v[92:95], off offset:512
	global_store_dwordx4 v[118:119], v[110:113], off offset:528

.LBB0_360:
	s_or_b64 exec, exec, s[28:29]
	s_waitcnt lgkmcnt(0)
	v_lshlrev_b64 v[88:89], 10, v[230:231]
	v_lshl_add_u64 v[92:93], v[88:89], 0, v[216:217]
	v_lshlrev_b32_e32 v88, 16, v166
	v_and_b32_e32 v89, 0xffff0000, v166
	v_fma_f32 v80, v80, 0.5, v88
	v_fma_f32 v81, v81, 0.5, v89
	v_lshlrev_b32_e32 v88, 16, v167
	v_and_b32_e32 v89, 0xffff0000, v167
	v_fma_f32 v82, v82, 0.5, v88
	v_fma_f32 v83, v83, 0.5, v89
	v_lshlrev_b32_e32 v88, 16, v168
	v_and_b32_e32 v89, 0xffff0000, v168
	v_fma_f32 v88, v76, 0.5, v88
	v_fma_f32 v89, v77, 0.5, v89
	v_lshlrev_b32_e32 v76, 16, v169
	v_and_b32_e32 v77, 0xffff0000, v169
	v_fma_f32 v90, v78, 0.5, v76
	v_fma_f32 v91, v79, 0.5, v77
	v_cvt_pk_bf16_f32 v76, v80, v81
	v_cvt_pk_bf16_f32 v77, v82, v83
	v_cvt_pk_bf16_f32 v78, v88, v89
	s_and_b64 vcc, exec, s[6:7]
	v_cvt_pk_bf16_f32 v79, v90, v91
	v_lshl_add_u64 v[92:93], v[92:93], 2, s[8:9]
	global_store_dwordx4 v[232:233], v[76:79], off sc1
	s_nop 1
	s_cbranch_vccnz .LBB0_362
	global_store_dwordx4 v[92:93], v[80:83], off
	global_store_dwordx4 v[92:93], v[88:91], off offset:16
.LBB0_362:
	s_nop 0
	v_lshlrev_b32_e32 v80, 16, v162
	v_and_b32_e32 v81, 0xffff0000, v162
	v_fma_f32 v68, v68, 0.5, v80
	v_fma_f32 v69, v69, 0.5, v81
	v_lshlrev_b32_e32 v80, 16, v163
	v_and_b32_e32 v81, 0xffff0000, v163
	v_fma_f32 v70, v70, 0.5, v80
	v_fma_f32 v71, v71, 0.5, v81
	v_lshlrev_b32_e32 v80, 16, v164
	v_and_b32_e32 v81, 0xffff0000, v164
	v_fma_f32 v80, v64, 0.5, v80
	v_fma_f32 v81, v65, 0.5, v81
	v_lshlrev_b32_e32 v64, 16, v165
	v_and_b32_e32 v65, 0xffff0000, v165
	v_fma_f32 v82, v66, 0.5, v64
	v_fma_f32 v83, v67, 0.5, v65
	v_cvt_pk_bf16_f32 v64, v68, v69
	v_cvt_pk_bf16_f32 v65, v70, v71
	v_cvt_pk_bf16_f32 v66, v80, v81
	v_lshl_add_u64 v[88:89], v[232:233], 0, s[66:67]
	v_cvt_pk_bf16_f32 v67, v82, v83
	s_and_b64 vcc, exec, s[6:7]
	global_store_dwordx4 v[88:89], v[64:67], off sc1
	s_nop 1
	s_cbranch_vccnz .LBB0_364
	global_store_dwordx4 v[92:93], v[68:71], off offset:512
	global_store_dwordx4 v[92:93], v[80:83], off offset:528

.LBB0_366:
	s_or_b64 exec, exec, s[28:29]
	s_waitcnt lgkmcnt(0)
	v_lshlrev_b64 v[64:65], 10, v[226:227]
	v_lshl_add_u64 v[68:69], v[64:65], 0, v[216:217]
	v_lshlrev_b32_e32 v64, 16, v150
	v_and_b32_e32 v65, 0xffff0000, v150
	v_fma_f32 v60, v60, 0.5, v64
	v_fma_f32 v61, v61, 0.5, v65
	v_lshlrev_b32_e32 v64, 16, v151
	v_and_b32_e32 v65, 0xffff0000, v151
	v_fma_f32 v62, v62, 0.5, v64
	v_fma_f32 v63, v63, 0.5, v65
	v_lshlrev_b32_e32 v64, 16, v152
	v_and_b32_e32 v65, 0xffff0000, v152
	v_fma_f32 v64, v56, 0.5, v64
	v_fma_f32 v65, v57, 0.5, v65
	v_lshlrev_b32_e32 v56, 16, v153
	v_and_b32_e32 v57, 0xffff0000, v153
	v_fma_f32 v66, v58, 0.5, v56
	v_fma_f32 v67, v59, 0.5, v57
	v_cvt_pk_bf16_f32 v56, v60, v61
	v_cvt_pk_bf16_f32 v57, v62, v63
	v_cvt_pk_bf16_f32 v58, v64, v65
	s_and_b64 vcc, exec, s[6:7]
	v_cvt_pk_bf16_f32 v59, v66, v67
	v_lshl_add_u64 v[68:69], v[68:69], 2, s[8:9]
	global_store_dwordx4 v[228:229], v[56:59], off sc1
	s_nop 1
	s_cbranch_vccnz .LBB0_368
	global_store_dwordx4 v[68:69], v[60:63], off
	global_store_dwordx4 v[68:69], v[64:67], off offset:16
.LBB0_368:
	s_nop 0
	v_lshlrev_b32_e32 v60, 16, v142
	v_and_b32_e32 v61, 0xffff0000, v142
	v_fma_f32 v52, v52, 0.5, v60
	v_fma_f32 v53, v53, 0.5, v61
	v_lshlrev_b32_e32 v60, 16, v143
	v_and_b32_e32 v61, 0xffff0000, v143
	v_fma_f32 v54, v54, 0.5, v60
	v_fma_f32 v55, v55, 0.5, v61
	v_lshlrev_b32_e32 v60, 16, v144
	v_and_b32_e32 v61, 0xffff0000, v144
	v_fma_f32 v60, v48, 0.5, v60
	v_fma_f32 v61, v49, 0.5, v61
	v_lshlrev_b32_e32 v48, 16, v145
	v_and_b32_e32 v49, 0xffff0000, v145
	v_fma_f32 v62, v50, 0.5, v48
	v_fma_f32 v63, v51, 0.5, v49
	v_cvt_pk_bf16_f32 v48, v52, v53
	v_cvt_pk_bf16_f32 v49, v54, v55
	v_cvt_pk_bf16_f32 v50, v60, v61
	v_lshl_add_u64 v[64:65], v[228:229], 0, s[66:67]
	v_cvt_pk_bf16_f32 v51, v62, v63
	s_and_b64 vcc, exec, s[6:7]
	global_store_dwordx4 v[64:65], v[48:51], off sc1
	s_nop 1
	s_cbranch_vccnz .LBB0_370
	global_store_dwordx4 v[68:69], v[52:55], off offset:512
	global_store_dwordx4 v[68:69], v[60:63], off offset:528

.LBB0_372:
	s_or_b64 exec, exec, s[28:29]
	s_waitcnt lgkmcnt(0)
	v_lshlrev_b64 v[48:49], 10, v[222:223]
	v_lshl_add_u64 v[52:53], v[48:49], 0, v[216:217]
	v_lshlrev_b32_e32 v48, 16, v126
	v_and_b32_e32 v49, 0xffff0000, v126
	v_fma_f32 v44, v44, 0.5, v48
	v_fma_f32 v45, v45, 0.5, v49
	v_lshlrev_b32_e32 v48, 16, v127
	v_and_b32_e32 v49, 0xffff0000, v127
	v_fma_f32 v46, v46, 0.5, v48
	v_fma_f32 v47, v47, 0.5, v49
	v_lshlrev_b32_e32 v48, 16, v128
	v_and_b32_e32 v49, 0xffff0000, v128
	v_fma_f32 v48, v40, 0.5, v48
	v_fma_f32 v49, v41, 0.5, v49
	v_lshlrev_b32_e32 v40, 16, v129
	v_and_b32_e32 v41, 0xffff0000, v129
	v_fma_f32 v50, v42, 0.5, v40
	v_fma_f32 v51, v43, 0.5, v41
	v_cvt_pk_bf16_f32 v40, v44, v45
	v_cvt_pk_bf16_f32 v41, v46, v47
	v_cvt_pk_bf16_f32 v42, v48, v49
	s_and_b64 vcc, exec, s[6:7]
	v_cvt_pk_bf16_f32 v43, v50, v51
	v_lshl_add_u64 v[52:53], v[52:53], 2, s[8:9]
	global_store_dwordx4 v[224:225], v[40:43], off sc1
	s_nop 1
	s_cbranch_vccnz .LBB0_374
	global_store_dwordx4 v[52:53], v[44:47], off
	global_store_dwordx4 v[52:53], v[48:51], off offset:16
.LBB0_374:
	s_nop 0
	v_lshlrev_b32_e32 v44, 16, v122
	v_and_b32_e32 v45, 0xffff0000, v122
	v_fma_f32 v36, v36, 0.5, v44
	v_fma_f32 v37, v37, 0.5, v45
	v_lshlrev_b32_e32 v44, 16, v123
	v_and_b32_e32 v45, 0xffff0000, v123
	v_fma_f32 v38, v38, 0.5, v44
	v_fma_f32 v39, v39, 0.5, v45
	v_lshlrev_b32_e32 v44, 16, v124
	v_and_b32_e32 v45, 0xffff0000, v124
	v_fma_f32 v44, v32, 0.5, v44
	v_fma_f32 v45, v33, 0.5, v45
	v_lshlrev_b32_e32 v32, 16, v125
	v_and_b32_e32 v33, 0xffff0000, v125
	v_fma_f32 v46, v34, 0.5, v32
	v_fma_f32 v47, v35, 0.5, v33
	v_cvt_pk_bf16_f32 v32, v36, v37
	v_cvt_pk_bf16_f32 v33, v38, v39
	v_cvt_pk_bf16_f32 v34, v44, v45
	v_lshl_add_u64 v[48:49], v[224:225], 0, s[66:67]
	v_cvt_pk_bf16_f32 v35, v46, v47
	s_and_b64 vcc, exec, s[6:7]
	global_store_dwordx4 v[48:49], v[32:35], off sc1
	s_nop 1
	s_cbranch_vccnz .LBB0_376
	global_store_dwordx4 v[52:53], v[36:39], off offset:512
	global_store_dwordx4 v[52:53], v[44:47], off offset:528

.LBB0_378:
	s_or_b64 exec, exec, s[28:29]
	s_waitcnt lgkmcnt(0)
	v_lshlrev_b64 v[32:33], 10, v[218:219]
	v_lshl_add_u64 v[36:37], v[32:33], 0, v[216:217]
	v_lshlrev_b32_e32 v32, 16, v106
	v_and_b32_e32 v33, 0xffff0000, v106
	v_fma_f32 v28, v28, 0.5, v32
	v_fma_f32 v29, v29, 0.5, v33
	v_lshlrev_b32_e32 v32, 16, v107
	v_and_b32_e32 v33, 0xffff0000, v107
	v_fma_f32 v30, v30, 0.5, v32
	v_fma_f32 v31, v31, 0.5, v33
	v_lshlrev_b32_e32 v32, 16, v108
	v_and_b32_e32 v33, 0xffff0000, v108
	v_fma_f32 v32, v24, 0.5, v32
	v_fma_f32 v33, v25, 0.5, v33
	v_lshlrev_b32_e32 v24, 16, v109
	v_and_b32_e32 v25, 0xffff0000, v109
	v_fma_f32 v34, v26, 0.5, v24
	v_fma_f32 v35, v27, 0.5, v25
	v_cvt_pk_bf16_f32 v24, v28, v29
	v_cvt_pk_bf16_f32 v25, v30, v31
	v_cvt_pk_bf16_f32 v26, v32, v33
	s_and_b64 vcc, exec, s[6:7]
	v_cvt_pk_bf16_f32 v27, v34, v35
	v_lshl_add_u64 v[36:37], v[36:37], 2, s[8:9]
	global_store_dwordx4 v[220:221], v[24:27], off sc1
	s_nop 1
	s_cbranch_vccnz .LBB0_380
	global_store_dwordx4 v[36:37], v[28:31], off
	global_store_dwordx4 v[36:37], v[32:35], off offset:16
.LBB0_380:
	s_nop 0
	v_lshlrev_b32_e32 v28, 16, v98
	v_and_b32_e32 v29, 0xffff0000, v98
	v_fma_f32 v20, v20, 0.5, v28
	v_fma_f32 v21, v21, 0.5, v29
	v_lshlrev_b32_e32 v28, 16, v99
	v_and_b32_e32 v29, 0xffff0000, v99
	v_fma_f32 v22, v22, 0.5, v28
	v_fma_f32 v23, v23, 0.5, v29
	v_lshlrev_b32_e32 v28, 16, v100
	v_and_b32_e32 v29, 0xffff0000, v100
	v_fma_f32 v28, v16, 0.5, v28
	v_fma_f32 v29, v17, 0.5, v29
	v_lshlrev_b32_e32 v16, 16, v101
	v_and_b32_e32 v17, 0xffff0000, v101
	v_fma_f32 v30, v18, 0.5, v16
	v_fma_f32 v31, v19, 0.5, v17
	v_cvt_pk_bf16_f32 v16, v20, v21
	v_cvt_pk_bf16_f32 v17, v22, v23
	v_cvt_pk_bf16_f32 v18, v28, v29
	v_lshl_add_u64 v[32:33], v[220:221], 0, s[66:67]
	v_cvt_pk_bf16_f32 v19, v30, v31
	s_and_b64 vcc, exec, s[6:7]
	global_store_dwordx4 v[32:33], v[16:19], off sc1
	s_nop 1
	s_cbranch_vccnz .LBB0_382
	global_store_dwordx4 v[36:37], v[20:23], off offset:512
	global_store_dwordx4 v[36:37], v[28:31], off offset:528

.LBB0_384:
	s_or_b64 exec, exec, s[28:29]
	s_waitcnt lgkmcnt(0)
	v_lshlrev_b64 v[16:17], 10, v[212:213]
	v_lshl_add_u64 v[20:21], v[16:17], 0, v[216:217]
	v_lshlrev_b32_e32 v16, 16, v84
	v_and_b32_e32 v17, 0xffff0000, v84
	v_fma_f32 v12, v12, 0.5, v16
	v_fma_f32 v13, v13, 0.5, v17
	v_lshlrev_b32_e32 v16, 16, v85
	v_and_b32_e32 v17, 0xffff0000, v85
	v_fma_f32 v14, v14, 0.5, v16
	v_fma_f32 v15, v15, 0.5, v17
	v_lshlrev_b32_e32 v16, 16, v86
	v_and_b32_e32 v17, 0xffff0000, v86
	v_fma_f32 v16, v8, 0.5, v16
	v_fma_f32 v17, v9, 0.5, v17
	v_lshlrev_b32_e32 v8, 16, v87
	v_and_b32_e32 v9, 0xffff0000, v87
	v_fma_f32 v18, v10, 0.5, v8
	v_fma_f32 v19, v11, 0.5, v9
	v_cvt_pk_bf16_f32 v8, v12, v13
	v_cvt_pk_bf16_f32 v9, v14, v15
	v_cvt_pk_bf16_f32 v10, v16, v17
	s_and_b64 vcc, exec, s[6:7]
	v_cvt_pk_bf16_f32 v11, v18, v19
	v_lshl_add_u64 v[20:21], v[20:21], 2, s[8:9]
	global_store_dwordx4 v[214:215], v[8:11], off sc1
	s_nop 1
	s_cbranch_vccnz .LBB0_386
	global_store_dwordx4 v[20:21], v[12:15], off
	global_store_dwordx4 v[20:21], v[16:19], off offset:16
.LBB0_386:
	s_nop 0
	v_lshlrev_b32_e32 v12, 16, v72
	v_and_b32_e32 v13, 0xffff0000, v72
	v_fma_f32 v4, v4, 0.5, v12
	v_fma_f32 v5, v5, 0.5, v13
	v_lshlrev_b32_e32 v12, 16, v73
	v_and_b32_e32 v13, 0xffff0000, v73
	v_fma_f32 v6, v6, 0.5, v12
	v_fma_f32 v7, v7, 0.5, v13
	v_lshlrev_b32_e32 v12, 16, v74
	v_and_b32_e32 v13, 0xffff0000, v74
	v_fma_f32 v12, v0, 0.5, v12
	v_fma_f32 v13, v1, 0.5, v13
	v_lshlrev_b32_e32 v0, 16, v75
	v_and_b32_e32 v1, 0xffff0000, v75
	v_fma_f32 v14, v2, 0.5, v0
	v_fma_f32 v15, v3, 0.5, v1
	v_cvt_pk_bf16_f32 v0, v4, v5
	v_cvt_pk_bf16_f32 v1, v6, v7
	v_cvt_pk_bf16_f32 v2, v12, v13
	v_lshl_add_u64 v[16:17], v[214:215], 0, s[66:67]
	v_cvt_pk_bf16_f32 v3, v14, v15
	s_and_b64 vcc, exec, s[6:7]
	global_store_dwordx4 v[16:17], v[0:3], off sc1
	s_nop 1
	s_cbranch_vccnz .LBB0_388
	global_store_dwordx4 v[20:21], v[4:7], off offset:512
	global_store_dwordx4 v[20:21], v[12:15], off offset:528

.LBB0_464:
	s_bitcmp1_b32 s5, 0
	s_cselect_b64 s[28:29], -1, 0
	s_and_b64 vcc, exec, s[28:29]
	s_cbranch_vccnz .LBB0_466
	s_and_b64 s[28:29], s[16:17], exec
	s_cselect_b32 s19, s26, s27
	v_lshl_or_b32 v144, s19, 8, v149
	v_ashrrev_i32_e32 v145, 31, v144
	v_lshlrev_b64 v[144:145], 6, v[144:145]
	v_lshl_add_u64 v[162:163], s[6:7], 0, v[144:145]
	global_load_dwordx4 v[144:147], v[162:163], off offset:48
	global_load_dwordx4 v[154:157], v[162:163], off offset:32
	global_load_dwordx4 v[158:161], v[162:163], off offset:16
	s_nop 0
	global_load_dwordx4 v[162:165], v[162:163], off
	s_waitcnt vmcnt(0)
	v_add_f32_e32 v154, v154, v155
	v_add_f32_e32 v156, v156, v157
	v_mov_b32_e32 v166, v163
	v_mov_b32_e32 v167, v164
	v_mov_b32_e32 v163, v165
	v_mov_b32_e32 v164, v159
	v_mov_b32_e32 v165, v160
	v_mov_b32_e32 v159, v161
	v_add_f32_e64 v162, v166, v162
	v_add_f32_e64 v163, v167, v163
	v_add_f32_e64 v158, v164, v158
	v_add_f32_e64 v159, v165, v159
	v_add_f32_e64 v162, v162, v163
	v_mov_b32_e32 v163, v162
	v_add_f32_e64 v158, v158, v159
	v_mov_b32_e32 v159, v158
	v_mov_b32_e32 v163, v144
	v_mov_b32_e32 v159, v145
	v_mov_b32_e32 v155, v146
	v_mov_b32_e32 v157, v147
	v_add_f32_e64 v144, v162, v158
	v_add_f32_e64 v145, v163, v159
	v_add_f32_e64 v146, v154, v156
	v_add_f32_e64 v147, v155, v157
	s_nop 0
	v_add_f32_e64 v144, v144, v146
	v_add_f32_e64 v145, v145, v147
	s_nop 0
	v_add_f32_e32 v96, v144, v145
	v_fmamk_f32 v96, v96, 0x3a800000, v249
	v_rsq_f32_e32 v96, v96
	ds_write_b32 v151, v96
	s_waitcnt lgkmcnt(0)
	s_barrier
.LBB0_466:
	s_and_b32 s5, s5, 1
	s_lshl_b32 s5, s5, 10
	v_add_u32_e32 v153, s5, v150
	ds_read_b32 v146, v153
	s_cmp_gt_i32 s4, 7
	s_cselect_b64 s[30:31], -1, 0
	s_lshl_b32 s5, s4, 8
	v_lshl_add_u32 v144, s26, 8, v139
	s_add_i32 s26, s5, 0xfffff800
	s_ashr_i32 s27, s26, 31
	s_waitcnt lgkmcnt(0)
	v_mov_b32_e32 v147, v146
	s_cmp_lt_i32 s4, 8
	v_mul_f32_e64 v128, v128, v146
	v_mul_f32_e64 v129, v129, v146
	v_mul_f32_e64 v126, v126, v146
	v_mul_f32_e64 v127, v127, v146
	s_mov_b64 s[34:35], -1
	v_ashrrev_i32_e32 v145, 31, v144
	v_mul_f32_e64 v122, v122, v146
	v_mul_f32_e64 v123, v123, v147
	v_lshlrev_b32_e32 v96, 1, v138
	v_mul_f32_e64 v118, v118, v146
	v_mul_f32_e64 v119, v119, v147
	v_mul_f32_e64 v114, v114, v146
	v_mul_f32_e64 v115, v115, v147
	s_cbranch_scc1 .LBB0_468
	v_lshlrev_b64 v[158:159], 11, v[144:145]
	v_mov_b32_e32 v147, v146
	v_lshl_add_u64 v[158:159], s[12:13], 0, v[158:159]
	v_mul_f32_e64 v156, v124, v146
	v_mul_f32_e64 v157, v125, v147
	v_lshl_add_u64 v[158:159], s[26:27], 1, v[158:159]
	s_lshl_b32 s60, s47, 1
	v_cvt_pk_bf16_f32 v154, v122, v123
	v_cvt_pk_bf16_f32 v155, v156, v157
	v_cvt_pk_bf16_f32 v156, v126, v127
	v_cvt_pk_bf16_f32 v157, v128, v129
	v_lshl_add_u64 v[158:159], v[158:159], 0, s[60:61]
	v_lshl_add_u64 v[158:159], v[158:159], 0, v[96:97]
	global_store_dwordx4 v[158:159], v[154:157], off sc1
	s_nop 1
	v_mul_f32_e64 v156, v120, v146
	v_mul_f32_e64 v157, v121, v147
	v_mul_f32_e64 v160, v116, v146
	v_mul_f32_e64 v161, v117, v147
	v_cvt_pk_bf16_f32 v154, v118, v119
	v_cvt_pk_bf16_f32 v155, v156, v157
	v_cvt_pk_bf16_f32 v156, v114, v115
	v_lshl_add_u64 v[158:159], v[158:159], 0, s[66:67]
	v_cvt_pk_bf16_f32 v157, v160, v161
	s_mov_b64 s[34:35], 0
	global_store_dwordx4 v[158:159], v[154:157], off sc1
	s_nop 1
.LBB0_468:
	s_lshl_b32 s28, s4, 7
	s_andn2_b64 vcc, exec, s[34:35]
	s_ashr_i32 s29, s28, 31
	s_cbranch_vccnz .LBB0_470
	v_mov_b32_e32 v147, v146
	v_mul_f32_e64 v118, v122, v118
	v_mul_f32_e64 v119, v123, v119
	v_mul_f32_e64 v116, v116, v146
	v_mul_f32_e64 v117, v117, v147
	s_lshl_b32 s60, s47, 1
	v_mul_f32_e64 v122, v128, v116
	v_mul_f32_e64 v123, v129, v117
	v_mul_f32_e64 v116, v126, v114
	v_mul_f32_e64 v117, v127, v115
	v_cvt_pk_bf16_f32 v114, v118, v119
	v_lshlrev_b64 v[118:119], 11, v[144:145]
	v_lshl_add_u64 v[118:119], s[10:11], 0, v[118:119]
	v_lshl_add_u64 v[118:119], s[28:29], 1, v[118:119]
	v_mul_f32_e64 v124, v124, v146
	v_mul_f32_e64 v125, v125, v147
	v_mul_f32_e64 v120, v120, v146
	v_mul_f32_e64 v121, v121, v147
	v_lshl_add_u64 v[118:119], v[118:119], 0, s[60:61]
	v_mul_f32_e64 v120, v124, v120
	v_mul_f32_e64 v121, v125, v121
	v_lshl_add_u64 v[118:119], v[118:119], 0, v[96:97]
	v_cvt_pk_bf16_f32 v115, v120, v121
	v_cvt_pk_bf16_f32 v116, v116, v117
	v_cvt_pk_bf16_f32 v117, v122, v123
	s_nop 0
	global_store_dwordx4 v[118:119], v[114:117], off sc1
	s_nop 1
.LBB0_470:
	ds_read_b32 v116, v153 offset:64
	v_or_b32_e32 v114, 16, v144
	v_cndmask_b32_e64 v115, 0, 1, s[30:31]
	s_mov_b64 s[34:35], -1
	v_cmp_ne_u32_e64 s[4:5], 1, v115
	s_waitcnt lgkmcnt(0)
	v_mov_b32_e32 v117, v116
	v_mul_f32_e64 v112, v112, v116
	v_mul_f32_e64 v113, v113, v116
	v_mul_f32_e64 v110, v110, v116
	v_mul_f32_e64 v111, v111, v116
	s_andn2_b64 vcc, exec, s[30:31]
	v_ashrrev_i32_e32 v115, 31, v114
	v_mul_f32_e64 v106, v106, v116
	v_mul_f32_e64 v107, v107, v117
	v_mul_f32_e64 v102, v102, v116
	v_mul_f32_e64 v103, v103, v117
	v_mul_f32_e64 v98, v98, v116
	v_mul_f32_e64 v99, v99, v117
	s_cbranch_vccnz .LBB0_472
	v_lshlrev_b64 v[122:123], 11, v[114:115]
	v_mov_b32_e32 v117, v116
	v_lshl_add_u64 v[122:123], s[12:13], 0, v[122:123]
	v_mul_f32_e64 v120, v108, v116
	v_mul_f32_e64 v121, v109, v117
	v_lshl_add_u64 v[122:123], s[26:27], 1, v[122:123]
	s_lshl_b32 s60, s47, 1
	v_cvt_pk_bf16_f32 v118, v106, v107
	v_cvt_pk_bf16_f32 v119, v120, v121
	v_cvt_pk_bf16_f32 v120, v110, v111
	v_cvt_pk_bf16_f32 v121, v112, v113
	v_lshl_add_u64 v[122:123], v[122:123], 0, s[60:61]
	v_lshl_add_u64 v[122:123], v[122:123], 0, v[96:97]
	global_store_dwordx4 v[122:123], v[118:121], off sc1
	s_nop 1
	v_mul_f32_e64 v120, v104, v116
	v_mul_f32_e64 v121, v105, v117
	v_mul_f32_e64 v124, v100, v116
	v_mul_f32_e64 v125, v101, v117
	v_cvt_pk_bf16_f32 v118, v102, v103
	v_cvt_pk_bf16_f32 v119, v120, v121
	v_cvt_pk_bf16_f32 v120, v98, v99
	v_lshl_add_u64 v[122:123], v[122:123], 0, s[66:67]
	v_cvt_pk_bf16_f32 v121, v124, v125
	s_mov_b64 s[34:35], 0
	global_store_dwordx4 v[122:123], v[118:121], off sc1
	s_nop 1
.LBB0_472:
	s_andn2_b64 vcc, exec, s[34:35]
	s_cbranch_vccnz .LBB0_474
	v_mov_b32_e32 v117, v116
	v_mul_f32_e64 v102, v106, v102
	v_mul_f32_e64 v103, v107, v103
	v_mul_f32_e64 v100, v100, v116
	v_mul_f32_e64 v101, v101, v117
	s_lshl_b32 s60, s47, 1
	v_mul_f32_e64 v106, v112, v100
	v_mul_f32_e64 v107, v113, v101
	v_mul_f32_e64 v100, v110, v98
	v_mul_f32_e64 v101, v111, v99
	v_cvt_pk_bf16_f32 v98, v102, v103
	v_lshlrev_b64 v[102:103], 11, v[114:115]
	v_lshl_add_u64 v[102:103], s[10:11], 0, v[102:103]
	v_lshl_add_u64 v[102:103], s[28:29], 1, v[102:103]
	v_mul_f32_e64 v108, v108, v116
	v_mul_f32_e64 v109, v109, v117
	v_mul_f32_e64 v104, v104, v116
	v_mul_f32_e64 v105, v105, v117
	v_lshl_add_u64 v[102:103], v[102:103], 0, s[60:61]
	v_mul_f32_e64 v104, v108, v104
	v_mul_f32_e64 v105, v109, v105
	v_lshl_add_u64 v[102:103], v[102:103], 0, v[96:97]
	v_cvt_pk_bf16_f32 v99, v104, v105
	v_cvt_pk_bf16_f32 v100, v100, v101
	v_cvt_pk_bf16_f32 v101, v106, v107
	s_nop 0
	global_store_dwordx4 v[102:103], v[98:101], off sc1
	s_nop 1
.LBB0_474:
	ds_read_b32 v100, v153 offset:128
	v_or_b32_e32 v98, 32, v144
	s_mov_b64 s[30:31], -1
	s_and_b64 vcc, exec, s[4:5]
	v_ashrrev_i32_e32 v99, 31, v98
	s_waitcnt lgkmcnt(0)
	v_mov_b32_e32 v101, v100
	v_mul_f32_e64 v94, v94, v100
	v_mul_f32_e64 v95, v95, v100
	v_mul_f32_e64 v92, v92, v100
	v_mul_f32_e64 v93, v93, v100
	v_mul_f32_e64 v88, v88, v100
	v_mul_f32_e64 v89, v89, v101
	v_mul_f32_e64 v84, v84, v100
	v_mul_f32_e64 v85, v85, v101
	v_mul_f32_e64 v80, v80, v100
	v_mul_f32_e64 v81, v81, v101
	s_cbranch_vccnz .LBB0_476
	v_lshlrev_b64 v[106:107], 11, v[98:99]
	v_mov_b32_e32 v101, v100
	v_lshl_add_u64 v[106:107], s[12:13], 0, v[106:107]
	v_mul_f32_e64 v104, v90, v100
	v_mul_f32_e64 v105, v91, v101
	v_lshl_add_u64 v[106:107], s[26:27], 1, v[106:107]
	s_lshl_b32 s60, s47, 1
	v_cvt_pk_bf16_f32 v102, v88, v89
	v_cvt_pk_bf16_f32 v103, v104, v105
	v_cvt_pk_bf16_f32 v104, v92, v93
	v_cvt_pk_bf16_f32 v105, v94, v95
	v_lshl_add_u64 v[106:107], v[106:107], 0, s[60:61]
	v_lshl_add_u64 v[106:107], v[106:107], 0, v[96:97]
	global_store_dwordx4 v[106:107], v[102:105], off sc1
	s_nop 1
	v_mul_f32_e64 v104, v86, v100
	v_mul_f32_e64 v105, v87, v101
	v_mul_f32_e64 v108, v82, v100
	v_mul_f32_e64 v109, v83, v101
	v_cvt_pk_bf16_f32 v102, v84, v85
	v_cvt_pk_bf16_f32 v103, v104, v105
	v_cvt_pk_bf16_f32 v104, v80, v81
	v_lshl_add_u64 v[106:107], v[106:107], 0, s[66:67]
	v_cvt_pk_bf16_f32 v105, v108, v109
	s_mov_b64 s[30:31], 0
	global_store_dwordx4 v[106:107], v[102:105], off sc1
	s_nop 1
.LBB0_476:
	s_andn2_b64 vcc, exec, s[30:31]
	s_cbranch_vccnz .LBB0_478
	v_mov_b32_e32 v101, v100
	v_mul_f32_e64 v84, v88, v84
	v_mul_f32_e64 v85, v89, v85
	v_mul_f32_e64 v82, v82, v100
	v_mul_f32_e64 v83, v83, v101
	s_lshl_b32 s60, s47, 1
	v_mul_f32_e64 v88, v94, v82
	v_mul_f32_e64 v89, v95, v83
	v_mul_f32_e64 v82, v92, v80
	v_mul_f32_e64 v83, v93, v81
	v_cvt_pk_bf16_f32 v80, v84, v85
	v_lshlrev_b64 v[84:85], 11, v[98:99]
	v_lshl_add_u64 v[84:85], s[10:11], 0, v[84:85]
	v_lshl_add_u64 v[84:85], s[28:29], 1, v[84:85]
	v_mul_f32_e64 v90, v90, v100
	v_mul_f32_e64 v91, v91, v101
	v_mul_f32_e64 v86, v86, v100
	v_mul_f32_e64 v87, v87, v101
	v_lshl_add_u64 v[84:85], v[84:85], 0, s[60:61]
	v_mul_f32_e64 v86, v90, v86
	v_mul_f32_e64 v87, v91, v87
	v_lshl_add_u64 v[84:85], v[84:85], 0, v[96:97]
	v_cvt_pk_bf16_f32 v81, v86, v87
	v_cvt_pk_bf16_f32 v82, v82, v83
	v_cvt_pk_bf16_f32 v83, v88, v89
	s_nop 0
	global_store_dwordx4 v[84:85], v[80:83], off sc1
	s_nop 1
.LBB0_478:
	ds_read_b32 v82, v153 offset:192
	v_or_b32_e32 v80, 48, v144
	s_mov_b64 s[30:31], -1
	s_and_b64 vcc, exec, s[4:5]
	v_ashrrev_i32_e32 v81, 31, v80
	s_waitcnt lgkmcnt(0)
	v_mov_b32_e32 v83, v82
	v_mul_f32_e64 v78, v78, v82
	v_mul_f32_e64 v79, v79, v82
	v_mul_f32_e64 v76, v76, v82
	v_mul_f32_e64 v77, v77, v82
	v_mul_f32_e64 v72, v72, v82
	v_mul_f32_e64 v73, v73, v83
	v_mul_f32_e64 v68, v68, v82
	v_mul_f32_e64 v69, v69, v83
	v_mul_f32_e64 v64, v64, v82
	v_mul_f32_e64 v65, v65, v83
	s_cbranch_vccnz .LBB0_480
	v_lshlrev_b64 v[88:89], 11, v[80:81]
	v_mov_b32_e32 v83, v82
	v_lshl_add_u64 v[88:89], s[12:13], 0, v[88:89]
	v_mul_f32_e64 v86, v74, v82
	v_mul_f32_e64 v87, v75, v83
	v_lshl_add_u64 v[88:89], s[26:27], 1, v[88:89]
	s_lshl_b32 s60, s47, 1
	v_cvt_pk_bf16_f32 v84, v72, v73
	v_cvt_pk_bf16_f32 v85, v86, v87
	v_cvt_pk_bf16_f32 v86, v76, v77
	v_cvt_pk_bf16_f32 v87, v78, v79
	v_lshl_add_u64 v[88:89], v[88:89], 0, s[60:61]
	v_lshl_add_u64 v[88:89], v[88:89], 0, v[96:97]
	global_store_dwordx4 v[88:89], v[84:87], off sc1
	s_nop 1
	v_mul_f32_e64 v86, v70, v82
	v_mul_f32_e64 v87, v71, v83
	v_mul_f32_e64 v90, v66, v82
	v_mul_f32_e64 v91, v67, v83
	v_cvt_pk_bf16_f32 v84, v68, v69
	v_cvt_pk_bf16_f32 v85, v86, v87
	v_cvt_pk_bf16_f32 v86, v64, v65
	v_lshl_add_u64 v[88:89], v[88:89], 0, s[66:67]
	v_cvt_pk_bf16_f32 v87, v90, v91
	s_mov_b64 s[30:31], 0
	global_store_dwordx4 v[88:89], v[84:87], off sc1
	s_nop 1
.LBB0_480:
	s_andn2_b64 vcc, exec, s[30:31]
	s_cbranch_vccnz .LBB0_482
	v_mov_b32_e32 v83, v82
	v_mul_f32_e64 v68, v72, v68
	v_mul_f32_e64 v69, v73, v69
	v_mul_f32_e64 v66, v66, v82
	v_mul_f32_e64 v67, v67, v83
	s_lshl_b32 s60, s47, 1
	v_mul_f32_e64 v72, v78, v66
	v_mul_f32_e64 v73, v79, v67
	v_mul_f32_e64 v66, v76, v64
	v_mul_f32_e64 v67, v77, v65
	v_cvt_pk_bf16_f32 v64, v68, v69
	v_lshlrev_b64 v[68:69], 11, v[80:81]
	v_lshl_add_u64 v[68:69], s[10:11], 0, v[68:69]
	v_lshl_add_u64 v[68:69], s[28:29], 1, v[68:69]
	v_mul_f32_e64 v74, v74, v82
	v_mul_f32_e64 v75, v75, v83
	v_mul_f32_e64 v70, v70, v82
	v_mul_f32_e64 v71, v71, v83
	v_lshl_add_u64 v[68:69], v[68:69], 0, s[60:61]
	v_mul_f32_e64 v70, v74, v70
	v_mul_f32_e64 v71, v75, v71
	v_lshl_add_u64 v[68:69], v[68:69], 0, v[96:97]
	v_cvt_pk_bf16_f32 v65, v70, v71
	v_cvt_pk_bf16_f32 v66, v66, v67
	v_cvt_pk_bf16_f32 v67, v72, v73
	s_nop 0
	global_store_dwordx4 v[68:69], v[64:67], off sc1
	s_nop 1
.LBB0_482:
	ds_read_b32 v66, v153 offset:512
	v_add_u32_e32 v64, 0x80, v144
	s_mov_b64 s[30:31], -1
	s_and_b64 vcc, exec, s[4:5]
	v_ashrrev_i32_e32 v65, 31, v64
	s_waitcnt lgkmcnt(0)
	v_mov_b32_e32 v67, v66
	v_mul_f32_e64 v62, v62, v66
	v_mul_f32_e64 v63, v63, v66
	v_mul_f32_e64 v60, v60, v66
	v_mul_f32_e64 v61, v61, v66
	v_mul_f32_e64 v56, v56, v66
	v_mul_f32_e64 v57, v57, v67
	v_mul_f32_e64 v52, v52, v66
	v_mul_f32_e64 v53, v53, v67
	v_mul_f32_e64 v48, v48, v66
	v_mul_f32_e64 v49, v49, v67
	s_cbranch_vccnz .LBB0_484
	v_lshlrev_b64 v[72:73], 11, v[64:65]
	v_mov_b32_e32 v67, v66
	v_lshl_add_u64 v[72:73], s[12:13], 0, v[72:73]
	v_mul_f32_e64 v70, v58, v66
	v_mul_f32_e64 v71, v59, v67
	v_lshl_add_u64 v[72:73], s[26:27], 1, v[72:73]
	s_lshl_b32 s60, s47, 1
	v_cvt_pk_bf16_f32 v68, v56, v57
	v_cvt_pk_bf16_f32 v69, v70, v71
	v_cvt_pk_bf16_f32 v70, v60, v61
	v_cvt_pk_bf16_f32 v71, v62, v63
	v_lshl_add_u64 v[72:73], v[72:73], 0, s[60:61]
	v_lshl_add_u64 v[72:73], v[72:73], 0, v[96:97]
	global_store_dwordx4 v[72:73], v[68:71], off sc1
	s_nop 1
	v_mul_f32_e64 v70, v54, v66
	v_mul_f32_e64 v71, v55, v67
	v_mul_f32_e64 v74, v50, v66
	v_mul_f32_e64 v75, v51, v67
	v_cvt_pk_bf16_f32 v68, v52, v53
	v_cvt_pk_bf16_f32 v69, v70, v71
	v_cvt_pk_bf16_f32 v70, v48, v49
	v_lshl_add_u64 v[72:73], v[72:73], 0, s[66:67]
	v_cvt_pk_bf16_f32 v71, v74, v75
	s_mov_b64 s[30:31], 0
	global_store_dwordx4 v[72:73], v[68:71], off sc1
	s_nop 1
.LBB0_484:
	s_andn2_b64 vcc, exec, s[30:31]
	s_cbranch_vccnz .LBB0_486
	v_mov_b32_e32 v67, v66
	v_mul_f32_e64 v52, v56, v52
	v_mul_f32_e64 v53, v57, v53
	v_mul_f32_e64 v50, v50, v66
	v_mul_f32_e64 v51, v51, v67
	s_lshl_b32 s60, s47, 1
	v_mul_f32_e64 v56, v62, v50
	v_mul_f32_e64 v57, v63, v51
	v_mul_f32_e64 v50, v60, v48
	v_mul_f32_e64 v51, v61, v49
	v_cvt_pk_bf16_f32 v48, v52, v53
	v_lshlrev_b64 v[52:53], 11, v[64:65]
	v_lshl_add_u64 v[52:53], s[10:11], 0, v[52:53]
	v_lshl_add_u64 v[52:53], s[28:29], 1, v[52:53]
	v_mul_f32_e64 v58, v58, v66
	v_mul_f32_e64 v59, v59, v67
	v_mul_f32_e64 v54, v54, v66
	v_mul_f32_e64 v55, v55, v67
	v_lshl_add_u64 v[52:53], v[52:53], 0, s[60:61]
	v_mul_f32_e64 v54, v58, v54
	v_mul_f32_e64 v55, v59, v55
	v_lshl_add_u64 v[52:53], v[52:53], 0, v[96:97]
	v_cvt_pk_bf16_f32 v49, v54, v55
	v_cvt_pk_bf16_f32 v50, v50, v51
	v_cvt_pk_bf16_f32 v51, v56, v57
	s_nop 0
	global_store_dwordx4 v[52:53], v[48:51], off sc1
	s_nop 1
.LBB0_486:
	ds_read_b32 v50, v153 offset:576
	v_add_u32_e32 v48, 0x90, v144
	s_mov_b64 s[30:31], -1
	s_and_b64 vcc, exec, s[4:5]
	v_ashrrev_i32_e32 v49, 31, v48
	s_waitcnt lgkmcnt(0)
	v_mov_b32_e32 v51, v50
	v_mul_f32_e64 v46, v46, v50
	v_mul_f32_e64 v47, v47, v50
	v_mul_f32_e64 v44, v44, v50
	v_mul_f32_e64 v45, v45, v50
	v_mul_f32_e64 v40, v40, v50
	v_mul_f32_e64 v41, v41, v51
	v_mul_f32_e64 v36, v36, v50
	v_mul_f32_e64 v37, v37, v51
	v_mul_f32_e64 v32, v32, v50
	v_mul_f32_e64 v33, v33, v51
	s_cbranch_vccnz .LBB0_488
	v_lshlrev_b64 v[56:57], 11, v[48:49]
	v_mov_b32_e32 v51, v50
	v_lshl_add_u64 v[56:57], s[12:13], 0, v[56:57]
	v_mul_f32_e64 v54, v42, v50
	v_mul_f32_e64 v55, v43, v51
	v_lshl_add_u64 v[56:57], s[26:27], 1, v[56:57]
	s_lshl_b32 s60, s47, 1
	v_cvt_pk_bf16_f32 v52, v40, v41
	v_cvt_pk_bf16_f32 v53, v54, v55
	v_cvt_pk_bf16_f32 v54, v44, v45
	v_cvt_pk_bf16_f32 v55, v46, v47
	v_lshl_add_u64 v[56:57], v[56:57], 0, s[60:61]
	v_lshl_add_u64 v[56:57], v[56:57], 0, v[96:97]
	global_store_dwordx4 v[56:57], v[52:55], off sc1
	s_nop 1
	v_mul_f32_e64 v54, v38, v50
	v_mul_f32_e64 v55, v39, v51
	v_mul_f32_e64 v58, v34, v50
	v_mul_f32_e64 v59, v35, v51
	v_cvt_pk_bf16_f32 v52, v36, v37
	v_cvt_pk_bf16_f32 v53, v54, v55
	v_cvt_pk_bf16_f32 v54, v32, v33
	v_lshl_add_u64 v[56:57], v[56:57], 0, s[66:67]
	v_cvt_pk_bf16_f32 v55, v58, v59
	s_mov_b64 s[30:31], 0
	global_store_dwordx4 v[56:57], v[52:55], off sc1
	s_nop 1
.LBB0_488:
	s_andn2_b64 vcc, exec, s[30:31]
	s_cbranch_vccnz .LBB0_490
	v_mov_b32_e32 v51, v50
	v_mul_f32_e64 v36, v40, v36
	v_mul_f32_e64 v37, v41, v37
	v_mul_f32_e64 v34, v34, v50
	v_mul_f32_e64 v35, v35, v51
	s_lshl_b32 s60, s47, 1
	v_mul_f32_e64 v40, v46, v34
	v_mul_f32_e64 v41, v47, v35
	v_mul_f32_e64 v34, v44, v32
	v_mul_f32_e64 v35, v45, v33
	v_cvt_pk_bf16_f32 v32, v36, v37
	v_lshlrev_b64 v[36:37], 11, v[48:49]
	v_lshl_add_u64 v[36:37], s[10:11], 0, v[36:37]
	v_lshl_add_u64 v[36:37], s[28:29], 1, v[36:37]
	v_mul_f32_e64 v42, v42, v50
	v_mul_f32_e64 v43, v43, v51
	v_mul_f32_e64 v38, v38, v50
	v_mul_f32_e64 v39, v39, v51
	v_lshl_add_u64 v[36:37], v[36:37], 0, s[60:61]
	v_mul_f32_e64 v38, v42, v38
	v_mul_f32_e64 v39, v43, v39
	v_lshl_add_u64 v[36:37], v[36:37], 0, v[96:97]
	v_cvt_pk_bf16_f32 v33, v38, v39
	v_cvt_pk_bf16_f32 v34, v34, v35
	v_cvt_pk_bf16_f32 v35, v40, v41
	s_nop 0
	global_store_dwordx4 v[36:37], v[32:35], off sc1
	s_nop 1
.LBB0_490:
	ds_read_b32 v34, v153 offset:640
	v_add_u32_e32 v32, 0xa0, v144
	s_mov_b64 s[30:31], -1
	s_and_b64 vcc, exec, s[4:5]
	v_ashrrev_i32_e32 v33, 31, v32
	s_waitcnt lgkmcnt(0)
	v_mov_b32_e32 v35, v34
	v_mul_f32_e64 v30, v30, v34
	v_mul_f32_e64 v31, v31, v34
	v_mul_f32_e64 v28, v28, v34
	v_mul_f32_e64 v29, v29, v34
	v_mul_f32_e64 v24, v24, v34
	v_mul_f32_e64 v25, v25, v35
	v_mul_f32_e64 v20, v20, v34
	v_mul_f32_e64 v21, v21, v35
	v_mul_f32_e64 v16, v16, v34
	v_mul_f32_e64 v17, v17, v35
	s_cbranch_vccnz .LBB0_492
	v_lshlrev_b64 v[40:41], 11, v[32:33]
	v_mov_b32_e32 v35, v34
	v_lshl_add_u64 v[40:41], s[12:13], 0, v[40:41]
	v_mul_f32_e64 v38, v26, v34
	v_mul_f32_e64 v39, v27, v35
	v_lshl_add_u64 v[40:41], s[26:27], 1, v[40:41]
	s_lshl_b32 s60, s47, 1
	v_cvt_pk_bf16_f32 v36, v24, v25
	v_cvt_pk_bf16_f32 v37, v38, v39
	v_cvt_pk_bf16_f32 v38, v28, v29
	v_cvt_pk_bf16_f32 v39, v30, v31
	v_lshl_add_u64 v[40:41], v[40:41], 0, s[60:61]
	v_lshl_add_u64 v[40:41], v[40:41], 0, v[96:97]
	global_store_dwordx4 v[40:41], v[36:39], off sc1
	s_nop 1
	v_mul_f32_e64 v38, v22, v34
	v_mul_f32_e64 v39, v23, v35
	v_mul_f32_e64 v42, v18, v34
	v_mul_f32_e64 v43, v19, v35
	v_cvt_pk_bf16_f32 v36, v20, v21
	v_cvt_pk_bf16_f32 v37, v38, v39
	v_cvt_pk_bf16_f32 v38, v16, v17
	v_lshl_add_u64 v[40:41], v[40:41], 0, s[66:67]
	v_cvt_pk_bf16_f32 v39, v42, v43
	s_mov_b64 s[30:31], 0
	global_store_dwordx4 v[40:41], v[36:39], off sc1
	s_nop 1
.LBB0_492:
	s_andn2_b64 vcc, exec, s[30:31]
	s_cbranch_vccnz .LBB0_494
	v_mov_b32_e32 v35, v34
	v_mul_f32_e64 v20, v24, v20
	v_mul_f32_e64 v21, v25, v21
	v_mul_f32_e64 v18, v18, v34
	v_mul_f32_e64 v19, v19, v35
	s_lshl_b32 s60, s47, 1
	v_mul_f32_e64 v24, v30, v18
	v_mul_f32_e64 v25, v31, v19
	v_mul_f32_e64 v18, v28, v16
	v_mul_f32_e64 v19, v29, v17
	v_cvt_pk_bf16_f32 v16, v20, v21
	v_lshlrev_b64 v[20:21], 11, v[32:33]
	v_lshl_add_u64 v[20:21], s[10:11], 0, v[20:21]
	v_lshl_add_u64 v[20:21], s[28:29], 1, v[20:21]
	v_mul_f32_e64 v26, v26, v34
	v_mul_f32_e64 v27, v27, v35
	v_mul_f32_e64 v22, v22, v34
	v_mul_f32_e64 v23, v23, v35
	v_lshl_add_u64 v[20:21], v[20:21], 0, s[60:61]
	v_mul_f32_e64 v22, v26, v22
	v_mul_f32_e64 v23, v27, v23
	v_lshl_add_u64 v[20:21], v[20:21], 0, v[96:97]
	v_cvt_pk_bf16_f32 v17, v22, v23
	v_cvt_pk_bf16_f32 v18, v18, v19
	v_cvt_pk_bf16_f32 v19, v24, v25
	s_nop 0
	global_store_dwordx4 v[20:21], v[16:19], off sc1
	s_nop 1
.LBB0_494:
	ds_read_b32 v18, v153 offset:704
	v_add_u32_e32 v16, 0xb0, v144
	s_mov_b64 s[30:31], -1
	s_and_b64 vcc, exec, s[4:5]
	v_ashrrev_i32_e32 v17, 31, v16
	s_waitcnt lgkmcnt(0)
	v_mov_b32_e32 v19, v18
	v_mul_f32_e64 v14, v14, v18
	v_mul_f32_e64 v15, v15, v18
	v_mul_f32_e64 v12, v12, v18
	v_mul_f32_e64 v13, v13, v18
	v_mul_f32_e64 v8, v8, v18
	v_mul_f32_e64 v9, v9, v19
	v_mul_f32_e64 v4, v4, v18
	v_mul_f32_e64 v5, v5, v19
	v_mul_f32_e64 v0, v0, v18
	v_mul_f32_e64 v1, v1, v19
	s_cbranch_vccz .LBB0_497
	s_andn2_b64 vcc, exec, s[30:31]
	s_cbranch_vccz .LBB0_498

.LBB0_497:
	v_lshlrev_b64 v[24:25], 11, v[16:17]
	v_mov_b32_e32 v19, v18
	v_lshl_add_u64 v[24:25], s[12:13], 0, v[24:25]
	v_mul_f32_e64 v22, v10, v18
	v_mul_f32_e64 v23, v11, v19
	v_lshl_add_u64 v[24:25], s[26:27], 1, v[24:25]
	s_lshl_b32 s60, s47, 1
	v_cvt_pk_bf16_f32 v20, v8, v9
	v_cvt_pk_bf16_f32 v21, v22, v23
	v_cvt_pk_bf16_f32 v22, v12, v13
	v_cvt_pk_bf16_f32 v23, v14, v15
	v_lshl_add_u64 v[24:25], v[24:25], 0, s[60:61]
	v_lshl_add_u64 v[24:25], v[24:25], 0, v[96:97]
	global_store_dwordx4 v[24:25], v[20:23], off sc1
	s_nop 1
	v_mul_f32_e64 v22, v6, v18
	v_mul_f32_e64 v23, v7, v19
	v_mul_f32_e64 v26, v2, v18
	v_mul_f32_e64 v27, v3, v19
	v_cvt_pk_bf16_f32 v20, v4, v5
	v_cvt_pk_bf16_f32 v21, v22, v23
	v_cvt_pk_bf16_f32 v22, v0, v1
	v_lshl_add_u64 v[24:25], v[24:25], 0, s[66:67]
	v_cvt_pk_bf16_f32 v23, v26, v27
	s_nop 0
	global_store_dwordx4 v[24:25], v[20:23], off sc1
	s_nop 1
	s_cbranch_execnz .LBB0_496
.LBB0_498:
	v_mov_b32_e32 v19, v18
	v_mul_f32_e64 v4, v8, v4
	v_mul_f32_e64 v5, v9, v5
	v_mul_f32_e64 v2, v2, v18
	v_mul_f32_e64 v3, v3, v19
	s_lshl_b32 s60, s47, 1
	v_mul_f32_e64 v8, v14, v2
	v_mul_f32_e64 v9, v15, v3
	v_mul_f32_e64 v2, v12, v0
	v_mul_f32_e64 v3, v13, v1
	v_cvt_pk_bf16_f32 v0, v4, v5
	v_lshlrev_b64 v[4:5], 11, v[16:17]
	v_lshl_add_u64 v[4:5], s[10:11], 0, v[4:5]
	v_lshl_add_u64 v[4:5], s[28:29], 1, v[4:5]
	v_mul_f32_e64 v10, v10, v18
	v_mul_f32_e64 v11, v11, v19
	v_mul_f32_e64 v6, v6, v18
	v_mul_f32_e64 v7, v7, v19
	v_lshl_add_u64 v[4:5], v[4:5], 0, s[60:61]
	v_mul_f32_e64 v6, v10, v6
	v_mul_f32_e64 v7, v11, v7
	v_lshl_add_u64 v[4:5], v[4:5], 0, v[96:97]
	v_cvt_pk_bf16_f32 v1, v6, v7
	v_cvt_pk_bf16_f32 v2, v2, v3
	v_cvt_pk_bf16_f32 v3, v8, v9
	s_nop 0
	global_store_dwordx4 v[4:5], v[0:3], off sc1
	s_nop 1
	s_andn2_b64 vcc, exec, s[2:3]
	s_mov_b64 s[2:3], -1
	s_cbranch_vccnz .LBB0_457

.LBB0_560:
	v_ashrrev_i32_e32 v40, 7, v38
	v_max_i32_e32 v1, 1, v40
	v_add_u32_e32 v96, -1, v1
	v_max_i32_e32 v1, 2, v40
	v_ashrrev_i32_e32 v41, 31, v40
	v_add_u32_e32 v48, -2, v1
	v_lshlrev_b64 v[56:57], 11, v[40:41]
	v_lshlrev_b64 v[44:45], 11, v[96:97]
	v_mov_b32_e32 v49, v97
	v_cmp_lt_i32_e32 vcc, 0, v40
	v_cmp_lt_i32_e64 s[2:3], 1, v40
	v_lshl_add_u64 v[40:41], v[24:25], 0, v[56:57]
	v_lshl_add_u64 v[44:45], v[24:25], 0, v[44:45]
	v_lshlrev_b64 v[48:49], 11, v[48:49]
	global_load_dwordx4 v[40:43], v[40:41], off
	v_lshl_add_u64 v[48:49], v[24:25], 0, v[48:49]
	global_load_dwordx4 v[44:47], v[44:45], off
	v_lshl_add_u64 v[52:53], v[26:27], 0, v[56:57]
	global_load_dwordx4 v[48:51], v[48:49], off
	v_cndmask_b32_e64 v31, 0, 1.0, vcc
	global_load_dwordx4 v[52:55], v[52:53], off
	v_cndmask_b32_e64 v39, 0, 1.0, s[2:3]
	s_waitcnt vmcnt(7)
	v_mul_f32_e32 v1, v8, v31
	s_waitcnt vmcnt(5)
	v_mul_f32_e32 v3, v16, v39
	v_mul_f32_e32 v37, v9, v31
	v_mul_f32_e32 v35, v11, v31
	v_add_u32_e32 v38, s8, v38
	s_mov_b32 s2, 0x1fffff
	v_cmp_lt_i32_e32 vcc, s2, v38
	s_or_b64 s[6:7], vcc, s[6:7]
	s_waitcnt vmcnt(3)
	v_lshlrev_b32_e32 v58, 16, v40
	s_waitcnt vmcnt(2)
	v_lshlrev_b32_e32 v59, 16, v44
	v_mul_f32_e64 v58, v0, v58
	v_mul_f32_e64 v59, v1, v59
	s_waitcnt vmcnt(1)
	v_lshlrev_b32_e32 v5, 16, v48
	v_fma_f32 v1, v3, v5, v59
	v_add_f32_e32 v1, v58, v1
	v_and_b32_e32 v59, 0xffff0000, v44
	v_and_b32_e32 v58, 0xffff0000, v40
	v_mul_f32_e32 v3, v17, v39
	v_and_b32_e32 v5, 0xffff0000, v48
	v_mul_f32_e64 v58, v36, v58
	v_mul_f32_e64 v59, v37, v59
	v_lshlrev_b32_e32 v7, 16, v49
	v_fma_f32 v3, v3, v5, v59
	v_add_f32_e32 v37, v58, v3
	v_mul_f32_e32 v3, v10, v31
	v_lshlrev_b32_e32 v58, 16, v41
	v_lshlrev_b32_e32 v59, 16, v45
	v_mul_f32_e32 v5, v18, v39
	v_mul_f32_e64 v58, v2, v58
	v_mul_f32_e64 v59, v3, v59
	v_and_b32_e32 v45, 0xffff0000, v45
	v_and_b32_e32 v44, 0xffff0000, v41
	v_fma_f32 v3, v5, v7, v59
	v_mul_f32_e32 v5, v19, v39
	v_and_b32_e32 v7, 0xffff0000, v49
	v_mul_f32_e64 v40, v34, v44
	v_mul_f32_e64 v41, v35, v45
	v_lshlrev_b32_e32 v33, 16, v50
	v_fma_f32 v5, v5, v7, v41
	v_add_f32_e32 v35, v40, v5
	v_mul_f32_e32 v5, v12, v31
	v_lshlrev_b32_e32 v40, 16, v42
	v_lshlrev_b32_e32 v41, 16, v46
	v_mul_f32_e32 v7, v20, v39
	v_mul_f32_e64 v40, v4, v40
	v_mul_f32_e64 v41, v5, v41
	v_and_b32_e32 v44, 0xffff0000, v50
	v_fma_f32 v5, v7, v33, v41
	v_add_f32_e32 v5, v40, v5
	v_mul_f32_e32 v33, v13, v31
	v_and_b32_e32 v41, 0xffff0000, v46
	v_and_b32_e32 v40, 0xffff0000, v42
	v_mul_f32_e32 v7, v21, v39
	v_mul_f32_e64 v40, v32, v40
	v_mul_f32_e64 v41, v33, v41
	v_mul_f32_e32 v42, v22, v39
	v_fma_f32 v7, v7, v44, v41
	v_add_f32_e32 v33, v40, v7
	v_mul_f32_e32 v7, v14, v31
	v_lshlrev_b32_e32 v40, 16, v43
	v_lshlrev_b32_e32 v41, 16, v47
	v_lshlrev_b32_e32 v44, 16, v51
	v_mul_f32_e64 v40, v6, v40
	v_mul_f32_e64 v41, v7, v41
	v_mul_f32_e32 v31, v15, v31
	v_fma_f32 v7, v42, v44, v41
	v_add_f32_e32 v7, v40, v7
	v_and_b32_e32 v41, 0xffff0000, v47
	v_and_b32_e32 v40, 0xffff0000, v43
	v_mul_f32_e32 v39, v23, v39
	v_and_b32_e32 v42, 0xffff0000, v51
	v_mul_f32_e64 v40, v30, v40
	v_mul_f32_e64 v41, v31, v41
	v_add_f32_e32 v3, v58, v3
	v_fma_f32 v31, v39, v42, v41
	s_waitcnt vmcnt(0)
	v_lshlrev_b32_e32 v39, 16, v52
	v_mul_f32_e32 v1, v1, v39
	v_and_b32_e32 v39, 0xffff0000, v52
	v_add_f32_e32 v31, v40, v31
	v_mul_f32_e32 v37, v37, v39
	v_cvt_pk_bf16_f32 v40, v1, v37
	v_lshlrev_b32_e32 v1, 16, v53
	v_mul_f32_e32 v1, v3, v1
	v_and_b32_e32 v3, 0xffff0000, v53
	v_mul_f32_e32 v3, v35, v3
	v_cvt_pk_bf16_f32 v41, v1, v3
	v_lshlrev_b32_e32 v1, 16, v54
	v_and_b32_e32 v3, 0xffff0000, v54
	v_mul_f32_e32 v1, v5, v1
	v_mul_f32_e32 v3, v33, v3
	v_cvt_pk_bf16_f32 v42, v1, v3
	v_lshlrev_b32_e32 v1, 16, v55
	v_and_b32_e32 v3, 0xffff0000, v55
	v_lshl_add_u64 v[44:45], v[28:29], 0, v[56:57]
	v_mul_f32_e32 v1, v7, v1
	v_mul_f32_e32 v3, v31, v3
	v_cvt_pk_bf16_f32 v43, v1, v3
	global_store_dwordx4 v[44:45], v[40:43], off
	s_andn2_b64 exec, exec, s[6:7]
	s_cbranch_execnz .LBB0_560

.LBB0_725:
	s_bitcmp1_b32 s46, 0
	s_cselect_b64 s[24:25], -1, 0
	s_and_b64 vcc, exec, s[24:25]
	s_cbranch_vccnz .LBB0_727
	s_and_b64 s[24:25], s[12:13], exec
	s_cselect_b32 s15, s22, s47
	v_lshl_or_b32 v148, s15, 8, v143
	v_ashrrev_i32_e32 v149, 31, v148
	v_lshlrev_b64 v[148:149], 6, v[148:149]
	v_lshl_add_u64 v[160:161], s[4:5], 0, v[148:149]
	global_load_dwordx4 v[148:151], v[160:161], off offset:48
	global_load_dwordx4 v[152:155], v[160:161], off offset:32
	global_load_dwordx4 v[156:159], v[160:161], off offset:16
	s_nop 0
	global_load_dwordx4 v[160:163], v[160:161], off
	s_waitcnt vmcnt(0)
	v_add_f32_e32 v152, v152, v153
	v_add_f32_e32 v154, v154, v155
	v_mov_b32_e32 v164, v161
	v_mov_b32_e32 v165, v162
	v_mov_b32_e32 v161, v163
	v_mov_b32_e32 v162, v157
	v_mov_b32_e32 v163, v158
	v_mov_b32_e32 v157, v159
	v_add_f32_e64 v160, v164, v160
	v_add_f32_e64 v161, v165, v161
	v_add_f32_e64 v156, v162, v156
	v_add_f32_e64 v157, v163, v157
	v_add_f32_e64 v160, v160, v161
	v_mov_b32_e32 v161, v160
	v_add_f32_e64 v156, v156, v157
	v_mov_b32_e32 v157, v156
	v_mov_b32_e32 v161, v148
	v_mov_b32_e32 v157, v149
	v_mov_b32_e32 v153, v150
	v_mov_b32_e32 v155, v151
	v_add_f32_e64 v148, v160, v156
	v_add_f32_e64 v149, v161, v157
	v_add_f32_e64 v150, v152, v154
	v_add_f32_e64 v151, v153, v155
	s_nop 0
	v_add_f32_e64 v148, v148, v150
	v_add_f32_e64 v149, v149, v151
	s_nop 0
	v_add_f32_e32 v147, v148, v149
	v_fmamk_f32 v147, v147, 0x3a800000, v249
	v_rsq_f32_e32 v147, v147
	ds_write_b32 v145, v147
	s_waitcnt lgkmcnt(0)
	s_barrier
.LBB0_727:
	s_and_b32 s15, s46, 1
	v_lshl_add_u32 v147, s15, 10, v144
	ds_read_b32 v148, v147
	v_lshl_add_u32 v149, s22, 8, v140
	v_lshl_or_b32 v150, s45, 8, v142
	v_ashrrev_i32_e32 v151, 31, v150
	s_andn2_b64 vcc, exec, s[2:3]
	s_waitcnt lgkmcnt(0)
	v_mul_f32_e64 v128, v128, v148
	v_mul_f32_e64 v129, v129, v148
	v_mul_f32_e64 v126, v126, v148
	v_mul_f32_e64 v127, v127, v148
	v_mul_f32_e64 v122, v122, v148
	v_mul_f32_e64 v123, v123, v148
	v_mul_f32_e64 v124, v124, v148
	v_mul_f32_e64 v125, v125, v148
	v_cvt_pk_bf16_f32 v126, v126, v127
	v_cvt_pk_bf16_f32 v127, v128, v129
	v_cvt_pk_bf16_f32 v128, v122, v123
	v_mov_b64_e32 v[122:123], s[8:9]
	v_cvt_pk_bf16_f32 v129, v124, v125
	v_mad_i64_i32 v[152:153], s[24:25], v149, s77, v[122:123]
	v_lshlrev_b64 v[124:125], 1, v[150:151]
	v_lshl_add_u64 v[150:151], v[152:153], 0, v[124:125]
	global_store_dwordx4 v[150:151], v[126:129], off sc1
	s_nop 1
	v_mul_f32_e64 v118, v118, v148
	v_mul_f32_e64 v119, v119, v148
	v_mul_f32_e64 v126, v112, v148
	v_mul_f32_e64 v127, v113, v148
	v_mul_f32_e64 v112, v110, v148
	v_mul_f32_e64 v113, v111, v148
	v_mul_f32_e64 v120, v120, v148
	v_mul_f32_e64 v121, v121, v148
	v_cvt_pk_bf16_f32 v110, v118, v119
	v_lshl_add_u64 v[118:119], v[150:151], 0, s[66:67]
	v_cvt_pk_bf16_f32 v111, v120, v121
	v_cvt_pk_bf16_f32 v112, v112, v113
	v_cvt_pk_bf16_f32 v113, v126, v127
	s_mov_b64 s[2:3], -1
	global_store_dwordx4 v[118:119], v[110:113], off sc1
	s_nop 1
	ds_read_b32 v110, v147 offset:64
	v_or_b32_e32 v111, 16, v149
	s_waitcnt lgkmcnt(0)
	v_mul_f32_e64 v112, v116, v110
	v_mul_f32_e64 v113, v117, v110
	v_mul_f32_e64 v114, v114, v110
	v_mul_f32_e64 v115, v115, v110
	v_mul_f32_e64 v116, v108, v110
	v_mul_f32_e64 v117, v109, v110
	v_mul_f32_e64 v108, v106, v110
	v_mul_f32_e64 v109, v107, v110
	v_cvt_pk_bf16_f32 v106, v114, v115
	v_cvt_pk_bf16_f32 v107, v112, v113
	v_mad_i64_i32 v[112:113], s[24:25], v111, s77, v[122:123]
	v_cvt_pk_bf16_f32 v108, v108, v109
	v_cvt_pk_bf16_f32 v109, v116, v117
	v_lshl_add_u64 v[112:113], v[112:113], 0, v[124:125]
	global_store_dwordx4 v[112:113], v[106:109], off sc1
	s_nop 1
	v_mul_f32_e64 v102, v102, v110
	v_mul_f32_e64 v103, v103, v110
	v_mul_f32_e64 v106, v94, v110
	v_mul_f32_e64 v107, v95, v110
	v_mul_f32_e64 v94, v92, v110
	v_mul_f32_e64 v95, v93, v110
	v_mul_f32_e64 v104, v104, v110
	v_mul_f32_e64 v105, v105, v110
	v_cvt_pk_bf16_f32 v92, v102, v103
	v_lshl_add_u64 v[102:103], v[112:113], 0, s[66:67]
	v_cvt_pk_bf16_f32 v93, v104, v105
	v_cvt_pk_bf16_f32 v94, v94, v95
	v_cvt_pk_bf16_f32 v95, v106, v107
	s_nop 0
	global_store_dwordx4 v[102:103], v[92:95], off sc1
	s_nop 1
	ds_read_b32 v92, v147 offset:128
	v_or_b32_e32 v93, 32, v149
	s_waitcnt lgkmcnt(0)
	v_mul_f32_e64 v94, v100, v92
	v_mul_f32_e64 v95, v101, v92
	v_mul_f32_e64 v98, v98, v92
	v_mul_f32_e64 v99, v99, v92
	v_mul_f32_e64 v100, v90, v92
	v_mul_f32_e64 v101, v91, v92
	v_mul_f32_e64 v90, v88, v92
	v_mul_f32_e64 v91, v89, v92
	v_cvt_pk_bf16_f32 v88, v98, v99
	v_cvt_pk_bf16_f32 v89, v94, v95
	v_mad_i64_i32 v[94:95], s[24:25], v93, s77, v[122:123]
	v_cvt_pk_bf16_f32 v90, v90, v91
	v_cvt_pk_bf16_f32 v91, v100, v101
	v_lshl_add_u64 v[94:95], v[94:95], 0, v[124:125]
	global_store_dwordx4 v[94:95], v[88:91], off sc1
	s_nop 1
	v_mul_f32_e64 v84, v84, v92
	v_mul_f32_e64 v85, v85, v92
	v_mul_f32_e64 v88, v78, v92
	v_mul_f32_e64 v89, v79, v92
	v_mul_f32_e64 v78, v76, v92
	v_mul_f32_e64 v79, v77, v92
	v_mul_f32_e64 v86, v86, v92
	v_mul_f32_e64 v87, v87, v92
	v_cvt_pk_bf16_f32 v76, v84, v85
	v_lshl_add_u64 v[84:85], v[94:95], 0, s[66:67]
	v_cvt_pk_bf16_f32 v77, v86, v87
	v_cvt_pk_bf16_f32 v78, v78, v79
	v_cvt_pk_bf16_f32 v79, v88, v89
	s_nop 0
	global_store_dwordx4 v[84:85], v[76:79], off sc1
	s_nop 1
	ds_read_b32 v76, v147 offset:192
	v_or_b32_e32 v77, 48, v149
	s_waitcnt lgkmcnt(0)
	v_mul_f32_e64 v78, v82, v76
	v_mul_f32_e64 v79, v83, v76
	v_mul_f32_e64 v80, v80, v76
	v_mul_f32_e64 v81, v81, v76
	v_mul_f32_e64 v82, v74, v76
	v_mul_f32_e64 v83, v75, v76
	v_mul_f32_e64 v74, v72, v76
	v_mul_f32_e64 v75, v73, v76
	v_cvt_pk_bf16_f32 v72, v80, v81
	v_cvt_pk_bf16_f32 v73, v78, v79
	v_mad_i64_i32 v[78:79], s[24:25], v77, s77, v[122:123]
	v_cvt_pk_bf16_f32 v74, v74, v75
	v_cvt_pk_bf16_f32 v75, v82, v83
	v_lshl_add_u64 v[78:79], v[78:79], 0, v[124:125]
	global_store_dwordx4 v[78:79], v[72:75], off sc1
	s_nop 1
	v_mul_f32_e64 v68, v68, v76
	v_mul_f32_e64 v69, v69, v76
	v_mul_f32_e64 v72, v66, v76
	v_mul_f32_e64 v73, v67, v76
	v_mul_f32_e64 v66, v64, v76
	v_mul_f32_e64 v67, v65, v76
	v_mul_f32_e64 v70, v70, v76
	v_mul_f32_e64 v71, v71, v76
	v_cvt_pk_bf16_f32 v64, v68, v69
	v_lshl_add_u64 v[68:69], v[78:79], 0, s[66:67]
	v_cvt_pk_bf16_f32 v65, v70, v71
	v_cvt_pk_bf16_f32 v66, v66, v67
	v_cvt_pk_bf16_f32 v67, v72, v73
	s_nop 0
	global_store_dwordx4 v[68:69], v[64:67], off sc1
	s_nop 1
	ds_read_b32 v64, v147 offset:512
	v_add_u32_e32 v65, 0x80, v149
	s_waitcnt lgkmcnt(0)
	v_mul_f32_e64 v60, v60, v64
	v_mul_f32_e64 v61, v61, v64
	v_mul_f32_e64 v62, v62, v64
	v_mul_f32_e64 v63, v63, v64
	v_mul_f32_e64 v66, v58, v64
	v_mul_f32_e64 v67, v59, v64
	v_mul_f32_e64 v58, v56, v64
	v_mul_f32_e64 v59, v57, v64
	v_cvt_pk_bf16_f32 v56, v60, v61
	v_cvt_pk_bf16_f32 v57, v62, v63
	v_mad_i64_i32 v[60:61], s[24:25], v65, s77, v[122:123]
	v_cvt_pk_bf16_f32 v58, v58, v59
	v_cvt_pk_bf16_f32 v59, v66, v67
	v_lshl_add_u64 v[60:61], v[60:61], 0, v[124:125]
	global_store_dwordx4 v[60:61], v[56:59], off sc1
	s_nop 1
	v_mul_f32_e64 v52, v52, v64
	v_mul_f32_e64 v53, v53, v64
	v_mul_f32_e64 v56, v46, v64
	v_mul_f32_e64 v57, v47, v64
	v_mul_f32_e64 v46, v44, v64
	v_mul_f32_e64 v47, v45, v64
	v_mul_f32_e64 v54, v54, v64
	v_mul_f32_e64 v55, v55, v64
	v_cvt_pk_bf16_f32 v44, v52, v53
	v_lshl_add_u64 v[52:53], v[60:61], 0, s[66:67]
	v_cvt_pk_bf16_f32 v45, v54, v55
	v_cvt_pk_bf16_f32 v46, v46, v47
	v_cvt_pk_bf16_f32 v47, v56, v57
	s_nop 0
	global_store_dwordx4 v[52:53], v[44:47], off sc1
	s_nop 1
	ds_read_b32 v44, v147 offset:576
	v_add_u32_e32 v45, 0x90, v149
	s_waitcnt lgkmcnt(0)
	v_mul_f32_e64 v46, v50, v44
	v_mul_f32_e64 v47, v51, v44
	v_mul_f32_e64 v48, v48, v44
	v_mul_f32_e64 v49, v49, v44
	v_mul_f32_e64 v50, v42, v44
	v_mul_f32_e64 v51, v43, v44
	v_mul_f32_e64 v42, v40, v44
	v_mul_f32_e64 v43, v41, v44
	v_cvt_pk_bf16_f32 v40, v48, v49
	v_cvt_pk_bf16_f32 v41, v46, v47
	v_mad_i64_i32 v[46:47], s[24:25], v45, s77, v[122:123]
	v_cvt_pk_bf16_f32 v42, v42, v43
	v_cvt_pk_bf16_f32 v43, v50, v51
	v_lshl_add_u64 v[46:47], v[46:47], 0, v[124:125]
	global_store_dwordx4 v[46:47], v[40:43], off sc1
	s_nop 1
	v_mul_f32_e64 v36, v36, v44
	v_mul_f32_e64 v37, v37, v44
	v_mul_f32_e64 v40, v30, v44
	v_mul_f32_e64 v41, v31, v44
	v_mul_f32_e64 v30, v28, v44
	v_mul_f32_e64 v31, v29, v44
	v_mul_f32_e64 v38, v38, v44
	v_mul_f32_e64 v39, v39, v44
	v_cvt_pk_bf16_f32 v28, v36, v37
	v_lshl_add_u64 v[36:37], v[46:47], 0, s[66:67]
	v_cvt_pk_bf16_f32 v29, v38, v39
	v_cvt_pk_bf16_f32 v30, v30, v31
	v_cvt_pk_bf16_f32 v31, v40, v41
	s_nop 0
	global_store_dwordx4 v[36:37], v[28:31], off sc1
	s_nop 1
	ds_read_b32 v28, v147 offset:640
	v_add_u32_e32 v29, 0xa0, v149
	s_waitcnt lgkmcnt(0)
	v_mul_f32_e64 v30, v34, v28
	v_mul_f32_e64 v31, v35, v28
	v_mul_f32_e64 v32, v32, v28
	v_mul_f32_e64 v33, v33, v28
	v_mul_f32_e64 v34, v26, v28
	v_mul_f32_e64 v35, v27, v28
	v_mul_f32_e64 v26, v24, v28
	v_mul_f32_e64 v27, v25, v28
	v_cvt_pk_bf16_f32 v24, v32, v33
	v_cvt_pk_bf16_f32 v25, v30, v31
	v_mad_i64_i32 v[30:31], s[24:25], v29, s77, v[122:123]
	v_cvt_pk_bf16_f32 v26, v26, v27
	v_cvt_pk_bf16_f32 v27, v34, v35
	v_lshl_add_u64 v[30:31], v[30:31], 0, v[124:125]
	global_store_dwordx4 v[30:31], v[24:27], off sc1
	s_nop 1
	v_mul_f32_e64 v20, v20, v28
	v_mul_f32_e64 v21, v21, v28
	v_mul_f32_e64 v24, v14, v28
	v_mul_f32_e64 v25, v15, v28
	v_mul_f32_e64 v14, v12, v28
	v_mul_f32_e64 v15, v13, v28
	v_mul_f32_e64 v22, v22, v28
	v_mul_f32_e64 v23, v23, v28
	v_cvt_pk_bf16_f32 v12, v20, v21
	v_lshl_add_u64 v[20:21], v[30:31], 0, s[66:67]
	v_cvt_pk_bf16_f32 v13, v22, v23
	v_cvt_pk_bf16_f32 v14, v14, v15
	v_cvt_pk_bf16_f32 v15, v24, v25
	s_nop 0
	global_store_dwordx4 v[20:21], v[12:15], off sc1
	s_nop 1
	ds_read_b32 v12, v147 offset:704
	v_add_u32_e32 v13, 0xb0, v149
	s_waitcnt lgkmcnt(0)
	v_mul_f32_e64 v14, v18, v12
	v_mul_f32_e64 v15, v19, v12
	v_mul_f32_e64 v16, v16, v12
	v_mul_f32_e64 v17, v17, v12
	v_mul_f32_e64 v18, v10, v12
	v_mul_f32_e64 v19, v11, v12
	v_mul_f32_e64 v10, v8, v12
	v_mul_f32_e64 v11, v9, v12
	v_cvt_pk_bf16_f32 v8, v16, v17
	v_cvt_pk_bf16_f32 v9, v14, v15
	v_mad_i64_i32 v[14:15], s[24:25], v13, s77, v[122:123]
	v_cvt_pk_bf16_f32 v10, v10, v11
	v_cvt_pk_bf16_f32 v11, v18, v19
	v_lshl_add_u64 v[14:15], v[14:15], 0, v[124:125]
	global_store_dwordx4 v[14:15], v[8:11], off sc1
	s_nop 1
	v_mul_f32_e64 v4, v4, v12
	v_mul_f32_e64 v5, v5, v12
	v_mul_f32_e64 v8, v2, v12
	v_mul_f32_e64 v9, v3, v12
	v_mul_f32_e64 v2, v0, v12
	v_mul_f32_e64 v3, v1, v12
	v_mul_f32_e64 v6, v6, v12
	v_mul_f32_e64 v7, v7, v12
	v_cvt_pk_bf16_f32 v0, v4, v5
	v_lshl_add_u64 v[4:5], v[14:15], 0, s[66:67]
	v_cvt_pk_bf16_f32 v1, v6, v7
	v_cvt_pk_bf16_f32 v2, v2, v3
	v_cvt_pk_bf16_f32 v3, v8, v9
	s_nop 0
	global_store_dwordx4 v[4:5], v[0:3], off sc1
	s_nop 1
	s_cbranch_vccnz .LBB0_718
	s_andn2_b64 vcc, exec, s[6:7]
	s_cbranch_vccnz .LBB0_717
	s_barrier
	s_branch .LBB0_717

.LBB0_866:
	s_and_b32 s18, s46, 1
	v_lshl_add_u32 v147, s18, 10, v144
	ds_read_b32 v148, v147
	v_lshl_add_u32 v149, s44, 8, v140
	v_lshl_or_b32 v150, s45, 8, v142
	v_ashrrev_i32_e32 v151, 31, v150
	s_and_b64 vcc, exec, s[2:3]
	s_waitcnt lgkmcnt(0)
	v_mul_f32_e64 v128, v128, v148
	v_mul_f32_e64 v129, v129, v148
	v_mul_f32_e64 v126, v126, v148
	v_mul_f32_e64 v127, v127, v148
	v_mul_f32_e64 v122, v122, v148
	v_mul_f32_e64 v123, v123, v148
	v_mul_f32_e64 v124, v124, v148
	v_mul_f32_e64 v125, v125, v148
	v_cvt_pk_bf16_f32 v126, v126, v127
	v_cvt_pk_bf16_f32 v127, v128, v129
	v_cvt_pk_bf16_f32 v128, v122, v123
	v_mov_b64_e32 v[122:123], s[8:9]
	v_cvt_pk_bf16_f32 v129, v124, v125
	v_mad_i64_i32 v[152:153], s[18:19], v149, s84, v[122:123]
	v_lshlrev_b64 v[124:125], 1, v[150:151]
	v_lshl_add_u64 v[150:151], v[152:153], 0, v[124:125]
	global_store_dwordx4 v[150:151], v[126:129], off sc1
	s_nop 1
	v_mul_f32_e64 v118, v118, v148
	v_mul_f32_e64 v119, v119, v148
	v_mul_f32_e64 v126, v112, v148
	v_mul_f32_e64 v127, v113, v148
	v_mul_f32_e64 v112, v110, v148
	v_mul_f32_e64 v113, v111, v148
	v_mul_f32_e64 v120, v120, v148
	v_mul_f32_e64 v121, v121, v148
	v_cvt_pk_bf16_f32 v110, v118, v119
	v_lshl_add_u64 v[118:119], v[150:151], 0, s[66:67]
	v_cvt_pk_bf16_f32 v111, v120, v121
	v_cvt_pk_bf16_f32 v112, v112, v113
	v_cvt_pk_bf16_f32 v113, v126, v127
	s_mov_b64 s[2:3], -1
	global_store_dwordx4 v[118:119], v[110:113], off sc1
	s_nop 1
	ds_read_b32 v110, v147 offset:64
	v_or_b32_e32 v111, 16, v149
	s_waitcnt lgkmcnt(0)
	v_mul_f32_e64 v112, v116, v110
	v_mul_f32_e64 v113, v117, v110
	v_mul_f32_e64 v114, v114, v110
	v_mul_f32_e64 v115, v115, v110
	v_mul_f32_e64 v116, v108, v110
	v_mul_f32_e64 v117, v109, v110
	v_mul_f32_e64 v108, v106, v110
	v_mul_f32_e64 v109, v107, v110
	v_cvt_pk_bf16_f32 v106, v114, v115
	v_cvt_pk_bf16_f32 v107, v112, v113
	v_mad_i64_i32 v[112:113], s[18:19], v111, s84, v[122:123]
	v_cvt_pk_bf16_f32 v108, v108, v109
	v_cvt_pk_bf16_f32 v109, v116, v117
	v_lshl_add_u64 v[112:113], v[112:113], 0, v[124:125]
	global_store_dwordx4 v[112:113], v[106:109], off sc1
	s_nop 1
	v_mul_f32_e64 v102, v102, v110
	v_mul_f32_e64 v103, v103, v110
	v_mul_f32_e64 v106, v94, v110
	v_mul_f32_e64 v107, v95, v110
	v_mul_f32_e64 v94, v92, v110
	v_mul_f32_e64 v95, v93, v110
	v_mul_f32_e64 v104, v104, v110
	v_mul_f32_e64 v105, v105, v110
	v_cvt_pk_bf16_f32 v92, v102, v103
	v_lshl_add_u64 v[102:103], v[112:113], 0, s[66:67]
	v_cvt_pk_bf16_f32 v93, v104, v105
	v_cvt_pk_bf16_f32 v94, v94, v95
	v_cvt_pk_bf16_f32 v95, v106, v107
	s_nop 0
	global_store_dwordx4 v[102:103], v[92:95], off sc1
	s_nop 1
	ds_read_b32 v92, v147 offset:128
	v_or_b32_e32 v93, 32, v149
	s_waitcnt lgkmcnt(0)
	v_mul_f32_e64 v94, v100, v92
	v_mul_f32_e64 v95, v101, v92
	v_mul_f32_e64 v98, v98, v92
	v_mul_f32_e64 v99, v99, v92
	v_mul_f32_e64 v100, v90, v92
	v_mul_f32_e64 v101, v91, v92
	v_mul_f32_e64 v90, v88, v92
	v_mul_f32_e64 v91, v89, v92
	v_cvt_pk_bf16_f32 v88, v98, v99
	v_cvt_pk_bf16_f32 v89, v94, v95
	v_mad_i64_i32 v[94:95], s[18:19], v93, s84, v[122:123]
	v_cvt_pk_bf16_f32 v90, v90, v91
	v_cvt_pk_bf16_f32 v91, v100, v101
	v_lshl_add_u64 v[94:95], v[94:95], 0, v[124:125]
	global_store_dwordx4 v[94:95], v[88:91], off sc1
	s_nop 1
	v_mul_f32_e64 v84, v84, v92
	v_mul_f32_e64 v85, v85, v92
	v_mul_f32_e64 v88, v78, v92
	v_mul_f32_e64 v89, v79, v92
	v_mul_f32_e64 v78, v76, v92
	v_mul_f32_e64 v79, v77, v92
	v_mul_f32_e64 v86, v86, v92
	v_mul_f32_e64 v87, v87, v92
	v_cvt_pk_bf16_f32 v76, v84, v85
	v_lshl_add_u64 v[84:85], v[94:95], 0, s[66:67]
	v_cvt_pk_bf16_f32 v77, v86, v87
	v_cvt_pk_bf16_f32 v78, v78, v79
	v_cvt_pk_bf16_f32 v79, v88, v89
	s_nop 0
	global_store_dwordx4 v[84:85], v[76:79], off sc1
	s_nop 1
	ds_read_b32 v76, v147 offset:192
	v_or_b32_e32 v77, 48, v149
	s_waitcnt lgkmcnt(0)
	v_mul_f32_e64 v78, v82, v76
	v_mul_f32_e64 v79, v83, v76
	v_mul_f32_e64 v80, v80, v76
	v_mul_f32_e64 v81, v81, v76
	v_mul_f32_e64 v82, v74, v76
	v_mul_f32_e64 v83, v75, v76
	v_mul_f32_e64 v74, v72, v76
	v_mul_f32_e64 v75, v73, v76
	v_cvt_pk_bf16_f32 v72, v80, v81
	v_cvt_pk_bf16_f32 v73, v78, v79
	v_mad_i64_i32 v[78:79], s[18:19], v77, s84, v[122:123]
	v_cvt_pk_bf16_f32 v74, v74, v75
	v_cvt_pk_bf16_f32 v75, v82, v83
	v_lshl_add_u64 v[78:79], v[78:79], 0, v[124:125]
	global_store_dwordx4 v[78:79], v[72:75], off sc1
	s_nop 1
	v_mul_f32_e64 v68, v68, v76
	v_mul_f32_e64 v69, v69, v76
	v_mul_f32_e64 v72, v66, v76
	v_mul_f32_e64 v73, v67, v76
	v_mul_f32_e64 v66, v64, v76
	v_mul_f32_e64 v67, v65, v76
	v_mul_f32_e64 v70, v70, v76
	v_mul_f32_e64 v71, v71, v76
	v_cvt_pk_bf16_f32 v64, v68, v69
	v_lshl_add_u64 v[68:69], v[78:79], 0, s[66:67]
	v_cvt_pk_bf16_f32 v65, v70, v71
	v_cvt_pk_bf16_f32 v66, v66, v67
	v_cvt_pk_bf16_f32 v67, v72, v73
	s_nop 0
	global_store_dwordx4 v[68:69], v[64:67], off sc1
	s_nop 1
	ds_read_b32 v64, v147 offset:512
	v_add_u32_e32 v65, 0x80, v149
	s_waitcnt lgkmcnt(0)
	v_mul_f32_e64 v60, v60, v64
	v_mul_f32_e64 v61, v61, v64
	v_mul_f32_e64 v62, v62, v64
	v_mul_f32_e64 v63, v63, v64
	v_mul_f32_e64 v66, v58, v64
	v_mul_f32_e64 v67, v59, v64
	v_mul_f32_e64 v58, v56, v64
	v_mul_f32_e64 v59, v57, v64
	v_cvt_pk_bf16_f32 v56, v60, v61
	v_cvt_pk_bf16_f32 v57, v62, v63
	v_mad_i64_i32 v[60:61], s[18:19], v65, s84, v[122:123]
	v_cvt_pk_bf16_f32 v58, v58, v59
	v_cvt_pk_bf16_f32 v59, v66, v67
	v_lshl_add_u64 v[60:61], v[60:61], 0, v[124:125]
	global_store_dwordx4 v[60:61], v[56:59], off sc1
	s_nop 1
	v_mul_f32_e64 v52, v52, v64
	v_mul_f32_e64 v53, v53, v64
	v_mul_f32_e64 v56, v46, v64
	v_mul_f32_e64 v57, v47, v64
	v_mul_f32_e64 v46, v44, v64
	v_mul_f32_e64 v47, v45, v64
	v_mul_f32_e64 v54, v54, v64
	v_mul_f32_e64 v55, v55, v64
	v_cvt_pk_bf16_f32 v44, v52, v53
	v_lshl_add_u64 v[52:53], v[60:61], 0, s[66:67]
	v_cvt_pk_bf16_f32 v45, v54, v55
	v_cvt_pk_bf16_f32 v46, v46, v47
	v_cvt_pk_bf16_f32 v47, v56, v57
	s_nop 0
	global_store_dwordx4 v[52:53], v[44:47], off sc1
	s_nop 1
	ds_read_b32 v44, v147 offset:576
	v_add_u32_e32 v45, 0x90, v149
	s_waitcnt lgkmcnt(0)
	v_mul_f32_e64 v46, v50, v44
	v_mul_f32_e64 v47, v51, v44
	v_mul_f32_e64 v48, v48, v44
	v_mul_f32_e64 v49, v49, v44
	v_mul_f32_e64 v50, v42, v44
	v_mul_f32_e64 v51, v43, v44
	v_mul_f32_e64 v42, v40, v44
	v_mul_f32_e64 v43, v41, v44
	v_cvt_pk_bf16_f32 v40, v48, v49
	v_cvt_pk_bf16_f32 v41, v46, v47
	v_mad_i64_i32 v[46:47], s[18:19], v45, s84, v[122:123]
	v_cvt_pk_bf16_f32 v42, v42, v43
	v_cvt_pk_bf16_f32 v43, v50, v51
	v_lshl_add_u64 v[46:47], v[46:47], 0, v[124:125]
	global_store_dwordx4 v[46:47], v[40:43], off sc1
	s_nop 1
	v_mul_f32_e64 v36, v36, v44
	v_mul_f32_e64 v37, v37, v44
	v_mul_f32_e64 v40, v30, v44
	v_mul_f32_e64 v41, v31, v44
	v_mul_f32_e64 v30, v28, v44
	v_mul_f32_e64 v31, v29, v44
	v_mul_f32_e64 v38, v38, v44
	v_mul_f32_e64 v39, v39, v44
	v_cvt_pk_bf16_f32 v28, v36, v37
	v_lshl_add_u64 v[36:37], v[46:47], 0, s[66:67]
	v_cvt_pk_bf16_f32 v29, v38, v39
	v_cvt_pk_bf16_f32 v30, v30, v31
	v_cvt_pk_bf16_f32 v31, v40, v41
	s_nop 0
	global_store_dwordx4 v[36:37], v[28:31], off sc1
	s_nop 1
	ds_read_b32 v28, v147 offset:640
	v_add_u32_e32 v29, 0xa0, v149
	s_waitcnt lgkmcnt(0)
	v_mul_f32_e64 v30, v34, v28
	v_mul_f32_e64 v31, v35, v28
	v_mul_f32_e64 v32, v32, v28
	v_mul_f32_e64 v33, v33, v28
	v_mul_f32_e64 v34, v26, v28
	v_mul_f32_e64 v35, v27, v28
	v_mul_f32_e64 v26, v24, v28
	v_mul_f32_e64 v27, v25, v28
	v_cvt_pk_bf16_f32 v24, v32, v33
	v_cvt_pk_bf16_f32 v25, v30, v31
	v_mad_i64_i32 v[30:31], s[18:19], v29, s84, v[122:123]
	v_cvt_pk_bf16_f32 v26, v26, v27
	v_cvt_pk_bf16_f32 v27, v34, v35
	v_lshl_add_u64 v[30:31], v[30:31], 0, v[124:125]
	global_store_dwordx4 v[30:31], v[24:27], off sc1
	s_nop 1
	v_mul_f32_e64 v20, v20, v28
	v_mul_f32_e64 v21, v21, v28
	v_mul_f32_e64 v24, v14, v28
	v_mul_f32_e64 v25, v15, v28
	v_mul_f32_e64 v14, v12, v28
	v_mul_f32_e64 v15, v13, v28
	v_mul_f32_e64 v22, v22, v28
	v_mul_f32_e64 v23, v23, v28
	v_cvt_pk_bf16_f32 v12, v20, v21
	v_lshl_add_u64 v[20:21], v[30:31], 0, s[66:67]
	v_cvt_pk_bf16_f32 v13, v22, v23
	v_cvt_pk_bf16_f32 v14, v14, v15
	v_cvt_pk_bf16_f32 v15, v24, v25
	s_nop 0
	global_store_dwordx4 v[20:21], v[12:15], off sc1
	s_nop 1
	ds_read_b32 v12, v147 offset:704
	v_add_u32_e32 v13, 0xb0, v149
	s_waitcnt lgkmcnt(0)
	v_mul_f32_e64 v14, v18, v12
	v_mul_f32_e64 v15, v19, v12
	v_mul_f32_e64 v16, v16, v12
	v_mul_f32_e64 v17, v17, v12
	v_mul_f32_e64 v18, v10, v12
	v_mul_f32_e64 v19, v11, v12
	v_mul_f32_e64 v10, v8, v12
	v_mul_f32_e64 v11, v9, v12
	v_cvt_pk_bf16_f32 v8, v16, v17
	v_cvt_pk_bf16_f32 v9, v14, v15
	v_mad_i64_i32 v[14:15], s[18:19], v13, s84, v[122:123]
	v_cvt_pk_bf16_f32 v10, v10, v11
	v_cvt_pk_bf16_f32 v11, v18, v19
	v_lshl_add_u64 v[14:15], v[14:15], 0, v[124:125]
	global_store_dwordx4 v[14:15], v[8:11], off sc1
	s_nop 1
	v_mul_f32_e64 v4, v4, v12
	v_mul_f32_e64 v5, v5, v12
	v_mul_f32_e64 v8, v2, v12
	v_mul_f32_e64 v9, v3, v12
	v_mul_f32_e64 v2, v0, v12
	v_mul_f32_e64 v3, v1, v12
	v_mul_f32_e64 v6, v6, v12
	v_mul_f32_e64 v7, v7, v12
	v_cvt_pk_bf16_f32 v0, v4, v5
	v_lshl_add_u64 v[4:5], v[14:15], 0, s[66:67]
	v_cvt_pk_bf16_f32 v1, v6, v7
	v_cvt_pk_bf16_f32 v2, v2, v3
	v_cvt_pk_bf16_f32 v3, v8, v9
	s_nop 0
	global_store_dwordx4 v[4:5], v[0:3], off sc1
	s_nop 1
	s_cbranch_vccnz .LBB0_853
	s_andn2_b64 vcc, exec, s[6:7]
	s_cbranch_vccnz .LBB0_852
	s_barrier
	s_branch .LBB0_852

.LBB0_890:
	s_and_b32 s4, s57, 1
	v_lshl_add_u32 v143, s4, 10, v140
	ds_read_b32 v144, v143
	v_lshl_add_u32 v148, s55, 8, v136
	v_lshl_or_b32 v146, s56, 8, v138
	v_ashrrev_i32_e32 v149, 31, v148
	v_ashrrev_i32_e32 v147, 31, v146
	s_waitcnt lgkmcnt(0)
	v_mul_f32_e64 v126, v126, v144
	v_mul_f32_e64 v127, v127, v144
	v_mul_f32_e64 v122, v122, v144
	v_mul_f32_e64 v123, v123, v144
	v_mul_f32_e64 v128, v128, v144
	v_mul_f32_e64 v129, v129, v144
	v_mul_f32_e64 v150, v124, v144
	v_mul_f32_e64 v151, v125, v144
	v_cvt_pk_bf16_f32 v124, v126, v127
	v_cvt_pk_bf16_f32 v125, v128, v129
	v_cvt_pk_bf16_f32 v126, v122, v123
	v_lshlrev_b64 v[122:123], 10, v[148:149]
	v_lshl_add_u64 v[122:123], s[10:11], 0, v[122:123]
	v_lshlrev_b64 v[128:129], 1, v[146:147]
	v_cvt_pk_bf16_f32 v127, v150, v151
	v_lshl_add_u64 v[122:123], v[122:123], 0, v[128:129]
	global_store_dwordx4 v[122:123], v[124:127], off sc1
	s_nop 1
	v_mul_f32_e64 v118, v118, v144
	v_mul_f32_e64 v119, v119, v144
	v_mul_f32_e64 v124, v116, v144
	v_mul_f32_e64 v125, v117, v144
	v_mul_f32_e64 v116, v114, v144
	v_mul_f32_e64 v117, v115, v144
	v_mul_f32_e64 v120, v120, v144
	v_mul_f32_e64 v121, v121, v144
	v_cvt_pk_bf16_f32 v114, v118, v119
	v_lshl_add_u64 v[118:119], v[122:123], 0, s[66:67]
	v_cvt_pk_bf16_f32 v115, v120, v121
	v_cvt_pk_bf16_f32 v116, v116, v117
	v_cvt_pk_bf16_f32 v117, v124, v125
	s_mov_b64 s[4:5], 0x20000
	global_store_dwordx4 v[118:119], v[114:117], off sc1
	s_nop 1
	ds_read_b32 v114, v143 offset:64
	v_or_b32_e32 v116, 16, v148
	v_ashrrev_i32_e32 v117, 31, v116
	s_and_b64 vcc, exec, s[2:3]
	s_mov_b64 s[2:3], -1
	s_waitcnt lgkmcnt(0)
	v_mul_f32_e64 v110, v110, v114
	v_mul_f32_e64 v111, v111, v114
	v_mul_f32_e64 v118, v108, v114
	v_mul_f32_e64 v119, v109, v114
	v_mul_f32_e64 v108, v106, v114
	v_mul_f32_e64 v109, v107, v114
	v_cvt_pk_bf16_f32 v106, v110, v111
	v_lshlrev_b64 v[110:111], 10, v[116:117]
	v_mul_f32_e64 v112, v112, v114
	v_mul_f32_e64 v113, v113, v114
	v_lshl_add_u64 v[110:111], s[10:11], 0, v[110:111]
	v_cvt_pk_bf16_f32 v107, v112, v113
	v_cvt_pk_bf16_f32 v108, v108, v109
	v_cvt_pk_bf16_f32 v109, v118, v119
	v_lshl_add_u64 v[110:111], v[110:111], 0, v[128:129]
	global_store_dwordx4 v[110:111], v[106:109], off sc1
	s_nop 1
	v_mul_f32_e64 v102, v102, v114
	v_mul_f32_e64 v103, v103, v114
	v_mul_f32_e64 v106, v100, v114
	v_mul_f32_e64 v107, v101, v114
	v_mul_f32_e64 v100, v98, v114
	v_mul_f32_e64 v101, v99, v114
	v_mul_f32_e64 v104, v104, v114
	v_mul_f32_e64 v105, v105, v114
	v_cvt_pk_bf16_f32 v98, v102, v103
	v_lshl_add_u64 v[102:103], v[110:111], 0, s[66:67]
	v_cvt_pk_bf16_f32 v99, v104, v105
	v_cvt_pk_bf16_f32 v100, v100, v101
	v_cvt_pk_bf16_f32 v101, v106, v107
	s_nop 0
	global_store_dwordx4 v[102:103], v[98:101], off sc1
	s_nop 1
	ds_read_b32 v98, v143 offset:128
	v_or_b32_e32 v100, 32, v148
	v_ashrrev_i32_e32 v101, 31, v100
	s_waitcnt lgkmcnt(0)
	v_mul_f32_e64 v92, v92, v98
	v_mul_f32_e64 v93, v93, v98
	v_mul_f32_e64 v102, v90, v98
	v_mul_f32_e64 v103, v91, v98
	v_mul_f32_e64 v90, v88, v98
	v_mul_f32_e64 v91, v89, v98
	v_cvt_pk_bf16_f32 v88, v92, v93
	v_lshlrev_b64 v[92:93], 10, v[100:101]
	v_mul_f32_e64 v94, v94, v98
	v_mul_f32_e64 v95, v95, v98
	v_lshl_add_u64 v[92:93], s[10:11], 0, v[92:93]
	v_cvt_pk_bf16_f32 v89, v94, v95
	v_cvt_pk_bf16_f32 v90, v90, v91
	v_cvt_pk_bf16_f32 v91, v102, v103
	v_lshl_add_u64 v[92:93], v[92:93], 0, v[128:129]
	global_store_dwordx4 v[92:93], v[88:91], off sc1
	s_nop 1
	v_mul_f32_e64 v84, v84, v98
	v_mul_f32_e64 v85, v85, v98
	v_mul_f32_e64 v88, v82, v98
	v_mul_f32_e64 v89, v83, v98
	v_mul_f32_e64 v82, v80, v98
	v_mul_f32_e64 v83, v81, v98
	v_mul_f32_e64 v86, v86, v98
	v_mul_f32_e64 v87, v87, v98
	v_cvt_pk_bf16_f32 v80, v84, v85
	v_lshl_add_u64 v[84:85], v[92:93], 0, s[66:67]
	v_cvt_pk_bf16_f32 v81, v86, v87
	v_cvt_pk_bf16_f32 v82, v82, v83
	v_cvt_pk_bf16_f32 v83, v88, v89
	s_nop 0
	global_store_dwordx4 v[84:85], v[80:83], off sc1
	s_nop 1
	ds_read_b32 v80, v143 offset:192
	v_or_b32_e32 v82, 48, v148
	v_ashrrev_i32_e32 v83, 31, v82
	s_waitcnt lgkmcnt(0)
	v_mul_f32_e64 v76, v76, v80
	v_mul_f32_e64 v77, v77, v80
	v_mul_f32_e64 v84, v74, v80
	v_mul_f32_e64 v85, v75, v80
	v_mul_f32_e64 v74, v72, v80
	v_mul_f32_e64 v75, v73, v80
	v_cvt_pk_bf16_f32 v72, v76, v77
	v_lshlrev_b64 v[76:77], 10, v[82:83]
	v_mul_f32_e64 v78, v78, v80
	v_mul_f32_e64 v79, v79, v80
	v_lshl_add_u64 v[76:77], s[10:11], 0, v[76:77]
	v_cvt_pk_bf16_f32 v73, v78, v79
	v_cvt_pk_bf16_f32 v74, v74, v75
	v_cvt_pk_bf16_f32 v75, v84, v85
	v_lshl_add_u64 v[76:77], v[76:77], 0, v[128:129]
	global_store_dwordx4 v[76:77], v[72:75], off sc1
	s_nop 1
	v_mul_f32_e64 v68, v68, v80
	v_mul_f32_e64 v69, v69, v80
	v_mul_f32_e64 v72, v66, v80
	v_mul_f32_e64 v73, v67, v80
	v_mul_f32_e64 v66, v64, v80
	v_mul_f32_e64 v67, v65, v80
	v_mul_f32_e64 v70, v70, v80
	v_mul_f32_e64 v71, v71, v80
	v_cvt_pk_bf16_f32 v64, v68, v69
	v_lshl_add_u64 v[68:69], v[76:77], 0, s[66:67]
	v_cvt_pk_bf16_f32 v65, v70, v71
	v_cvt_pk_bf16_f32 v66, v66, v67
	v_cvt_pk_bf16_f32 v67, v72, v73
	s_nop 0
	global_store_dwordx4 v[68:69], v[64:67], off sc1
	s_nop 1
	ds_read_b32 v64, v143 offset:512
	s_waitcnt lgkmcnt(0)
	v_mul_f32_e64 v62, v62, v64
	v_mul_f32_e64 v63, v63, v64
	v_mul_f32_e64 v60, v60, v64
	v_mul_f32_e64 v61, v61, v64
	v_mul_f32_e64 v66, v58, v64
	v_mul_f32_e64 v67, v59, v64
	v_mul_f32_e64 v58, v56, v64
	v_mul_f32_e64 v59, v57, v64
	v_cvt_pk_bf16_f32 v56, v60, v61
	v_cvt_pk_bf16_f32 v57, v62, v63
	v_lshl_add_u64 v[60:61], v[122:123], 0, s[4:5]
	v_cvt_pk_bf16_f32 v58, v58, v59
	v_cvt_pk_bf16_f32 v59, v66, v67
	v_mul_f32_e64 v52, v52, v64
	v_mul_f32_e64 v53, v53, v64
	global_store_dwordx4 v[60:61], v[56:59], off sc1
	s_nop 1
	v_mul_f32_e64 v56, v46, v64
	v_mul_f32_e64 v57, v47, v64
	v_mul_f32_e64 v46, v44, v64
	v_mul_f32_e64 v47, v45, v64
	s_mov_b64 s[4:5], 0x20100
	v_mul_f32_e64 v54, v54, v64
	v_mul_f32_e64 v55, v55, v64
	v_cvt_pk_bf16_f32 v44, v52, v53
	v_lshl_add_u64 v[52:53], v[122:123], 0, s[4:5]
	v_cvt_pk_bf16_f32 v45, v54, v55
	v_cvt_pk_bf16_f32 v46, v46, v47
	v_cvt_pk_bf16_f32 v47, v56, v57
	s_mov_b64 s[4:5], 0x24000
	global_store_dwordx4 v[52:53], v[44:47], off sc1
	s_nop 1
	ds_read_b32 v44, v143 offset:576
	s_waitcnt lgkmcnt(0)
	v_mul_f32_e64 v46, v50, v44
	v_mul_f32_e64 v47, v51, v44
	v_mul_f32_e64 v48, v48, v44
	v_mul_f32_e64 v49, v49, v44
	v_mul_f32_e64 v50, v42, v44
	v_mul_f32_e64 v51, v43, v44
	v_mul_f32_e64 v42, v40, v44
	v_mul_f32_e64 v43, v41, v44
	v_cvt_pk_bf16_f32 v40, v48, v49
	v_cvt_pk_bf16_f32 v41, v46, v47
	v_lshl_add_u64 v[46:47], v[122:123], 0, s[4:5]
	v_cvt_pk_bf16_f32 v42, v42, v43
	v_cvt_pk_bf16_f32 v43, v50, v51
	v_mul_f32_e64 v36, v36, v44
	v_mul_f32_e64 v37, v37, v44
	global_store_dwordx4 v[46:47], v[40:43], off sc1
	s_nop 1
	v_mul_f32_e64 v40, v30, v44
	v_mul_f32_e64 v41, v31, v44
	v_mul_f32_e64 v30, v28, v44
	v_mul_f32_e64 v31, v29, v44
	s_mov_b64 s[4:5], 0x24100
	v_mul_f32_e64 v38, v38, v44
	v_mul_f32_e64 v39, v39, v44
	v_cvt_pk_bf16_f32 v28, v36, v37
	v_lshl_add_u64 v[36:37], v[122:123], 0, s[4:5]
	v_cvt_pk_bf16_f32 v29, v38, v39
	v_cvt_pk_bf16_f32 v30, v30, v31
	v_cvt_pk_bf16_f32 v31, v40, v41
	s_mov_b64 s[4:5], 0x28000
	global_store_dwordx4 v[36:37], v[28:31], off sc1
	s_nop 1
	ds_read_b32 v28, v143 offset:640
	s_waitcnt lgkmcnt(0)
	v_mul_f32_e64 v30, v34, v28
	v_mul_f32_e64 v31, v35, v28
	v_mul_f32_e64 v32, v32, v28
	v_mul_f32_e64 v33, v33, v28
	v_mul_f32_e64 v34, v26, v28
	v_mul_f32_e64 v35, v27, v28
	v_mul_f32_e64 v26, v24, v28
	v_mul_f32_e64 v27, v25, v28
	v_cvt_pk_bf16_f32 v24, v32, v33
	v_cvt_pk_bf16_f32 v25, v30, v31
	v_lshl_add_u64 v[30:31], v[122:123], 0, s[4:5]
	v_cvt_pk_bf16_f32 v26, v26, v27
	v_cvt_pk_bf16_f32 v27, v34, v35
	v_mul_f32_e64 v20, v20, v28
	v_mul_f32_e64 v21, v21, v28
	global_store_dwordx4 v[30:31], v[24:27], off sc1
	s_nop 1
	v_mul_f32_e64 v24, v14, v28
	v_mul_f32_e64 v25, v15, v28
	v_mul_f32_e64 v14, v12, v28
	v_mul_f32_e64 v15, v13, v28
	s_mov_b64 s[4:5], 0x28100
	v_mul_f32_e64 v22, v22, v28
	v_mul_f32_e64 v23, v23, v28
	v_cvt_pk_bf16_f32 v12, v20, v21
	v_lshl_add_u64 v[20:21], v[122:123], 0, s[4:5]
	v_cvt_pk_bf16_f32 v13, v22, v23
	v_cvt_pk_bf16_f32 v14, v14, v15
	v_cvt_pk_bf16_f32 v15, v24, v25
	s_mov_b64 s[4:5], 0x2c000
	global_store_dwordx4 v[20:21], v[12:15], off sc1
	s_nop 1
	ds_read_b32 v12, v143 offset:704
	s_waitcnt lgkmcnt(0)
	v_mul_f32_e64 v14, v18, v12
	v_mul_f32_e64 v15, v19, v12
	v_mul_f32_e64 v16, v16, v12
	v_mul_f32_e64 v17, v17, v12
	v_mul_f32_e64 v18, v10, v12
	v_mul_f32_e64 v19, v11, v12
	v_mul_f32_e64 v10, v8, v12
	v_mul_f32_e64 v11, v9, v12
	v_cvt_pk_bf16_f32 v8, v16, v17
	v_cvt_pk_bf16_f32 v9, v14, v15
	v_lshl_add_u64 v[14:15], v[122:123], 0, s[4:5]
	v_cvt_pk_bf16_f32 v10, v10, v11
	v_cvt_pk_bf16_f32 v11, v18, v19
	v_mul_f32_e64 v4, v4, v12
	v_mul_f32_e64 v5, v5, v12
	global_store_dwordx4 v[14:15], v[8:11], off sc1
	s_nop 1
	v_mul_f32_e64 v8, v2, v12
	v_mul_f32_e64 v9, v3, v12
	v_mul_f32_e64 v2, v0, v12
	v_mul_f32_e64 v3, v1, v12
	s_mov_b64 s[4:5], 0x2c100
	v_mul_f32_e64 v6, v6, v12
	v_mul_f32_e64 v7, v7, v12
	v_cvt_pk_bf16_f32 v0, v4, v5
	v_lshl_add_u64 v[4:5], v[122:123], 0, s[4:5]
	v_cvt_pk_bf16_f32 v1, v6, v7
	v_cvt_pk_bf16_f32 v2, v2, v3
	v_cvt_pk_bf16_f32 v3, v8, v9
	s_nop 0
	global_store_dwordx4 v[4:5], v[0:3], off sc1
	s_nop 1
	s_cbranch_vccnz .LBB0_875
	s_andn2_b64 vcc, exec, s[8:9]
	s_cbranch_vccnz .LBB0_874
	s_barrier
	s_branch .LBB0_874

.LBB0_972:
	v_ashrrev_i32_e32 v74, 3, v49
	v_mad_i64_i32 v[0:1], s[2:3], v74, s84, v[44:45]
	global_load_dwordx4 v[66:69], v[0:1], off
	global_load_dwordx4 v[70:73], v[0:1], off offset:64
	global_load_dwordx4 v[12:15], v[0:1], off offset:128
	v_cvt_f64_i32_e32 v[64:65], v74
	v_mul_f64 v[50:51], v[16:17], v[64:65]
	v_mul_f64 v[52:53], v[50:51], s[58:59]
	v_rndne_f64_e32 v[52:53], v[52:53]
	v_fma_f64 v[50:51], v[50:51], s[58:59], -v[52:53]
	v_mul_f64 v[52:53], v[18:19], v[64:65]
	v_mul_f64 v[54:55], v[52:53], s[58:59]
	v_rndne_f64_e32 v[54:55], v[54:55]
	v_fma_f64 v[52:53], v[52:53], s[58:59], -v[54:55]
	v_mul_f64 v[54:55], v[20:21], v[64:65]
	v_mul_f64 v[56:57], v[54:55], s[58:59]
	v_rndne_f64_e32 v[56:57], v[56:57]
	v_fma_f64 v[54:55], v[54:55], s[58:59], -v[56:57]
	v_mul_f64 v[56:57], v[22:23], v[64:65]
	v_mul_f64 v[58:59], v[56:57], s[58:59]
	v_rndne_f64_e32 v[58:59], v[58:59]
	v_fma_f64 v[56:57], v[56:57], s[58:59], -v[58:59]
	v_mul_f64 v[58:59], v[24:25], v[64:65]
	v_mul_f64 v[60:61], v[58:59], s[58:59]
	v_rndne_f64_e32 v[60:61], v[60:61]
	v_fma_f64 v[58:59], v[58:59], s[58:59], -v[60:61]
	v_mul_f64 v[60:61], v[26:27], v[64:65]
	v_mul_f64 v[62:63], v[60:61], s[58:59]
	v_rndne_f64_e32 v[62:63], v[62:63]
	v_fma_f64 v[60:61], v[60:61], s[58:59], -v[62:63]
	v_mul_f64 v[62:63], v[28:29], v[64:65]
	v_ashrrev_i32_e32 v75, 31, v74
	v_mul_f64 v[76:77], v[62:63], s[58:59]
	v_lshlrev_b64 v[0:1], 10, v[74:75]
	v_rndne_f64_e32 v[76:77], v[76:77]
	v_mul_f64 v[64:65], v[30:31], v[64:65]
	v_lshl_add_u64 v[0:1], v[46:47], 0, v[0:1]
	v_fma_f64 v[62:63], v[62:63], s[58:59], -v[76:77]
	v_mul_f64 v[76:77], v[64:65], s[58:59]
	global_load_dwordx4 v[8:11], v[0:1], off
	global_load_dwordx4 v[4:7], v[0:1], off offset:64
	v_mov_b64_e32 v[0:1], s[4:5]
	v_rndne_f64_e32 v[76:77], v[76:77]
	v_mad_i64_i32 v[0:1], s[2:3], v74, s77, v[0:1]
	v_fma_f64 v[64:65], v[64:65], s[58:59], -v[76:77]
	v_add_u32_e32 v88, v48, v74
	v_lshl_add_u64 v[0:1], v[0:1], 0, v[96:97]
	s_mov_b32 s2, 0xc200000
	v_add_co_u32_e64 v0, s[2:3], s2, v0
	v_cvt_f32_f64_e32 v51, v[50:51]
	s_nop 0
	v_addc_co_u32_e64 v1, s[2:3], 0, v1, s[2:3]
	global_load_dwordx4 v[0:3], v[0:1], off offset:2304
	v_cos_f32_e32 v50, v51
	v_sin_f32_e32 v51, v51
	v_cvt_f32_f64_e32 v53, v[52:53]
	v_cos_f32_e32 v52, v53
	v_sin_f32_e32 v53, v53
	v_cvt_f32_f64_e32 v55, v[54:55]
	v_cos_f32_e32 v54, v55
	v_sin_f32_e32 v55, v55
	v_cvt_f32_f64_e32 v57, v[56:57]
	v_cvt_f32_f64_e32 v59, v[58:59]
	v_cos_f32_e32 v56, v57
	v_sin_f32_e32 v57, v57
	v_cos_f32_e32 v58, v59
	v_sin_f32_e32 v59, v59
	v_cvt_f32_f64_e32 v61, v[60:61]
	v_cos_f32_e32 v60, v61
	v_sin_f32_e32 v61, v61
	v_cvt_f32_f64_e32 v63, v[62:63]
	v_cos_f32_e32 v62, v63
	v_sin_f32_e32 v63, v63
	v_cvt_f32_f64_e32 v65, v[64:65]
	v_cos_f32_e32 v64, v65
	v_sin_f32_e32 v65, v65
	v_add_u32_e32 v49, s12, v49
	s_waitcnt vmcnt(5)
	v_and_b32_e32 v81, 0xffff0000, v67
	v_and_b32_e32 v83, 0xffff0000, v66
	v_and_b32_e32 v82, 0xffff0000, v68
	v_lshlrev_b32_e32 v80, 16, v67
	v_mul_f32_e32 v74, v81, v81
	v_lshlrev_b32_e32 v85, 16, v66
	v_lshlrev_b32_e32 v84, 16, v68
	v_mul_f32_e64 v66, v82, v82
	v_mul_f32_e64 v67, v83, v83
	s_waitcnt vmcnt(4)
	v_and_b32_e32 v79, 0xffff0000, v70
	v_and_b32_e32 v77, 0xffff0000, v71
	v_fma_f32 v75, v81, v81, v74
	v_fma_f32 v74, v80, v80, v74
	v_fma_f32 v66, v84, v84, v66
	v_fma_f32 v67, v85, v85, v67
	v_lshlrev_b32_e32 v78, 16, v70
	v_lshlrev_b32_e32 v76, 16, v71
	s_waitcnt vmcnt(3)
	v_lshlrev_b32_e32 v90, 16, v13
	v_and_b32_e32 v91, 0xffff0000, v13
	v_mul_f32_e32 v98, v79, v79
	v_mul_f32_e32 v100, v77, v77
	v_add_f32_e64 v74, v67, v74
	v_add_f32_e64 v75, v66, v75
	v_lshlrev_b32_e32 v92, 16, v69
	v_and_b32_e32 v93, 0xffff0000, v69
	v_mul_f32_e32 v95, v90, v90
	v_mul_f32_e32 v102, v91, v91
	v_and_b32_e32 v69, 0xffff0000, v12
	v_and_b32_e32 v68, 0xffff0000, v72
	v_fma_f32 v99, v79, v79, v98
	v_fma_f32 v98, v78, v78, v98
	v_fma_f32 v101, v77, v77, v100
	v_fma_f32 v100, v76, v76, v100
	v_add_f32_e64 v86, v66, v74
	v_add_f32_e64 v87, v67, v75
	v_lshlrev_b32_e32 v71, 16, v12
	v_lshlrev_b32_e32 v70, 16, v72
	v_mul_f32_e64 v74, v68, v68
	v_mul_f32_e64 v75, v69, v69
	v_mov_b32_e32 v99, v95
	v_mov_b32_e32 v101, v102
	v_fma_f32 v74, v70, v70, v74
	v_fma_f32 v75, v71, v71, v75
	v_add_f32_e64 v98, v98, v100
	v_add_f32_e64 v99, v99, v101
	v_pk_mov_b32 v[100:101], v[72:73], v[14:15] op_sel:[1,0]
	v_add_f32_e64 v98, v74, v98
	v_add_f32_e64 v99, v75, v99
	v_lshlrev_b32_e32 v74, 16, v73
	v_and_b32_e32 v73, 0xffff0000, v101
	v_and_b32_e32 v72, 0xffff0000, v100
	v_lshlrev_b32_e32 v67, 16, v15
	v_lshlrev_b32_e32 v75, 16, v14
	v_mul_f32_e64 v100, v72, v72
	v_mul_f32_e64 v101, v73, v73
	v_mul_f32_e32 v66, v92, v92
	v_mul_f32_e32 v94, v93, v93
	v_fma_f32 v100, v74, v74, v100
	v_fma_f32 v101, v75, v75, v101
	v_mov_b32_e32 v95, v67
	v_and_b32_e32 v89, 0xffff0000, v15
	v_add_f32_e64 v98, v100, v98
	v_add_f32_e64 v99, v101, v99
	v_add_f32_e64 v94, v66, v94
	v_add_f32_e64 v95, v67, v95
	v_mul_f32_e64 v100, v66, v66
	v_mul_f32_e64 v101, v67, v67
	v_mul_f32_e32 v87, v89, v89
	v_mov_b32_e32 v95, v101
	v_add_f32_e64 v86, v94, v86
	v_add_f32_e64 v87, v95, v87
	s_nop 0
	v_add_f32_e64 v86, v86, v98
	v_add_f32_e64 v87, v87, v99
	s_nop 0
	v_add_f32_e32 v66, v86, v87
	v_mov_b32_e32 v86, v248
	s_nop 0
	v_lshlrev_b32_e32 v86, 2, v86
	v_xor_b32_e32 v86, 4, v86
	ds_bpermute_b32 v86, v86, v66
	s_waitcnt lgkmcnt(0)
	v_add_f32_e32 v66, v66, v86
	v_mov_b32_e32 v86, v248
	global_load_dwordx4 v[98:101], v[34:35], off offset:16
	global_load_dwordx4 v[102:105], v[34:35], off
	v_lshlrev_b32_e32 v86, 2, v86
	v_xor_b32_e32 v86, 8, v86
	ds_bpermute_b32 v86, v86, v66
	s_waitcnt lgkmcnt(0)
	v_add_f32_e32 v66, v66, v86
	v_fmamk_f32 v66, v66, 0x3c2aaaab, v249
	v_rsq_f32_e32 v66, v66
	v_mad_i64_i32 v[86:87], s[2:3], v88, s63, v[32:33]
	v_mul_f32_e32 v106, 0x3e16c740, v66
	v_mul_f32_e32 v66, v106, v85
	v_mul_f32_e32 v83, v106, v83
	v_mul_f32_e32 v68, v106, v68
	s_waitcnt vmcnt(0)
	v_mul_f32_e32 v66, v102, v66
	v_mul_f32_e32 v83, v103, v83
	v_cvt_pk_bf16_f32 v102, v66, v83
	v_mul_f32_e32 v66, v106, v80
	v_mul_f32_e32 v80, v106, v81
	v_mul_f32_e32 v66, v104, v66
	v_mul_f32_e32 v80, v105, v80
	v_cvt_pk_bf16_f32 v103, v66, v80
	v_mul_f32_e32 v66, v106, v84
	v_mul_f32_e32 v80, v106, v82
	v_mul_f32_e32 v66, v98, v66
	v_mul_f32_e32 v80, v99, v80
	v_cvt_pk_bf16_f32 v104, v66, v80
	v_mul_f32_e32 v66, v106, v92
	v_mul_f32_e32 v80, v106, v93
	v_mul_f32_e32 v66, v100, v66
	v_mul_f32_e32 v80, v101, v80
	v_cvt_pk_bf16_f32 v105, v66, v80
	global_store_dwordx4 v[86:87], v[102:105], off
	global_load_dwordx4 v[80:83], v[34:35], off offset:144
	global_load_dwordx4 v[92:95], v[34:35], off offset:128
	v_mul_f32_e32 v66, v106, v78
	v_mul_f32_e32 v78, v106, v79
	s_waitcnt vmcnt(1)
	v_mul_f32_e32 v68, v68, v81
	s_waitcnt vmcnt(0)
	v_mul_f32_e32 v66, v92, v66
	v_mul_f32_e32 v78, v93, v78
	v_cvt_pk_bf16_f32 v78, v66, v78
	v_mul_f32_e32 v66, v106, v76
	v_mul_f32_e32 v66, v94, v66
	v_mul_f32_e32 v76, v106, v77
	v_mul_f32_e32 v76, v95, v76
	v_cvt_pk_bf16_f32 v79, v66, v76
	v_mul_f32_e32 v66, v106, v70
	v_mul_f32_e32 v66, v66, v80
	v_cvt_pk_bf16_f32 v80, v66, v68
	v_mul_f32_e32 v66, v106, v74
	v_mul_f32_e32 v66, v66, v82
	v_mul_f32_e32 v68, v106, v72
	v_mul_f32_e32 v68, v68, v83
	v_cvt_pk_bf16_f32 v81, v66, v68
	v_mov_b32_e32 v66, v248
	global_store_dwordx4 v[86:87], v[78:81], off offset:64
	v_mul_f32_e32 v68, v106, v69
	v_lshlrev_b32_e32 v66, 2, v66
	v_xor_b32_e32 v66, 8, v66
	ds_bpermute_b32 v84, v66, v12
	v_mov_b32_e32 v12, v248
	v_mul_f32_e32 v69, v106, v90
	v_lshlrev_b32_e32 v12, 2, v12
	v_xor_b32_e32 v12, 8, v12
	ds_bpermute_b32 v85, v12, v13
	v_mov_b32_e32 v12, v248
	v_mul_f32_e32 v66, v106, v71
	v_lshlrev_b32_e32 v12, 2, v12
	v_xor_b32_e32 v12, 8, v12
	ds_bpermute_b32 v98, v12, v14
	v_mov_b32_e32 v12, v248
	s_nop 0
	v_lshlrev_b32_e32 v12, 2, v12
	v_xor_b32_e32 v12, 8, v12
	ds_bpermute_b32 v99, v12, v15
	global_load_dwordx4 v[12:15], v[34:35], off offset:272
	global_load_dwordx4 v[76:79], v[34:35], off offset:256
	global_load_dwordx4 v[80:83], v[36:37], off offset:272
	global_load_dwordx4 v[92:95], v[36:37], off offset:256
	s_waitcnt vmcnt(2)
	v_mul_f32_e32 v70, v69, v78
	v_mul_f32_e32 v69, v106, v91
	v_mul_f32_e32 v72, v69, v79
	v_mul_f32_e32 v69, v106, v75
	v_mul_f32_e32 v12, v69, v12
	v_mul_f32_e32 v69, v106, v73
	v_mul_f32_e32 v74, v69, v13
	v_mul_f32_e32 v13, v106, v67
	s_waitcnt lgkmcnt(2)
	v_lshlrev_b32_e32 v67, 16, v85
	v_mul_f32_e32 v67, v106, v67
	s_waitcnt vmcnt(0)
	v_mul_f32_e32 v71, v67, v94
	v_and_b32_e32 v67, 0xffff0000, v85
	v_mul_f32_e32 v67, v106, v67
	v_mul_f32_e32 v73, v67, v95
	s_waitcnt lgkmcnt(1)
	v_lshlrev_b32_e32 v67, 16, v98
	v_mul_f32_e32 v67, v106, v67
	v_mul_f32_e32 v75, v67, v80
	v_and_b32_e32 v67, 0xffff0000, v98
	v_mul_f32_e32 v67, v106, v67
	v_mul_f32_e32 v68, v68, v77
	v_mul_f32_e32 v14, v13, v14
	v_mul_f32_e32 v13, v106, v89
	v_mul_f32_e32 v77, v67, v81
	s_waitcnt lgkmcnt(0)
	v_lshlrev_b32_e32 v67, 16, v99
	v_mul_f32_e32 v66, v66, v76
	v_mul_f32_e32 v76, v13, v15
	v_lshlrev_b32_e32 v13, 16, v84
	v_mul_f32_e32 v67, v106, v67
	v_mul_f32_e32 v13, v106, v13
	v_and_b32_e32 v15, 0xffff0000, v84
	v_mul_f32_e32 v78, v67, v82
	v_and_b32_e32 v67, 0xffff0000, v99
	v_mul_f32_e32 v13, v13, v92
	v_mul_f32_e32 v15, v106, v15
	v_mul_f32_e32 v67, v106, v67
	v_mul_f32_e32 v15, v15, v93
	v_mul_f32_e32 v79, v67, v83
	v_cndmask_b32_e64 v67, v13, -v13, vcc
	v_mul_f32_e64 v66, v50, v66
	v_mul_f32_e64 v67, v51, v67
	v_cndmask_b32_e64 v69, v15, -v15, vcc
	v_add_f32_e32 v80, v66, v67
	v_mul_f32_e64 v66, v52, v68
	v_mul_f32_e64 v67, v53, v69
	v_cndmask_b32_e64 v71, v71, -v71, vcc
	v_add_f32_e32 v68, v66, v67
	v_mul_f32_e64 v66, v54, v70
	v_mul_f32_e64 v67, v55, v71
	v_cndmask_b32_e64 v73, v73, -v73, vcc
	v_cndmask_b32_e64 v13, v75, -v75, vcc
	v_add_f32_e32 v69, v66, v67
	v_mul_f32_e64 v66, v56, v72
	v_mul_f32_e64 v67, v57, v73
	v_mul_f32_e64 v12, v58, v12
	v_mul_f32_e64 v13, v59, v13
	v_cndmask_b32_e64 v75, v77, -v77, vcc
	v_add_f32_e32 v66, v66, v67
	v_add_f32_e32 v67, v12, v13
	v_mul_f32_e64 v12, v60, v74
	v_mul_f32_e64 v13, v61, v75
	v_cndmask_b32_e64 v15, v78, -v78, vcc
	v_add_f32_e32 v70, v12, v13
	v_mul_f32_e64 v12, v62, v14
	v_mul_f32_e64 v13, v63, v15
	v_cndmask_b32_e64 v77, v79, -v79, vcc
	v_add_f32_e32 v15, v12, v13
	v_mul_f32_e64 v12, v64, v76
	v_mul_f32_e64 v13, v65, v77
	v_and_b32_e32 v77, 0xffff0000, v9
	v_add_f32_e32 v71, v12, v13
	v_cvt_pk_bf16_f32 v12, v80, v68
	v_cvt_pk_bf16_f32 v13, v69, v66
	v_cvt_pk_bf16_f32 v14, v67, v70
	v_cvt_pk_bf16_f32 v15, v15, v71
	v_and_b32_e32 v71, 0xffff0000, v4
	global_store_dwordx4 v[86:87], v[12:15], off offset:128
	v_and_b32_e32 v73, 0xffff0000, v8
	v_and_b32_e32 v72, 0xffff0000, v10
	v_lshlrev_b32_e32 v70, 16, v4
	v_lshlrev_b32_e32 v81, 16, v1
	v_mul_f32_e32 v14, v71, v71
	v_lshlrev_b32_e32 v76, 16, v9
	v_mul_f32_e32 v12, v77, v77
	v_lshlrev_b32_e32 v75, 16, v8
	v_lshlrev_b32_e32 v74, 16, v10
	v_mul_f32_e64 v8, v72, v72
	v_mul_f32_e64 v9, v73, v73
	v_and_b32_e32 v69, 0xffff0000, v5
	v_mul_f32_e32 v66, v81, v81
	v_fma_f32 v15, v71, v71, v14
	v_fma_f32 v14, v70, v70, v14
	v_fma_f32 v13, v77, v77, v12
	v_fma_f32 v12, v76, v76, v12
	v_fma_f32 v8, v74, v74, v8
	v_fma_f32 v9, v75, v75, v9
	v_lshlrev_b32_e32 v68, 16, v5
	v_and_b32_e32 v82, 0xffff0000, v1
	v_mov_b32_e32 v15, v66
	v_mul_f32_e32 v66, v69, v69
	v_add_f32_e64 v12, v9, v12
	v_add_f32_e64 v13, v8, v13
	v_lshlrev_b32_e32 v84, 16, v11
	v_and_b32_e32 v83, 0xffff0000, v11
	v_mul_f32_e32 v85, v82, v82
	v_and_b32_e32 v11, 0xffff0000, v0
	v_and_b32_e32 v10, 0xffff0000, v6
	v_fma_f32 v67, v69, v69, v66
	v_fma_f32 v66, v68, v68, v66
	v_add_f32_e64 v78, v8, v12
	v_add_f32_e64 v79, v9, v13
	v_lshlrev_b32_e32 v13, 16, v0
	v_lshlrev_b32_e32 v12, 16, v6
	v_mul_f32_e64 v4, v10, v10
	v_mul_f32_e64 v5, v11, v11
	v_mov_b32_e32 v67, v85
	v_fma_f32 v4, v12, v12, v4
	v_fma_f32 v5, v13, v13, v5
	v_add_f32_e64 v14, v14, v66
	v_add_f32_e64 v15, v15, v67
	v_lshlrev_b32_e32 v9, 16, v3
	v_add_f32_e64 v4, v4, v14
	v_add_f32_e64 v5, v5, v15
	v_pk_mov_b32 v[14:15], v[6:7], v[2:3] op_sel:[1,0]
	v_lshlrev_b32_e32 v67, 16, v2
	v_and_b32_e32 v15, 0xffff0000, v15
	v_and_b32_e32 v14, 0xffff0000, v14
	v_lshlrev_b32_e32 v66, 16, v7
	v_mul_f32_e64 v6, v14, v14
	v_mul_f32_e64 v7, v15, v15
	v_mul_f32_e32 v8, v84, v84
	v_mul_f32_e32 v86, v83, v83
	v_fma_f32 v6, v66, v66, v6
	v_fma_f32 v7, v67, v67, v7
	v_mov_b32_e32 v87, v9
	v_and_b32_e32 v80, 0xffff0000, v3
	v_add_f32_e64 v4, v6, v4
	v_add_f32_e64 v5, v7, v5
	v_add_f32_e64 v6, v8, v86
	v_add_f32_e64 v7, v9, v87
	v_mul_f32_e64 v86, v8, v8
	v_mul_f32_e64 v87, v9, v9
	v_mul_f32_e32 v79, v80, v80
	v_mov_b32_e32 v7, v87
	v_add_f32_e64 v6, v6, v78
	v_add_f32_e64 v7, v7, v79
	v_mad_i64_i32 v[78:79], s[2:3], v88, s63, v[38:39]
	v_add_f32_e64 v4, v6, v4
	v_add_f32_e64 v5, v7, v5
	s_mov_b32 s2, 0x1ffff
	v_add_f32_e32 v4, v4, v5
	v_mov_b32_e32 v5, v248
	v_cmp_lt_i32_e64 s[2:3], s2, v49
	v_lshlrev_b32_e32 v5, 2, v5
	v_xor_b32_e32 v5, 4, v5
	ds_bpermute_b32 v5, v5, v4
	s_or_b64 s[8:9], s[2:3], s[8:9]
	s_waitcnt lgkmcnt(0)
	v_add_f32_e32 v4, v4, v5
	v_mov_b32_e32 v5, v248
	s_nop 0
	v_lshlrev_b32_e32 v5, 2, v5
	v_xor_b32_e32 v5, 8, v5
	ds_bpermute_b32 v5, v5, v4
	s_waitcnt lgkmcnt(0)
	v_add_f32_e32 v4, v4, v5
	v_fmamk_f32 v4, v4, 0x3c2aaaab, v249
	v_rsq_f32_e32 v8, v4
	global_load_dwordx4 v[4:7], v[40:41], off offset:16
	global_load_dwordx4 v[86:89], v[40:41], off
	v_mul_f32_e32 v73, v8, v73
	v_mul_f32_e32 v75, v8, v75
	v_mul_f32_e32 v72, v8, v72
	v_mul_f32_e32 v70, v8, v70
	v_mul_f32_e32 v71, v8, v71
	v_mul_f32_e32 v12, v8, v12
	v_mul_f32_e32 v68, v8, v68
	v_mul_f32_e32 v69, v8, v69
	v_mul_f32_e32 v10, v8, v10
	s_waitcnt vmcnt(1)
	v_mul_f32_e32 v5, v5, v72
	s_waitcnt vmcnt(0)
	v_mul_f32_e32 v73, v87, v73
	v_mul_f32_e32 v75, v86, v75
	v_cvt_pk_bf16_f32 v86, v75, v73
	v_mul_f32_e32 v73, v8, v76
	v_mul_f32_e32 v73, v88, v73
	v_mul_f32_e32 v75, v8, v77
	v_mul_f32_e32 v75, v89, v75
	v_cvt_pk_bf16_f32 v87, v73, v75
	v_mul_f32_e32 v73, v8, v74
	v_mul_f32_e32 v4, v4, v73
	v_cvt_pk_bf16_f32 v88, v4, v5
	v_mul_f32_e32 v4, v8, v84
	v_mul_f32_e32 v5, v8, v83
	v_mul_f32_e32 v4, v6, v4
	v_mul_f32_e32 v5, v7, v5
	v_cvt_pk_bf16_f32 v89, v4, v5
	global_store_dwordx4 v[78:79], v[86:89], off
	global_load_dwordx4 v[4:7], v[40:41], off offset:144
	global_load_dwordx4 v[72:75], v[40:41], off offset:128
	s_waitcnt vmcnt(1)
	v_mul_f32_e32 v4, v12, v4
	s_waitcnt vmcnt(0)
	v_mul_f32_e32 v70, v70, v72
	v_mul_f32_e32 v71, v71, v73
	v_cvt_pk_bf16_f32 v70, v70, v71
	v_mul_f32_e32 v68, v68, v74
	v_mul_f32_e32 v69, v69, v75
	v_cvt_pk_bf16_f32 v71, v68, v69
	v_mul_f32_e32 v5, v10, v5
	v_cvt_pk_bf16_f32 v72, v4, v5
	v_mul_f32_e32 v4, v8, v66
	v_mul_f32_e32 v4, v4, v6
	v_mul_f32_e32 v5, v8, v14
	v_mul_f32_e32 v5, v5, v7
	v_cvt_pk_bf16_f32 v73, v4, v5
	v_mov_b32_e32 v4, v248
	global_store_dwordx4 v[78:79], v[70:73], off offset:64
	v_mul_f32_e32 v10, v8, v13
	v_lshlrev_b32_e32 v4, 2, v4
	v_xor_b32_e32 v4, 8, v4
	ds_bpermute_b32 v76, v4, v0
	v_mov_b32_e32 v0, v248
	s_nop 0
	v_lshlrev_b32_e32 v0, 2, v0
	v_xor_b32_e32 v0, 8, v0
	ds_bpermute_b32 v77, v0, v1
	v_mov_b32_e32 v0, v248
	s_nop 0
	v_lshlrev_b32_e32 v0, 2, v0
	v_xor_b32_e32 v0, 8, v0
	ds_bpermute_b32 v83, v0, v2
	v_mov_b32_e32 v0, v248
	s_nop 0
	v_lshlrev_b32_e32 v0, 2, v0
	v_xor_b32_e32 v0, 8, v0
	ds_bpermute_b32 v84, v0, v3
	global_load_dwordx4 v[0:3], v[40:41], off offset:272
	global_load_dwordx4 v[4:7], v[40:41], off offset:256
	global_load_dwordx4 v[68:71], v[42:43], off offset:272
	global_load_dwordx4 v[72:75], v[42:43], off offset:256
	s_waitcnt vmcnt(2)
	v_mul_f32_e32 v4, v10, v4
	v_mul_f32_e32 v10, v8, v11
	v_mul_f32_e32 v10, v10, v5
	v_mul_f32_e32 v5, v8, v81
	v_mul_f32_e32 v6, v5, v6
	v_mul_f32_e32 v5, v8, v82
	v_mul_f32_e32 v12, v5, v7
	v_mul_f32_e32 v5, v8, v67
	v_mul_f32_e32 v0, v5, v0
	v_mul_f32_e32 v5, v8, v15
	v_mul_f32_e32 v14, v5, v1
	s_waitcnt lgkmcnt(2)
	v_lshlrev_b32_e32 v5, 16, v77
	v_mul_f32_e32 v5, v8, v5
	s_waitcnt vmcnt(0)
	v_mul_f32_e32 v7, v5, v74
	v_and_b32_e32 v5, 0xffff0000, v77
	v_mul_f32_e32 v5, v8, v5
	v_mul_f32_e32 v1, v8, v9
	v_mul_f32_e32 v9, v5, v75
	s_waitcnt lgkmcnt(1)
	v_lshlrev_b32_e32 v5, 16, v83
	v_mul_f32_e32 v5, v8, v5
	v_mul_f32_e32 v15, v5, v68
	v_and_b32_e32 v5, 0xffff0000, v83
	v_mul_f32_e32 v5, v8, v5
	v_mul_f32_e32 v2, v1, v2
	v_mul_f32_e32 v1, v8, v80
	v_mul_f32_e32 v67, v5, v69
	s_waitcnt lgkmcnt(0)
	v_lshlrev_b32_e32 v5, 16, v84
	v_mul_f32_e32 v66, v1, v3
	v_lshlrev_b32_e32 v1, 16, v76
	v_mul_f32_e32 v5, v8, v5
	v_mul_f32_e32 v1, v8, v1
	v_and_b32_e32 v3, 0xffff0000, v76
	v_mul_f32_e32 v68, v5, v70
	v_and_b32_e32 v5, 0xffff0000, v84
	v_mul_f32_e32 v1, v1, v72
	v_mul_f32_e32 v3, v8, v3
	v_mul_f32_e32 v5, v8, v5
	v_mul_f32_e32 v3, v3, v73
	v_mul_f32_e32 v8, v5, v71
	v_cndmask_b32_e64 v5, v1, -v1, vcc
	v_mul_f32_e64 v4, v50, v4
	v_mul_f32_e64 v5, v51, v5
	v_cndmask_b32_e64 v11, v3, -v3, vcc
	v_add_f32_e32 v50, v4, v5
	v_mul_f32_e64 v4, v52, v10
	v_mul_f32_e64 v5, v53, v11
	v_cndmask_b32_e64 v7, v7, -v7, vcc
	v_add_f32_e32 v10, v4, v5
	v_mul_f32_e64 v4, v54, v6
	v_mul_f32_e64 v5, v55, v7
	v_cndmask_b32_e64 v13, v9, -v9, vcc
	v_cndmask_b32_e64 v1, v15, -v15, vcc
	v_add_f32_e32 v6, v4, v5
	v_mul_f32_e64 v4, v56, v12
	v_mul_f32_e64 v5, v57, v13
	v_mul_f32_e64 v0, v58, v0
	v_mul_f32_e64 v1, v59, v1
	v_cndmask_b32_e64 v15, v67, -v67, vcc
	v_add_f32_e32 v4, v4, v5
	v_add_f32_e32 v5, v0, v1
	v_mul_f32_e64 v0, v60, v14
	v_mul_f32_e64 v1, v61, v15
	v_cndmask_b32_e64 v3, v68, -v68, vcc
	v_add_f32_e32 v7, v0, v1
	v_mul_f32_e64 v0, v62, v2
	v_mul_f32_e64 v1, v63, v3
	v_cndmask_b32_e64 v67, v8, -v8, vcc
	v_add_f32_e32 v3, v0, v1
	v_mul_f32_e64 v0, v64, v66
	v_mul_f32_e64 v1, v65, v67
	s_nop 0
	v_add_f32_e32 v8, v0, v1
	v_cvt_pk_bf16_f32 v0, v50, v10
	v_cvt_pk_bf16_f32 v1, v6, v4
	v_cvt_pk_bf16_f32 v2, v5, v7
	v_cvt_pk_bf16_f32 v3, v3, v8
	global_store_dwordx4 v[78:79], v[0:3], off offset:128
	s_andn2_b64 exec, exec, s[8:9]
	s_cbranch_execnz .LBB0_972

.LBB0_1070:
	ds_read_b128 v[164:167], v198 offset:39936
	ds_read_b128 v[156:159], v198 offset:39968
	ds_read_b128 v[160:163], v198 offset:44544
	ds_read_b128 v[152:155], v198 offset:44576
	ds_read_b128 v[148:151], v198 offset:40000
	ds_read_b128 v[140:143], v198 offset:40032
	s_waitcnt lgkmcnt(6)
	ds_read_b128 v[144:147], v198 offset:44608
	ds_read_b128 v[136:139], v198 offset:44640
	v_exp_f32_e32 v177, v48
	v_exp_f32_e32 v176, v32
	v_exp_f32_e32 v179, v49
	v_exp_f32_e32 v178, v33
	v_exp_f32_e32 v181, v50
	v_exp_f32_e32 v180, v34
	v_exp_f32_e32 v183, v51
	v_exp_f32_e32 v182, v35
	v_exp_f32_e32 v52, v52
	v_exp_f32_e32 v36, v36
	v_add_f32_e64 v32, v176, 0
	v_add_f32_e64 v33, v177, 0
	v_exp_f32_e32 v53, v53
	v_exp_f32_e32 v37, v37
	v_add_f32_e64 v32, v178, v32
	v_add_f32_e64 v33, v179, v33
	v_exp_f32_e32 v54, v54
	v_exp_f32_e32 v38, v38
	v_add_f32_e64 v32, v180, v32
	v_add_f32_e64 v33, v181, v33
	v_exp_f32_e32 v55, v55
	v_exp_f32_e32 v39, v39
	v_add_f32_e64 v186, v182, v32
	v_add_f32_e64 v187, v183, v33
	v_exp_f32_e32 v56, v56
	v_exp_f32_e32 v40, v40
	v_mov_b32_e32 v188, v36
	v_mov_b32_e32 v189, v52
	v_exp_f32_e32 v57, v57
	v_exp_f32_e32 v41, v41
	v_add_f32_e64 v186, v188, v186
	v_add_f32_e64 v187, v189, v187
	v_mov_b32_e32 v188, v37
	v_mov_b32_e32 v189, v53
	v_exp_f32_e32 v58, v58
	v_exp_f32_e32 v42, v42
	v_add_f32_e64 v186, v188, v186
	v_add_f32_e64 v187, v189, v187
	v_mov_b32_e32 v188, v38
	v_mov_b32_e32 v189, v54
	v_exp_f32_e32 v59, v59
	v_exp_f32_e32 v43, v43
	v_add_f32_e64 v186, v188, v186
	v_add_f32_e64 v187, v189, v187
	v_mov_b32_e32 v188, v39
	v_mov_b32_e32 v189, v55
	v_exp_f32_e32 v60, v60
	v_exp_f32_e32 v44, v44
	v_add_f32_e64 v186, v188, v186
	v_add_f32_e64 v187, v189, v187
	v_mov_b32_e32 v188, v40
	v_mov_b32_e32 v189, v56
	v_exp_f32_e32 v61, v61
	v_exp_f32_e32 v45, v45
	v_add_f32_e64 v186, v188, v186
	v_add_f32_e64 v187, v189, v187
	v_mov_b32_e32 v188, v41
	v_mov_b32_e32 v189, v57
	v_exp_f32_e32 v62, v62
	v_exp_f32_e32 v46, v46
	v_add_f32_e64 v186, v188, v186
	v_add_f32_e64 v187, v189, v187
	v_mov_b32_e32 v188, v42
	v_mov_b32_e32 v189, v58
	v_exp_f32_e32 v63, v63
	v_exp_f32_e32 v47, v47
	v_add_f32_e64 v186, v188, v186
	v_add_f32_e64 v187, v189, v187
	v_mov_b32_e32 v188, v43
	v_mov_b32_e32 v189, v59
	v_add_f32_e64 v186, v188, v186
	v_add_f32_e64 v187, v189, v187
	v_mov_b32_e32 v188, v44
	v_mov_b32_e32 v189, v60
	v_add_f32_e64 v186, v188, v186
	v_add_f32_e64 v187, v189, v187
	v_mov_b32_e32 v188, v45
	v_mov_b32_e32 v189, v61
	v_add_f32_e64 v186, v188, v186
	v_add_f32_e64 v187, v189, v187
	v_mov_b32_e32 v188, v46
	v_mov_b32_e32 v189, v62
	v_add_f32_e64 v186, v188, v186
	v_add_f32_e64 v187, v189, v187
	v_mov_b32_e32 v188, v47
	v_mov_b32_e32 v189, v63
	v_add_f32_e64 v186, v188, v186
	v_add_f32_e64 v187, v189, v187
	v_mov_b32_e32 v48, v177
	v_add_f32_e32 v186, v186, v187
	v_add_f32_e32 v199, v199, v186
	v_cvt_pk_bf16_f32 v186, v177, v179
	v_cvt_pk_bf16_f32 v187, v181, v183
	v_cvt_pk_bf16_f32 v188, v52, v53
	v_cvt_pk_bf16_f32 v189, v54, v55
	v_mov_b32_e32 v49, v179
	s_waitcnt lgkmcnt(7)
	v_mfma_f32_32x32x16_bf16 v[16:31], v[186:189], v[164:167], v[16:31]
	v_mov_b32_e32 v50, v181
	v_mov_b32_e32 v51, v183
	v_mov_b32_e32 v32, v176
	v_mov_b32_e32 v33, v178
	v_mov_b32_e32 v34, v180
	v_mov_b32_e32 v35, v182
	s_waitcnt lgkmcnt(5)
	v_mfma_f32_32x32x16_bf16 v[0:15], v[186:189], v[160:163], v[0:15]
	v_cvt_pk_bf16_f32 v160, v56, v57
	v_cvt_pk_bf16_f32 v161, v58, v59
	v_cvt_pk_bf16_f32 v162, v60, v61
	v_cvt_pk_bf16_f32 v163, v62, v63
	s_nop 0
	v_mfma_f32_32x32x16_bf16 v[16:31], v[160:163], v[156:159], v[16:31]
	s_waitcnt lgkmcnt(4)
	v_mfma_f32_32x32x16_bf16 v[0:15], v[160:163], v[152:155], v[0:15]
	v_cvt_pk_bf16_f32 v152, v176, v178
	v_cvt_pk_bf16_f32 v153, v180, v182
	v_cvt_pk_bf16_f32 v154, v36, v37
	v_cvt_pk_bf16_f32 v155, v38, v39
	s_waitcnt lgkmcnt(3)
	v_mfma_f32_32x32x16_bf16 v[16:31], v[152:155], v[148:151], v[16:31]
	s_waitcnt lgkmcnt(1)
	v_mfma_f32_32x32x16_bf16 v[0:15], v[152:155], v[144:147], v[0:15]
	v_cvt_pk_bf16_f32 v144, v40, v41
	v_cvt_pk_bf16_f32 v145, v42, v43
	v_cvt_pk_bf16_f32 v146, v44, v45
	v_cvt_pk_bf16_f32 v147, v46, v47
	s_nop 0
	v_mfma_f32_32x32x16_bf16 v[16:31], v[144:147], v[140:143], v[16:31]
	s_waitcnt lgkmcnt(0)
	v_mfma_f32_32x32x16_bf16 v[0:15], v[144:147], v[136:139], v[0:15]

.LBB0_1090:
	ds_read_b128 v[164:167], v198 offset:49152
	ds_read_b128 v[156:159], v198 offset:49184
	ds_read_b128 v[160:163], v198 offset:53760
	ds_read_b128 v[152:155], v198 offset:53792
	ds_read_b128 v[148:151], v198 offset:49216
	ds_read_b128 v[140:143], v198 offset:49248
	ds_read_b128 v[144:147], v198 offset:53824
	ds_read_b128 v[136:139], v198 offset:53856
	v_exp_f32_e32 v172, v64
	v_exp_f32_e32 v173, v80
	v_exp_f32_e32 v174, v65
	v_exp_f32_e32 v175, v81
	v_exp_f32_e32 v176, v66
	v_exp_f32_e32 v177, v82
	v_exp_f32_e32 v178, v67
	v_exp_f32_e32 v179, v83
	v_exp_f32_e32 v68, v68
	v_exp_f32_e32 v84, v84
	v_add_f32_e64 v64, v172, 0
	v_add_f32_e64 v65, v173, 0
	v_exp_f32_e32 v69, v69
	v_exp_f32_e32 v85, v85
	v_add_f32_e64 v64, v174, v64
	v_add_f32_e64 v65, v175, v65
	v_exp_f32_e32 v70, v70
	v_exp_f32_e32 v86, v86
	v_add_f32_e64 v64, v176, v64
	v_add_f32_e64 v65, v177, v65
	v_exp_f32_e32 v71, v71
	v_exp_f32_e32 v87, v87
	v_add_f32_e64 v180, v178, v64
	v_add_f32_e64 v181, v179, v65
	v_exp_f32_e32 v72, v72
	v_exp_f32_e32 v88, v88
	v_mov_b32_e32 v182, v68
	v_mov_b32_e32 v183, v84
	v_exp_f32_e32 v73, v73
	v_exp_f32_e32 v89, v89
	v_add_f32_e64 v180, v182, v180
	v_add_f32_e64 v181, v183, v181
	v_mov_b32_e32 v182, v69
	v_mov_b32_e32 v183, v85
	v_exp_f32_e32 v74, v74
	v_exp_f32_e32 v90, v90
	v_add_f32_e64 v180, v182, v180
	v_add_f32_e64 v181, v183, v181
	v_mov_b32_e32 v182, v70
	v_mov_b32_e32 v183, v86
	v_exp_f32_e32 v75, v75
	v_exp_f32_e32 v91, v91
	v_add_f32_e64 v180, v182, v180
	v_add_f32_e64 v181, v183, v181
	v_mov_b32_e32 v182, v71
	v_mov_b32_e32 v183, v87
	v_exp_f32_e32 v76, v76
	v_exp_f32_e32 v92, v92
	v_add_f32_e64 v180, v182, v180
	v_add_f32_e64 v181, v183, v181
	v_mov_b32_e32 v182, v72
	v_mov_b32_e32 v183, v88
	v_exp_f32_e32 v77, v77
	v_exp_f32_e32 v93, v93
	v_add_f32_e64 v180, v182, v180
	v_add_f32_e64 v181, v183, v181
	v_mov_b32_e32 v182, v73
	v_mov_b32_e32 v183, v89
	v_exp_f32_e32 v78, v78
	v_exp_f32_e32 v94, v94
	v_add_f32_e64 v180, v182, v180
	v_add_f32_e64 v181, v183, v181
	v_mov_b32_e32 v182, v74
	v_mov_b32_e32 v183, v90
	v_exp_f32_e32 v79, v79
	v_exp_f32_e32 v95, v95
	v_add_f32_e64 v180, v182, v180
	v_add_f32_e64 v181, v183, v181
	v_mov_b32_e32 v182, v75
	v_mov_b32_e32 v183, v91
	v_add_f32_e64 v180, v182, v180
	v_add_f32_e64 v181, v183, v181
	v_mov_b32_e32 v182, v76
	v_mov_b32_e32 v183, v92
	v_add_f32_e64 v180, v182, v180
	v_add_f32_e64 v181, v183, v181
	v_mov_b32_e32 v182, v77
	v_mov_b32_e32 v183, v93
	v_add_f32_e64 v180, v182, v180
	v_add_f32_e64 v181, v183, v181
	v_mov_b32_e32 v182, v78
	v_mov_b32_e32 v183, v94
	v_add_f32_e64 v180, v182, v180
	v_add_f32_e64 v181, v183, v181
	v_mov_b32_e32 v182, v79
	v_mov_b32_e32 v183, v95
	v_add_f32_e64 v180, v182, v180
	v_add_f32_e64 v181, v183, v181
	v_mov_b32_e32 v64, v172
	v_add_f32_e32 v180, v180, v181
	v_add_f32_e32 v199, v199, v180
	v_cvt_pk_bf16_f32 v180, v172, v174
	v_cvt_pk_bf16_f32 v181, v176, v178
	v_cvt_pk_bf16_f32 v182, v68, v69
	v_cvt_pk_bf16_f32 v183, v70, v71
	v_mov_b32_e32 v65, v174
	s_waitcnt lgkmcnt(7)
	v_mfma_f32_32x32x16_bf16 v[16:31], v[180:183], v[164:167], v[16:31]
	v_mov_b32_e32 v66, v176
	v_mov_b32_e32 v67, v178
	v_mov_b32_e32 v80, v173
	v_mov_b32_e32 v81, v175
	v_mov_b32_e32 v82, v177
	v_mov_b32_e32 v83, v179
	s_waitcnt lgkmcnt(5)
	v_mfma_f32_32x32x16_bf16 v[0:15], v[180:183], v[160:163], v[0:15]
	v_cvt_pk_bf16_f32 v160, v72, v73
	v_cvt_pk_bf16_f32 v161, v74, v75
	v_cvt_pk_bf16_f32 v162, v76, v77
	v_cvt_pk_bf16_f32 v163, v78, v79
	s_nop 0
	v_mfma_f32_32x32x16_bf16 v[16:31], v[160:163], v[156:159], v[16:31]
	s_waitcnt lgkmcnt(4)
	v_mfma_f32_32x32x16_bf16 v[0:15], v[160:163], v[152:155], v[0:15]
	v_cvt_pk_bf16_f32 v152, v173, v175
	v_cvt_pk_bf16_f32 v153, v177, v179
	v_cvt_pk_bf16_f32 v154, v84, v85
	v_cvt_pk_bf16_f32 v155, v86, v87
	s_waitcnt lgkmcnt(3)
	v_mfma_f32_32x32x16_bf16 v[16:31], v[152:155], v[148:151], v[16:31]
	s_waitcnt lgkmcnt(1)
	v_mfma_f32_32x32x16_bf16 v[0:15], v[152:155], v[144:147], v[0:15]
	v_cvt_pk_bf16_f32 v144, v88, v89
	v_cvt_pk_bf16_f32 v145, v90, v91
	v_cvt_pk_bf16_f32 v146, v92, v93
	v_cvt_pk_bf16_f32 v147, v94, v95
	s_nop 0
	v_mfma_f32_32x32x16_bf16 v[16:31], v[144:147], v[140:143], v[16:31]
	s_waitcnt lgkmcnt(0)
	v_mfma_f32_32x32x16_bf16 v[0:15], v[144:147], v[136:139], v[0:15]

.LBB0_1136:
	v_add_u32_e32 v136, v208, v184
	ds_read_b128 v[164:167], v136 offset:39936
	ds_read_b128 v[156:159], v136 offset:39968
	ds_read_b128 v[160:163], v136 offset:44544
	ds_read_b128 v[152:155], v136 offset:44576
	ds_read_b128 v[148:151], v136 offset:40000
	ds_read_b128 v[140:143], v136 offset:40032
	s_waitcnt lgkmcnt(6)
	ds_read_b128 v[144:147], v136 offset:44608
	ds_read_b128 v[136:139], v136 offset:44640
	v_exp_f32_e32 v177, v48
	v_exp_f32_e32 v176, v32
	v_exp_f32_e32 v179, v49
	v_exp_f32_e32 v178, v33
	v_exp_f32_e32 v181, v50
	v_exp_f32_e32 v180, v34
	v_exp_f32_e32 v183, v51
	v_exp_f32_e32 v182, v35
	v_exp_f32_e32 v52, v52
	v_exp_f32_e32 v36, v36
	v_add_f32_e64 v32, v176, 0
	v_add_f32_e64 v33, v177, 0
	v_exp_f32_e32 v53, v53
	v_exp_f32_e32 v37, v37
	v_add_f32_e64 v32, v178, v32
	v_add_f32_e64 v33, v179, v33
	v_exp_f32_e32 v54, v54
	v_exp_f32_e32 v38, v38
	v_add_f32_e64 v32, v180, v32
	v_add_f32_e64 v33, v181, v33
	v_exp_f32_e32 v55, v55
	v_exp_f32_e32 v39, v39
	v_add_f32_e64 v186, v182, v32
	v_add_f32_e64 v187, v183, v33
	v_exp_f32_e32 v56, v56
	v_exp_f32_e32 v40, v40
	v_mov_b32_e32 v188, v36
	v_mov_b32_e32 v189, v52
	v_exp_f32_e32 v57, v57
	v_exp_f32_e32 v41, v41
	v_add_f32_e64 v186, v188, v186
	v_add_f32_e64 v187, v189, v187
	v_mov_b32_e32 v188, v37
	v_mov_b32_e32 v189, v53
	v_exp_f32_e32 v58, v58
	v_exp_f32_e32 v42, v42
	v_add_f32_e64 v186, v188, v186
	v_add_f32_e64 v187, v189, v187
	v_mov_b32_e32 v188, v38
	v_mov_b32_e32 v189, v54
	v_exp_f32_e32 v59, v59
	v_exp_f32_e32 v43, v43
	v_add_f32_e64 v186, v188, v186
	v_add_f32_e64 v187, v189, v187
	v_mov_b32_e32 v188, v39
	v_mov_b32_e32 v189, v55
	v_exp_f32_e32 v60, v60
	v_exp_f32_e32 v44, v44
	v_add_f32_e64 v186, v188, v186
	v_add_f32_e64 v187, v189, v187
	v_mov_b32_e32 v188, v40
	v_mov_b32_e32 v189, v56
	v_exp_f32_e32 v61, v61
	v_exp_f32_e32 v45, v45
	v_add_f32_e64 v186, v188, v186
	v_add_f32_e64 v187, v189, v187
	v_mov_b32_e32 v188, v41
	v_mov_b32_e32 v189, v57
	v_exp_f32_e32 v62, v62
	v_exp_f32_e32 v46, v46
	v_add_f32_e64 v186, v188, v186
	v_add_f32_e64 v187, v189, v187
	v_mov_b32_e32 v188, v42
	v_mov_b32_e32 v189, v58
	v_exp_f32_e32 v63, v63
	v_exp_f32_e32 v47, v47
	v_add_f32_e64 v186, v188, v186
	v_add_f32_e64 v187, v189, v187
	v_mov_b32_e32 v188, v43
	v_mov_b32_e32 v189, v59
	v_add_f32_e64 v186, v188, v186
	v_add_f32_e64 v187, v189, v187
	v_mov_b32_e32 v188, v44
	v_mov_b32_e32 v189, v60
	v_add_f32_e64 v186, v188, v186
	v_add_f32_e64 v187, v189, v187
	v_mov_b32_e32 v188, v45
	v_mov_b32_e32 v189, v61
	v_add_f32_e64 v186, v188, v186
	v_add_f32_e64 v187, v189, v187
	v_mov_b32_e32 v188, v46
	v_mov_b32_e32 v189, v62
	v_add_f32_e64 v186, v188, v186
	v_add_f32_e64 v187, v189, v187
	v_mov_b32_e32 v188, v47
	v_mov_b32_e32 v189, v63
	v_add_f32_e64 v186, v188, v186
	v_add_f32_e64 v187, v189, v187
	v_mov_b32_e32 v48, v177
	v_add_f32_e32 v186, v186, v187
	v_add_f32_e32 v198, v198, v186
	v_cvt_pk_bf16_f32 v186, v177, v179
	v_cvt_pk_bf16_f32 v187, v181, v183
	v_cvt_pk_bf16_f32 v188, v52, v53
	v_cvt_pk_bf16_f32 v189, v54, v55
	v_mov_b32_e32 v49, v179
	s_waitcnt lgkmcnt(7)
	v_mfma_f32_32x32x16_bf16 v[16:31], v[186:189], v[164:167], v[16:31]
	v_mov_b32_e32 v50, v181
	v_mov_b32_e32 v51, v183
	v_mov_b32_e32 v32, v176
	v_mov_b32_e32 v33, v178
	v_mov_b32_e32 v34, v180
	v_mov_b32_e32 v35, v182
	s_waitcnt lgkmcnt(5)
	v_mfma_f32_32x32x16_bf16 v[0:15], v[186:189], v[160:163], v[0:15]
	v_cvt_pk_bf16_f32 v160, v56, v57
	v_cvt_pk_bf16_f32 v161, v58, v59
	v_cvt_pk_bf16_f32 v162, v60, v61
	v_cvt_pk_bf16_f32 v163, v62, v63
	s_nop 0
	v_mfma_f32_32x32x16_bf16 v[16:31], v[160:163], v[156:159], v[16:31]
	s_waitcnt lgkmcnt(4)
	v_mfma_f32_32x32x16_bf16 v[0:15], v[160:163], v[152:155], v[0:15]
	v_cvt_pk_bf16_f32 v152, v176, v178
	v_cvt_pk_bf16_f32 v153, v180, v182
	v_cvt_pk_bf16_f32 v154, v36, v37
	v_cvt_pk_bf16_f32 v155, v38, v39
	s_waitcnt lgkmcnt(3)
	v_mfma_f32_32x32x16_bf16 v[16:31], v[152:155], v[148:151], v[16:31]
	s_waitcnt lgkmcnt(1)
	v_mfma_f32_32x32x16_bf16 v[0:15], v[152:155], v[144:147], v[0:15]
	v_cvt_pk_bf16_f32 v144, v40, v41
	v_cvt_pk_bf16_f32 v145, v42, v43
	v_cvt_pk_bf16_f32 v146, v44, v45
	v_cvt_pk_bf16_f32 v147, v46, v47
	s_nop 0
	v_mfma_f32_32x32x16_bf16 v[16:31], v[144:147], v[140:143], v[16:31]
	s_waitcnt lgkmcnt(0)
	v_mfma_f32_32x32x16_bf16 v[0:15], v[144:147], v[136:139], v[0:15]

.LBB0_1156:
	v_add_u32_e32 v136, v208, v184
	ds_read_b128 v[164:167], v136 offset:49152
	ds_read_b128 v[156:159], v136 offset:49184
	ds_read_b128 v[160:163], v136 offset:53760
	ds_read_b128 v[152:155], v136 offset:53792
	ds_read_b128 v[148:151], v136 offset:49216
	ds_read_b128 v[140:143], v136 offset:49248
	ds_read_b128 v[144:147], v136 offset:53824
	ds_read_b128 v[136:139], v136 offset:53856
	v_exp_f32_e32 v172, v64
	v_exp_f32_e32 v173, v80
	v_exp_f32_e32 v174, v65
	v_exp_f32_e32 v175, v81
	v_exp_f32_e32 v176, v66
	v_exp_f32_e32 v177, v82
	v_exp_f32_e32 v178, v67
	v_exp_f32_e32 v179, v83
	v_exp_f32_e32 v68, v68
	v_exp_f32_e32 v84, v84
	v_add_f32_e64 v64, v172, 0
	v_add_f32_e64 v65, v173, 0
	v_exp_f32_e32 v69, v69
	v_exp_f32_e32 v85, v85
	v_add_f32_e64 v64, v174, v64
	v_add_f32_e64 v65, v175, v65
	v_exp_f32_e32 v70, v70
	v_exp_f32_e32 v86, v86
	v_add_f32_e64 v64, v176, v64
	v_add_f32_e64 v65, v177, v65
	v_exp_f32_e32 v71, v71
	v_exp_f32_e32 v87, v87
	v_add_f32_e64 v180, v178, v64
	v_add_f32_e64 v181, v179, v65
	v_exp_f32_e32 v72, v72
	v_exp_f32_e32 v88, v88
	v_mov_b32_e32 v182, v68
	v_mov_b32_e32 v183, v84
	v_exp_f32_e32 v73, v73
	v_exp_f32_e32 v89, v89
	v_add_f32_e64 v180, v182, v180
	v_add_f32_e64 v181, v183, v181
	v_mov_b32_e32 v182, v69
	v_mov_b32_e32 v183, v85
	v_exp_f32_e32 v74, v74
	v_exp_f32_e32 v90, v90
	v_add_f32_e64 v180, v182, v180
	v_add_f32_e64 v181, v183, v181
	v_mov_b32_e32 v182, v70
	v_mov_b32_e32 v183, v86
	v_exp_f32_e32 v75, v75
	v_exp_f32_e32 v91, v91
	v_add_f32_e64 v180, v182, v180
	v_add_f32_e64 v181, v183, v181
	v_mov_b32_e32 v182, v71
	v_mov_b32_e32 v183, v87
	v_exp_f32_e32 v76, v76
	v_exp_f32_e32 v92, v92
	v_add_f32_e64 v180, v182, v180
	v_add_f32_e64 v181, v183, v181
	v_mov_b32_e32 v182, v72
	v_mov_b32_e32 v183, v88
	v_exp_f32_e32 v77, v77
	v_exp_f32_e32 v93, v93
	v_add_f32_e64 v180, v182, v180
	v_add_f32_e64 v181, v183, v181
	v_mov_b32_e32 v182, v73
	v_mov_b32_e32 v183, v89
	v_exp_f32_e32 v78, v78
	v_exp_f32_e32 v94, v94
	v_add_f32_e64 v180, v182, v180
	v_add_f32_e64 v181, v183, v181
	v_mov_b32_e32 v182, v74
	v_mov_b32_e32 v183, v90
	v_exp_f32_e32 v79, v79
	v_exp_f32_e32 v95, v95
	v_add_f32_e64 v180, v182, v180
	v_add_f32_e64 v181, v183, v181
	v_mov_b32_e32 v182, v75
	v_mov_b32_e32 v183, v91
	v_add_f32_e64 v180, v182, v180
	v_add_f32_e64 v181, v183, v181
	v_mov_b32_e32 v182, v76
	v_mov_b32_e32 v183, v92
	v_add_f32_e64 v180, v182, v180
	v_add_f32_e64 v181, v183, v181
	v_mov_b32_e32 v182, v77
	v_mov_b32_e32 v183, v93
	v_add_f32_e64 v180, v182, v180
	v_add_f32_e64 v181, v183, v181
	v_mov_b32_e32 v182, v78
	v_mov_b32_e32 v183, v94
	v_add_f32_e64 v180, v182, v180
	v_add_f32_e64 v181, v183, v181
	v_mov_b32_e32 v182, v79
	v_mov_b32_e32 v183, v95
	v_add_f32_e64 v180, v182, v180
	v_add_f32_e64 v181, v183, v181
	v_mov_b32_e32 v64, v172
	v_add_f32_e32 v180, v180, v181
	v_add_f32_e32 v198, v198, v180
	v_cvt_pk_bf16_f32 v180, v172, v174
	v_cvt_pk_bf16_f32 v181, v176, v178
	v_cvt_pk_bf16_f32 v182, v68, v69
	v_cvt_pk_bf16_f32 v183, v70, v71
	v_mov_b32_e32 v65, v174
	s_waitcnt lgkmcnt(7)
	v_mfma_f32_32x32x16_bf16 v[16:31], v[180:183], v[164:167], v[16:31]
	v_mov_b32_e32 v66, v176
	v_mov_b32_e32 v67, v178
	v_mov_b32_e32 v80, v173
	v_mov_b32_e32 v81, v175
	v_mov_b32_e32 v82, v177
	v_mov_b32_e32 v83, v179
	s_waitcnt lgkmcnt(5)
	v_mfma_f32_32x32x16_bf16 v[0:15], v[180:183], v[160:163], v[0:15]
	v_cvt_pk_bf16_f32 v160, v72, v73
	v_cvt_pk_bf16_f32 v161, v74, v75
	v_cvt_pk_bf16_f32 v162, v76, v77
	v_cvt_pk_bf16_f32 v163, v78, v79
	s_nop 0
	v_mfma_f32_32x32x16_bf16 v[16:31], v[160:163], v[156:159], v[16:31]
	s_waitcnt lgkmcnt(4)
	v_mfma_f32_32x32x16_bf16 v[0:15], v[160:163], v[152:155], v[0:15]
	v_cvt_pk_bf16_f32 v152, v173, v175
	v_cvt_pk_bf16_f32 v153, v177, v179
	v_cvt_pk_bf16_f32 v154, v84, v85
	v_cvt_pk_bf16_f32 v155, v86, v87
	s_waitcnt lgkmcnt(3)
	v_mfma_f32_32x32x16_bf16 v[16:31], v[152:155], v[148:151], v[16:31]
	s_waitcnt lgkmcnt(1)
	v_mfma_f32_32x32x16_bf16 v[0:15], v[152:155], v[144:147], v[0:15]
	v_cvt_pk_bf16_f32 v144, v88, v89
	v_cvt_pk_bf16_f32 v145, v90, v91
	v_cvt_pk_bf16_f32 v146, v92, v93
	v_cvt_pk_bf16_f32 v147, v94, v95
	s_nop 0
	v_mfma_f32_32x32x16_bf16 v[16:31], v[144:147], v[140:143], v[16:31]
	s_waitcnt lgkmcnt(0)
	v_mfma_f32_32x32x16_bf16 v[0:15], v[144:147], v[136:139], v[0:15]
